# baseline (speedup 1.0000x reference)
.LBB0_65:
	ds_read_b128 v[128:131], v173
	ds_read_b128 v[132:135], v173 offset:1024
	ds_read_b128 v[158:161], v173 offset:2048
	ds_read_b128 v[178:181], v173 offset:3072
	ds_read_b128 v[182:185], v174
	ds_read_b128 v[186:189], v174 offset:1024
	ds_read_b128 v[190:193], v174 offset:2048
	ds_read_b128 v[194:197], v174 offset:3072
	s_add_u32 s3, s14, 0xfff80080
	s_addc_u32 s34, s15, -1
	s_cmp_eq_u32 s37, 28
	s_cselect_b32 s91, s0, s34
	s_cselect_b32 s90, s1, s3
	s_cselect_b32 s35, s7, s36
	s_cselect_b32 s34, s13, s24
	s_add_i32 m0, s27, 0xc000
	ds_read_b128 v[198:201], v175
	ds_read_b128 v[202:205], v175 offset:1024
	ds_read_b128 v[206:209], v175 offset:2048
	ds_read_b128 v[210:213], v175 offset:3072
	ds_read_b128 v[214:217], v175 offset:4096
	ds_read_b128 v[218:221], v175 offset:5120
	ds_read_b128 v[222:225], v175 offset:6144
	ds_read_b128 v[230:233], v175 offset:7168
	global_load_lds_dwordx4 v148, s[14:15]
	s_add_i32 m0, s27, 0xe000
	s_nop 0
	global_load_lds_dwordx4 v150, s[14:15]
	s_waitcnt vmcnt(8)
	s_waitcnt lgkmcnt(0)
	s_barrier
	s_setprio 1
	s_waitcnt lgkmcnt(0)
	v_mfma_f32_16x16x32_bf16 v[124:127], v[128:131], v[198:201], v[124:127]
	v_mfma_f32_16x16x32_bf16 v[120:123], v[158:161], v[198:201], v[120:123]
	v_mfma_f32_16x16x32_bf16 v[108:111], v[128:131], v[206:209], v[108:111]
	v_mfma_f32_16x16x32_bf16 v[104:107], v[158:161], v[206:209], v[104:107]
	v_mfma_f32_16x16x32_bf16 v[92:95], v[128:131], v[214:217], v[92:95]
	v_mfma_f32_16x16x32_bf16 v[88:91], v[158:161], v[214:217], v[88:91]
	v_mfma_f32_16x16x32_bf16 v[76:79], v[128:131], v[222:225], v[76:79]
	v_mfma_f32_16x16x32_bf16 v[72:75], v[158:161], v[222:225], v[72:75]
	v_mfma_f32_16x16x32_bf16 v[124:127], v[132:135], v[202:205], v[124:127]
	v_mfma_f32_16x16x32_bf16 v[120:123], v[178:181], v[202:205], v[120:123]
	v_mfma_f32_16x16x32_bf16 v[108:111], v[132:135], v[210:213], v[108:111]
	v_mfma_f32_16x16x32_bf16 v[104:107], v[178:181], v[210:213], v[104:107]
	v_mfma_f32_16x16x32_bf16 v[92:95], v[132:135], v[218:221], v[92:95]
	v_mfma_f32_16x16x32_bf16 v[88:91], v[178:181], v[218:221], v[88:91]
	v_mfma_f32_16x16x32_bf16 v[76:79], v[132:135], v[230:233], v[76:79]
	v_mfma_f32_16x16x32_bf16 v[72:75], v[178:181], v[230:233], v[72:75]
	s_setprio 0
	s_setprio 1
	v_mfma_f32_16x16x32_bf16 v[116:119], v[182:185], v[198:201], v[116:119]
	v_mfma_f32_16x16x32_bf16 v[112:115], v[190:193], v[198:201], v[112:115]
	v_mfma_f32_16x16x32_bf16 v[100:103], v[182:185], v[206:209], v[100:103]
	v_mfma_f32_16x16x32_bf16 v[96:99], v[190:193], v[206:209], v[96:99]
	v_mfma_f32_16x16x32_bf16 v[84:87], v[182:185], v[214:217], v[84:87]
	v_mfma_f32_16x16x32_bf16 v[80:83], v[190:193], v[214:217], v[80:83]
	v_mfma_f32_16x16x32_bf16 v[68:71], v[182:185], v[222:225], v[68:71]
	v_mfma_f32_16x16x32_bf16 v[64:67], v[190:193], v[222:225], v[64:67]
	v_mfma_f32_16x16x32_bf16 v[116:119], v[186:189], v[202:205], v[116:119]
	v_mfma_f32_16x16x32_bf16 v[112:115], v[194:197], v[202:205], v[112:115]
	v_mfma_f32_16x16x32_bf16 v[100:103], v[186:189], v[210:213], v[100:103]
	v_mfma_f32_16x16x32_bf16 v[96:99], v[194:197], v[210:213], v[96:99]
	v_mfma_f32_16x16x32_bf16 v[84:87], v[186:189], v[218:221], v[84:87]
	v_mfma_f32_16x16x32_bf16 v[80:83], v[194:197], v[218:221], v[80:83]
	v_mfma_f32_16x16x32_bf16 v[68:71], v[186:189], v[230:233], v[68:71]
	v_mfma_f32_16x16x32_bf16 v[64:67], v[194:197], v[230:233], v[64:67]
	s_setprio 0
	s_barrier
	s_add_i32 s3, s78, s25
	s_mov_b32 m0, s3
	ds_read_b128 v[198:201], v175 offset:16384
	ds_read_b128 v[202:205], v175 offset:17408
	ds_read_b128 v[206:209], v175 offset:18432
	ds_read_b128 v[210:213], v175 offset:19456
	ds_read_b128 v[214:217], v175 offset:20480
	ds_read_b128 v[218:221], v175 offset:21504
	ds_read_b128 v[222:225], v175 offset:22528
	ds_read_b128 v[230:233], v175 offset:23552
	global_load_lds_dwordx4 v138, s[34:35]
	s_add_i32 m0, s3, 0x2000
	s_add_u32 s42, s34, 0x80000
	s_addc_u32 s43, s35, 0
	s_add_i32 s3, s79, s25
	global_load_lds_dwordx4 v142, s[34:35]
	s_mov_b32 m0, s3
	s_nop 0
	global_load_lds_dwordx4 v138, s[42:43]
	s_add_i32 m0, s3, 0x2000
	s_nop 0
	global_load_lds_dwordx4 v142, s[42:43]
	s_mov_b32 m0, s27
	s_nop 0
	global_load_lds_dwordx4 v136, s[90:91]
	s_mov_b32 m0, s30
	s_nop 0
	global_load_lds_dwordx4 v140, s[90:91]
	s_waitcnt vmcnt(8)
	s_waitcnt lgkmcnt(0)
	s_barrier
	s_setprio 1
	s_waitcnt lgkmcnt(0)
	v_mfma_f32_16x16x32_bf16 v[60:63], v[128:131], v[198:201], v[60:63]
	v_mfma_f32_16x16x32_bf16 v[56:59], v[158:161], v[198:201], v[56:59]
	v_mfma_f32_16x16x32_bf16 v[44:47], v[128:131], v[206:209], v[44:47]
	v_mfma_f32_16x16x32_bf16 v[40:43], v[158:161], v[206:209], v[40:43]
	v_mfma_f32_16x16x32_bf16 v[28:31], v[128:131], v[214:217], v[28:31]
	v_mfma_f32_16x16x32_bf16 v[24:27], v[158:161], v[214:217], v[24:27]
	v_mfma_f32_16x16x32_bf16 v[12:15], v[128:131], v[222:225], v[12:15]
	v_mfma_f32_16x16x32_bf16 v[8:11], v[158:161], v[222:225], v[8:11]
	v_mfma_f32_16x16x32_bf16 v[60:63], v[132:135], v[202:205], v[60:63]
	v_mfma_f32_16x16x32_bf16 v[56:59], v[178:181], v[202:205], v[56:59]
	v_mfma_f32_16x16x32_bf16 v[44:47], v[132:135], v[210:213], v[44:47]
	v_mfma_f32_16x16x32_bf16 v[40:43], v[178:181], v[210:213], v[40:43]
	v_mfma_f32_16x16x32_bf16 v[28:31], v[132:135], v[218:221], v[28:31]
	v_mfma_f32_16x16x32_bf16 v[24:27], v[178:181], v[218:221], v[24:27]
	v_mfma_f32_16x16x32_bf16 v[12:15], v[132:135], v[230:233], v[12:15]
	v_mfma_f32_16x16x32_bf16 v[8:11], v[178:181], v[230:233], v[8:11]
	s_setprio 0
	s_setprio 1
	v_mfma_f32_16x16x32_bf16 v[52:55], v[182:185], v[198:201], v[52:55]
	v_mfma_f32_16x16x32_bf16 v[48:51], v[190:193], v[198:201], v[48:51]
	v_mfma_f32_16x16x32_bf16 v[36:39], v[182:185], v[206:209], v[36:39]
	v_mfma_f32_16x16x32_bf16 v[32:35], v[190:193], v[206:209], v[32:35]
	v_mfma_f32_16x16x32_bf16 v[20:23], v[182:185], v[214:217], v[20:23]
	v_mfma_f32_16x16x32_bf16 v[16:19], v[190:193], v[214:217], v[16:19]
	v_mfma_f32_16x16x32_bf16 v[4:7], v[182:185], v[222:225], v[4:7]
	v_mfma_f32_16x16x32_bf16 v[0:3], v[190:193], v[222:225], v[0:3]
	v_mfma_f32_16x16x32_bf16 v[52:55], v[186:189], v[202:205], v[52:55]
	v_mfma_f32_16x16x32_bf16 v[48:51], v[194:197], v[202:205], v[48:51]
	v_mfma_f32_16x16x32_bf16 v[36:39], v[186:189], v[210:213], v[36:39]
	v_mfma_f32_16x16x32_bf16 v[32:35], v[194:197], v[210:213], v[32:35]
	v_mfma_f32_16x16x32_bf16 v[20:23], v[186:189], v[218:221], v[20:23]
	v_mfma_f32_16x16x32_bf16 v[16:19], v[194:197], v[218:221], v[16:19]
	v_mfma_f32_16x16x32_bf16 v[4:7], v[186:189], v[230:233], v[4:7]
	v_mfma_f32_16x16x32_bf16 v[0:3], v[194:197], v[230:233], v[0:3]
	s_setprio 0
	s_barrier
	s_add_i32 s3, 0, 0x18000
	v_add_u32_e32 v144, s3, v165
	s_add_i32 s44, 0, 0x1c000
	ds_read_b128 v[128:131], v144
	ds_read_b128 v[132:135], v144 offset:1024
	ds_read_b128 v[158:161], v144 offset:2048
	ds_read_b128 v[178:181], v144 offset:3072
	v_add_u32_e32 v144, s44, v165
	ds_read_b128 v[182:185], v144
	ds_read_b128 v[186:189], v144 offset:1024
	ds_read_b128 v[190:193], v144 offset:2048
	ds_read_b128 v[194:197], v144 offset:3072
	s_add_u32 s42, s90, 0x80000
	s_addc_u32 s43, s91, 0
	s_mov_b32 m0, s31
	ds_read_b128 v[198:201], v175 offset:32768
	ds_read_b128 v[202:205], v175 offset:33792
	ds_read_b128 v[206:209], v175 offset:34816
	ds_read_b128 v[210:213], v175 offset:35840
	ds_read_b128 v[214:217], v175 offset:36864
	ds_read_b128 v[218:221], v175 offset:37888
	ds_read_b128 v[222:225], v175 offset:38912
	ds_read_b128 v[230:233], v175 offset:39936
	global_load_lds_dwordx4 v136, s[42:43]
	s_mov_b32 m0, s33
	s_nop 0
	global_load_lds_dwordx4 v140, s[42:43]
	s_waitcnt vmcnt(8)
	s_waitcnt lgkmcnt(0)
	s_barrier
	s_setprio 1
	s_waitcnt lgkmcnt(0)
	v_mfma_f32_16x16x32_bf16 v[124:127], v[128:131], v[198:201], v[124:127]
	v_mfma_f32_16x16x32_bf16 v[120:123], v[158:161], v[198:201], v[120:123]
	v_mfma_f32_16x16x32_bf16 v[108:111], v[128:131], v[206:209], v[108:111]
	v_mfma_f32_16x16x32_bf16 v[104:107], v[158:161], v[206:209], v[104:107]
	v_mfma_f32_16x16x32_bf16 v[92:95], v[128:131], v[214:217], v[92:95]
	v_mfma_f32_16x16x32_bf16 v[88:91], v[158:161], v[214:217], v[88:91]
	v_mfma_f32_16x16x32_bf16 v[76:79], v[128:131], v[222:225], v[76:79]
	v_mfma_f32_16x16x32_bf16 v[72:75], v[158:161], v[222:225], v[72:75]
	v_mfma_f32_16x16x32_bf16 v[124:127], v[132:135], v[202:205], v[124:127]
	v_mfma_f32_16x16x32_bf16 v[120:123], v[178:181], v[202:205], v[120:123]
	v_mfma_f32_16x16x32_bf16 v[108:111], v[132:135], v[210:213], v[108:111]
	v_mfma_f32_16x16x32_bf16 v[104:107], v[178:181], v[210:213], v[104:107]
	v_mfma_f32_16x16x32_bf16 v[92:95], v[132:135], v[218:221], v[92:95]
	v_mfma_f32_16x16x32_bf16 v[88:91], v[178:181], v[218:221], v[88:91]
	v_mfma_f32_16x16x32_bf16 v[76:79], v[132:135], v[230:233], v[76:79]
	v_mfma_f32_16x16x32_bf16 v[72:75], v[178:181], v[230:233], v[72:75]
	s_setprio 0
	s_setprio 1
	v_mfma_f32_16x16x32_bf16 v[116:119], v[182:185], v[198:201], v[116:119]
	v_mfma_f32_16x16x32_bf16 v[112:115], v[190:193], v[198:201], v[112:115]
	v_mfma_f32_16x16x32_bf16 v[100:103], v[182:185], v[206:209], v[100:103]
	v_mfma_f32_16x16x32_bf16 v[96:99], v[190:193], v[206:209], v[96:99]
	v_mfma_f32_16x16x32_bf16 v[84:87], v[182:185], v[214:217], v[84:87]
	v_mfma_f32_16x16x32_bf16 v[80:83], v[190:193], v[214:217], v[80:83]
	v_mfma_f32_16x16x32_bf16 v[68:71], v[182:185], v[222:225], v[68:71]
	v_mfma_f32_16x16x32_bf16 v[64:67], v[190:193], v[222:225], v[64:67]
	v_mfma_f32_16x16x32_bf16 v[116:119], v[186:189], v[202:205], v[116:119]
	v_mfma_f32_16x16x32_bf16 v[112:115], v[194:197], v[202:205], v[112:115]
	v_mfma_f32_16x16x32_bf16 v[100:103], v[186:189], v[210:213], v[100:103]
	v_mfma_f32_16x16x32_bf16 v[96:99], v[194:197], v[210:213], v[96:99]
	v_mfma_f32_16x16x32_bf16 v[84:87], v[186:189], v[218:221], v[84:87]
	v_mfma_f32_16x16x32_bf16 v[80:83], v[194:197], v[218:221], v[80:83]
	v_mfma_f32_16x16x32_bf16 v[68:71], v[186:189], v[230:233], v[68:71]
	v_mfma_f32_16x16x32_bf16 v[64:67], v[194:197], v[230:233], v[64:67]
	s_setprio 0
	s_barrier
	s_add_i32 s3, s3, s25
	s_add_u32 s34, s34, 0x80
	s_addc_u32 s35, s35, 0
	s_mov_b32 m0, s3
	ds_read_b128 v[198:201], v175 offset:49152
	ds_read_b128 v[202:205], v175 offset:50176
	ds_read_b128 v[206:209], v175 offset:51200
	ds_read_b128 v[210:213], v175 offset:52224
	ds_read_b128 v[214:217], v175 offset:53248
	ds_read_b128 v[218:221], v175 offset:54272
	ds_read_b128 v[222:225], v175 offset:55296
	ds_read_b128 v[230:233], v175 offset:56320
	global_load_lds_dwordx4 v138, s[34:35]
	s_add_i32 m0, s3, 0x2000
	s_add_i32 s3, s44, s25
	global_load_lds_dwordx4 v142, s[34:35]
	s_add_u32 s34, s34, 0x80000
	s_addc_u32 s35, s35, 0
	s_mov_b32 m0, s3
	s_nop 0
	global_load_lds_dwordx4 v138, s[34:35]
	s_add_i32 m0, s3, 0x2000
	s_nop 0
	global_load_lds_dwordx4 v142, s[34:35]
	s_add_u32 s90, s90, 0x80
	s_addc_u32 s91, s91, 0
	s_mov_b32 m0, s58
	s_nop 0
	global_load_lds_dwordx4 v136, s[90:91]
	s_mov_b32 m0, s59
	s_nop 0
	global_load_lds_dwordx4 v140, s[90:91]
	s_waitcnt vmcnt(8)
	s_waitcnt lgkmcnt(0)
	s_barrier
	s_setprio 1
	s_waitcnt lgkmcnt(0)
	v_mfma_f32_16x16x32_bf16 v[60:63], v[128:131], v[198:201], v[60:63]
	v_mfma_f32_16x16x32_bf16 v[56:59], v[158:161], v[198:201], v[56:59]
	v_mfma_f32_16x16x32_bf16 v[44:47], v[128:131], v[206:209], v[44:47]
	v_mfma_f32_16x16x32_bf16 v[40:43], v[158:161], v[206:209], v[40:43]
	v_mfma_f32_16x16x32_bf16 v[28:31], v[128:131], v[214:217], v[28:31]
	v_mfma_f32_16x16x32_bf16 v[24:27], v[158:161], v[214:217], v[24:27]
	v_mfma_f32_16x16x32_bf16 v[12:15], v[128:131], v[222:225], v[12:15]
	v_mfma_f32_16x16x32_bf16 v[8:11], v[158:161], v[222:225], v[8:11]
	v_mfma_f32_16x16x32_bf16 v[60:63], v[132:135], v[202:205], v[60:63]
	v_mfma_f32_16x16x32_bf16 v[56:59], v[178:181], v[202:205], v[56:59]
	v_mfma_f32_16x16x32_bf16 v[44:47], v[132:135], v[210:213], v[44:47]
	v_mfma_f32_16x16x32_bf16 v[40:43], v[178:181], v[210:213], v[40:43]
	v_mfma_f32_16x16x32_bf16 v[28:31], v[132:135], v[218:221], v[28:31]
	v_mfma_f32_16x16x32_bf16 v[24:27], v[178:181], v[218:221], v[24:27]
	v_mfma_f32_16x16x32_bf16 v[12:15], v[132:135], v[230:233], v[12:15]
	v_mfma_f32_16x16x32_bf16 v[8:11], v[178:181], v[230:233], v[8:11]
	s_setprio 0
	s_setprio 1
	v_mfma_f32_16x16x32_bf16 v[52:55], v[182:185], v[198:201], v[52:55]
	v_mfma_f32_16x16x32_bf16 v[48:51], v[190:193], v[198:201], v[48:51]
	v_mfma_f32_16x16x32_bf16 v[36:39], v[182:185], v[206:209], v[36:39]
	v_mfma_f32_16x16x32_bf16 v[32:35], v[190:193], v[206:209], v[32:35]
	v_mfma_f32_16x16x32_bf16 v[20:23], v[182:185], v[214:217], v[20:23]
	v_mfma_f32_16x16x32_bf16 v[16:19], v[190:193], v[214:217], v[16:19]
	v_mfma_f32_16x16x32_bf16 v[4:7], v[182:185], v[222:225], v[4:7]
	v_mfma_f32_16x16x32_bf16 v[0:3], v[190:193], v[222:225], v[0:3]
	v_mfma_f32_16x16x32_bf16 v[52:55], v[186:189], v[202:205], v[52:55]
	v_mfma_f32_16x16x32_bf16 v[48:51], v[194:197], v[202:205], v[48:51]
	v_mfma_f32_16x16x32_bf16 v[36:39], v[186:189], v[210:213], v[36:39]
	v_mfma_f32_16x16x32_bf16 v[32:35], v[194:197], v[210:213], v[32:35]
	v_mfma_f32_16x16x32_bf16 v[20:23], v[186:189], v[218:221], v[20:23]
	v_mfma_f32_16x16x32_bf16 v[16:19], v[194:197], v[218:221], v[16:19]
	v_mfma_f32_16x16x32_bf16 v[4:7], v[186:189], v[230:233], v[4:7]
	v_mfma_f32_16x16x32_bf16 v[0:3], v[194:197], v[230:233], v[0:3]
	s_setprio 0
	s_barrier
	s_add_i32 s37, s37, 2
	s_add_u32 s14, s14, 0x100
	s_addc_u32 s15, s15, 0
	s_add_u32 s24, s24, 0x100
	s_addc_u32 s36, s36, 0
	s_cmp_gt_u32 s37, 29
	s_cbranch_scc0 .LBB0_65
	s_and_b64 vcc, exec, s[48:49]
	s_cbranch_vccz .LBB0_68
	s_barrier

.LBB0_395:
	s_cmp_eq_u32 s56, 0
	s_cselect_b64 s[0:1], -1, 0
	s_or_b64 s[0:1], s[76:77], s[0:1]
	s_and_b64 vcc, exec, s[0:1]
	s_cbranch_vccnz .Lfz1_c0
	s_add_i32 s0, s86, 0xc000
	s_and_b32 s0, s0, 0xc000
	v_add_u32_e32 v0, s0, v234
	ds_read_b64_tr_b16 v[160:161], v0 offset:0x2000
	ds_read_b64_tr_b16 v[162:163], v0 offset:0x2100
	ds_read_b64_tr_b16 v[164:165], v0 offset:0x3000
	ds_read_b64_tr_b16 v[166:167], v0 offset:0x3100
	s_waitcnt lgkmcnt(2)
	v_mfma_f32_32x32x16_bf16 v[128:143], v[6:9], v[160:163], v[128:143]
	ds_read_b64_tr_b16 v[168:169], v0 offset:0x2200
	v_mfma_f32_32x32x16_bf16 v[96:111], v[2:5], v[160:163], v[96:111]
	ds_read_b64_tr_b16 v[170:171], v0 offset:0x2300
	s_waitcnt lgkmcnt(2)
	v_mfma_f32_32x32x16_bf16 v[128:143], v[208:211], v[164:167], v[128:143]
	ds_read_b64_tr_b16 v[172:173], v0 offset:0x3200
	v_mfma_f32_32x32x16_bf16 v[96:111], v[10:13], v[164:167], v[96:111]
	ds_read_b64_tr_b16 v[174:175], v0 offset:0x3300
	s_waitcnt lgkmcnt(2)
	v_mfma_f32_32x32x16_bf16 v[112:127], v[6:9], v[168:171], v[112:127]
	ds_read_b64_tr_b16 v[160:161], v0 offset:0x2400
	v_mfma_f32_32x32x16_bf16 v[80:95], v[2:5], v[168:171], v[80:95]
	ds_read_b64_tr_b16 v[162:163], v0 offset:0x2500
	s_waitcnt lgkmcnt(2)
	v_mfma_f32_32x32x16_bf16 v[112:127], v[208:211], v[172:175], v[112:127]
	ds_read_b64_tr_b16 v[164:165], v0 offset:0x3400
	v_mfma_f32_32x32x16_bf16 v[80:95], v[10:13], v[172:175], v[80:95]
	ds_read_b64_tr_b16 v[166:167], v0 offset:0x3500
	s_waitcnt lgkmcnt(2)
	v_mfma_f32_32x32x16_bf16 v[64:79], v[6:9], v[160:163], v[64:79]
	ds_read_b64_tr_b16 v[168:169], v0 offset:0x2600
	v_mfma_f32_32x32x16_bf16 v[32:47], v[2:5], v[160:163], v[32:47]
	ds_read_b64_tr_b16 v[170:171], v0 offset:0x2700
	s_waitcnt lgkmcnt(2)
	v_mfma_f32_32x32x16_bf16 v[64:79], v[208:211], v[164:167], v[64:79]
	ds_read_b64_tr_b16 v[172:173], v0 offset:0x3600
	v_mfma_f32_32x32x16_bf16 v[32:47], v[10:13], v[164:167], v[32:47]
	ds_read_b64_tr_b16 v[174:175], v0 offset:0x3700
	s_waitcnt lgkmcnt(2)
	v_mfma_f32_32x32x16_bf16 v[48:63], v[6:9], v[168:171], v[48:63]
	v_mfma_f32_32x32x16_bf16 v[16:31], v[2:5], v[168:171], v[16:31]
	s_waitcnt lgkmcnt(0)
	v_mfma_f32_32x32x16_bf16 v[48:63], v[208:211], v[172:175], v[48:63]
	v_mfma_f32_32x32x16_bf16 v[16:31], v[10:13], v[172:175], v[16:31]
.Lfz1_c0:
	s_and_b32 s27, s86, 0xc000
	v_add_u32_e32 v241, s27, v233
	ds_read_b128 v[144:147], v241 offset:0
	v_xor_b32_e32 v240, 32, v241
	ds_read_b128 v[148:151], v240 offset:0
	v_xor_b32_e32 v239, 64, v241
	ds_read_b128 v[152:155], v239 offset:0
	v_xor_b32_e32 v0, 0x60, v241
	ds_read_b128 v[156:159], v0 offset:0
	s_waitcnt lgkmcnt(0)
	v_mfma_f32_32x32x16_bf16 v[212:227], v[144:147], v[176:179], 0
	v_mfma_f32_32x32x16_bf16 v[212:227], v[148:151], v[180:183], v[212:227]
	v_mfma_f32_32x32x16_bf16 v[212:227], v[152:155], v[184:187], v[212:227]
	v_mfma_f32_32x32x16_bf16 v[212:227], v[156:159], v[188:191], v[212:227]
	ds_read_b128 v[144:147], v241 offset:0x80
	ds_read_b128 v[148:151], v240 offset:0x80
	ds_read_b128 v[152:155], v239 offset:0x80
	ds_read_b128 v[156:159], v0 offset:0x80
	v_cmp_eq_f32_e32 vcc, 0, v238
	v_cmp_eq_f32_e64 s[10:11], 0, v237
	s_and_b64 s[0:1], vcc, s[10:11]
	s_cmp_eq_u64 s[0:1], exec
	s_waitcnt lgkmcnt(0)
	v_mfma_f32_32x32x16_bf16 v[160:175], v[144:147], v[192:195], 0
	v_mfma_f32_32x32x16_bf16 v[160:175], v[148:151], v[196:199], v[160:175]
	v_mfma_f32_32x32x16_bf16 v[160:175], v[152:155], v[200:203], v[160:175]
	v_mfma_f32_32x32x16_bf16 v[160:175], v[156:159], v[204:207], v[160:175]
	s_cbranch_scc0 .LBB0_397
	v_exp_f32_e32 v144, v212
	v_exp_f32_e32 v145, v213
	v_exp_f32_e32 v146, v214
	v_exp_f32_e32 v147, v215
	v_exp_f32_e32 v148, v216
	v_exp_f32_e32 v149, v217
	v_exp_f32_e32 v150, v218
	v_exp_f32_e32 v151, v219
	v_exp_f32_e32 v152, v220
	v_exp_f32_e32 v153, v221
	v_exp_f32_e32 v154, v222
	v_exp_f32_e32 v155, v223
	v_exp_f32_e32 v156, v224
	v_exp_f32_e32 v157, v225
	v_exp_f32_e32 v158, v226
	v_exp_f32_e32 v159, v227
	v_add_f32_e32 v252, v144, v145
	v_add_f32_e32 v253, v146, v147
	v_add_f32_e32 v254, v148, v149
	v_add_f32_e32 v255, v150, v151
	v_add_f32_e32 v252, v252, v152
	v_add_f32_e32 v253, v253, v153
	v_add_f32_e32 v254, v254, v154
	v_add_f32_e32 v255, v255, v155
	v_add_f32_e32 v252, v252, v156
	v_add_f32_e32 v253, v253, v157
	v_add_f32_e32 v254, v254, v158
	v_add_f32_e32 v255, v255, v159
	v_cvt_pk_bf16_f32 v216, v144, v145
	v_cvt_pk_bf16_f32 v217, v146, v147
	v_add_f32_e32 v252, v252, v253
	v_add_f32_e32 v254, v254, v255
	v_cvt_pk_bf16_f32 v218, v148, v149
	v_cvt_pk_bf16_f32 v219, v150, v151
	v_cvt_pk_bf16_f32 v224, v152, v153
	v_add_f32_e32 v252, v252, v254
	v_cvt_pk_bf16_f32 v225, v154, v155
	v_cvt_pk_bf16_f32 v226, v156, v157
	v_cvt_pk_bf16_f32 v227, v158, v159
	v_add_u32_e32 v253, 0xde801b54, v252
	v_cmp_gt_u32_e32 vcc, 0x3bff7543, v253
	s_cmp_lg_u64 vcc, exec
	s_cbranch_scc1 .LBB0_432
	v_add_f32_e32 v15, v15, v252
	v_exp_f32_e32 v144, v160
	v_exp_f32_e32 v145, v161
	v_exp_f32_e32 v146, v162
	v_exp_f32_e32 v147, v163
	v_exp_f32_e32 v148, v164
	v_exp_f32_e32 v149, v165
	v_exp_f32_e32 v150, v166
	v_exp_f32_e32 v151, v167
	v_exp_f32_e32 v152, v168
	v_exp_f32_e32 v153, v169
	v_exp_f32_e32 v154, v170
	v_exp_f32_e32 v155, v171
	v_exp_f32_e32 v156, v172
	v_exp_f32_e32 v157, v173
	v_exp_f32_e32 v158, v174
	v_exp_f32_e32 v159, v175
	v_add_f32_e32 v252, v144, v145
	v_add_f32_e32 v253, v146, v147
	v_add_f32_e32 v254, v148, v149
	v_add_f32_e32 v255, v150, v151
	v_add_f32_e32 v252, v252, v152
	v_add_f32_e32 v253, v253, v153
	v_add_f32_e32 v254, v254, v154
	v_add_f32_e32 v255, v255, v155
	v_add_f32_e32 v252, v252, v156
	v_add_f32_e32 v253, v253, v157
	v_add_f32_e32 v254, v254, v158
	v_add_f32_e32 v255, v255, v159
	v_cvt_pk_bf16_f32 v212, v144, v145
	v_cvt_pk_bf16_f32 v213, v146, v147
	v_add_f32_e32 v252, v252, v253
	v_add_f32_e32 v254, v254, v255
	v_cvt_pk_bf16_f32 v214, v148, v149
	v_cvt_pk_bf16_f32 v215, v150, v151
	v_cvt_pk_bf16_f32 v220, v152, v153
	v_add_f32_e32 v252, v252, v254
	v_cvt_pk_bf16_f32 v221, v154, v155
	v_cvt_pk_bf16_f32 v222, v156, v157
	v_cvt_pk_bf16_f32 v223, v158, v159
	v_add_u32_e32 v253, 0xde801b54, v252
	v_cmp_gt_u32_e32 vcc, 0x3bff7543, v253
	s_cmp_lg_u64 vcc, exec
	s_cbranch_scc1 .Lfzsb1_c0
	v_add_f32_e32 v14, v14, v252
	s_branch .LBB0_413

.LBB0_413:
	v_add_u32_e32 v242, s27, v234
	ds_read_b64_tr_b16 v[160:161], v242 offset:0x0
	ds_read_b64_tr_b16 v[162:163], v242 offset:0x100
	ds_read_b64_tr_b16 v[164:165], v242 offset:0x1000
	ds_read_b64_tr_b16 v[166:167], v242 offset:0x1100
	s_waitcnt lgkmcnt(2)
	v_mfma_f32_32x32x16_bf16 v[128:143], v[216:219], v[160:163], v[128:143]
	ds_read_b64_tr_b16 v[168:169], v242 offset:0x200
	v_mfma_f32_32x32x16_bf16 v[96:111], v[212:215], v[160:163], v[96:111]
	ds_read_b64_tr_b16 v[170:171], v242 offset:0x300
	s_waitcnt lgkmcnt(2)
	v_mfma_f32_32x32x16_bf16 v[128:143], v[224:227], v[164:167], v[128:143]
	ds_read_b64_tr_b16 v[172:173], v242 offset:0x1200
	v_mfma_f32_32x32x16_bf16 v[96:111], v[220:223], v[164:167], v[96:111]
	ds_read_b64_tr_b16 v[174:175], v242 offset:0x1300
	s_waitcnt lgkmcnt(2)
	v_mfma_f32_32x32x16_bf16 v[112:127], v[216:219], v[168:171], v[112:127]
	ds_read_b64_tr_b16 v[160:161], v242 offset:0x400
	v_mfma_f32_32x32x16_bf16 v[80:95], v[212:215], v[168:171], v[80:95]
	ds_read_b64_tr_b16 v[162:163], v242 offset:0x500
	s_waitcnt lgkmcnt(2)
	v_mfma_f32_32x32x16_bf16 v[112:127], v[224:227], v[172:175], v[112:127]
	ds_read_b64_tr_b16 v[164:165], v242 offset:0x1400
	v_mfma_f32_32x32x16_bf16 v[80:95], v[220:223], v[172:175], v[80:95]
	ds_read_b64_tr_b16 v[166:167], v242 offset:0x1500
	ds_read_b128 v[144:147], v241 offset:0x2000
	ds_read_b128 v[148:151], v240 offset:0x2000
	ds_read_b128 v[152:155], v239 offset:0x2000
	ds_read_b128 v[156:159], v0 offset:0x2000
	s_waitcnt lgkmcnt(6)
	v_mfma_f32_32x32x16_bf16 v[64:79], v[216:219], v[160:163], v[64:79]
	ds_read_b64_tr_b16 v[168:169], v242 offset:0x600
	v_mfma_f32_32x32x16_bf16 v[32:47], v[212:215], v[160:163], v[32:47]
	ds_read_b64_tr_b16 v[170:171], v242 offset:0x700
	s_waitcnt lgkmcnt(6)
	v_mfma_f32_32x32x16_bf16 v[64:79], v[224:227], v[164:167], v[64:79]
	ds_read_b64_tr_b16 v[172:173], v242 offset:0x1600
	v_mfma_f32_32x32x16_bf16 v[32:47], v[220:223], v[164:167], v[32:47]
	ds_read_b64_tr_b16 v[174:175], v242 offset:0x1700
	s_waitcnt lgkmcnt(2)
	v_mfma_f32_32x32x16_bf16 v[48:63], v[216:219], v[168:171], v[48:63]
	v_mfma_f32_32x32x16_bf16 v[16:31], v[212:215], v[168:171], v[16:31]
	s_waitcnt lgkmcnt(0)
	v_mfma_f32_32x32x16_bf16 v[48:63], v[224:227], v[172:175], v[48:63]
	v_mfma_f32_32x32x16_bf16 v[16:31], v[220:223], v[172:175], v[16:31]
	s_waitcnt lgkmcnt(0)
	v_mfma_f32_32x32x16_bf16 v[212:227], v[144:147], v[176:179], 0
	v_mfma_f32_32x32x16_bf16 v[212:227], v[148:151], v[180:183], v[212:227]
	v_mfma_f32_32x32x16_bf16 v[212:227], v[152:155], v[184:187], v[212:227]
	v_mfma_f32_32x32x16_bf16 v[212:227], v[156:159], v[188:191], v[212:227]
	ds_read_b128 v[144:147], v241 offset:0x2080
	ds_read_b128 v[148:151], v240 offset:0x2080
	ds_read_b128 v[152:155], v239 offset:0x2080
	ds_read_b128 v[156:159], v0 offset:0x2080
	v_cmp_eq_f32_e32 vcc, 0, v238
	v_cmp_eq_f32_e64 s[10:11], 0, v237
	s_and_b64 s[0:1], vcc, s[10:11]
	s_cmp_eq_u64 s[0:1], exec
	s_waitcnt lgkmcnt(0)
	v_mfma_f32_32x32x16_bf16 v[160:175], v[144:147], v[192:195], 0
	v_mfma_f32_32x32x16_bf16 v[160:175], v[148:151], v[196:199], v[160:175]
	v_mfma_f32_32x32x16_bf16 v[160:175], v[152:155], v[200:203], v[160:175]
	v_mfma_f32_32x32x16_bf16 v[160:175], v[156:159], v[204:207], v[160:175]
	s_cbranch_scc0 .Lfz2o_c0
	v_exp_f32_e32 v144, v212
	v_exp_f32_e32 v145, v213
	v_exp_f32_e32 v146, v214
	v_exp_f32_e32 v147, v215
	v_exp_f32_e32 v148, v216
	v_exp_f32_e32 v149, v217
	v_exp_f32_e32 v150, v218
	v_exp_f32_e32 v151, v219
	v_exp_f32_e32 v152, v220
	v_exp_f32_e32 v153, v221
	v_exp_f32_e32 v154, v222
	v_exp_f32_e32 v155, v223
	v_exp_f32_e32 v156, v224
	v_exp_f32_e32 v157, v225
	v_exp_f32_e32 v158, v226
	v_exp_f32_e32 v159, v227
	v_add_f32_e32 v252, v144, v145
	v_add_f32_e32 v253, v146, v147
	v_add_f32_e32 v254, v148, v149
	v_add_f32_e32 v255, v150, v151
	v_add_f32_e32 v252, v252, v152
	v_add_f32_e32 v253, v253, v153
	v_add_f32_e32 v254, v254, v154
	v_add_f32_e32 v255, v255, v155
	v_add_f32_e32 v252, v252, v156
	v_add_f32_e32 v253, v253, v157
	v_add_f32_e32 v254, v254, v158
	v_add_f32_e32 v255, v255, v159
	v_cvt_pk_bf16_f32 v6, v144, v145
	v_cvt_pk_bf16_f32 v7, v146, v147
	v_add_f32_e32 v252, v252, v253
	v_add_f32_e32 v254, v254, v255
	v_cvt_pk_bf16_f32 v8, v148, v149
	v_cvt_pk_bf16_f32 v9, v150, v151
	v_cvt_pk_bf16_f32 v208, v152, v153
	v_add_f32_e32 v252, v252, v254
	v_cvt_pk_bf16_f32 v209, v154, v155
	v_cvt_pk_bf16_f32 v210, v156, v157
	v_cvt_pk_bf16_f32 v211, v158, v159
	v_add_u32_e32 v253, 0xde801b54, v252
	v_cmp_gt_u32_e32 vcc, 0x3bff7543, v253
	s_cmp_lg_u64 vcc, exec
	s_cbranch_scc1 .LBB0_444
	v_add_f32_e32 v15, v15, v252
	v_exp_f32_e32 v144, v160
	v_exp_f32_e32 v145, v161
	v_exp_f32_e32 v146, v162
	v_exp_f32_e32 v147, v163
	v_exp_f32_e32 v148, v164
	v_exp_f32_e32 v149, v165
	v_exp_f32_e32 v150, v166
	v_exp_f32_e32 v151, v167
	v_exp_f32_e32 v152, v168
	v_exp_f32_e32 v153, v169
	v_exp_f32_e32 v154, v170
	v_exp_f32_e32 v155, v171
	v_exp_f32_e32 v156, v172
	v_exp_f32_e32 v157, v173
	v_exp_f32_e32 v158, v174
	v_exp_f32_e32 v159, v175
	v_add_f32_e32 v252, v144, v145
	v_add_f32_e32 v253, v146, v147
	v_add_f32_e32 v254, v148, v149
	v_add_f32_e32 v255, v150, v151
	v_add_f32_e32 v252, v252, v152
	v_add_f32_e32 v253, v253, v153
	v_add_f32_e32 v254, v254, v154
	v_add_f32_e32 v255, v255, v155
	v_add_f32_e32 v252, v252, v156
	v_add_f32_e32 v253, v253, v157
	v_add_f32_e32 v254, v254, v158
	v_add_f32_e32 v255, v255, v159
	v_cvt_pk_bf16_f32 v2, v144, v145
	v_cvt_pk_bf16_f32 v3, v146, v147
	v_add_f32_e32 v252, v252, v253
	v_add_f32_e32 v254, v254, v255
	v_cvt_pk_bf16_f32 v4, v148, v149
	v_cvt_pk_bf16_f32 v5, v150, v151
	v_cvt_pk_bf16_f32 v10, v152, v153
	v_add_f32_e32 v252, v252, v254
	v_cvt_pk_bf16_f32 v11, v154, v155
	v_cvt_pk_bf16_f32 v12, v156, v157
	v_cvt_pk_bf16_f32 v13, v158, v159
	v_add_u32_e32 v253, 0xde801b54, v252
	v_cmp_gt_u32_e32 vcc, 0x3bff7543, v253
	s_cmp_lg_u64 vcc, exec
	s_cbranch_scc1 .Lfzsb2_c0
	v_add_f32_e32 v14, v14, v252
	s_branch .LBB0_429

.LBB0_429:
	s_andn2_b64 vcc, exec, s[46:47]
	s_cbranch_vccnz .LBB0_388
	ds_read_b64_tr_b16 v[160:161], v242 offset:0x2000
	ds_read_b64_tr_b16 v[162:163], v242 offset:0x2100
	ds_read_b64_tr_b16 v[164:165], v242 offset:0x3000
	ds_read_b64_tr_b16 v[166:167], v242 offset:0x3100
	s_waitcnt lgkmcnt(2)
	v_mfma_f32_32x32x16_bf16 v[128:143], v[6:9], v[160:163], v[128:143]
	ds_read_b64_tr_b16 v[168:169], v242 offset:0x2200
	v_mfma_f32_32x32x16_bf16 v[96:111], v[2:5], v[160:163], v[96:111]
	ds_read_b64_tr_b16 v[170:171], v242 offset:0x2300
	s_waitcnt lgkmcnt(2)
	v_mfma_f32_32x32x16_bf16 v[128:143], v[208:211], v[164:167], v[128:143]
	ds_read_b64_tr_b16 v[172:173], v242 offset:0x3200
	v_mfma_f32_32x32x16_bf16 v[96:111], v[10:13], v[164:167], v[96:111]
	ds_read_b64_tr_b16 v[174:175], v242 offset:0x3300
	s_waitcnt lgkmcnt(2)
	v_mfma_f32_32x32x16_bf16 v[112:127], v[6:9], v[168:171], v[112:127]
	ds_read_b64_tr_b16 v[160:161], v242 offset:0x2400
	v_mfma_f32_32x32x16_bf16 v[80:95], v[2:5], v[168:171], v[80:95]
	ds_read_b64_tr_b16 v[162:163], v242 offset:0x2500
	s_waitcnt lgkmcnt(2)
	v_mfma_f32_32x32x16_bf16 v[112:127], v[208:211], v[172:175], v[112:127]
	ds_read_b64_tr_b16 v[164:165], v242 offset:0x3400
	v_mfma_f32_32x32x16_bf16 v[80:95], v[10:13], v[172:175], v[80:95]
	ds_read_b64_tr_b16 v[166:167], v242 offset:0x3500
	s_waitcnt lgkmcnt(2)
	v_mfma_f32_32x32x16_bf16 v[64:79], v[6:9], v[160:163], v[64:79]
	ds_read_b64_tr_b16 v[168:169], v242 offset:0x2600
	v_mfma_f32_32x32x16_bf16 v[32:47], v[2:5], v[160:163], v[32:47]
	ds_read_b64_tr_b16 v[170:171], v242 offset:0x2700
	s_waitcnt lgkmcnt(2)
	v_mfma_f32_32x32x16_bf16 v[64:79], v[208:211], v[164:167], v[64:79]
	ds_read_b64_tr_b16 v[172:173], v242 offset:0x3600
	v_mfma_f32_32x32x16_bf16 v[32:47], v[10:13], v[164:167], v[32:47]
	ds_read_b64_tr_b16 v[174:175], v242 offset:0x3700
	s_waitcnt lgkmcnt(2)
	v_mfma_f32_32x32x16_bf16 v[48:63], v[6:9], v[168:171], v[48:63]
	v_mfma_f32_32x32x16_bf16 v[16:31], v[2:5], v[168:171], v[16:31]
	s_waitcnt lgkmcnt(0)
	v_mfma_f32_32x32x16_bf16 v[48:63], v[208:211], v[172:175], v[48:63]
	v_mfma_f32_32x32x16_bf16 v[16:31], v[10:13], v[172:175], v[16:31]
	s_branch .LBB0_388

.LBB0_463:
	s_and_b64 vcc, exec, s[34:35]
	s_cbranch_vccz .LBB0_465
	s_cmp_lg_u32 0, -1
	s_cselect_b32 s0, 0, 0
	s_add_i32 s0, s0, 0xc000
	v_add_u32_e32 v0, s0, v232
	ds_read_b64_tr_b16 v[160:161], v0 offset:0x2000
	ds_read_b64_tr_b16 v[162:163], v0 offset:0x2100
	ds_read_b64_tr_b16 v[164:165], v0 offset:0x3000
	ds_read_b64_tr_b16 v[166:167], v0 offset:0x3100
	s_waitcnt lgkmcnt(2)
	v_mfma_f32_32x32x16_bf16 v[128:143], v[6:9], v[160:163], v[128:143]
	ds_read_b64_tr_b16 v[168:169], v0 offset:0x2200
	v_mfma_f32_32x32x16_bf16 v[96:111], v[2:5], v[160:163], v[96:111]
	ds_read_b64_tr_b16 v[170:171], v0 offset:0x2300
	s_waitcnt lgkmcnt(2)
	v_mfma_f32_32x32x16_bf16 v[128:143], v[208:211], v[164:167], v[128:143]
	ds_read_b64_tr_b16 v[172:173], v0 offset:0x3200
	v_mfma_f32_32x32x16_bf16 v[96:111], v[10:13], v[164:167], v[96:111]
	ds_read_b64_tr_b16 v[174:175], v0 offset:0x3300
	s_waitcnt lgkmcnt(2)
	v_mfma_f32_32x32x16_bf16 v[112:127], v[6:9], v[168:171], v[112:127]
	ds_read_b64_tr_b16 v[160:161], v0 offset:0x2400
	v_mfma_f32_32x32x16_bf16 v[80:95], v[2:5], v[168:171], v[80:95]
	ds_read_b64_tr_b16 v[162:163], v0 offset:0x2500
	s_waitcnt lgkmcnt(2)
	v_mfma_f32_32x32x16_bf16 v[112:127], v[208:211], v[172:175], v[112:127]
	ds_read_b64_tr_b16 v[164:165], v0 offset:0x3400
	v_mfma_f32_32x32x16_bf16 v[80:95], v[10:13], v[172:175], v[80:95]
	ds_read_b64_tr_b16 v[166:167], v0 offset:0x3500
	s_waitcnt lgkmcnt(2)
	v_mfma_f32_32x32x16_bf16 v[64:79], v[6:9], v[160:163], v[64:79]
	ds_read_b64_tr_b16 v[168:169], v0 offset:0x2600
	v_mfma_f32_32x32x16_bf16 v[32:47], v[2:5], v[160:163], v[32:47]
	ds_read_b64_tr_b16 v[170:171], v0 offset:0x2700
	s_waitcnt lgkmcnt(2)
	v_mfma_f32_32x32x16_bf16 v[64:79], v[208:211], v[164:167], v[64:79]
	ds_read_b64_tr_b16 v[172:173], v0 offset:0x3600
	v_mfma_f32_32x32x16_bf16 v[32:47], v[10:13], v[164:167], v[32:47]
	ds_read_b64_tr_b16 v[174:175], v0 offset:0x3700
	s_waitcnt lgkmcnt(2)
	v_mfma_f32_32x32x16_bf16 v[48:63], v[6:9], v[168:171], v[48:63]
	v_mfma_f32_32x32x16_bf16 v[16:31], v[2:5], v[168:171], v[16:31]
	s_waitcnt lgkmcnt(0)
	v_mfma_f32_32x32x16_bf16 v[48:63], v[208:211], v[172:175], v[48:63]
	v_mfma_f32_32x32x16_bf16 v[16:31], v[10:13], v[172:175], v[16:31]

.LBB0_539:
	ds_read_b128 v[144:147], v153
	ds_read_b128 v[156:159], v153 offset:1024
	ds_read_b128 v[160:163], v153 offset:2048
	ds_read_b128 v[164:167], v153 offset:3072
	ds_read_b128 v[168:171], v154
	ds_read_b128 v[172:175], v154 offset:1024
	ds_read_b128 v[176:179], v154 offset:2048
	ds_read_b128 v[180:183], v154 offset:3072
	s_add_u32 s3, s86, 0xfffc0080
	s_addc_u32 s37, s87, -1
	s_cmp_eq_u32 s36, 12
	s_cselect_b32 s91, s0, s37
	s_cselect_b32 s90, s1, s3
	s_cselect_b32 s89, s17, s35
	s_cselect_b32 s88, s27, s33
	s_add_i32 m0, s19, 0xc000
	ds_read_b128 v[184:187], v155
	ds_read_b128 v[188:191], v155 offset:1024
	ds_read_b128 v[192:195], v155 offset:2048
	ds_read_b128 v[196:199], v155 offset:3072
	ds_read_b128 v[200:203], v155 offset:4096
	ds_read_b128 v[204:207], v155 offset:5120
	ds_read_b128 v[208:211], v155 offset:6144
	ds_read_b128 v[212:215], v155 offset:7168
	global_load_lds_dwordx4 v136, s[86:87]
	s_add_i32 m0, s19, 0xe000
	s_nop 0
	global_load_lds_dwordx4 v138, s[86:87]
	s_waitcnt vmcnt(8)
	s_waitcnt lgkmcnt(0)
	s_barrier
	s_setprio 1
	s_waitcnt lgkmcnt(0)
	v_mfma_f32_16x16x32_bf16 v[124:127], v[144:147], v[184:187], v[124:127]
	v_mfma_f32_16x16x32_bf16 v[120:123], v[160:163], v[184:187], v[120:123]
	v_mfma_f32_16x16x32_bf16 v[108:111], v[144:147], v[192:195], v[108:111]
	v_mfma_f32_16x16x32_bf16 v[104:107], v[160:163], v[192:195], v[104:107]
	v_mfma_f32_16x16x32_bf16 v[92:95], v[144:147], v[200:203], v[92:95]
	v_mfma_f32_16x16x32_bf16 v[88:91], v[160:163], v[200:203], v[88:91]
	v_mfma_f32_16x16x32_bf16 v[76:79], v[144:147], v[208:211], v[76:79]
	v_mfma_f32_16x16x32_bf16 v[72:75], v[160:163], v[208:211], v[72:75]
	v_mfma_f32_16x16x32_bf16 v[124:127], v[156:159], v[188:191], v[124:127]
	v_mfma_f32_16x16x32_bf16 v[120:123], v[164:167], v[188:191], v[120:123]
	v_mfma_f32_16x16x32_bf16 v[108:111], v[156:159], v[196:199], v[108:111]
	v_mfma_f32_16x16x32_bf16 v[104:107], v[164:167], v[196:199], v[104:107]
	v_mfma_f32_16x16x32_bf16 v[92:95], v[156:159], v[204:207], v[92:95]
	v_mfma_f32_16x16x32_bf16 v[88:91], v[164:167], v[204:207], v[88:91]
	v_mfma_f32_16x16x32_bf16 v[76:79], v[156:159], v[212:215], v[76:79]
	v_mfma_f32_16x16x32_bf16 v[72:75], v[164:167], v[212:215], v[72:75]
	s_setprio 0
	s_setprio 1
	v_mfma_f32_16x16x32_bf16 v[116:119], v[168:171], v[184:187], v[116:119]
	v_mfma_f32_16x16x32_bf16 v[112:115], v[176:179], v[184:187], v[112:115]
	v_mfma_f32_16x16x32_bf16 v[100:103], v[168:171], v[192:195], v[100:103]
	v_mfma_f32_16x16x32_bf16 v[96:99], v[176:179], v[192:195], v[96:99]
	v_mfma_f32_16x16x32_bf16 v[84:87], v[168:171], v[200:203], v[84:87]
	v_mfma_f32_16x16x32_bf16 v[80:83], v[176:179], v[200:203], v[80:83]
	v_mfma_f32_16x16x32_bf16 v[68:71], v[168:171], v[208:211], v[68:71]
	v_mfma_f32_16x16x32_bf16 v[64:67], v[176:179], v[208:211], v[64:67]
	v_mfma_f32_16x16x32_bf16 v[116:119], v[172:175], v[188:191], v[116:119]
	v_mfma_f32_16x16x32_bf16 v[112:115], v[180:183], v[188:191], v[112:115]
	v_mfma_f32_16x16x32_bf16 v[100:103], v[172:175], v[196:199], v[100:103]
	v_mfma_f32_16x16x32_bf16 v[96:99], v[180:183], v[196:199], v[96:99]
	v_mfma_f32_16x16x32_bf16 v[84:87], v[172:175], v[204:207], v[84:87]
	v_mfma_f32_16x16x32_bf16 v[80:83], v[180:183], v[204:207], v[80:83]
	v_mfma_f32_16x16x32_bf16 v[68:71], v[172:175], v[212:215], v[68:71]
	v_mfma_f32_16x16x32_bf16 v[64:67], v[180:183], v[212:215], v[64:67]
	s_setprio 0
	s_barrier
	s_add_i32 s3, s57, s18
	s_mov_b32 m0, s3
	ds_read_b128 v[184:187], v155 offset:16384
	ds_read_b128 v[188:191], v155 offset:17408
	ds_read_b128 v[192:195], v155 offset:18432
	ds_read_b128 v[196:199], v155 offset:19456
	ds_read_b128 v[200:203], v155 offset:20480
	ds_read_b128 v[204:207], v155 offset:21504
	ds_read_b128 v[208:211], v155 offset:22528
	ds_read_b128 v[212:215], v155 offset:23552
	global_load_lds_dwordx4 v130, s[88:89]
	s_add_i32 m0, s3, 0x2000
	s_add_u32 s42, s88, 0x40000
	s_addc_u32 s43, s89, 0
	s_add_i32 s3, s58, s18
	global_load_lds_dwordx4 v134, s[88:89]
	s_mov_b32 m0, s3
	s_nop 0
	global_load_lds_dwordx4 v130, s[42:43]
	s_add_i32 m0, s3, 0x2000
	s_nop 0
	global_load_lds_dwordx4 v134, s[42:43]
	s_mov_b32 m0, s19
	s_nop 0
	global_load_lds_dwordx4 v128, s[90:91]
	s_mov_b32 m0, s25
	s_nop 0
	global_load_lds_dwordx4 v132, s[90:91]
	s_waitcnt vmcnt(8)
	s_waitcnt lgkmcnt(0)
	s_barrier
	s_setprio 1
	s_waitcnt lgkmcnt(0)
	v_mfma_f32_16x16x32_bf16 v[60:63], v[144:147], v[184:187], v[60:63]
	v_mfma_f32_16x16x32_bf16 v[56:59], v[160:163], v[184:187], v[56:59]
	v_mfma_f32_16x16x32_bf16 v[44:47], v[144:147], v[192:195], v[44:47]
	v_mfma_f32_16x16x32_bf16 v[40:43], v[160:163], v[192:195], v[40:43]
	v_mfma_f32_16x16x32_bf16 v[28:31], v[144:147], v[200:203], v[28:31]
	v_mfma_f32_16x16x32_bf16 v[24:27], v[160:163], v[200:203], v[24:27]
	v_mfma_f32_16x16x32_bf16 v[12:15], v[144:147], v[208:211], v[12:15]
	v_mfma_f32_16x16x32_bf16 v[8:11], v[160:163], v[208:211], v[8:11]
	v_mfma_f32_16x16x32_bf16 v[60:63], v[156:159], v[188:191], v[60:63]
	v_mfma_f32_16x16x32_bf16 v[56:59], v[164:167], v[188:191], v[56:59]
	v_mfma_f32_16x16x32_bf16 v[44:47], v[156:159], v[196:199], v[44:47]
	v_mfma_f32_16x16x32_bf16 v[40:43], v[164:167], v[196:199], v[40:43]
	v_mfma_f32_16x16x32_bf16 v[28:31], v[156:159], v[204:207], v[28:31]
	v_mfma_f32_16x16x32_bf16 v[24:27], v[164:167], v[204:207], v[24:27]
	v_mfma_f32_16x16x32_bf16 v[12:15], v[156:159], v[212:215], v[12:15]
	v_mfma_f32_16x16x32_bf16 v[8:11], v[164:167], v[212:215], v[8:11]
	s_setprio 0
	s_setprio 1
	v_mfma_f32_16x16x32_bf16 v[52:55], v[168:171], v[184:187], v[52:55]
	v_mfma_f32_16x16x32_bf16 v[48:51], v[176:179], v[184:187], v[48:51]
	v_mfma_f32_16x16x32_bf16 v[36:39], v[168:171], v[192:195], v[36:39]
	v_mfma_f32_16x16x32_bf16 v[32:35], v[176:179], v[192:195], v[32:35]
	v_mfma_f32_16x16x32_bf16 v[20:23], v[168:171], v[200:203], v[20:23]
	v_mfma_f32_16x16x32_bf16 v[16:19], v[176:179], v[200:203], v[16:19]
	v_mfma_f32_16x16x32_bf16 v[4:7], v[168:171], v[208:211], v[4:7]
	v_mfma_f32_16x16x32_bf16 v[0:3], v[176:179], v[208:211], v[0:3]
	v_mfma_f32_16x16x32_bf16 v[52:55], v[172:175], v[188:191], v[52:55]
	v_mfma_f32_16x16x32_bf16 v[48:51], v[180:183], v[188:191], v[48:51]
	v_mfma_f32_16x16x32_bf16 v[36:39], v[172:175], v[196:199], v[36:39]
	v_mfma_f32_16x16x32_bf16 v[32:35], v[180:183], v[196:199], v[32:35]
	v_mfma_f32_16x16x32_bf16 v[20:23], v[172:175], v[204:207], v[20:23]
	v_mfma_f32_16x16x32_bf16 v[16:19], v[180:183], v[204:207], v[16:19]
	v_mfma_f32_16x16x32_bf16 v[4:7], v[172:175], v[212:215], v[4:7]
	v_mfma_f32_16x16x32_bf16 v[0:3], v[180:183], v[212:215], v[0:3]
	s_setprio 0
	s_barrier
	s_add_i32 s3, 0, 0x18000
	s_add_i32 s37, 0, 0x1c000
	v_add_u32_e32 v164, s3, v151
	v_add_u32_e32 v180, s37, v151
	ds_read_b128 v[144:147], v164
	ds_read_b128 v[156:159], v164 offset:1024
	ds_read_b128 v[160:163], v164 offset:2048
	ds_read_b128 v[164:167], v164 offset:3072
	ds_read_b128 v[168:171], v180
	ds_read_b128 v[172:175], v180 offset:1024
	ds_read_b128 v[176:179], v180 offset:2048
	ds_read_b128 v[180:183], v180 offset:3072
	s_add_u32 s42, s90, 0x40000
	s_addc_u32 s43, s91, 0
	s_mov_b32 m0, s30
	ds_read_b128 v[184:187], v155 offset:32768
	ds_read_b128 v[188:191], v155 offset:33792
	ds_read_b128 v[192:195], v155 offset:34816
	ds_read_b128 v[196:199], v155 offset:35840
	ds_read_b128 v[200:203], v155 offset:36864
	ds_read_b128 v[204:207], v155 offset:37888
	ds_read_b128 v[208:211], v155 offset:38912
	ds_read_b128 v[212:215], v155 offset:39936
	global_load_lds_dwordx4 v128, s[42:43]
	v_lshl_add_u64 v[222:223], s[42:43], 0, v[132:133]
	s_mov_b32 m0, s31
	s_nop 0
	global_load_lds_dwordx4 v[222:223], off
	s_waitcnt vmcnt(8)
	s_waitcnt lgkmcnt(0)
	s_barrier
	s_setprio 1
	s_waitcnt lgkmcnt(0)
	v_mfma_f32_16x16x32_bf16 v[124:127], v[144:147], v[184:187], v[124:127]
	v_mfma_f32_16x16x32_bf16 v[120:123], v[160:163], v[184:187], v[120:123]
	v_mfma_f32_16x16x32_bf16 v[108:111], v[144:147], v[192:195], v[108:111]
	v_mfma_f32_16x16x32_bf16 v[104:107], v[160:163], v[192:195], v[104:107]
	v_mfma_f32_16x16x32_bf16 v[92:95], v[144:147], v[200:203], v[92:95]
	v_mfma_f32_16x16x32_bf16 v[88:91], v[160:163], v[200:203], v[88:91]
	v_mfma_f32_16x16x32_bf16 v[76:79], v[144:147], v[208:211], v[76:79]
	v_mfma_f32_16x16x32_bf16 v[72:75], v[160:163], v[208:211], v[72:75]
	v_mfma_f32_16x16x32_bf16 v[124:127], v[156:159], v[188:191], v[124:127]
	v_mfma_f32_16x16x32_bf16 v[120:123], v[164:167], v[188:191], v[120:123]
	v_mfma_f32_16x16x32_bf16 v[108:111], v[156:159], v[196:199], v[108:111]
	v_mfma_f32_16x16x32_bf16 v[104:107], v[164:167], v[196:199], v[104:107]
	v_mfma_f32_16x16x32_bf16 v[92:95], v[156:159], v[204:207], v[92:95]
	v_mfma_f32_16x16x32_bf16 v[88:91], v[164:167], v[204:207], v[88:91]
	v_mfma_f32_16x16x32_bf16 v[76:79], v[156:159], v[212:215], v[76:79]
	v_mfma_f32_16x16x32_bf16 v[72:75], v[164:167], v[212:215], v[72:75]
	s_setprio 0
	s_setprio 1
	v_mfma_f32_16x16x32_bf16 v[116:119], v[168:171], v[184:187], v[116:119]
	v_mfma_f32_16x16x32_bf16 v[112:115], v[176:179], v[184:187], v[112:115]
	v_mfma_f32_16x16x32_bf16 v[100:103], v[168:171], v[192:195], v[100:103]
	v_mfma_f32_16x16x32_bf16 v[96:99], v[176:179], v[192:195], v[96:99]
	v_mfma_f32_16x16x32_bf16 v[84:87], v[168:171], v[200:203], v[84:87]
	v_mfma_f32_16x16x32_bf16 v[80:83], v[176:179], v[200:203], v[80:83]
	v_mfma_f32_16x16x32_bf16 v[68:71], v[168:171], v[208:211], v[68:71]
	v_mfma_f32_16x16x32_bf16 v[64:67], v[176:179], v[208:211], v[64:67]
	v_mfma_f32_16x16x32_bf16 v[116:119], v[172:175], v[188:191], v[116:119]
	v_mfma_f32_16x16x32_bf16 v[112:115], v[180:183], v[188:191], v[112:115]
	v_mfma_f32_16x16x32_bf16 v[100:103], v[172:175], v[196:199], v[100:103]
	v_mfma_f32_16x16x32_bf16 v[96:99], v[180:183], v[196:199], v[96:99]
	v_mfma_f32_16x16x32_bf16 v[84:87], v[172:175], v[204:207], v[84:87]
	v_mfma_f32_16x16x32_bf16 v[80:83], v[180:183], v[204:207], v[80:83]
	v_mfma_f32_16x16x32_bf16 v[68:71], v[172:175], v[212:215], v[68:71]
	v_mfma_f32_16x16x32_bf16 v[64:67], v[180:183], v[212:215], v[64:67]
	s_setprio 0
	s_barrier
	s_add_i32 s3, s3, s18
	s_add_u32 s42, s88, 0x80
	s_addc_u32 s43, s89, 0
	s_mov_b32 m0, s3
	ds_read_b128 v[184:187], v155 offset:49152
	ds_read_b128 v[188:191], v155 offset:50176
	ds_read_b128 v[192:195], v155 offset:51200
	ds_read_b128 v[196:199], v155 offset:52224
	ds_read_b128 v[200:203], v155 offset:53248
	ds_read_b128 v[204:207], v155 offset:54272
	ds_read_b128 v[208:211], v155 offset:55296
	ds_read_b128 v[212:215], v155 offset:56320
	global_load_lds_dwordx4 v130, s[42:43]
	s_add_i32 m0, s3, 0x2000
	s_add_i32 s3, s37, s18
	global_load_lds_dwordx4 v134, s[42:43]
	s_add_u32 s42, s42, 0x40000
	s_addc_u32 s43, s43, 0
	s_mov_b32 m0, s3
	s_nop 0
	global_load_lds_dwordx4 v130, s[42:43]
	s_add_i32 m0, s3, 0x2000
	s_nop 0
	global_load_lds_dwordx4 v134, s[42:43]
	s_add_u32 s90, s90, 0x80
	s_addc_u32 s91, s91, 0
	s_mov_b32 m0, s49
	s_nop 0
	global_load_lds_dwordx4 v128, s[90:91]
	s_mov_b32 m0, s56
	s_nop 0
	global_load_lds_dwordx4 v132, s[90:91]
	s_waitcnt vmcnt(8)
	s_waitcnt lgkmcnt(0)
	s_barrier
	s_setprio 1
	s_waitcnt lgkmcnt(0)
	v_mfma_f32_16x16x32_bf16 v[60:63], v[144:147], v[184:187], v[60:63]
	v_mfma_f32_16x16x32_bf16 v[56:59], v[160:163], v[184:187], v[56:59]
	v_mfma_f32_16x16x32_bf16 v[44:47], v[144:147], v[192:195], v[44:47]
	v_mfma_f32_16x16x32_bf16 v[40:43], v[160:163], v[192:195], v[40:43]
	v_mfma_f32_16x16x32_bf16 v[28:31], v[144:147], v[200:203], v[28:31]
	v_mfma_f32_16x16x32_bf16 v[24:27], v[160:163], v[200:203], v[24:27]
	v_mfma_f32_16x16x32_bf16 v[12:15], v[144:147], v[208:211], v[12:15]
	v_mfma_f32_16x16x32_bf16 v[8:11], v[160:163], v[208:211], v[8:11]
	v_mfma_f32_16x16x32_bf16 v[60:63], v[156:159], v[188:191], v[60:63]
	v_mfma_f32_16x16x32_bf16 v[56:59], v[164:167], v[188:191], v[56:59]
	v_mfma_f32_16x16x32_bf16 v[44:47], v[156:159], v[196:199], v[44:47]
	v_mfma_f32_16x16x32_bf16 v[40:43], v[164:167], v[196:199], v[40:43]
	v_mfma_f32_16x16x32_bf16 v[28:31], v[156:159], v[204:207], v[28:31]
	v_mfma_f32_16x16x32_bf16 v[24:27], v[164:167], v[204:207], v[24:27]
	v_mfma_f32_16x16x32_bf16 v[12:15], v[156:159], v[212:215], v[12:15]
	v_mfma_f32_16x16x32_bf16 v[8:11], v[164:167], v[212:215], v[8:11]
	s_setprio 0
	s_setprio 1
	v_mfma_f32_16x16x32_bf16 v[52:55], v[168:171], v[184:187], v[52:55]
	v_mfma_f32_16x16x32_bf16 v[48:51], v[176:179], v[184:187], v[48:51]
	v_mfma_f32_16x16x32_bf16 v[36:39], v[168:171], v[192:195], v[36:39]
	v_mfma_f32_16x16x32_bf16 v[32:35], v[176:179], v[192:195], v[32:35]
	v_mfma_f32_16x16x32_bf16 v[20:23], v[168:171], v[200:203], v[20:23]
	v_mfma_f32_16x16x32_bf16 v[16:19], v[176:179], v[200:203], v[16:19]
	v_mfma_f32_16x16x32_bf16 v[4:7], v[168:171], v[208:211], v[4:7]
	v_mfma_f32_16x16x32_bf16 v[0:3], v[176:179], v[208:211], v[0:3]
	v_mfma_f32_16x16x32_bf16 v[52:55], v[172:175], v[188:191], v[52:55]
	v_mfma_f32_16x16x32_bf16 v[48:51], v[180:183], v[188:191], v[48:51]
	v_mfma_f32_16x16x32_bf16 v[36:39], v[172:175], v[196:199], v[36:39]
	v_mfma_f32_16x16x32_bf16 v[32:35], v[180:183], v[196:199], v[32:35]
	v_mfma_f32_16x16x32_bf16 v[20:23], v[172:175], v[204:207], v[20:23]
	v_mfma_f32_16x16x32_bf16 v[16:19], v[180:183], v[204:207], v[16:19]
	v_mfma_f32_16x16x32_bf16 v[4:7], v[172:175], v[212:215], v[4:7]
	v_mfma_f32_16x16x32_bf16 v[0:3], v[180:183], v[212:215], v[0:3]
	s_setprio 0
	s_barrier
	s_add_i32 s36, s36, 2
	s_add_u32 s86, s86, 0x100
	s_addc_u32 s87, s87, 0
	s_add_u32 s33, s33, 0x100
	s_addc_u32 s35, s35, 0
	s_cmp_gt_u32 s36, 13
	s_cbranch_scc0 .LBB0_539
	s_and_b64 vcc, exec, s[12:13]
	s_cbranch_vccz .LBB0_542
	s_barrier

.LBB0_563:
	ds_read_b128 v[144:147], v157
	ds_read_b128 v[148:151], v157 offset:1024
	ds_read_b128 v[160:163], v157 offset:2048
	ds_read_b128 v[164:167], v157 offset:3072
	ds_read_b128 v[168:171], v158
	ds_read_b128 v[172:175], v158 offset:1024
	ds_read_b128 v[176:179], v158 offset:2048
	ds_read_b128 v[180:183], v158 offset:3072
	s_add_u32 s3, s34, 0xfffe0080
	s_addc_u32 s42, s35, -1
	s_cmp_eq_u32 s37, 4
	s_cselect_b32 s91, s0, s42
	s_cselect_b32 s90, s1, s3
	s_cselect_b32 s89, s24, s36
	s_cselect_b32 s88, s27, s33
	s_add_i32 m0, s19, 0xc000
	ds_read_b128 v[184:187], v159
	ds_read_b128 v[188:191], v159 offset:1024
	ds_read_b128 v[192:195], v159 offset:2048
	ds_read_b128 v[196:199], v159 offset:3072
	ds_read_b128 v[200:203], v159 offset:4096
	ds_read_b128 v[204:207], v159 offset:5120
	ds_read_b128 v[208:211], v159 offset:6144
	ds_read_b128 v[212:215], v159 offset:7168
	global_load_lds_dwordx4 v136, s[34:35]
	s_add_i32 m0, s19, 0xe000
	s_nop 0
	global_load_lds_dwordx4 v138, s[34:35]
	s_waitcnt vmcnt(8)
	s_waitcnt lgkmcnt(0)
	s_barrier
	s_setprio 1
	s_waitcnt lgkmcnt(0)
	v_mfma_f32_16x16x32_bf16 v[124:127], v[144:147], v[184:187], v[124:127]
	v_mfma_f32_16x16x32_bf16 v[120:123], v[160:163], v[184:187], v[120:123]
	v_mfma_f32_16x16x32_bf16 v[108:111], v[144:147], v[192:195], v[108:111]
	v_mfma_f32_16x16x32_bf16 v[104:107], v[160:163], v[192:195], v[104:107]
	v_mfma_f32_16x16x32_bf16 v[92:95], v[144:147], v[200:203], v[92:95]
	v_mfma_f32_16x16x32_bf16 v[88:91], v[160:163], v[200:203], v[88:91]
	v_mfma_f32_16x16x32_bf16 v[76:79], v[144:147], v[208:211], v[76:79]
	v_mfma_f32_16x16x32_bf16 v[72:75], v[160:163], v[208:211], v[72:75]
	v_mfma_f32_16x16x32_bf16 v[124:127], v[148:151], v[188:191], v[124:127]
	v_mfma_f32_16x16x32_bf16 v[120:123], v[164:167], v[188:191], v[120:123]
	v_mfma_f32_16x16x32_bf16 v[108:111], v[148:151], v[196:199], v[108:111]
	v_mfma_f32_16x16x32_bf16 v[104:107], v[164:167], v[196:199], v[104:107]
	v_mfma_f32_16x16x32_bf16 v[92:95], v[148:151], v[204:207], v[92:95]
	v_mfma_f32_16x16x32_bf16 v[88:91], v[164:167], v[204:207], v[88:91]
	v_mfma_f32_16x16x32_bf16 v[76:79], v[148:151], v[212:215], v[76:79]
	v_mfma_f32_16x16x32_bf16 v[72:75], v[164:167], v[212:215], v[72:75]
	s_setprio 0
	s_setprio 1
	v_mfma_f32_16x16x32_bf16 v[116:119], v[168:171], v[184:187], v[116:119]
	v_mfma_f32_16x16x32_bf16 v[112:115], v[176:179], v[184:187], v[112:115]
	v_mfma_f32_16x16x32_bf16 v[100:103], v[168:171], v[192:195], v[100:103]
	v_mfma_f32_16x16x32_bf16 v[96:99], v[176:179], v[192:195], v[96:99]
	v_mfma_f32_16x16x32_bf16 v[84:87], v[168:171], v[200:203], v[84:87]
	v_mfma_f32_16x16x32_bf16 v[80:83], v[176:179], v[200:203], v[80:83]
	v_mfma_f32_16x16x32_bf16 v[68:71], v[168:171], v[208:211], v[68:71]
	v_mfma_f32_16x16x32_bf16 v[64:67], v[176:179], v[208:211], v[64:67]
	v_mfma_f32_16x16x32_bf16 v[116:119], v[172:175], v[188:191], v[116:119]
	v_mfma_f32_16x16x32_bf16 v[112:115], v[180:183], v[188:191], v[112:115]
	v_mfma_f32_16x16x32_bf16 v[100:103], v[172:175], v[196:199], v[100:103]
	v_mfma_f32_16x16x32_bf16 v[96:99], v[180:183], v[196:199], v[96:99]
	v_mfma_f32_16x16x32_bf16 v[84:87], v[172:175], v[204:207], v[84:87]
	v_mfma_f32_16x16x32_bf16 v[80:83], v[180:183], v[204:207], v[80:83]
	v_mfma_f32_16x16x32_bf16 v[68:71], v[172:175], v[212:215], v[68:71]
	v_mfma_f32_16x16x32_bf16 v[64:67], v[180:183], v[212:215], v[64:67]
	s_setprio 0
	s_barrier
	s_add_i32 s3, s78, s18
	s_mov_b32 m0, s3
	ds_read_b128 v[184:187], v159 offset:16384
	ds_read_b128 v[188:191], v159 offset:17408
	ds_read_b128 v[192:195], v159 offset:18432
	ds_read_b128 v[196:199], v159 offset:19456
	ds_read_b128 v[200:203], v159 offset:20480
	ds_read_b128 v[204:207], v159 offset:21504
	ds_read_b128 v[208:211], v159 offset:22528
	ds_read_b128 v[212:215], v159 offset:23552
	global_load_lds_dwordx4 v130, s[88:89]
	s_add_i32 m0, s3, 0x2000
	s_add_u32 s42, s88, 0x20000
	s_addc_u32 s43, s89, 0
	s_add_i32 s3, s79, s18
	global_load_lds_dwordx4 v134, s[88:89]
	s_mov_b32 m0, s3
	s_nop 0
	global_load_lds_dwordx4 v130, s[42:43]
	s_add_i32 m0, s3, 0x2000
	s_nop 0
	global_load_lds_dwordx4 v134, s[42:43]
	s_mov_b32 m0, s19
	s_nop 0
	global_load_lds_dwordx4 v128, s[90:91]
	s_mov_b32 m0, s25
	s_nop 0
	global_load_lds_dwordx4 v132, s[90:91]
	s_waitcnt vmcnt(8)
	s_waitcnt lgkmcnt(0)
	s_barrier
	s_setprio 1
	s_waitcnt lgkmcnt(0)
	v_mfma_f32_16x16x32_bf16 v[60:63], v[144:147], v[184:187], v[60:63]
	v_mfma_f32_16x16x32_bf16 v[56:59], v[160:163], v[184:187], v[56:59]
	v_mfma_f32_16x16x32_bf16 v[44:47], v[144:147], v[192:195], v[44:47]
	v_mfma_f32_16x16x32_bf16 v[40:43], v[160:163], v[192:195], v[40:43]
	v_mfma_f32_16x16x32_bf16 v[28:31], v[144:147], v[200:203], v[28:31]
	v_mfma_f32_16x16x32_bf16 v[24:27], v[160:163], v[200:203], v[24:27]
	v_mfma_f32_16x16x32_bf16 v[12:15], v[144:147], v[208:211], v[12:15]
	v_mfma_f32_16x16x32_bf16 v[8:11], v[160:163], v[208:211], v[8:11]
	v_mfma_f32_16x16x32_bf16 v[60:63], v[148:151], v[188:191], v[60:63]
	v_mfma_f32_16x16x32_bf16 v[56:59], v[164:167], v[188:191], v[56:59]
	v_mfma_f32_16x16x32_bf16 v[44:47], v[148:151], v[196:199], v[44:47]
	v_mfma_f32_16x16x32_bf16 v[40:43], v[164:167], v[196:199], v[40:43]
	v_mfma_f32_16x16x32_bf16 v[28:31], v[148:151], v[204:207], v[28:31]
	v_mfma_f32_16x16x32_bf16 v[24:27], v[164:167], v[204:207], v[24:27]
	v_mfma_f32_16x16x32_bf16 v[12:15], v[148:151], v[212:215], v[12:15]
	v_mfma_f32_16x16x32_bf16 v[8:11], v[164:167], v[212:215], v[8:11]
	s_setprio 0
	s_setprio 1
	v_mfma_f32_16x16x32_bf16 v[52:55], v[168:171], v[184:187], v[52:55]
	v_mfma_f32_16x16x32_bf16 v[48:51], v[176:179], v[184:187], v[48:51]
	v_mfma_f32_16x16x32_bf16 v[36:39], v[168:171], v[192:195], v[36:39]
	v_mfma_f32_16x16x32_bf16 v[32:35], v[176:179], v[192:195], v[32:35]
	v_mfma_f32_16x16x32_bf16 v[20:23], v[168:171], v[200:203], v[20:23]
	v_mfma_f32_16x16x32_bf16 v[16:19], v[176:179], v[200:203], v[16:19]
	v_mfma_f32_16x16x32_bf16 v[4:7], v[168:171], v[208:211], v[4:7]
	v_mfma_f32_16x16x32_bf16 v[0:3], v[176:179], v[208:211], v[0:3]
	v_mfma_f32_16x16x32_bf16 v[52:55], v[172:175], v[188:191], v[52:55]
	v_mfma_f32_16x16x32_bf16 v[48:51], v[180:183], v[188:191], v[48:51]
	v_mfma_f32_16x16x32_bf16 v[36:39], v[172:175], v[196:199], v[36:39]
	v_mfma_f32_16x16x32_bf16 v[32:35], v[180:183], v[196:199], v[32:35]
	v_mfma_f32_16x16x32_bf16 v[20:23], v[172:175], v[204:207], v[20:23]
	v_mfma_f32_16x16x32_bf16 v[16:19], v[180:183], v[204:207], v[16:19]
	v_mfma_f32_16x16x32_bf16 v[4:7], v[172:175], v[212:215], v[4:7]
	v_mfma_f32_16x16x32_bf16 v[0:3], v[180:183], v[212:215], v[0:3]
	s_setprio 0
	s_barrier
	s_add_i32 s3, 0, 0x18000
	s_add_i32 s44, 0, 0x1c000
	v_add_u32_e32 v164, s3, v155
	v_add_u32_e32 v180, s44, v155
	ds_read_b128 v[144:147], v164
	ds_read_b128 v[148:151], v164 offset:1024
	ds_read_b128 v[160:163], v164 offset:2048
	ds_read_b128 v[164:167], v164 offset:3072
	ds_read_b128 v[168:171], v180
	ds_read_b128 v[172:175], v180 offset:1024
	ds_read_b128 v[176:179], v180 offset:2048
	ds_read_b128 v[180:183], v180 offset:3072
	s_add_u32 s42, s90, 0x20000
	s_addc_u32 s43, s91, 0
	s_mov_b32 m0, s30
	ds_read_b128 v[184:187], v159 offset:32768
	ds_read_b128 v[188:191], v159 offset:33792
	ds_read_b128 v[192:195], v159 offset:34816
	ds_read_b128 v[196:199], v159 offset:35840
	ds_read_b128 v[200:203], v159 offset:36864
	ds_read_b128 v[204:207], v159 offset:37888
	ds_read_b128 v[208:211], v159 offset:38912
	ds_read_b128 v[212:215], v159 offset:39936
	global_load_lds_dwordx4 v128, s[42:43]
	v_lshl_add_u64 v[222:223], s[42:43], 0, v[132:133]
	s_mov_b32 m0, s31
	s_nop 0
	global_load_lds_dwordx4 v[222:223], off
	s_waitcnt vmcnt(8)
	s_waitcnt lgkmcnt(0)
	s_barrier
	s_setprio 1
	s_waitcnt lgkmcnt(0)
	v_mfma_f32_16x16x32_bf16 v[124:127], v[144:147], v[184:187], v[124:127]
	v_mfma_f32_16x16x32_bf16 v[120:123], v[160:163], v[184:187], v[120:123]
	v_mfma_f32_16x16x32_bf16 v[108:111], v[144:147], v[192:195], v[108:111]
	v_mfma_f32_16x16x32_bf16 v[104:107], v[160:163], v[192:195], v[104:107]
	v_mfma_f32_16x16x32_bf16 v[92:95], v[144:147], v[200:203], v[92:95]
	v_mfma_f32_16x16x32_bf16 v[88:91], v[160:163], v[200:203], v[88:91]
	v_mfma_f32_16x16x32_bf16 v[76:79], v[144:147], v[208:211], v[76:79]
	v_mfma_f32_16x16x32_bf16 v[72:75], v[160:163], v[208:211], v[72:75]
	v_mfma_f32_16x16x32_bf16 v[124:127], v[148:151], v[188:191], v[124:127]
	v_mfma_f32_16x16x32_bf16 v[120:123], v[164:167], v[188:191], v[120:123]
	v_mfma_f32_16x16x32_bf16 v[108:111], v[148:151], v[196:199], v[108:111]
	v_mfma_f32_16x16x32_bf16 v[104:107], v[164:167], v[196:199], v[104:107]
	v_mfma_f32_16x16x32_bf16 v[92:95], v[148:151], v[204:207], v[92:95]
	v_mfma_f32_16x16x32_bf16 v[88:91], v[164:167], v[204:207], v[88:91]
	v_mfma_f32_16x16x32_bf16 v[76:79], v[148:151], v[212:215], v[76:79]
	v_mfma_f32_16x16x32_bf16 v[72:75], v[164:167], v[212:215], v[72:75]
	s_setprio 0
	s_setprio 1
	v_mfma_f32_16x16x32_bf16 v[116:119], v[168:171], v[184:187], v[116:119]
	v_mfma_f32_16x16x32_bf16 v[112:115], v[176:179], v[184:187], v[112:115]
	v_mfma_f32_16x16x32_bf16 v[100:103], v[168:171], v[192:195], v[100:103]
	v_mfma_f32_16x16x32_bf16 v[96:99], v[176:179], v[192:195], v[96:99]
	v_mfma_f32_16x16x32_bf16 v[84:87], v[168:171], v[200:203], v[84:87]
	v_mfma_f32_16x16x32_bf16 v[80:83], v[176:179], v[200:203], v[80:83]
	v_mfma_f32_16x16x32_bf16 v[68:71], v[168:171], v[208:211], v[68:71]
	v_mfma_f32_16x16x32_bf16 v[64:67], v[176:179], v[208:211], v[64:67]
	v_mfma_f32_16x16x32_bf16 v[116:119], v[172:175], v[188:191], v[116:119]
	v_mfma_f32_16x16x32_bf16 v[112:115], v[180:183], v[188:191], v[112:115]
	v_mfma_f32_16x16x32_bf16 v[100:103], v[172:175], v[196:199], v[100:103]
	v_mfma_f32_16x16x32_bf16 v[96:99], v[180:183], v[196:199], v[96:99]
	v_mfma_f32_16x16x32_bf16 v[84:87], v[172:175], v[204:207], v[84:87]
	v_mfma_f32_16x16x32_bf16 v[80:83], v[180:183], v[204:207], v[80:83]
	v_mfma_f32_16x16x32_bf16 v[68:71], v[172:175], v[212:215], v[68:71]
	v_mfma_f32_16x16x32_bf16 v[64:67], v[180:183], v[212:215], v[64:67]
	s_setprio 0
	s_barrier
	s_add_i32 s3, s3, s18
	s_add_u32 s42, s88, 0x80
	s_addc_u32 s43, s89, 0
	s_mov_b32 m0, s3
	ds_read_b128 v[184:187], v159 offset:49152
	ds_read_b128 v[188:191], v159 offset:50176
	ds_read_b128 v[192:195], v159 offset:51200
	ds_read_b128 v[196:199], v159 offset:52224
	ds_read_b128 v[200:203], v159 offset:53248
	ds_read_b128 v[204:207], v159 offset:54272
	ds_read_b128 v[208:211], v159 offset:55296
	ds_read_b128 v[212:215], v159 offset:56320
	global_load_lds_dwordx4 v130, s[42:43]
	s_add_i32 m0, s3, 0x2000
	s_add_i32 s3, s44, s18
	global_load_lds_dwordx4 v134, s[42:43]
	s_add_u32 s42, s42, 0x20000
	s_addc_u32 s43, s43, 0
	s_mov_b32 m0, s3
	s_nop 0
	global_load_lds_dwordx4 v130, s[42:43]
	s_add_i32 m0, s3, 0x2000
	s_nop 0
	global_load_lds_dwordx4 v134, s[42:43]
	s_add_u32 s90, s90, 0x80
	s_addc_u32 s91, s91, 0
	s_mov_b32 m0, s58
	s_nop 0
	global_load_lds_dwordx4 v128, s[90:91]
	s_mov_b32 m0, s59
	s_nop 0
	global_load_lds_dwordx4 v132, s[90:91]
	s_waitcnt vmcnt(8)
	s_waitcnt lgkmcnt(0)
	s_barrier
	s_setprio 1
	s_waitcnt lgkmcnt(0)
	v_mfma_f32_16x16x32_bf16 v[60:63], v[144:147], v[184:187], v[60:63]
	v_mfma_f32_16x16x32_bf16 v[56:59], v[160:163], v[184:187], v[56:59]
	v_mfma_f32_16x16x32_bf16 v[44:47], v[144:147], v[192:195], v[44:47]
	v_mfma_f32_16x16x32_bf16 v[40:43], v[160:163], v[192:195], v[40:43]
	v_mfma_f32_16x16x32_bf16 v[28:31], v[144:147], v[200:203], v[28:31]
	v_mfma_f32_16x16x32_bf16 v[24:27], v[160:163], v[200:203], v[24:27]
	v_mfma_f32_16x16x32_bf16 v[12:15], v[144:147], v[208:211], v[12:15]
	v_mfma_f32_16x16x32_bf16 v[8:11], v[160:163], v[208:211], v[8:11]
	v_mfma_f32_16x16x32_bf16 v[60:63], v[148:151], v[188:191], v[60:63]
	v_mfma_f32_16x16x32_bf16 v[56:59], v[164:167], v[188:191], v[56:59]
	v_mfma_f32_16x16x32_bf16 v[44:47], v[148:151], v[196:199], v[44:47]
	v_mfma_f32_16x16x32_bf16 v[40:43], v[164:167], v[196:199], v[40:43]
	v_mfma_f32_16x16x32_bf16 v[28:31], v[148:151], v[204:207], v[28:31]
	v_mfma_f32_16x16x32_bf16 v[24:27], v[164:167], v[204:207], v[24:27]
	v_mfma_f32_16x16x32_bf16 v[12:15], v[148:151], v[212:215], v[12:15]
	v_mfma_f32_16x16x32_bf16 v[8:11], v[164:167], v[212:215], v[8:11]
	s_setprio 0
	s_setprio 1
	v_mfma_f32_16x16x32_bf16 v[52:55], v[168:171], v[184:187], v[52:55]
	v_mfma_f32_16x16x32_bf16 v[48:51], v[176:179], v[184:187], v[48:51]
	v_mfma_f32_16x16x32_bf16 v[36:39], v[168:171], v[192:195], v[36:39]
	v_mfma_f32_16x16x32_bf16 v[32:35], v[176:179], v[192:195], v[32:35]
	v_mfma_f32_16x16x32_bf16 v[20:23], v[168:171], v[200:203], v[20:23]
	v_mfma_f32_16x16x32_bf16 v[16:19], v[176:179], v[200:203], v[16:19]
	v_mfma_f32_16x16x32_bf16 v[4:7], v[168:171], v[208:211], v[4:7]
	v_mfma_f32_16x16x32_bf16 v[0:3], v[176:179], v[208:211], v[0:3]
	v_mfma_f32_16x16x32_bf16 v[52:55], v[172:175], v[188:191], v[52:55]
	v_mfma_f32_16x16x32_bf16 v[48:51], v[180:183], v[188:191], v[48:51]
	v_mfma_f32_16x16x32_bf16 v[36:39], v[172:175], v[196:199], v[36:39]
	v_mfma_f32_16x16x32_bf16 v[32:35], v[180:183], v[196:199], v[32:35]
	v_mfma_f32_16x16x32_bf16 v[20:23], v[172:175], v[204:207], v[20:23]
	v_mfma_f32_16x16x32_bf16 v[16:19], v[180:183], v[204:207], v[16:19]
	v_mfma_f32_16x16x32_bf16 v[4:7], v[172:175], v[212:215], v[4:7]
	v_mfma_f32_16x16x32_bf16 v[0:3], v[180:183], v[212:215], v[0:3]
	s_setprio 0
	s_barrier
	s_add_i32 s37, s37, 2
	s_add_u32 s34, s34, 0x100
	s_addc_u32 s35, s35, 0
	s_add_u32 s33, s33, 0x100
	s_addc_u32 s36, s36, 0
	s_cmp_gt_u32 s37, 5
	s_cbranch_scc0 .LBB0_563
	s_and_b64 vcc, exec, s[14:15]
	s_cbranch_vccz .LBB0_566
	s_barrier

.LBB0_639:
	ds_read_b128 v[140:143], v149
	ds_read_b128 v[152:155], v149 offset:1024
	ds_read_b128 v[156:159], v149 offset:2048
	ds_read_b128 v[160:163], v149 offset:3072
	ds_read_b128 v[164:167], v150
	ds_read_b128 v[168:171], v150 offset:1024
	ds_read_b128 v[172:175], v150 offset:2048
	ds_read_b128 v[176:179], v150 offset:3072
	s_add_u32 s3, s86, 0xfff80080
	s_addc_u32 s33, s87, -1
	s_cmp_eq_u32 s27, 28
	s_cselect_b32 s91, s0, s33
	s_cselect_b32 s90, s1, s3
	s_cselect_b32 s89, s15, s24
	s_cselect_b32 s88, s17, s19
	s_add_i32 m0, s30, 0xc000
	ds_read_b128 v[180:183], v151
	ds_read_b128 v[184:187], v151 offset:1024
	ds_read_b128 v[188:191], v151 offset:2048
	ds_read_b128 v[192:195], v151 offset:3072
	ds_read_b128 v[196:199], v151 offset:4096
	ds_read_b128 v[200:203], v151 offset:5120
	ds_read_b128 v[204:207], v151 offset:6144
	ds_read_b128 v[208:211], v151 offset:7168
	global_load_lds_dwordx4 v132, s[86:87]
	s_add_i32 m0, s30, 0xe000
	s_nop 0
	global_load_lds_dwordx4 v134, s[86:87]
	s_waitcnt vmcnt(8)
	s_waitcnt lgkmcnt(0)
	s_barrier
	s_setprio 1
	s_waitcnt lgkmcnt(0)
	v_mfma_f32_16x16x32_bf16 v[124:127], v[140:143], v[180:183], v[124:127]
	v_mfma_f32_16x16x32_bf16 v[120:123], v[156:159], v[180:183], v[120:123]
	v_mfma_f32_16x16x32_bf16 v[108:111], v[140:143], v[188:191], v[108:111]
	v_mfma_f32_16x16x32_bf16 v[104:107], v[156:159], v[188:191], v[104:107]
	v_mfma_f32_16x16x32_bf16 v[92:95], v[140:143], v[196:199], v[92:95]
	v_mfma_f32_16x16x32_bf16 v[88:91], v[156:159], v[196:199], v[88:91]
	v_mfma_f32_16x16x32_bf16 v[76:79], v[140:143], v[204:207], v[76:79]
	v_mfma_f32_16x16x32_bf16 v[72:75], v[156:159], v[204:207], v[72:75]
	v_mfma_f32_16x16x32_bf16 v[124:127], v[152:155], v[184:187], v[124:127]
	v_mfma_f32_16x16x32_bf16 v[120:123], v[160:163], v[184:187], v[120:123]
	v_mfma_f32_16x16x32_bf16 v[108:111], v[152:155], v[192:195], v[108:111]
	v_mfma_f32_16x16x32_bf16 v[104:107], v[160:163], v[192:195], v[104:107]
	v_mfma_f32_16x16x32_bf16 v[92:95], v[152:155], v[200:203], v[92:95]
	v_mfma_f32_16x16x32_bf16 v[88:91], v[160:163], v[200:203], v[88:91]
	v_mfma_f32_16x16x32_bf16 v[76:79], v[152:155], v[208:211], v[76:79]
	v_mfma_f32_16x16x32_bf16 v[72:75], v[160:163], v[208:211], v[72:75]
	s_setprio 0
	s_setprio 1
	v_mfma_f32_16x16x32_bf16 v[116:119], v[164:167], v[180:183], v[116:119]
	v_mfma_f32_16x16x32_bf16 v[112:115], v[172:175], v[180:183], v[112:115]
	v_mfma_f32_16x16x32_bf16 v[100:103], v[164:167], v[188:191], v[100:103]
	v_mfma_f32_16x16x32_bf16 v[96:99], v[172:175], v[188:191], v[96:99]
	v_mfma_f32_16x16x32_bf16 v[84:87], v[164:167], v[196:199], v[84:87]
	v_mfma_f32_16x16x32_bf16 v[80:83], v[172:175], v[196:199], v[80:83]
	v_mfma_f32_16x16x32_bf16 v[68:71], v[164:167], v[204:207], v[68:71]
	v_mfma_f32_16x16x32_bf16 v[64:67], v[172:175], v[204:207], v[64:67]
	v_mfma_f32_16x16x32_bf16 v[116:119], v[168:171], v[184:187], v[116:119]
	v_mfma_f32_16x16x32_bf16 v[112:115], v[176:179], v[184:187], v[112:115]
	v_mfma_f32_16x16x32_bf16 v[100:103], v[168:171], v[192:195], v[100:103]
	v_mfma_f32_16x16x32_bf16 v[96:99], v[176:179], v[192:195], v[96:99]
	v_mfma_f32_16x16x32_bf16 v[84:87], v[168:171], v[200:203], v[84:87]
	v_mfma_f32_16x16x32_bf16 v[80:83], v[176:179], v[200:203], v[80:83]
	v_mfma_f32_16x16x32_bf16 v[68:71], v[168:171], v[208:211], v[68:71]
	v_mfma_f32_16x16x32_bf16 v[64:67], v[176:179], v[208:211], v[64:67]
	s_setprio 0
	s_barrier
	s_add_i32 s3, s59, s25
	s_mov_b32 m0, s3
	ds_read_b128 v[180:183], v151 offset:16384
	ds_read_b128 v[184:187], v151 offset:17408
	ds_read_b128 v[188:191], v151 offset:18432
	ds_read_b128 v[192:195], v151 offset:19456
	ds_read_b128 v[196:199], v151 offset:20480
	ds_read_b128 v[200:203], v151 offset:21504
	ds_read_b128 v[204:207], v151 offset:22528
	ds_read_b128 v[208:211], v151 offset:23552
	global_load_lds_dwordx4 v128, s[88:89]
	s_add_i32 m0, s3, 0x2000
	s_add_u32 s36, s88, 0x80000
	s_addc_u32 s37, s89, 0
	s_add_i32 s3, s68, s25
	global_load_lds_dwordx4 v130, s[88:89]
	s_mov_b32 m0, s3
	s_nop 0
	global_load_lds_dwordx4 v128, s[36:37]
	s_add_i32 m0, s3, 0x2000
	s_nop 0
	global_load_lds_dwordx4 v130, s[36:37]
	s_mov_b32 m0, s30
	s_nop 0
	global_load_lds_dwordx4 v128, s[90:91]
	s_mov_b32 m0, s31
	s_nop 0
	global_load_lds_dwordx4 v130, s[90:91]
	s_waitcnt vmcnt(8)
	s_waitcnt lgkmcnt(0)
	s_barrier
	s_setprio 1
	s_waitcnt lgkmcnt(0)
	v_mfma_f32_16x16x32_bf16 v[60:63], v[140:143], v[180:183], v[60:63]
	v_mfma_f32_16x16x32_bf16 v[56:59], v[156:159], v[180:183], v[56:59]
	v_mfma_f32_16x16x32_bf16 v[44:47], v[140:143], v[188:191], v[44:47]
	v_mfma_f32_16x16x32_bf16 v[40:43], v[156:159], v[188:191], v[40:43]
	v_mfma_f32_16x16x32_bf16 v[28:31], v[140:143], v[196:199], v[28:31]
	v_mfma_f32_16x16x32_bf16 v[24:27], v[156:159], v[196:199], v[24:27]
	v_mfma_f32_16x16x32_bf16 v[12:15], v[140:143], v[204:207], v[12:15]
	v_mfma_f32_16x16x32_bf16 v[8:11], v[156:159], v[204:207], v[8:11]
	v_mfma_f32_16x16x32_bf16 v[60:63], v[152:155], v[184:187], v[60:63]
	v_mfma_f32_16x16x32_bf16 v[56:59], v[160:163], v[184:187], v[56:59]
	v_mfma_f32_16x16x32_bf16 v[44:47], v[152:155], v[192:195], v[44:47]
	v_mfma_f32_16x16x32_bf16 v[40:43], v[160:163], v[192:195], v[40:43]
	v_mfma_f32_16x16x32_bf16 v[28:31], v[152:155], v[200:203], v[28:31]
	v_mfma_f32_16x16x32_bf16 v[24:27], v[160:163], v[200:203], v[24:27]
	v_mfma_f32_16x16x32_bf16 v[12:15], v[152:155], v[208:211], v[12:15]
	v_mfma_f32_16x16x32_bf16 v[8:11], v[160:163], v[208:211], v[8:11]
	s_setprio 0
	s_setprio 1
	v_mfma_f32_16x16x32_bf16 v[52:55], v[164:167], v[180:183], v[52:55]
	v_mfma_f32_16x16x32_bf16 v[48:51], v[172:175], v[180:183], v[48:51]
	v_mfma_f32_16x16x32_bf16 v[36:39], v[164:167], v[188:191], v[36:39]
	v_mfma_f32_16x16x32_bf16 v[32:35], v[172:175], v[188:191], v[32:35]
	v_mfma_f32_16x16x32_bf16 v[20:23], v[164:167], v[196:199], v[20:23]
	v_mfma_f32_16x16x32_bf16 v[16:19], v[172:175], v[196:199], v[16:19]
	v_mfma_f32_16x16x32_bf16 v[4:7], v[164:167], v[204:207], v[4:7]
	v_mfma_f32_16x16x32_bf16 v[0:3], v[172:175], v[204:207], v[0:3]
	v_mfma_f32_16x16x32_bf16 v[52:55], v[168:171], v[184:187], v[52:55]
	v_mfma_f32_16x16x32_bf16 v[48:51], v[176:179], v[184:187], v[48:51]
	v_mfma_f32_16x16x32_bf16 v[36:39], v[168:171], v[192:195], v[36:39]
	v_mfma_f32_16x16x32_bf16 v[32:35], v[176:179], v[192:195], v[32:35]
	v_mfma_f32_16x16x32_bf16 v[20:23], v[168:171], v[200:203], v[20:23]
	v_mfma_f32_16x16x32_bf16 v[16:19], v[176:179], v[200:203], v[16:19]
	v_mfma_f32_16x16x32_bf16 v[4:7], v[168:171], v[208:211], v[4:7]
	v_mfma_f32_16x16x32_bf16 v[0:3], v[176:179], v[208:211], v[0:3]
	s_setprio 0
	s_barrier
	s_add_i32 s3, 0, 0x18000
	s_add_i32 s33, 0, 0x1c000
	v_add_u32_e32 v160, s3, v147
	v_add_u32_e32 v176, s33, v147
	ds_read_b128 v[140:143], v160
	ds_read_b128 v[152:155], v160 offset:1024
	ds_read_b128 v[156:159], v160 offset:2048
	ds_read_b128 v[160:163], v160 offset:3072
	ds_read_b128 v[164:167], v176
	ds_read_b128 v[168:171], v176 offset:1024
	ds_read_b128 v[172:175], v176 offset:2048
	ds_read_b128 v[176:179], v176 offset:3072
	s_add_u32 s36, s90, 0x80000
	s_addc_u32 s37, s91, 0
	s_mov_b32 m0, s48
	ds_read_b128 v[180:183], v151 offset:32768
	ds_read_b128 v[184:187], v151 offset:33792
	ds_read_b128 v[188:191], v151 offset:34816
	ds_read_b128 v[192:195], v151 offset:35840
	ds_read_b128 v[196:199], v151 offset:36864
	ds_read_b128 v[200:203], v151 offset:37888
	ds_read_b128 v[204:207], v151 offset:38912
	ds_read_b128 v[208:211], v151 offset:39936
	global_load_lds_dwordx4 v128, s[36:37]
	v_lshl_add_u64 v[218:219], s[36:37], 0, v[130:131]
	s_mov_b32 m0, s49
	s_nop 0
	global_load_lds_dwordx4 v[218:219], off
	s_waitcnt vmcnt(8)
	s_waitcnt lgkmcnt(0)
	s_barrier
	s_setprio 1
	s_waitcnt lgkmcnt(0)
	v_mfma_f32_16x16x32_bf16 v[124:127], v[140:143], v[180:183], v[124:127]
	v_mfma_f32_16x16x32_bf16 v[120:123], v[156:159], v[180:183], v[120:123]
	v_mfma_f32_16x16x32_bf16 v[108:111], v[140:143], v[188:191], v[108:111]
	v_mfma_f32_16x16x32_bf16 v[104:107], v[156:159], v[188:191], v[104:107]
	v_mfma_f32_16x16x32_bf16 v[92:95], v[140:143], v[196:199], v[92:95]
	v_mfma_f32_16x16x32_bf16 v[88:91], v[156:159], v[196:199], v[88:91]
	v_mfma_f32_16x16x32_bf16 v[76:79], v[140:143], v[204:207], v[76:79]
	v_mfma_f32_16x16x32_bf16 v[72:75], v[156:159], v[204:207], v[72:75]
	v_mfma_f32_16x16x32_bf16 v[124:127], v[152:155], v[184:187], v[124:127]
	v_mfma_f32_16x16x32_bf16 v[120:123], v[160:163], v[184:187], v[120:123]
	v_mfma_f32_16x16x32_bf16 v[108:111], v[152:155], v[192:195], v[108:111]
	v_mfma_f32_16x16x32_bf16 v[104:107], v[160:163], v[192:195], v[104:107]
	v_mfma_f32_16x16x32_bf16 v[92:95], v[152:155], v[200:203], v[92:95]
	v_mfma_f32_16x16x32_bf16 v[88:91], v[160:163], v[200:203], v[88:91]
	v_mfma_f32_16x16x32_bf16 v[76:79], v[152:155], v[208:211], v[76:79]
	v_mfma_f32_16x16x32_bf16 v[72:75], v[160:163], v[208:211], v[72:75]
	s_setprio 0
	s_setprio 1
	v_mfma_f32_16x16x32_bf16 v[116:119], v[164:167], v[180:183], v[116:119]
	v_mfma_f32_16x16x32_bf16 v[112:115], v[172:175], v[180:183], v[112:115]
	v_mfma_f32_16x16x32_bf16 v[100:103], v[164:167], v[188:191], v[100:103]
	v_mfma_f32_16x16x32_bf16 v[96:99], v[172:175], v[188:191], v[96:99]
	v_mfma_f32_16x16x32_bf16 v[84:87], v[164:167], v[196:199], v[84:87]
	v_mfma_f32_16x16x32_bf16 v[80:83], v[172:175], v[196:199], v[80:83]
	v_mfma_f32_16x16x32_bf16 v[68:71], v[164:167], v[204:207], v[68:71]
	v_mfma_f32_16x16x32_bf16 v[64:67], v[172:175], v[204:207], v[64:67]
	v_mfma_f32_16x16x32_bf16 v[116:119], v[168:171], v[184:187], v[116:119]
	v_mfma_f32_16x16x32_bf16 v[112:115], v[176:179], v[184:187], v[112:115]
	v_mfma_f32_16x16x32_bf16 v[100:103], v[168:171], v[192:195], v[100:103]
	v_mfma_f32_16x16x32_bf16 v[96:99], v[176:179], v[192:195], v[96:99]
	v_mfma_f32_16x16x32_bf16 v[84:87], v[168:171], v[200:203], v[84:87]
	v_mfma_f32_16x16x32_bf16 v[80:83], v[176:179], v[200:203], v[80:83]
	v_mfma_f32_16x16x32_bf16 v[68:71], v[168:171], v[208:211], v[68:71]
	v_mfma_f32_16x16x32_bf16 v[64:67], v[176:179], v[208:211], v[64:67]
	s_setprio 0
	s_barrier
	s_add_i32 s3, s3, s25
	s_add_u32 s36, s88, 0x80
	s_addc_u32 s37, s89, 0
	s_mov_b32 m0, s3
	ds_read_b128 v[180:183], v151 offset:49152
	ds_read_b128 v[184:187], v151 offset:50176
	ds_read_b128 v[188:191], v151 offset:51200
	ds_read_b128 v[192:195], v151 offset:52224
	ds_read_b128 v[196:199], v151 offset:53248
	ds_read_b128 v[200:203], v151 offset:54272
	ds_read_b128 v[204:207], v151 offset:55296
	ds_read_b128 v[208:211], v151 offset:56320
	global_load_lds_dwordx4 v128, s[36:37]
	s_add_i32 m0, s3, 0x2000
	s_add_i32 s3, s33, s25
	global_load_lds_dwordx4 v130, s[36:37]
	s_add_u32 s36, s36, 0x80000
	s_addc_u32 s37, s37, 0
	s_mov_b32 m0, s3
	s_nop 0
	global_load_lds_dwordx4 v128, s[36:37]
	s_add_i32 m0, s3, 0x2000
	s_nop 0
	global_load_lds_dwordx4 v130, s[36:37]
	s_add_u32 s90, s90, 0x80
	s_addc_u32 s91, s91, 0
	s_mov_b32 m0, s57
	s_nop 0
	global_load_lds_dwordx4 v128, s[90:91]
	s_mov_b32 m0, s58
	s_nop 0
	global_load_lds_dwordx4 v130, s[90:91]
	s_waitcnt vmcnt(8)
	s_waitcnt lgkmcnt(0)
	s_barrier
	s_setprio 1
	s_waitcnt lgkmcnt(0)
	v_mfma_f32_16x16x32_bf16 v[60:63], v[140:143], v[180:183], v[60:63]
	v_mfma_f32_16x16x32_bf16 v[56:59], v[156:159], v[180:183], v[56:59]
	v_mfma_f32_16x16x32_bf16 v[44:47], v[140:143], v[188:191], v[44:47]
	v_mfma_f32_16x16x32_bf16 v[40:43], v[156:159], v[188:191], v[40:43]
	v_mfma_f32_16x16x32_bf16 v[28:31], v[140:143], v[196:199], v[28:31]
	v_mfma_f32_16x16x32_bf16 v[24:27], v[156:159], v[196:199], v[24:27]
	v_mfma_f32_16x16x32_bf16 v[12:15], v[140:143], v[204:207], v[12:15]
	v_mfma_f32_16x16x32_bf16 v[8:11], v[156:159], v[204:207], v[8:11]
	v_mfma_f32_16x16x32_bf16 v[60:63], v[152:155], v[184:187], v[60:63]
	v_mfma_f32_16x16x32_bf16 v[56:59], v[160:163], v[184:187], v[56:59]
	v_mfma_f32_16x16x32_bf16 v[44:47], v[152:155], v[192:195], v[44:47]
	v_mfma_f32_16x16x32_bf16 v[40:43], v[160:163], v[192:195], v[40:43]
	v_mfma_f32_16x16x32_bf16 v[28:31], v[152:155], v[200:203], v[28:31]
	v_mfma_f32_16x16x32_bf16 v[24:27], v[160:163], v[200:203], v[24:27]
	v_mfma_f32_16x16x32_bf16 v[12:15], v[152:155], v[208:211], v[12:15]
	v_mfma_f32_16x16x32_bf16 v[8:11], v[160:163], v[208:211], v[8:11]
	s_setprio 0
	s_setprio 1
	v_mfma_f32_16x16x32_bf16 v[52:55], v[164:167], v[180:183], v[52:55]
	v_mfma_f32_16x16x32_bf16 v[48:51], v[172:175], v[180:183], v[48:51]
	v_mfma_f32_16x16x32_bf16 v[36:39], v[164:167], v[188:191], v[36:39]
	v_mfma_f32_16x16x32_bf16 v[32:35], v[172:175], v[188:191], v[32:35]
	v_mfma_f32_16x16x32_bf16 v[20:23], v[164:167], v[196:199], v[20:23]
	v_mfma_f32_16x16x32_bf16 v[16:19], v[172:175], v[196:199], v[16:19]
	v_mfma_f32_16x16x32_bf16 v[4:7], v[164:167], v[204:207], v[4:7]
	v_mfma_f32_16x16x32_bf16 v[0:3], v[172:175], v[204:207], v[0:3]
	v_mfma_f32_16x16x32_bf16 v[52:55], v[168:171], v[184:187], v[52:55]
	v_mfma_f32_16x16x32_bf16 v[48:51], v[176:179], v[184:187], v[48:51]
	v_mfma_f32_16x16x32_bf16 v[36:39], v[168:171], v[192:195], v[36:39]
	v_mfma_f32_16x16x32_bf16 v[32:35], v[176:179], v[192:195], v[32:35]
	v_mfma_f32_16x16x32_bf16 v[20:23], v[168:171], v[200:203], v[20:23]
	v_mfma_f32_16x16x32_bf16 v[16:19], v[176:179], v[200:203], v[16:19]
	v_mfma_f32_16x16x32_bf16 v[4:7], v[168:171], v[208:211], v[4:7]
	v_mfma_f32_16x16x32_bf16 v[0:3], v[176:179], v[208:211], v[0:3]
	s_setprio 0
	s_barrier
	s_add_i32 s27, s27, 2
	s_add_u32 s86, s86, 0x100
	s_addc_u32 s87, s87, 0
	s_add_u32 s19, s19, 0x100
	s_addc_u32 s24, s24, 0
	s_cmp_gt_u32 s27, 29
	s_cbranch_scc0 .LBB0_639
	s_and_b64 vcc, exec, s[12:13]
	s_cbranch_vccz .LBB0_642
	s_barrier

.LBB0_770:
	ds_read_b128 v[154:157], v150
	ds_read_b128 v[158:161], v150 offset:1024
	ds_read_b128 v[162:165], v150 offset:2048
	ds_read_b128 v[166:169], v150 offset:3072
	ds_read_b128 v[170:173], v151
	ds_read_b128 v[174:177], v151 offset:1024
	ds_read_b128 v[178:181], v151 offset:2048
	ds_read_b128 v[182:185], v151 offset:3072
	s_add_u32 s3, s88, 0xfff80080
	s_addc_u32 s37, s89, -1
	s_cmp_eq_u32 s36, 28
	s_cselect_b32 s91, s0, s37
	s_cselect_b32 s90, s1, s3
	s_cselect_b32 s81, s17, s35
	s_cselect_b32 s80, s27, s33
	s_add_i32 m0, s19, 0xc000
	ds_read_b128 v[186:189], v152
	ds_read_b128 v[190:193], v152 offset:1024
	ds_read_b128 v[194:197], v152 offset:2048
	ds_read_b128 v[198:201], v152 offset:3072
	ds_read_b128 v[202:205], v152 offset:4096
	ds_read_b128 v[206:209], v152 offset:5120
	ds_read_b128 v[210:213], v152 offset:6144
	ds_read_b128 v[214:217], v152 offset:7168
	global_load_lds_dwordx4 v138, s[88:89]
	s_add_i32 m0, s19, 0xe000
	s_nop 0
	global_load_lds_dwordx4 v140, s[88:89]
	s_waitcnt vmcnt(8)
	s_waitcnt lgkmcnt(0)
	s_barrier
	s_setprio 1
	s_waitcnt lgkmcnt(0)
	v_mfma_f32_16x16x32_bf16 v[124:127], v[154:157], v[186:189], v[124:127]
	v_mfma_f32_16x16x32_bf16 v[120:123], v[162:165], v[186:189], v[120:123]
	v_mfma_f32_16x16x32_bf16 v[108:111], v[154:157], v[194:197], v[108:111]
	v_mfma_f32_16x16x32_bf16 v[104:107], v[162:165], v[194:197], v[104:107]
	v_mfma_f32_16x16x32_bf16 v[92:95], v[154:157], v[202:205], v[92:95]
	v_mfma_f32_16x16x32_bf16 v[88:91], v[162:165], v[202:205], v[88:91]
	v_mfma_f32_16x16x32_bf16 v[76:79], v[154:157], v[210:213], v[76:79]
	v_mfma_f32_16x16x32_bf16 v[72:75], v[162:165], v[210:213], v[72:75]
	v_mfma_f32_16x16x32_bf16 v[124:127], v[158:161], v[190:193], v[124:127]
	v_mfma_f32_16x16x32_bf16 v[120:123], v[166:169], v[190:193], v[120:123]
	v_mfma_f32_16x16x32_bf16 v[108:111], v[158:161], v[198:201], v[108:111]
	v_mfma_f32_16x16x32_bf16 v[104:107], v[166:169], v[198:201], v[104:107]
	v_mfma_f32_16x16x32_bf16 v[92:95], v[158:161], v[206:209], v[92:95]
	v_mfma_f32_16x16x32_bf16 v[88:91], v[166:169], v[206:209], v[88:91]
	v_mfma_f32_16x16x32_bf16 v[76:79], v[158:161], v[214:217], v[76:79]
	v_mfma_f32_16x16x32_bf16 v[72:75], v[166:169], v[214:217], v[72:75]
	s_setprio 0
	s_setprio 1
	v_mfma_f32_16x16x32_bf16 v[116:119], v[170:173], v[186:189], v[116:119]
	v_mfma_f32_16x16x32_bf16 v[112:115], v[178:181], v[186:189], v[112:115]
	v_mfma_f32_16x16x32_bf16 v[100:103], v[170:173], v[194:197], v[100:103]
	v_mfma_f32_16x16x32_bf16 v[96:99], v[178:181], v[194:197], v[96:99]
	v_mfma_f32_16x16x32_bf16 v[84:87], v[170:173], v[202:205], v[84:87]
	v_mfma_f32_16x16x32_bf16 v[80:83], v[178:181], v[202:205], v[80:83]
	v_mfma_f32_16x16x32_bf16 v[68:71], v[170:173], v[210:213], v[68:71]
	v_mfma_f32_16x16x32_bf16 v[64:67], v[178:181], v[210:213], v[64:67]
	v_mfma_f32_16x16x32_bf16 v[116:119], v[174:177], v[190:193], v[116:119]
	v_mfma_f32_16x16x32_bf16 v[112:115], v[182:185], v[190:193], v[112:115]
	v_mfma_f32_16x16x32_bf16 v[100:103], v[174:177], v[198:201], v[100:103]
	v_mfma_f32_16x16x32_bf16 v[96:99], v[182:185], v[198:201], v[96:99]
	v_mfma_f32_16x16x32_bf16 v[84:87], v[174:177], v[206:209], v[84:87]
	v_mfma_f32_16x16x32_bf16 v[80:83], v[182:185], v[206:209], v[80:83]
	v_mfma_f32_16x16x32_bf16 v[68:71], v[174:177], v[214:217], v[68:71]
	v_mfma_f32_16x16x32_bf16 v[64:67], v[182:185], v[214:217], v[64:67]
	s_setprio 0
	s_barrier
	s_add_i32 s3, s56, s18
	s_mov_b32 m0, s3
	ds_read_b128 v[186:189], v152 offset:16384
	ds_read_b128 v[190:193], v152 offset:17408
	ds_read_b128 v[194:197], v152 offset:18432
	ds_read_b128 v[198:201], v152 offset:19456
	ds_read_b128 v[202:205], v152 offset:20480
	ds_read_b128 v[206:209], v152 offset:21504
	ds_read_b128 v[210:213], v152 offset:22528
	ds_read_b128 v[214:217], v152 offset:23552
	global_load_lds_dwordx4 v130, s[80:81]
	s_add_i32 m0, s3, 0x2000
	s_add_u32 s42, s80, 0x80000
	s_addc_u32 s43, s81, 0
	s_add_i32 s3, s57, s18
	global_load_lds_dwordx4 v134, s[80:81]
	s_mov_b32 m0, s3
	s_nop 0
	global_load_lds_dwordx4 v130, s[42:43]
	s_add_i32 m0, s3, 0x2000
	s_nop 0
	global_load_lds_dwordx4 v134, s[42:43]
	s_mov_b32 m0, s19
	s_nop 0
	global_load_lds_dwordx4 v128, s[90:91]
	s_mov_b32 m0, s25
	s_nop 0
	global_load_lds_dwordx4 v132, s[90:91]
	s_waitcnt vmcnt(8)
	s_waitcnt lgkmcnt(0)
	s_barrier
	s_setprio 1
	s_waitcnt lgkmcnt(0)
	v_mfma_f32_16x16x32_bf16 v[60:63], v[154:157], v[186:189], v[60:63]
	v_mfma_f32_16x16x32_bf16 v[56:59], v[162:165], v[186:189], v[56:59]
	v_mfma_f32_16x16x32_bf16 v[44:47], v[154:157], v[194:197], v[44:47]
	v_mfma_f32_16x16x32_bf16 v[40:43], v[162:165], v[194:197], v[40:43]
	v_mfma_f32_16x16x32_bf16 v[28:31], v[154:157], v[202:205], v[28:31]
	v_mfma_f32_16x16x32_bf16 v[24:27], v[162:165], v[202:205], v[24:27]
	v_mfma_f32_16x16x32_bf16 v[12:15], v[154:157], v[210:213], v[12:15]
	v_mfma_f32_16x16x32_bf16 v[8:11], v[162:165], v[210:213], v[8:11]
	v_mfma_f32_16x16x32_bf16 v[60:63], v[158:161], v[190:193], v[60:63]
	v_mfma_f32_16x16x32_bf16 v[56:59], v[166:169], v[190:193], v[56:59]
	v_mfma_f32_16x16x32_bf16 v[44:47], v[158:161], v[198:201], v[44:47]
	v_mfma_f32_16x16x32_bf16 v[40:43], v[166:169], v[198:201], v[40:43]
	v_mfma_f32_16x16x32_bf16 v[28:31], v[158:161], v[206:209], v[28:31]
	v_mfma_f32_16x16x32_bf16 v[24:27], v[166:169], v[206:209], v[24:27]
	v_mfma_f32_16x16x32_bf16 v[12:15], v[158:161], v[214:217], v[12:15]
	v_mfma_f32_16x16x32_bf16 v[8:11], v[166:169], v[214:217], v[8:11]
	s_setprio 0
	s_setprio 1
	v_mfma_f32_16x16x32_bf16 v[52:55], v[170:173], v[186:189], v[52:55]
	v_mfma_f32_16x16x32_bf16 v[48:51], v[178:181], v[186:189], v[48:51]
	v_mfma_f32_16x16x32_bf16 v[36:39], v[170:173], v[194:197], v[36:39]
	v_mfma_f32_16x16x32_bf16 v[32:35], v[178:181], v[194:197], v[32:35]
	v_mfma_f32_16x16x32_bf16 v[20:23], v[170:173], v[202:205], v[20:23]
	v_mfma_f32_16x16x32_bf16 v[16:19], v[178:181], v[202:205], v[16:19]
	v_mfma_f32_16x16x32_bf16 v[4:7], v[170:173], v[210:213], v[4:7]
	v_mfma_f32_16x16x32_bf16 v[0:3], v[178:181], v[210:213], v[0:3]
	v_mfma_f32_16x16x32_bf16 v[52:55], v[174:177], v[190:193], v[52:55]
	v_mfma_f32_16x16x32_bf16 v[48:51], v[182:185], v[190:193], v[48:51]
	v_mfma_f32_16x16x32_bf16 v[36:39], v[174:177], v[198:201], v[36:39]
	v_mfma_f32_16x16x32_bf16 v[32:35], v[182:185], v[198:201], v[32:35]
	v_mfma_f32_16x16x32_bf16 v[20:23], v[174:177], v[206:209], v[20:23]
	v_mfma_f32_16x16x32_bf16 v[16:19], v[182:185], v[206:209], v[16:19]
	v_mfma_f32_16x16x32_bf16 v[4:7], v[174:177], v[214:217], v[4:7]
	v_mfma_f32_16x16x32_bf16 v[0:3], v[182:185], v[214:217], v[0:3]
	s_setprio 0
	s_barrier
	s_add_i32 s3, 0, 0x18000
	v_add_u32_e32 v153, s3, v149
	s_add_i32 s37, 0, 0x1c000
	ds_read_b128 v[154:157], v153
	ds_read_b128 v[158:161], v153 offset:1024
	ds_read_b128 v[162:165], v153 offset:2048
	ds_read_b128 v[166:169], v153 offset:3072
	v_add_u32_e32 v153, s37, v149
	ds_read_b128 v[170:173], v153
	ds_read_b128 v[174:177], v153 offset:1024
	ds_read_b128 v[178:181], v153 offset:2048
	ds_read_b128 v[182:185], v153 offset:3072
	s_add_u32 s42, s90, 0x80000
	s_addc_u32 s43, s91, 0
	s_mov_b32 m0, s30
	ds_read_b128 v[186:189], v152 offset:32768
	ds_read_b128 v[190:193], v152 offset:33792
	ds_read_b128 v[194:197], v152 offset:34816
	ds_read_b128 v[198:201], v152 offset:35840
	ds_read_b128 v[202:205], v152 offset:36864
	ds_read_b128 v[206:209], v152 offset:37888
	ds_read_b128 v[210:213], v152 offset:38912
	ds_read_b128 v[214:217], v152 offset:39936
	global_load_lds_dwordx4 v128, s[42:43]
	v_lshl_add_u64 v[224:225], s[42:43], 0, v[132:133]
	s_mov_b32 m0, s31
	s_nop 0
	global_load_lds_dwordx4 v[224:225], off
	s_waitcnt vmcnt(8)
	s_waitcnt lgkmcnt(0)
	s_barrier
	s_setprio 1
	s_waitcnt lgkmcnt(0)
	v_mfma_f32_16x16x32_bf16 v[124:127], v[154:157], v[186:189], v[124:127]
	v_mfma_f32_16x16x32_bf16 v[120:123], v[162:165], v[186:189], v[120:123]
	v_mfma_f32_16x16x32_bf16 v[108:111], v[154:157], v[194:197], v[108:111]
	v_mfma_f32_16x16x32_bf16 v[104:107], v[162:165], v[194:197], v[104:107]
	v_mfma_f32_16x16x32_bf16 v[92:95], v[154:157], v[202:205], v[92:95]
	v_mfma_f32_16x16x32_bf16 v[88:91], v[162:165], v[202:205], v[88:91]
	v_mfma_f32_16x16x32_bf16 v[76:79], v[154:157], v[210:213], v[76:79]
	v_mfma_f32_16x16x32_bf16 v[72:75], v[162:165], v[210:213], v[72:75]
	v_mfma_f32_16x16x32_bf16 v[124:127], v[158:161], v[190:193], v[124:127]
	v_mfma_f32_16x16x32_bf16 v[120:123], v[166:169], v[190:193], v[120:123]
	v_mfma_f32_16x16x32_bf16 v[108:111], v[158:161], v[198:201], v[108:111]
	v_mfma_f32_16x16x32_bf16 v[104:107], v[166:169], v[198:201], v[104:107]
	v_mfma_f32_16x16x32_bf16 v[92:95], v[158:161], v[206:209], v[92:95]
	v_mfma_f32_16x16x32_bf16 v[88:91], v[166:169], v[206:209], v[88:91]
	v_mfma_f32_16x16x32_bf16 v[76:79], v[158:161], v[214:217], v[76:79]
	v_mfma_f32_16x16x32_bf16 v[72:75], v[166:169], v[214:217], v[72:75]
	s_setprio 0
	s_setprio 1
	v_mfma_f32_16x16x32_bf16 v[116:119], v[170:173], v[186:189], v[116:119]
	v_mfma_f32_16x16x32_bf16 v[112:115], v[178:181], v[186:189], v[112:115]
	v_mfma_f32_16x16x32_bf16 v[100:103], v[170:173], v[194:197], v[100:103]
	v_mfma_f32_16x16x32_bf16 v[96:99], v[178:181], v[194:197], v[96:99]
	v_mfma_f32_16x16x32_bf16 v[84:87], v[170:173], v[202:205], v[84:87]
	v_mfma_f32_16x16x32_bf16 v[80:83], v[178:181], v[202:205], v[80:83]
	v_mfma_f32_16x16x32_bf16 v[68:71], v[170:173], v[210:213], v[68:71]
	v_mfma_f32_16x16x32_bf16 v[64:67], v[178:181], v[210:213], v[64:67]
	v_mfma_f32_16x16x32_bf16 v[116:119], v[174:177], v[190:193], v[116:119]
	v_mfma_f32_16x16x32_bf16 v[112:115], v[182:185], v[190:193], v[112:115]
	v_mfma_f32_16x16x32_bf16 v[100:103], v[174:177], v[198:201], v[100:103]
	v_mfma_f32_16x16x32_bf16 v[96:99], v[182:185], v[198:201], v[96:99]
	v_mfma_f32_16x16x32_bf16 v[84:87], v[174:177], v[206:209], v[84:87]
	v_mfma_f32_16x16x32_bf16 v[80:83], v[182:185], v[206:209], v[80:83]
	v_mfma_f32_16x16x32_bf16 v[68:71], v[174:177], v[214:217], v[68:71]
	v_mfma_f32_16x16x32_bf16 v[64:67], v[182:185], v[214:217], v[64:67]
	s_setprio 0
	s_barrier
	s_add_i32 s3, s3, s18
	s_add_u32 s42, s80, 0x80
	s_addc_u32 s43, s81, 0
	s_mov_b32 m0, s3
	ds_read_b128 v[186:189], v152 offset:49152
	ds_read_b128 v[190:193], v152 offset:50176
	ds_read_b128 v[194:197], v152 offset:51200
	ds_read_b128 v[198:201], v152 offset:52224
	ds_read_b128 v[202:205], v152 offset:53248
	ds_read_b128 v[206:209], v152 offset:54272
	ds_read_b128 v[210:213], v152 offset:55296
	ds_read_b128 v[214:217], v152 offset:56320
	global_load_lds_dwordx4 v130, s[42:43]
	s_add_i32 m0, s3, 0x2000
	s_add_i32 s3, s37, s18
	global_load_lds_dwordx4 v134, s[42:43]
	s_add_u32 s42, s42, 0x80000
	s_addc_u32 s43, s43, 0
	s_mov_b32 m0, s3
	s_nop 0
	global_load_lds_dwordx4 v130, s[42:43]
	s_add_i32 m0, s3, 0x2000
	s_nop 0
	global_load_lds_dwordx4 v134, s[42:43]
	s_add_u32 s90, s90, 0x80
	s_addc_u32 s91, s91, 0
	s_mov_b32 m0, s48
	s_nop 0
	global_load_lds_dwordx4 v128, s[90:91]
	s_mov_b32 m0, s49
	s_nop 0
	global_load_lds_dwordx4 v132, s[90:91]
	s_waitcnt vmcnt(8)
	s_waitcnt lgkmcnt(0)
	s_barrier
	s_setprio 1
	s_waitcnt lgkmcnt(0)
	v_mfma_f32_16x16x32_bf16 v[60:63], v[154:157], v[186:189], v[60:63]
	v_mfma_f32_16x16x32_bf16 v[56:59], v[162:165], v[186:189], v[56:59]
	v_mfma_f32_16x16x32_bf16 v[44:47], v[154:157], v[194:197], v[44:47]
	v_mfma_f32_16x16x32_bf16 v[40:43], v[162:165], v[194:197], v[40:43]
	v_mfma_f32_16x16x32_bf16 v[28:31], v[154:157], v[202:205], v[28:31]
	v_mfma_f32_16x16x32_bf16 v[24:27], v[162:165], v[202:205], v[24:27]
	v_mfma_f32_16x16x32_bf16 v[12:15], v[154:157], v[210:213], v[12:15]
	v_mfma_f32_16x16x32_bf16 v[8:11], v[162:165], v[210:213], v[8:11]
	v_mfma_f32_16x16x32_bf16 v[60:63], v[158:161], v[190:193], v[60:63]
	v_mfma_f32_16x16x32_bf16 v[56:59], v[166:169], v[190:193], v[56:59]
	v_mfma_f32_16x16x32_bf16 v[44:47], v[158:161], v[198:201], v[44:47]
	v_mfma_f32_16x16x32_bf16 v[40:43], v[166:169], v[198:201], v[40:43]
	v_mfma_f32_16x16x32_bf16 v[28:31], v[158:161], v[206:209], v[28:31]
	v_mfma_f32_16x16x32_bf16 v[24:27], v[166:169], v[206:209], v[24:27]
	v_mfma_f32_16x16x32_bf16 v[12:15], v[158:161], v[214:217], v[12:15]
	v_mfma_f32_16x16x32_bf16 v[8:11], v[166:169], v[214:217], v[8:11]
	s_setprio 0
	s_setprio 1
	v_mfma_f32_16x16x32_bf16 v[52:55], v[170:173], v[186:189], v[52:55]
	v_mfma_f32_16x16x32_bf16 v[48:51], v[178:181], v[186:189], v[48:51]
	v_mfma_f32_16x16x32_bf16 v[36:39], v[170:173], v[194:197], v[36:39]
	v_mfma_f32_16x16x32_bf16 v[32:35], v[178:181], v[194:197], v[32:35]
	v_mfma_f32_16x16x32_bf16 v[20:23], v[170:173], v[202:205], v[20:23]
	v_mfma_f32_16x16x32_bf16 v[16:19], v[178:181], v[202:205], v[16:19]
	v_mfma_f32_16x16x32_bf16 v[4:7], v[170:173], v[210:213], v[4:7]
	v_mfma_f32_16x16x32_bf16 v[0:3], v[178:181], v[210:213], v[0:3]
	v_mfma_f32_16x16x32_bf16 v[52:55], v[174:177], v[190:193], v[52:55]
	v_mfma_f32_16x16x32_bf16 v[48:51], v[182:185], v[190:193], v[48:51]
	v_mfma_f32_16x16x32_bf16 v[36:39], v[174:177], v[198:201], v[36:39]
	v_mfma_f32_16x16x32_bf16 v[32:35], v[182:185], v[198:201], v[32:35]
	v_mfma_f32_16x16x32_bf16 v[20:23], v[174:177], v[206:209], v[20:23]
	v_mfma_f32_16x16x32_bf16 v[16:19], v[182:185], v[206:209], v[16:19]
	v_mfma_f32_16x16x32_bf16 v[4:7], v[174:177], v[214:217], v[4:7]
	v_mfma_f32_16x16x32_bf16 v[0:3], v[182:185], v[214:217], v[0:3]
	s_setprio 0
	s_barrier
	s_add_i32 s36, s36, 2
	s_add_u32 s88, s88, 0x100
	s_addc_u32 s89, s89, 0
	s_add_u32 s33, s33, 0x100
	s_addc_u32 s35, s35, 0
	s_cmp_gt_u32 s36, 29
	s_cbranch_scc0 .LBB0_770
	s_and_b64 vcc, exec, s[14:15]
	s_cbranch_vccz .LBB0_773
	s_barrier

.LBB0_846:
	ds_read_b128 v[140:143], v149
	ds_read_b128 v[152:155], v149 offset:1024
	ds_read_b128 v[156:159], v149 offset:2048
	ds_read_b128 v[160:163], v149 offset:3072
	ds_read_b128 v[164:167], v150
	ds_read_b128 v[168:171], v150 offset:1024
	ds_read_b128 v[172:175], v150 offset:2048
	ds_read_b128 v[176:179], v150 offset:3072
	s_add_u32 s3, s84, 0xffe00080
	s_addc_u32 s37, s85, -1
	s_cmpk_eq_i32 s36, 0x7c
	s_cselect_b32 s87, s0, s37
	s_cselect_b32 s86, s1, s3
	s_cselect_b32 s81, s15, s33
	s_cselect_b32 s80, s17, s27
	s_add_i32 m0, s19, 0xc000
	ds_read_b128 v[180:183], v151
	ds_read_b128 v[184:187], v151 offset:1024
	ds_read_b128 v[188:191], v151 offset:2048
	ds_read_b128 v[192:195], v151 offset:3072
	ds_read_b128 v[196:199], v151 offset:4096
	ds_read_b128 v[200:203], v151 offset:5120
	ds_read_b128 v[204:207], v151 offset:6144
	ds_read_b128 v[208:211], v151 offset:7168
	global_load_lds_dwordx4 v132, s[84:85]
	s_add_i32 m0, s19, 0xe000
	s_nop 0
	global_load_lds_dwordx4 v134, s[84:85]
	s_waitcnt vmcnt(8)
	s_waitcnt lgkmcnt(0)
	s_barrier
	s_setprio 1
	s_waitcnt lgkmcnt(0)
	v_mfma_f32_16x16x32_bf16 v[124:127], v[140:143], v[180:183], v[124:127]
	v_mfma_f32_16x16x32_bf16 v[120:123], v[156:159], v[180:183], v[120:123]
	v_mfma_f32_16x16x32_bf16 v[112:115], v[140:143], v[188:191], v[112:115]
	v_mfma_f32_16x16x32_bf16 v[104:107], v[156:159], v[188:191], v[104:107]
	v_mfma_f32_16x16x32_bf16 v[96:99], v[140:143], v[196:199], v[96:99]
	v_mfma_f32_16x16x32_bf16 v[88:91], v[156:159], v[196:199], v[88:91]
	v_mfma_f32_16x16x32_bf16 v[80:83], v[140:143], v[204:207], v[80:83]
	v_mfma_f32_16x16x32_bf16 v[72:75], v[156:159], v[204:207], v[72:75]
	v_mfma_f32_16x16x32_bf16 v[124:127], v[152:155], v[184:187], v[124:127]
	v_mfma_f32_16x16x32_bf16 v[120:123], v[160:163], v[184:187], v[120:123]
	v_mfma_f32_16x16x32_bf16 v[112:115], v[152:155], v[192:195], v[112:115]
	v_mfma_f32_16x16x32_bf16 v[104:107], v[160:163], v[192:195], v[104:107]
	v_mfma_f32_16x16x32_bf16 v[96:99], v[152:155], v[200:203], v[96:99]
	v_mfma_f32_16x16x32_bf16 v[88:91], v[160:163], v[200:203], v[88:91]
	v_mfma_f32_16x16x32_bf16 v[80:83], v[152:155], v[208:211], v[80:83]
	v_mfma_f32_16x16x32_bf16 v[72:75], v[160:163], v[208:211], v[72:75]
	s_setprio 0
	s_setprio 1
	v_mfma_f32_16x16x32_bf16 v[116:119], v[164:167], v[180:183], v[116:119]
	v_mfma_f32_16x16x32_bf16 v[108:111], v[172:175], v[180:183], v[108:111]
	v_mfma_f32_16x16x32_bf16 v[100:103], v[164:167], v[188:191], v[100:103]
	v_mfma_f32_16x16x32_bf16 v[92:95], v[172:175], v[188:191], v[92:95]
	v_mfma_f32_16x16x32_bf16 v[84:87], v[164:167], v[196:199], v[84:87]
	v_mfma_f32_16x16x32_bf16 v[76:79], v[172:175], v[196:199], v[76:79]
	v_mfma_f32_16x16x32_bf16 v[68:71], v[164:167], v[204:207], v[68:71]
	v_mfma_f32_16x16x32_bf16 v[64:67], v[172:175], v[204:207], v[64:67]
	v_mfma_f32_16x16x32_bf16 v[116:119], v[168:171], v[184:187], v[116:119]
	v_mfma_f32_16x16x32_bf16 v[108:111], v[176:179], v[184:187], v[108:111]
	v_mfma_f32_16x16x32_bf16 v[100:103], v[168:171], v[192:195], v[100:103]
	v_mfma_f32_16x16x32_bf16 v[92:95], v[176:179], v[192:195], v[92:95]
	v_mfma_f32_16x16x32_bf16 v[84:87], v[168:171], v[200:203], v[84:87]
	v_mfma_f32_16x16x32_bf16 v[76:79], v[176:179], v[200:203], v[76:79]
	v_mfma_f32_16x16x32_bf16 v[68:71], v[168:171], v[208:211], v[68:71]
	v_mfma_f32_16x16x32_bf16 v[64:67], v[176:179], v[208:211], v[64:67]
	s_setprio 0
	s_barrier
	s_add_i32 s3, s57, s18
	s_mov_b32 m0, s3
	ds_read_b128 v[180:183], v151 offset:16384
	ds_read_b128 v[184:187], v151 offset:17408
	ds_read_b128 v[188:191], v151 offset:18432
	ds_read_b128 v[192:195], v151 offset:19456
	ds_read_b128 v[196:199], v151 offset:20480
	ds_read_b128 v[200:203], v151 offset:21504
	ds_read_b128 v[204:207], v151 offset:22528
	ds_read_b128 v[208:211], v151 offset:23552
	global_load_lds_dwordx4 v128, s[80:81]
	s_add_i32 m0, s3, 0x2000
	s_add_u32 s42, s80, 0x200000
	s_addc_u32 s43, s81, 0
	s_add_i32 s3, s58, s18
	global_load_lds_dwordx4 v130, s[80:81]
	s_mov_b32 m0, s3
	s_nop 0
	global_load_lds_dwordx4 v128, s[42:43]
	s_add_i32 m0, s3, 0x2000
	s_nop 0
	global_load_lds_dwordx4 v130, s[42:43]
	s_mov_b32 m0, s19
	s_nop 0
	global_load_lds_dwordx4 v128, s[86:87]
	s_mov_b32 m0, s25
	s_nop 0
	global_load_lds_dwordx4 v130, s[86:87]
	s_waitcnt vmcnt(8)
	s_waitcnt lgkmcnt(0)
	s_barrier
	s_setprio 1
	s_waitcnt lgkmcnt(0)
	v_mfma_f32_16x16x32_bf16 v[60:63], v[140:143], v[180:183], v[60:63]
	v_mfma_f32_16x16x32_bf16 v[56:59], v[156:159], v[180:183], v[56:59]
	v_mfma_f32_16x16x32_bf16 v[48:51], v[140:143], v[188:191], v[48:51]
	v_mfma_f32_16x16x32_bf16 v[40:43], v[156:159], v[188:191], v[40:43]
	v_mfma_f32_16x16x32_bf16 v[32:35], v[140:143], v[196:199], v[32:35]
	v_mfma_f32_16x16x32_bf16 v[24:27], v[156:159], v[196:199], v[24:27]
	v_mfma_f32_16x16x32_bf16 v[16:19], v[140:143], v[204:207], v[16:19]
	v_mfma_f32_16x16x32_bf16 v[8:11], v[156:159], v[204:207], v[8:11]
	v_mfma_f32_16x16x32_bf16 v[60:63], v[152:155], v[184:187], v[60:63]
	v_mfma_f32_16x16x32_bf16 v[56:59], v[160:163], v[184:187], v[56:59]
	v_mfma_f32_16x16x32_bf16 v[48:51], v[152:155], v[192:195], v[48:51]
	v_mfma_f32_16x16x32_bf16 v[40:43], v[160:163], v[192:195], v[40:43]
	v_mfma_f32_16x16x32_bf16 v[32:35], v[152:155], v[200:203], v[32:35]
	v_mfma_f32_16x16x32_bf16 v[24:27], v[160:163], v[200:203], v[24:27]
	v_mfma_f32_16x16x32_bf16 v[16:19], v[152:155], v[208:211], v[16:19]
	v_mfma_f32_16x16x32_bf16 v[8:11], v[160:163], v[208:211], v[8:11]
	s_setprio 0
	s_setprio 1
	v_mfma_f32_16x16x32_bf16 v[52:55], v[164:167], v[180:183], v[52:55]
	v_mfma_f32_16x16x32_bf16 v[44:47], v[172:175], v[180:183], v[44:47]
	v_mfma_f32_16x16x32_bf16 v[36:39], v[164:167], v[188:191], v[36:39]
	v_mfma_f32_16x16x32_bf16 v[28:31], v[172:175], v[188:191], v[28:31]
	v_mfma_f32_16x16x32_bf16 v[20:23], v[164:167], v[196:199], v[20:23]
	v_mfma_f32_16x16x32_bf16 v[12:15], v[172:175], v[196:199], v[12:15]
	v_mfma_f32_16x16x32_bf16 v[4:7], v[164:167], v[204:207], v[4:7]
	v_mfma_f32_16x16x32_bf16 v[0:3], v[172:175], v[204:207], v[0:3]
	v_mfma_f32_16x16x32_bf16 v[52:55], v[168:171], v[184:187], v[52:55]
	v_mfma_f32_16x16x32_bf16 v[44:47], v[176:179], v[184:187], v[44:47]
	v_mfma_f32_16x16x32_bf16 v[36:39], v[168:171], v[192:195], v[36:39]
	v_mfma_f32_16x16x32_bf16 v[28:31], v[176:179], v[192:195], v[28:31]
	v_mfma_f32_16x16x32_bf16 v[20:23], v[168:171], v[200:203], v[20:23]
	v_mfma_f32_16x16x32_bf16 v[12:15], v[176:179], v[200:203], v[12:15]
	v_mfma_f32_16x16x32_bf16 v[4:7], v[168:171], v[208:211], v[4:7]
	v_mfma_f32_16x16x32_bf16 v[0:3], v[176:179], v[208:211], v[0:3]
	s_setprio 0
	s_barrier
	s_add_i32 s3, 0, 0x18000
	s_add_i32 s37, 0, 0x1c000
	v_add_u32_e32 v160, s3, v147
	v_add_u32_e32 v176, s37, v147
	ds_read_b128 v[140:143], v160
	ds_read_b128 v[152:155], v160 offset:1024
	ds_read_b128 v[156:159], v160 offset:2048
	ds_read_b128 v[160:163], v160 offset:3072
	ds_read_b128 v[164:167], v176
	ds_read_b128 v[168:171], v176 offset:1024
	ds_read_b128 v[172:175], v176 offset:2048
	ds_read_b128 v[176:179], v176 offset:3072
	s_add_u32 s42, s86, 0x200000
	s_addc_u32 s43, s87, 0
	s_mov_b32 m0, s30
	ds_read_b128 v[180:183], v151 offset:32768
	ds_read_b128 v[184:187], v151 offset:33792
	ds_read_b128 v[188:191], v151 offset:34816
	ds_read_b128 v[192:195], v151 offset:35840
	ds_read_b128 v[196:199], v151 offset:36864
	ds_read_b128 v[200:203], v151 offset:37888
	ds_read_b128 v[204:207], v151 offset:38912
	ds_read_b128 v[208:211], v151 offset:39936
	global_load_lds_dwordx4 v128, s[42:43]
	v_lshl_add_u64 v[218:219], s[42:43], 0, v[130:131]
	s_mov_b32 m0, s31
	s_nop 0
	global_load_lds_dwordx4 v[218:219], off
	s_waitcnt vmcnt(8)
	s_waitcnt lgkmcnt(0)
	s_barrier
	s_setprio 1
	s_waitcnt lgkmcnt(0)
	v_mfma_f32_16x16x32_bf16 v[124:127], v[140:143], v[180:183], v[124:127]
	v_mfma_f32_16x16x32_bf16 v[120:123], v[156:159], v[180:183], v[120:123]
	v_mfma_f32_16x16x32_bf16 v[112:115], v[140:143], v[188:191], v[112:115]
	v_mfma_f32_16x16x32_bf16 v[104:107], v[156:159], v[188:191], v[104:107]
	v_mfma_f32_16x16x32_bf16 v[96:99], v[140:143], v[196:199], v[96:99]
	v_mfma_f32_16x16x32_bf16 v[88:91], v[156:159], v[196:199], v[88:91]
	v_mfma_f32_16x16x32_bf16 v[80:83], v[140:143], v[204:207], v[80:83]
	v_mfma_f32_16x16x32_bf16 v[72:75], v[156:159], v[204:207], v[72:75]
	v_mfma_f32_16x16x32_bf16 v[124:127], v[152:155], v[184:187], v[124:127]
	v_mfma_f32_16x16x32_bf16 v[120:123], v[160:163], v[184:187], v[120:123]
	v_mfma_f32_16x16x32_bf16 v[112:115], v[152:155], v[192:195], v[112:115]
	v_mfma_f32_16x16x32_bf16 v[104:107], v[160:163], v[192:195], v[104:107]
	v_mfma_f32_16x16x32_bf16 v[96:99], v[152:155], v[200:203], v[96:99]
	v_mfma_f32_16x16x32_bf16 v[88:91], v[160:163], v[200:203], v[88:91]
	v_mfma_f32_16x16x32_bf16 v[80:83], v[152:155], v[208:211], v[80:83]
	v_mfma_f32_16x16x32_bf16 v[72:75], v[160:163], v[208:211], v[72:75]
	s_setprio 0
	s_setprio 1
	v_mfma_f32_16x16x32_bf16 v[116:119], v[164:167], v[180:183], v[116:119]
	v_mfma_f32_16x16x32_bf16 v[108:111], v[172:175], v[180:183], v[108:111]
	v_mfma_f32_16x16x32_bf16 v[100:103], v[164:167], v[188:191], v[100:103]
	v_mfma_f32_16x16x32_bf16 v[92:95], v[172:175], v[188:191], v[92:95]
	v_mfma_f32_16x16x32_bf16 v[84:87], v[164:167], v[196:199], v[84:87]
	v_mfma_f32_16x16x32_bf16 v[76:79], v[172:175], v[196:199], v[76:79]
	v_mfma_f32_16x16x32_bf16 v[68:71], v[164:167], v[204:207], v[68:71]
	v_mfma_f32_16x16x32_bf16 v[64:67], v[172:175], v[204:207], v[64:67]
	v_mfma_f32_16x16x32_bf16 v[116:119], v[168:171], v[184:187], v[116:119]
	v_mfma_f32_16x16x32_bf16 v[108:111], v[176:179], v[184:187], v[108:111]
	v_mfma_f32_16x16x32_bf16 v[100:103], v[168:171], v[192:195], v[100:103]
	v_mfma_f32_16x16x32_bf16 v[92:95], v[176:179], v[192:195], v[92:95]
	v_mfma_f32_16x16x32_bf16 v[84:87], v[168:171], v[200:203], v[84:87]
	v_mfma_f32_16x16x32_bf16 v[76:79], v[176:179], v[200:203], v[76:79]
	v_mfma_f32_16x16x32_bf16 v[68:71], v[168:171], v[208:211], v[68:71]
	v_mfma_f32_16x16x32_bf16 v[64:67], v[176:179], v[208:211], v[64:67]
	s_setprio 0
	s_barrier
	s_add_i32 s3, s3, s18
	s_add_u32 s42, s80, 0x80
	s_addc_u32 s43, s81, 0
	s_mov_b32 m0, s3
	ds_read_b128 v[180:183], v151 offset:49152
	ds_read_b128 v[184:187], v151 offset:50176
	ds_read_b128 v[188:191], v151 offset:51200
	ds_read_b128 v[192:195], v151 offset:52224
	ds_read_b128 v[196:199], v151 offset:53248
	ds_read_b128 v[200:203], v151 offset:54272
	ds_read_b128 v[204:207], v151 offset:55296
	ds_read_b128 v[208:211], v151 offset:56320
	global_load_lds_dwordx4 v128, s[42:43]
	s_add_i32 m0, s3, 0x2000
	s_add_i32 s3, s37, s18
	global_load_lds_dwordx4 v130, s[42:43]
	s_add_u32 s42, s42, 0x200000
	s_addc_u32 s43, s43, 0
	s_mov_b32 m0, s3
	s_nop 0
	global_load_lds_dwordx4 v128, s[42:43]
	s_add_i32 m0, s3, 0x2000
	s_nop 0
	global_load_lds_dwordx4 v130, s[42:43]
	s_add_u32 s86, s86, 0x80
	s_addc_u32 s87, s87, 0
	s_mov_b32 m0, s49
	s_nop 0
	global_load_lds_dwordx4 v128, s[86:87]
	s_mov_b32 m0, s56
	s_nop 0
	global_load_lds_dwordx4 v130, s[86:87]
	s_waitcnt vmcnt(8)
	s_waitcnt lgkmcnt(0)
	s_barrier
	s_setprio 1
	s_waitcnt lgkmcnt(0)
	v_mfma_f32_16x16x32_bf16 v[60:63], v[140:143], v[180:183], v[60:63]
	v_mfma_f32_16x16x32_bf16 v[56:59], v[156:159], v[180:183], v[56:59]
	v_mfma_f32_16x16x32_bf16 v[48:51], v[140:143], v[188:191], v[48:51]
	v_mfma_f32_16x16x32_bf16 v[40:43], v[156:159], v[188:191], v[40:43]
	v_mfma_f32_16x16x32_bf16 v[32:35], v[140:143], v[196:199], v[32:35]
	v_mfma_f32_16x16x32_bf16 v[24:27], v[156:159], v[196:199], v[24:27]
	v_mfma_f32_16x16x32_bf16 v[16:19], v[140:143], v[204:207], v[16:19]
	v_mfma_f32_16x16x32_bf16 v[8:11], v[156:159], v[204:207], v[8:11]
	v_mfma_f32_16x16x32_bf16 v[60:63], v[152:155], v[184:187], v[60:63]
	v_mfma_f32_16x16x32_bf16 v[56:59], v[160:163], v[184:187], v[56:59]
	v_mfma_f32_16x16x32_bf16 v[48:51], v[152:155], v[192:195], v[48:51]
	v_mfma_f32_16x16x32_bf16 v[40:43], v[160:163], v[192:195], v[40:43]
	v_mfma_f32_16x16x32_bf16 v[32:35], v[152:155], v[200:203], v[32:35]
	v_mfma_f32_16x16x32_bf16 v[24:27], v[160:163], v[200:203], v[24:27]
	v_mfma_f32_16x16x32_bf16 v[16:19], v[152:155], v[208:211], v[16:19]
	v_mfma_f32_16x16x32_bf16 v[8:11], v[160:163], v[208:211], v[8:11]
	s_setprio 0
	s_setprio 1
	v_mfma_f32_16x16x32_bf16 v[52:55], v[164:167], v[180:183], v[52:55]
	v_mfma_f32_16x16x32_bf16 v[44:47], v[172:175], v[180:183], v[44:47]
	v_mfma_f32_16x16x32_bf16 v[36:39], v[164:167], v[188:191], v[36:39]
	v_mfma_f32_16x16x32_bf16 v[28:31], v[172:175], v[188:191], v[28:31]
	v_mfma_f32_16x16x32_bf16 v[20:23], v[164:167], v[196:199], v[20:23]
	v_mfma_f32_16x16x32_bf16 v[12:15], v[172:175], v[196:199], v[12:15]
	v_mfma_f32_16x16x32_bf16 v[4:7], v[164:167], v[204:207], v[4:7]
	v_mfma_f32_16x16x32_bf16 v[0:3], v[172:175], v[204:207], v[0:3]
	v_mfma_f32_16x16x32_bf16 v[52:55], v[168:171], v[184:187], v[52:55]
	v_mfma_f32_16x16x32_bf16 v[44:47], v[176:179], v[184:187], v[44:47]
	v_mfma_f32_16x16x32_bf16 v[36:39], v[168:171], v[192:195], v[36:39]
	v_mfma_f32_16x16x32_bf16 v[28:31], v[176:179], v[192:195], v[28:31]
	v_mfma_f32_16x16x32_bf16 v[20:23], v[168:171], v[200:203], v[20:23]
	v_mfma_f32_16x16x32_bf16 v[12:15], v[176:179], v[200:203], v[12:15]
	v_mfma_f32_16x16x32_bf16 v[4:7], v[168:171], v[208:211], v[4:7]
	v_mfma_f32_16x16x32_bf16 v[0:3], v[176:179], v[208:211], v[0:3]
	s_setprio 0
	s_barrier
	s_add_i32 s36, s36, 2
	s_add_u32 s84, s84, 0x100
	s_addc_u32 s85, s85, 0
	s_add_u32 s27, s27, 0x100
	s_addc_u32 s33, s33, 0
	s_cmpk_gt_u32 s36, 0x7d
	s_cbranch_scc0 .LBB0_846
	s_and_b64 vcc, exec, s[12:13]
	s_cbranch_vccz .LBB0_849
	s_barrier

.LBB0_919:
	ds_read_b128 v[128:131], v173
	ds_read_b128 v[132:135], v173 offset:1024
	ds_read_b128 v[158:161], v173 offset:2048
	ds_read_b128 v[178:181], v173 offset:3072
	ds_read_b128 v[182:185], v174
	ds_read_b128 v[186:189], v174 offset:1024
	ds_read_b128 v[190:193], v174 offset:2048
	ds_read_b128 v[194:197], v174 offset:3072
	s_add_u32 s3, s34, 0xfff80080
	s_addc_u32 s27, s35, -1
	s_cmp_eq_u32 s24, 28
	s_cselect_b32 vcc_hi, s0, s27
	s_cselect_b32 vcc_lo, s1, s3
	s_cselect_b32 s81, s15, s19
	s_cselect_b32 s80, s17, s18
	s_add_i32 m0, s30, 0xc000
	ds_read_b128 v[198:201], v175
	ds_read_b128 v[202:205], v175 offset:1024
	ds_read_b128 v[206:209], v175 offset:2048
	ds_read_b128 v[210:213], v175 offset:3072
	ds_read_b128 v[214:217], v175 offset:4096
	ds_read_b128 v[218:221], v175 offset:5120
	ds_read_b128 v[222:225], v175 offset:6144
	ds_read_b128 v[230:233], v175 offset:7168
	global_load_lds_dwordx4 v148, s[34:35]
	s_add_i32 m0, s30, 0xe000
	s_nop 0
	global_load_lds_dwordx4 v150, s[34:35]
	s_waitcnt vmcnt(8)
	s_waitcnt lgkmcnt(0)
	s_barrier
	s_setprio 1
	s_waitcnt lgkmcnt(0)
	v_mfma_f32_16x16x32_bf16 v[124:127], v[128:131], v[198:201], v[124:127]
	v_mfma_f32_16x16x32_bf16 v[120:123], v[158:161], v[198:201], v[120:123]
	v_mfma_f32_16x16x32_bf16 v[108:111], v[128:131], v[206:209], v[108:111]
	v_mfma_f32_16x16x32_bf16 v[104:107], v[158:161], v[206:209], v[104:107]
	v_mfma_f32_16x16x32_bf16 v[92:95], v[128:131], v[214:217], v[92:95]
	v_mfma_f32_16x16x32_bf16 v[88:91], v[158:161], v[214:217], v[88:91]
	v_mfma_f32_16x16x32_bf16 v[76:79], v[128:131], v[222:225], v[76:79]
	v_mfma_f32_16x16x32_bf16 v[72:75], v[158:161], v[222:225], v[72:75]
	v_mfma_f32_16x16x32_bf16 v[124:127], v[132:135], v[202:205], v[124:127]
	v_mfma_f32_16x16x32_bf16 v[120:123], v[178:181], v[202:205], v[120:123]
	v_mfma_f32_16x16x32_bf16 v[108:111], v[132:135], v[210:213], v[108:111]
	v_mfma_f32_16x16x32_bf16 v[104:107], v[178:181], v[210:213], v[104:107]
	v_mfma_f32_16x16x32_bf16 v[92:95], v[132:135], v[218:221], v[92:95]
	v_mfma_f32_16x16x32_bf16 v[88:91], v[178:181], v[218:221], v[88:91]
	v_mfma_f32_16x16x32_bf16 v[76:79], v[132:135], v[230:233], v[76:79]
	v_mfma_f32_16x16x32_bf16 v[72:75], v[178:181], v[230:233], v[72:75]
	s_setprio 0
	s_setprio 1
	v_mfma_f32_16x16x32_bf16 v[116:119], v[182:185], v[198:201], v[116:119]
	v_mfma_f32_16x16x32_bf16 v[112:115], v[190:193], v[198:201], v[112:115]
	v_mfma_f32_16x16x32_bf16 v[100:103], v[182:185], v[206:209], v[100:103]
	v_mfma_f32_16x16x32_bf16 v[96:99], v[190:193], v[206:209], v[96:99]
	v_mfma_f32_16x16x32_bf16 v[84:87], v[182:185], v[214:217], v[84:87]
	v_mfma_f32_16x16x32_bf16 v[80:83], v[190:193], v[214:217], v[80:83]
	v_mfma_f32_16x16x32_bf16 v[68:71], v[182:185], v[222:225], v[68:71]
	v_mfma_f32_16x16x32_bf16 v[64:67], v[190:193], v[222:225], v[64:67]
	v_mfma_f32_16x16x32_bf16 v[116:119], v[186:189], v[202:205], v[116:119]
	v_mfma_f32_16x16x32_bf16 v[112:115], v[194:197], v[202:205], v[112:115]
	v_mfma_f32_16x16x32_bf16 v[100:103], v[186:189], v[210:213], v[100:103]
	v_mfma_f32_16x16x32_bf16 v[96:99], v[194:197], v[210:213], v[96:99]
	v_mfma_f32_16x16x32_bf16 v[84:87], v[186:189], v[218:221], v[84:87]
	v_mfma_f32_16x16x32_bf16 v[80:83], v[194:197], v[218:221], v[80:83]
	v_mfma_f32_16x16x32_bf16 v[68:71], v[186:189], v[230:233], v[68:71]
	v_mfma_f32_16x16x32_bf16 v[64:67], v[194:197], v[230:233], v[64:67]
	s_setprio 0
	s_barrier
	s_add_i32 s3, s57, s25
	s_mov_b32 m0, s3
	ds_read_b128 v[198:201], v175 offset:16384
	ds_read_b128 v[202:205], v175 offset:17408
	ds_read_b128 v[206:209], v175 offset:18432
	ds_read_b128 v[210:213], v175 offset:19456
	ds_read_b128 v[214:217], v175 offset:20480
	ds_read_b128 v[218:221], v175 offset:21504
	ds_read_b128 v[222:225], v175 offset:22528
	ds_read_b128 v[230:233], v175 offset:23552
	global_load_lds_dwordx4 v138, s[80:81]
	s_add_i32 m0, s3, 0x2000
	s_add_u32 s36, s80, 0x80000
	s_addc_u32 s37, s81, 0
	s_add_i32 s3, s76, s25
	global_load_lds_dwordx4 v142, s[80:81]
	s_mov_b32 m0, s3
	s_nop 0
	global_load_lds_dwordx4 v138, s[36:37]
	s_add_i32 m0, s3, 0x2000
	s_nop 0
	global_load_lds_dwordx4 v142, s[36:37]
	s_mov_b32 m0, s30
	s_nop 0
	global_load_lds_dwordx4 v136, vcc
	s_mov_b32 m0, s31
	s_nop 0
	global_load_lds_dwordx4 v140, vcc
	s_waitcnt vmcnt(8)
	s_waitcnt lgkmcnt(0)
	s_barrier
	s_setprio 1
	s_waitcnt lgkmcnt(0)
	v_mfma_f32_16x16x32_bf16 v[60:63], v[128:131], v[198:201], v[60:63]
	v_mfma_f32_16x16x32_bf16 v[56:59], v[158:161], v[198:201], v[56:59]
	v_mfma_f32_16x16x32_bf16 v[44:47], v[128:131], v[206:209], v[44:47]
	v_mfma_f32_16x16x32_bf16 v[40:43], v[158:161], v[206:209], v[40:43]
	v_mfma_f32_16x16x32_bf16 v[28:31], v[128:131], v[214:217], v[28:31]
	v_mfma_f32_16x16x32_bf16 v[24:27], v[158:161], v[214:217], v[24:27]
	v_mfma_f32_16x16x32_bf16 v[12:15], v[128:131], v[222:225], v[12:15]
	v_mfma_f32_16x16x32_bf16 v[8:11], v[158:161], v[222:225], v[8:11]
	v_mfma_f32_16x16x32_bf16 v[60:63], v[132:135], v[202:205], v[60:63]
	v_mfma_f32_16x16x32_bf16 v[56:59], v[178:181], v[202:205], v[56:59]
	v_mfma_f32_16x16x32_bf16 v[44:47], v[132:135], v[210:213], v[44:47]
	v_mfma_f32_16x16x32_bf16 v[40:43], v[178:181], v[210:213], v[40:43]
	v_mfma_f32_16x16x32_bf16 v[28:31], v[132:135], v[218:221], v[28:31]
	v_mfma_f32_16x16x32_bf16 v[24:27], v[178:181], v[218:221], v[24:27]
	v_mfma_f32_16x16x32_bf16 v[12:15], v[132:135], v[230:233], v[12:15]
	v_mfma_f32_16x16x32_bf16 v[8:11], v[178:181], v[230:233], v[8:11]
	s_setprio 0
	s_setprio 1
	v_mfma_f32_16x16x32_bf16 v[52:55], v[182:185], v[198:201], v[52:55]
	v_mfma_f32_16x16x32_bf16 v[48:51], v[190:193], v[198:201], v[48:51]
	v_mfma_f32_16x16x32_bf16 v[36:39], v[182:185], v[206:209], v[36:39]
	v_mfma_f32_16x16x32_bf16 v[32:35], v[190:193], v[206:209], v[32:35]
	v_mfma_f32_16x16x32_bf16 v[20:23], v[182:185], v[214:217], v[20:23]
	v_mfma_f32_16x16x32_bf16 v[16:19], v[190:193], v[214:217], v[16:19]
	v_mfma_f32_16x16x32_bf16 v[4:7], v[182:185], v[222:225], v[4:7]
	v_mfma_f32_16x16x32_bf16 v[0:3], v[190:193], v[222:225], v[0:3]
	v_mfma_f32_16x16x32_bf16 v[52:55], v[186:189], v[202:205], v[52:55]
	v_mfma_f32_16x16x32_bf16 v[48:51], v[194:197], v[202:205], v[48:51]
	v_mfma_f32_16x16x32_bf16 v[36:39], v[186:189], v[210:213], v[36:39]
	v_mfma_f32_16x16x32_bf16 v[32:35], v[194:197], v[210:213], v[32:35]
	v_mfma_f32_16x16x32_bf16 v[20:23], v[186:189], v[218:221], v[20:23]
	v_mfma_f32_16x16x32_bf16 v[16:19], v[194:197], v[218:221], v[16:19]
	v_mfma_f32_16x16x32_bf16 v[4:7], v[186:189], v[230:233], v[4:7]
	v_mfma_f32_16x16x32_bf16 v[0:3], v[194:197], v[230:233], v[0:3]
	s_setprio 0
	s_barrier
	s_add_i32 s3, 0, 0x18000
	v_add_u32_e32 v144, s3, v165
	s_add_i32 s27, 0, 0x1c000
	ds_read_b128 v[128:131], v144
	ds_read_b128 v[132:135], v144 offset:1024
	ds_read_b128 v[158:161], v144 offset:2048
	ds_read_b128 v[178:181], v144 offset:3072
	v_add_u32_e32 v144, s27, v165
	ds_read_b128 v[182:185], v144
	ds_read_b128 v[186:189], v144 offset:1024
	ds_read_b128 v[190:193], v144 offset:2048
	ds_read_b128 v[194:197], v144 offset:3072
	s_add_u32 s36, vcc_lo, 0x80000
	s_addc_u32 s37, vcc_hi, 0
	s_mov_b32 m0, s58
	ds_read_b128 v[198:201], v175 offset:32768
	ds_read_b128 v[202:205], v175 offset:33792
	ds_read_b128 v[206:209], v175 offset:34816
	ds_read_b128 v[210:213], v175 offset:35840
	ds_read_b128 v[214:217], v175 offset:36864
	ds_read_b128 v[218:221], v175 offset:37888
	ds_read_b128 v[222:225], v175 offset:38912
	ds_read_b128 v[230:233], v175 offset:39936
	global_load_lds_dwordx4 v136, s[36:37]
	s_mov_b32 m0, s59
	s_nop 0
	global_load_lds_dwordx4 v140, s[36:37]
	s_waitcnt vmcnt(8)
	s_waitcnt lgkmcnt(0)
	s_barrier
	s_setprio 1
	s_waitcnt lgkmcnt(0)
	v_mfma_f32_16x16x32_bf16 v[124:127], v[128:131], v[198:201], v[124:127]
	v_mfma_f32_16x16x32_bf16 v[120:123], v[158:161], v[198:201], v[120:123]
	v_mfma_f32_16x16x32_bf16 v[108:111], v[128:131], v[206:209], v[108:111]
	v_mfma_f32_16x16x32_bf16 v[104:107], v[158:161], v[206:209], v[104:107]
	v_mfma_f32_16x16x32_bf16 v[92:95], v[128:131], v[214:217], v[92:95]
	v_mfma_f32_16x16x32_bf16 v[88:91], v[158:161], v[214:217], v[88:91]
	v_mfma_f32_16x16x32_bf16 v[76:79], v[128:131], v[222:225], v[76:79]
	v_mfma_f32_16x16x32_bf16 v[72:75], v[158:161], v[222:225], v[72:75]
	v_mfma_f32_16x16x32_bf16 v[124:127], v[132:135], v[202:205], v[124:127]
	v_mfma_f32_16x16x32_bf16 v[120:123], v[178:181], v[202:205], v[120:123]
	v_mfma_f32_16x16x32_bf16 v[108:111], v[132:135], v[210:213], v[108:111]
	v_mfma_f32_16x16x32_bf16 v[104:107], v[178:181], v[210:213], v[104:107]
	v_mfma_f32_16x16x32_bf16 v[92:95], v[132:135], v[218:221], v[92:95]
	v_mfma_f32_16x16x32_bf16 v[88:91], v[178:181], v[218:221], v[88:91]
	v_mfma_f32_16x16x32_bf16 v[76:79], v[132:135], v[230:233], v[76:79]
	v_mfma_f32_16x16x32_bf16 v[72:75], v[178:181], v[230:233], v[72:75]
	s_setprio 0
	s_setprio 1
	v_mfma_f32_16x16x32_bf16 v[116:119], v[182:185], v[198:201], v[116:119]
	v_mfma_f32_16x16x32_bf16 v[112:115], v[190:193], v[198:201], v[112:115]
	v_mfma_f32_16x16x32_bf16 v[100:103], v[182:185], v[206:209], v[100:103]
	v_mfma_f32_16x16x32_bf16 v[96:99], v[190:193], v[206:209], v[96:99]
	v_mfma_f32_16x16x32_bf16 v[84:87], v[182:185], v[214:217], v[84:87]
	v_mfma_f32_16x16x32_bf16 v[80:83], v[190:193], v[214:217], v[80:83]
	v_mfma_f32_16x16x32_bf16 v[68:71], v[182:185], v[222:225], v[68:71]
	v_mfma_f32_16x16x32_bf16 v[64:67], v[190:193], v[222:225], v[64:67]
	v_mfma_f32_16x16x32_bf16 v[116:119], v[186:189], v[202:205], v[116:119]
	v_mfma_f32_16x16x32_bf16 v[112:115], v[194:197], v[202:205], v[112:115]
	v_mfma_f32_16x16x32_bf16 v[100:103], v[186:189], v[210:213], v[100:103]
	v_mfma_f32_16x16x32_bf16 v[96:99], v[194:197], v[210:213], v[96:99]
	v_mfma_f32_16x16x32_bf16 v[84:87], v[186:189], v[218:221], v[84:87]
	v_mfma_f32_16x16x32_bf16 v[80:83], v[194:197], v[218:221], v[80:83]
	v_mfma_f32_16x16x32_bf16 v[68:71], v[186:189], v[230:233], v[68:71]
	v_mfma_f32_16x16x32_bf16 v[64:67], v[194:197], v[230:233], v[64:67]
	s_setprio 0
	s_barrier
	s_add_i32 s3, s3, s25
	s_add_u32 s36, s80, 0x80
	s_addc_u32 s37, s81, 0
	s_mov_b32 m0, s3
	ds_read_b128 v[198:201], v175 offset:49152
	ds_read_b128 v[202:205], v175 offset:50176
	ds_read_b128 v[206:209], v175 offset:51200
	ds_read_b128 v[210:213], v175 offset:52224
	ds_read_b128 v[214:217], v175 offset:53248
	ds_read_b128 v[218:221], v175 offset:54272
	ds_read_b128 v[222:225], v175 offset:55296
	ds_read_b128 v[230:233], v175 offset:56320
	global_load_lds_dwordx4 v138, s[36:37]
	s_add_i32 m0, s3, 0x2000
	s_add_i32 s3, s27, s25
	global_load_lds_dwordx4 v142, s[36:37]
	s_add_u32 s36, s36, 0x80000
	s_addc_u32 s37, s37, 0
	s_mov_b32 m0, s3
	s_nop 0
	global_load_lds_dwordx4 v138, s[36:37]
	s_add_i32 m0, s3, 0x2000
	s_nop 0
	global_load_lds_dwordx4 v142, s[36:37]
	s_add_u32 vcc_lo, vcc_lo, 0x80
	s_addc_u32 vcc_hi, vcc_hi, 0
	s_mov_b32 m0, s78
	s_nop 0
	global_load_lds_dwordx4 v136, vcc
	s_mov_b32 m0, s56
	s_nop 0
	global_load_lds_dwordx4 v140, vcc
	s_waitcnt vmcnt(8)
	s_waitcnt lgkmcnt(0)
	s_barrier
	s_setprio 1
	s_waitcnt lgkmcnt(0)
	v_mfma_f32_16x16x32_bf16 v[60:63], v[128:131], v[198:201], v[60:63]
	v_mfma_f32_16x16x32_bf16 v[56:59], v[158:161], v[198:201], v[56:59]
	v_mfma_f32_16x16x32_bf16 v[44:47], v[128:131], v[206:209], v[44:47]
	v_mfma_f32_16x16x32_bf16 v[40:43], v[158:161], v[206:209], v[40:43]
	v_mfma_f32_16x16x32_bf16 v[28:31], v[128:131], v[214:217], v[28:31]
	v_mfma_f32_16x16x32_bf16 v[24:27], v[158:161], v[214:217], v[24:27]
	v_mfma_f32_16x16x32_bf16 v[12:15], v[128:131], v[222:225], v[12:15]
	v_mfma_f32_16x16x32_bf16 v[8:11], v[158:161], v[222:225], v[8:11]
	v_mfma_f32_16x16x32_bf16 v[60:63], v[132:135], v[202:205], v[60:63]
	v_mfma_f32_16x16x32_bf16 v[56:59], v[178:181], v[202:205], v[56:59]
	v_mfma_f32_16x16x32_bf16 v[44:47], v[132:135], v[210:213], v[44:47]
	v_mfma_f32_16x16x32_bf16 v[40:43], v[178:181], v[210:213], v[40:43]
	v_mfma_f32_16x16x32_bf16 v[28:31], v[132:135], v[218:221], v[28:31]
	v_mfma_f32_16x16x32_bf16 v[24:27], v[178:181], v[218:221], v[24:27]
	v_mfma_f32_16x16x32_bf16 v[12:15], v[132:135], v[230:233], v[12:15]
	v_mfma_f32_16x16x32_bf16 v[8:11], v[178:181], v[230:233], v[8:11]
	s_setprio 0
	s_setprio 1
	v_mfma_f32_16x16x32_bf16 v[52:55], v[182:185], v[198:201], v[52:55]
	v_mfma_f32_16x16x32_bf16 v[48:51], v[190:193], v[198:201], v[48:51]
	v_mfma_f32_16x16x32_bf16 v[36:39], v[182:185], v[206:209], v[36:39]
	v_mfma_f32_16x16x32_bf16 v[32:35], v[190:193], v[206:209], v[32:35]
	v_mfma_f32_16x16x32_bf16 v[20:23], v[182:185], v[214:217], v[20:23]
	v_mfma_f32_16x16x32_bf16 v[16:19], v[190:193], v[214:217], v[16:19]
	v_mfma_f32_16x16x32_bf16 v[4:7], v[182:185], v[222:225], v[4:7]
	v_mfma_f32_16x16x32_bf16 v[0:3], v[190:193], v[222:225], v[0:3]
	v_mfma_f32_16x16x32_bf16 v[52:55], v[186:189], v[202:205], v[52:55]
	v_mfma_f32_16x16x32_bf16 v[48:51], v[194:197], v[202:205], v[48:51]
	v_mfma_f32_16x16x32_bf16 v[36:39], v[186:189], v[210:213], v[36:39]
	v_mfma_f32_16x16x32_bf16 v[32:35], v[194:197], v[210:213], v[32:35]
	v_mfma_f32_16x16x32_bf16 v[20:23], v[186:189], v[218:221], v[20:23]
	v_mfma_f32_16x16x32_bf16 v[16:19], v[194:197], v[218:221], v[16:19]
	v_mfma_f32_16x16x32_bf16 v[4:7], v[186:189], v[230:233], v[4:7]
	v_mfma_f32_16x16x32_bf16 v[0:3], v[194:197], v[230:233], v[0:3]
	s_setprio 0
	s_barrier
	s_add_i32 s24, s24, 2
	s_add_u32 s34, s34, 0x100
	s_addc_u32 s35, s35, 0
	s_add_u32 s18, s18, 0x100
	s_addc_u32 s19, s19, 0
	s_cmp_gt_u32 s24, 29
	s_cbranch_scc0 .LBB0_919
	s_and_b64 vcc, exec, s[86:87]
	s_cbranch_vccz .LBB0_922
	s_barrier

.LBB0_1249:
	s_cmp_eq_u32 s86, 0
	s_cselect_b64 s[0:1], -1, 0
	s_or_b64 s[0:1], s[88:89], s[0:1]
	s_and_b64 vcc, exec, s[0:1]
	s_cbranch_vccnz .Lfz1_c1
	s_add_i32 s0, s77, 0xc000
	s_and_b32 s0, s0, 0xc000
	v_add_u32_e32 v0, s0, v234
	ds_read_b64_tr_b16 v[160:161], v0 offset:0x2000
	ds_read_b64_tr_b16 v[162:163], v0 offset:0x2100
	ds_read_b64_tr_b16 v[164:165], v0 offset:0x3000
	ds_read_b64_tr_b16 v[166:167], v0 offset:0x3100
	s_waitcnt lgkmcnt(2)
	v_mfma_f32_32x32x16_bf16 v[128:143], v[6:9], v[160:163], v[128:143]
	ds_read_b64_tr_b16 v[168:169], v0 offset:0x2200
	v_mfma_f32_32x32x16_bf16 v[96:111], v[2:5], v[160:163], v[96:111]
	ds_read_b64_tr_b16 v[170:171], v0 offset:0x2300
	s_waitcnt lgkmcnt(2)
	v_mfma_f32_32x32x16_bf16 v[128:143], v[208:211], v[164:167], v[128:143]
	ds_read_b64_tr_b16 v[172:173], v0 offset:0x3200
	v_mfma_f32_32x32x16_bf16 v[96:111], v[10:13], v[164:167], v[96:111]
	ds_read_b64_tr_b16 v[174:175], v0 offset:0x3300
	s_waitcnt lgkmcnt(2)
	v_mfma_f32_32x32x16_bf16 v[112:127], v[6:9], v[168:171], v[112:127]
	ds_read_b64_tr_b16 v[160:161], v0 offset:0x2400
	v_mfma_f32_32x32x16_bf16 v[80:95], v[2:5], v[168:171], v[80:95]
	ds_read_b64_tr_b16 v[162:163], v0 offset:0x2500
	s_waitcnt lgkmcnt(2)
	v_mfma_f32_32x32x16_bf16 v[112:127], v[208:211], v[172:175], v[112:127]
	ds_read_b64_tr_b16 v[164:165], v0 offset:0x3400
	v_mfma_f32_32x32x16_bf16 v[80:95], v[10:13], v[172:175], v[80:95]
	ds_read_b64_tr_b16 v[166:167], v0 offset:0x3500
	s_waitcnt lgkmcnt(2)
	v_mfma_f32_32x32x16_bf16 v[64:79], v[6:9], v[160:163], v[64:79]
	ds_read_b64_tr_b16 v[168:169], v0 offset:0x2600
	v_mfma_f32_32x32x16_bf16 v[48:63], v[2:5], v[160:163], v[48:63]
	ds_read_b64_tr_b16 v[170:171], v0 offset:0x2700
	s_waitcnt lgkmcnt(2)
	v_mfma_f32_32x32x16_bf16 v[64:79], v[208:211], v[164:167], v[64:79]
	ds_read_b64_tr_b16 v[172:173], v0 offset:0x3600
	v_mfma_f32_32x32x16_bf16 v[48:63], v[10:13], v[164:167], v[48:63]
	ds_read_b64_tr_b16 v[174:175], v0 offset:0x3700
	s_waitcnt lgkmcnt(2)
	v_mfma_f32_32x32x16_bf16 v[32:47], v[6:9], v[168:171], v[32:47]
	v_mfma_f32_32x32x16_bf16 v[16:31], v[2:5], v[168:171], v[16:31]
	s_waitcnt lgkmcnt(0)
	v_mfma_f32_32x32x16_bf16 v[32:47], v[208:211], v[172:175], v[32:47]
	v_mfma_f32_32x32x16_bf16 v[16:31], v[10:13], v[172:175], v[16:31]
.Lfz1_c1:
	s_and_b32 s27, s77, 0xc000
	v_add_u32_e32 v241, s27, v233
	ds_read_b128 v[144:147], v241 offset:0
	v_xor_b32_e32 v240, 32, v241
	ds_read_b128 v[148:151], v240 offset:0
	v_xor_b32_e32 v239, 64, v241
	ds_read_b128 v[152:155], v239 offset:0
	v_xor_b32_e32 v0, 0x60, v241
	ds_read_b128 v[156:159], v0 offset:0
	s_waitcnt lgkmcnt(0)
	v_mfma_f32_32x32x16_bf16 v[212:227], v[144:147], v[176:179], 0
	v_mfma_f32_32x32x16_bf16 v[212:227], v[148:151], v[180:183], v[212:227]
	v_mfma_f32_32x32x16_bf16 v[212:227], v[152:155], v[184:187], v[212:227]
	v_mfma_f32_32x32x16_bf16 v[212:227], v[156:159], v[188:191], v[212:227]
	ds_read_b128 v[144:147], v241 offset:0x80
	ds_read_b128 v[148:151], v240 offset:0x80
	ds_read_b128 v[152:155], v239 offset:0x80
	ds_read_b128 v[156:159], v0 offset:0x80
	v_cmp_eq_f32_e32 vcc, 0, v238
	v_cmp_eq_f32_e64 s[10:11], 0, v237
	s_and_b64 s[0:1], vcc, s[10:11]
	s_cmp_eq_u64 s[0:1], exec
	s_waitcnt lgkmcnt(0)
	v_mfma_f32_32x32x16_bf16 v[160:175], v[144:147], v[192:195], 0
	v_mfma_f32_32x32x16_bf16 v[160:175], v[148:151], v[196:199], v[160:175]
	v_mfma_f32_32x32x16_bf16 v[160:175], v[152:155], v[200:203], v[160:175]
	v_mfma_f32_32x32x16_bf16 v[160:175], v[156:159], v[204:207], v[160:175]
	s_cbranch_scc0 .LBB0_1251
	v_exp_f32_e32 v144, v212
	v_exp_f32_e32 v145, v213
	v_exp_f32_e32 v146, v214
	v_exp_f32_e32 v147, v215
	v_exp_f32_e32 v148, v216
	v_exp_f32_e32 v149, v217
	v_exp_f32_e32 v150, v218
	v_exp_f32_e32 v151, v219
	v_exp_f32_e32 v152, v220
	v_exp_f32_e32 v153, v221
	v_exp_f32_e32 v154, v222
	v_exp_f32_e32 v155, v223
	v_exp_f32_e32 v156, v224
	v_exp_f32_e32 v157, v225
	v_exp_f32_e32 v158, v226
	v_exp_f32_e32 v159, v227
	v_add_f32_e32 v252, v144, v145
	v_add_f32_e32 v253, v146, v147
	v_add_f32_e32 v254, v148, v149
	v_add_f32_e32 v255, v150, v151
	v_add_f32_e32 v252, v252, v152
	v_add_f32_e32 v253, v253, v153
	v_add_f32_e32 v254, v254, v154
	v_add_f32_e32 v255, v255, v155
	v_add_f32_e32 v252, v252, v156
	v_add_f32_e32 v253, v253, v157
	v_add_f32_e32 v254, v254, v158
	v_add_f32_e32 v255, v255, v159
	v_cvt_pk_bf16_f32 v216, v144, v145
	v_cvt_pk_bf16_f32 v217, v146, v147
	v_add_f32_e32 v252, v252, v253
	v_add_f32_e32 v254, v254, v255
	v_cvt_pk_bf16_f32 v218, v148, v149
	v_cvt_pk_bf16_f32 v219, v150, v151
	v_cvt_pk_bf16_f32 v224, v152, v153
	v_add_f32_e32 v252, v252, v254
	v_cvt_pk_bf16_f32 v225, v154, v155
	v_cvt_pk_bf16_f32 v226, v156, v157
	v_cvt_pk_bf16_f32 v227, v158, v159
	v_add_u32_e32 v253, 0xde801b54, v252
	v_cmp_gt_u32_e32 vcc, 0x3bff7543, v253
	s_cmp_lg_u64 vcc, exec
	s_cbranch_scc1 .LBB0_1286
	v_add_f32_e32 v15, v15, v252
	v_exp_f32_e32 v144, v160
	v_exp_f32_e32 v145, v161
	v_exp_f32_e32 v146, v162
	v_exp_f32_e32 v147, v163
	v_exp_f32_e32 v148, v164
	v_exp_f32_e32 v149, v165
	v_exp_f32_e32 v150, v166
	v_exp_f32_e32 v151, v167
	v_exp_f32_e32 v152, v168
	v_exp_f32_e32 v153, v169
	v_exp_f32_e32 v154, v170
	v_exp_f32_e32 v155, v171
	v_exp_f32_e32 v156, v172
	v_exp_f32_e32 v157, v173
	v_exp_f32_e32 v158, v174
	v_exp_f32_e32 v159, v175
	v_add_f32_e32 v252, v144, v145
	v_add_f32_e32 v253, v146, v147
	v_add_f32_e32 v254, v148, v149
	v_add_f32_e32 v255, v150, v151
	v_add_f32_e32 v252, v252, v152
	v_add_f32_e32 v253, v253, v153
	v_add_f32_e32 v254, v254, v154
	v_add_f32_e32 v255, v255, v155
	v_add_f32_e32 v252, v252, v156
	v_add_f32_e32 v253, v253, v157
	v_add_f32_e32 v254, v254, v158
	v_add_f32_e32 v255, v255, v159
	v_cvt_pk_bf16_f32 v212, v144, v145
	v_cvt_pk_bf16_f32 v213, v146, v147
	v_add_f32_e32 v252, v252, v253
	v_add_f32_e32 v254, v254, v255
	v_cvt_pk_bf16_f32 v214, v148, v149
	v_cvt_pk_bf16_f32 v215, v150, v151
	v_cvt_pk_bf16_f32 v220, v152, v153
	v_add_f32_e32 v252, v252, v254
	v_cvt_pk_bf16_f32 v221, v154, v155
	v_cvt_pk_bf16_f32 v222, v156, v157
	v_cvt_pk_bf16_f32 v223, v158, v159
	v_add_u32_e32 v253, 0xde801b54, v252
	v_cmp_gt_u32_e32 vcc, 0x3bff7543, v253
	s_cmp_lg_u64 vcc, exec
	s_cbranch_scc1 .Lfzsb1_c1
	v_add_f32_e32 v14, v14, v252
	s_branch .LBB0_1267

.LBB0_1267:
	v_add_u32_e32 v242, s27, v234
	ds_read_b64_tr_b16 v[160:161], v242 offset:0x0
	ds_read_b64_tr_b16 v[162:163], v242 offset:0x100
	ds_read_b64_tr_b16 v[164:165], v242 offset:0x1000
	ds_read_b64_tr_b16 v[166:167], v242 offset:0x1100
	s_waitcnt lgkmcnt(2)
	v_mfma_f32_32x32x16_bf16 v[128:143], v[216:219], v[160:163], v[128:143]
	ds_read_b64_tr_b16 v[168:169], v242 offset:0x200
	v_mfma_f32_32x32x16_bf16 v[96:111], v[212:215], v[160:163], v[96:111]
	ds_read_b64_tr_b16 v[170:171], v242 offset:0x300
	s_waitcnt lgkmcnt(2)
	v_mfma_f32_32x32x16_bf16 v[128:143], v[224:227], v[164:167], v[128:143]
	ds_read_b64_tr_b16 v[172:173], v242 offset:0x1200
	v_mfma_f32_32x32x16_bf16 v[96:111], v[220:223], v[164:167], v[96:111]
	ds_read_b64_tr_b16 v[174:175], v242 offset:0x1300
	s_waitcnt lgkmcnt(2)
	v_mfma_f32_32x32x16_bf16 v[112:127], v[216:219], v[168:171], v[112:127]
	ds_read_b64_tr_b16 v[160:161], v242 offset:0x400
	v_mfma_f32_32x32x16_bf16 v[80:95], v[212:215], v[168:171], v[80:95]
	ds_read_b64_tr_b16 v[162:163], v242 offset:0x500
	s_waitcnt lgkmcnt(2)
	v_mfma_f32_32x32x16_bf16 v[112:127], v[224:227], v[172:175], v[112:127]
	ds_read_b64_tr_b16 v[164:165], v242 offset:0x1400
	v_mfma_f32_32x32x16_bf16 v[80:95], v[220:223], v[172:175], v[80:95]
	ds_read_b64_tr_b16 v[166:167], v242 offset:0x1500
	ds_read_b128 v[144:147], v241 offset:0x2000
	ds_read_b128 v[148:151], v240 offset:0x2000
	ds_read_b128 v[152:155], v239 offset:0x2000
	ds_read_b128 v[156:159], v0 offset:0x2000
	s_waitcnt lgkmcnt(6)
	v_mfma_f32_32x32x16_bf16 v[64:79], v[216:219], v[160:163], v[64:79]
	ds_read_b64_tr_b16 v[168:169], v242 offset:0x600
	v_mfma_f32_32x32x16_bf16 v[48:63], v[212:215], v[160:163], v[48:63]
	ds_read_b64_tr_b16 v[170:171], v242 offset:0x700
	s_waitcnt lgkmcnt(6)
	v_mfma_f32_32x32x16_bf16 v[64:79], v[224:227], v[164:167], v[64:79]
	ds_read_b64_tr_b16 v[172:173], v242 offset:0x1600
	v_mfma_f32_32x32x16_bf16 v[48:63], v[220:223], v[164:167], v[48:63]
	ds_read_b64_tr_b16 v[174:175], v242 offset:0x1700
	s_waitcnt lgkmcnt(2)
	v_mfma_f32_32x32x16_bf16 v[32:47], v[216:219], v[168:171], v[32:47]
	v_mfma_f32_32x32x16_bf16 v[16:31], v[212:215], v[168:171], v[16:31]
	s_waitcnt lgkmcnt(0)
	v_mfma_f32_32x32x16_bf16 v[32:47], v[224:227], v[172:175], v[32:47]
	v_mfma_f32_32x32x16_bf16 v[16:31], v[220:223], v[172:175], v[16:31]
	s_waitcnt lgkmcnt(0)
	v_mfma_f32_32x32x16_bf16 v[212:227], v[144:147], v[176:179], 0
	v_mfma_f32_32x32x16_bf16 v[212:227], v[148:151], v[180:183], v[212:227]
	v_mfma_f32_32x32x16_bf16 v[212:227], v[152:155], v[184:187], v[212:227]
	v_mfma_f32_32x32x16_bf16 v[212:227], v[156:159], v[188:191], v[212:227]
	ds_read_b128 v[144:147], v241 offset:0x2080
	ds_read_b128 v[148:151], v240 offset:0x2080
	ds_read_b128 v[152:155], v239 offset:0x2080
	ds_read_b128 v[156:159], v0 offset:0x2080
	v_cmp_eq_f32_e32 vcc, 0, v238
	v_cmp_eq_f32_e64 s[10:11], 0, v237
	s_and_b64 s[0:1], vcc, s[10:11]
	s_cmp_eq_u64 s[0:1], exec
	s_waitcnt lgkmcnt(0)
	v_mfma_f32_32x32x16_bf16 v[160:175], v[144:147], v[192:195], 0
	v_mfma_f32_32x32x16_bf16 v[160:175], v[148:151], v[196:199], v[160:175]
	v_mfma_f32_32x32x16_bf16 v[160:175], v[152:155], v[200:203], v[160:175]
	v_mfma_f32_32x32x16_bf16 v[160:175], v[156:159], v[204:207], v[160:175]
	s_cbranch_scc0 .Lfz2o_c1
	v_exp_f32_e32 v144, v212
	v_exp_f32_e32 v145, v213
	v_exp_f32_e32 v146, v214
	v_exp_f32_e32 v147, v215
	v_exp_f32_e32 v148, v216
	v_exp_f32_e32 v149, v217
	v_exp_f32_e32 v150, v218
	v_exp_f32_e32 v151, v219
	v_exp_f32_e32 v152, v220
	v_exp_f32_e32 v153, v221
	v_exp_f32_e32 v154, v222
	v_exp_f32_e32 v155, v223
	v_exp_f32_e32 v156, v224
	v_exp_f32_e32 v157, v225
	v_exp_f32_e32 v158, v226
	v_exp_f32_e32 v159, v227
	v_add_f32_e32 v252, v144, v145
	v_add_f32_e32 v253, v146, v147
	v_add_f32_e32 v254, v148, v149
	v_add_f32_e32 v255, v150, v151
	v_add_f32_e32 v252, v252, v152
	v_add_f32_e32 v253, v253, v153
	v_add_f32_e32 v254, v254, v154
	v_add_f32_e32 v255, v255, v155
	v_add_f32_e32 v252, v252, v156
	v_add_f32_e32 v253, v253, v157
	v_add_f32_e32 v254, v254, v158
	v_add_f32_e32 v255, v255, v159
	v_cvt_pk_bf16_f32 v6, v144, v145
	v_cvt_pk_bf16_f32 v7, v146, v147
	v_add_f32_e32 v252, v252, v253
	v_add_f32_e32 v254, v254, v255
	v_cvt_pk_bf16_f32 v8, v148, v149
	v_cvt_pk_bf16_f32 v9, v150, v151
	v_cvt_pk_bf16_f32 v208, v152, v153
	v_add_f32_e32 v252, v252, v254
	v_cvt_pk_bf16_f32 v209, v154, v155
	v_cvt_pk_bf16_f32 v210, v156, v157
	v_cvt_pk_bf16_f32 v211, v158, v159
	v_add_u32_e32 v253, 0xde801b54, v252
	v_cmp_gt_u32_e32 vcc, 0x3bff7543, v253
	s_cmp_lg_u64 vcc, exec
	s_cbranch_scc1 .LBB0_1298
	v_add_f32_e32 v15, v15, v252
	v_exp_f32_e32 v144, v160
	v_exp_f32_e32 v145, v161
	v_exp_f32_e32 v146, v162
	v_exp_f32_e32 v147, v163
	v_exp_f32_e32 v148, v164
	v_exp_f32_e32 v149, v165
	v_exp_f32_e32 v150, v166
	v_exp_f32_e32 v151, v167
	v_exp_f32_e32 v152, v168
	v_exp_f32_e32 v153, v169
	v_exp_f32_e32 v154, v170
	v_exp_f32_e32 v155, v171
	v_exp_f32_e32 v156, v172
	v_exp_f32_e32 v157, v173
	v_exp_f32_e32 v158, v174
	v_exp_f32_e32 v159, v175
	v_add_f32_e32 v252, v144, v145
	v_add_f32_e32 v253, v146, v147
	v_add_f32_e32 v254, v148, v149
	v_add_f32_e32 v255, v150, v151
	v_add_f32_e32 v252, v252, v152
	v_add_f32_e32 v253, v253, v153
	v_add_f32_e32 v254, v254, v154
	v_add_f32_e32 v255, v255, v155
	v_add_f32_e32 v252, v252, v156
	v_add_f32_e32 v253, v253, v157
	v_add_f32_e32 v254, v254, v158
	v_add_f32_e32 v255, v255, v159
	v_cvt_pk_bf16_f32 v2, v144, v145
	v_cvt_pk_bf16_f32 v3, v146, v147
	v_add_f32_e32 v252, v252, v253
	v_add_f32_e32 v254, v254, v255
	v_cvt_pk_bf16_f32 v4, v148, v149
	v_cvt_pk_bf16_f32 v5, v150, v151
	v_cvt_pk_bf16_f32 v10, v152, v153
	v_add_f32_e32 v252, v252, v254
	v_cvt_pk_bf16_f32 v11, v154, v155
	v_cvt_pk_bf16_f32 v12, v156, v157
	v_cvt_pk_bf16_f32 v13, v158, v159
	v_add_u32_e32 v253, 0xde801b54, v252
	v_cmp_gt_u32_e32 vcc, 0x3bff7543, v253
	s_cmp_lg_u64 vcc, exec
	s_cbranch_scc1 .Lfzsb2_c1
	v_add_f32_e32 v14, v14, v252
	s_branch .LBB0_1283

.LBB0_1283:
	s_andn2_b64 vcc, exec, s[84:85]
	s_cbranch_vccnz .LBB0_1242
	ds_read_b64_tr_b16 v[160:161], v242 offset:0x2000
	ds_read_b64_tr_b16 v[162:163], v242 offset:0x2100
	ds_read_b64_tr_b16 v[164:165], v242 offset:0x3000
	ds_read_b64_tr_b16 v[166:167], v242 offset:0x3100
	s_waitcnt lgkmcnt(2)
	v_mfma_f32_32x32x16_bf16 v[128:143], v[6:9], v[160:163], v[128:143]
	ds_read_b64_tr_b16 v[168:169], v242 offset:0x2200
	v_mfma_f32_32x32x16_bf16 v[96:111], v[2:5], v[160:163], v[96:111]
	ds_read_b64_tr_b16 v[170:171], v242 offset:0x2300
	s_waitcnt lgkmcnt(2)
	v_mfma_f32_32x32x16_bf16 v[128:143], v[208:211], v[164:167], v[128:143]
	ds_read_b64_tr_b16 v[172:173], v242 offset:0x3200
	v_mfma_f32_32x32x16_bf16 v[96:111], v[10:13], v[164:167], v[96:111]
	ds_read_b64_tr_b16 v[174:175], v242 offset:0x3300
	s_waitcnt lgkmcnt(2)
	v_mfma_f32_32x32x16_bf16 v[112:127], v[6:9], v[168:171], v[112:127]
	ds_read_b64_tr_b16 v[160:161], v242 offset:0x2400
	v_mfma_f32_32x32x16_bf16 v[80:95], v[2:5], v[168:171], v[80:95]
	ds_read_b64_tr_b16 v[162:163], v242 offset:0x2500
	s_waitcnt lgkmcnt(2)
	v_mfma_f32_32x32x16_bf16 v[112:127], v[208:211], v[172:175], v[112:127]
	ds_read_b64_tr_b16 v[164:165], v242 offset:0x3400
	v_mfma_f32_32x32x16_bf16 v[80:95], v[10:13], v[172:175], v[80:95]
	ds_read_b64_tr_b16 v[166:167], v242 offset:0x3500
	s_waitcnt lgkmcnt(2)
	v_mfma_f32_32x32x16_bf16 v[64:79], v[6:9], v[160:163], v[64:79]
	ds_read_b64_tr_b16 v[168:169], v242 offset:0x2600
	v_mfma_f32_32x32x16_bf16 v[48:63], v[2:5], v[160:163], v[48:63]
	ds_read_b64_tr_b16 v[170:171], v242 offset:0x2700
	s_waitcnt lgkmcnt(2)
	v_mfma_f32_32x32x16_bf16 v[64:79], v[208:211], v[164:167], v[64:79]
	ds_read_b64_tr_b16 v[172:173], v242 offset:0x3600
	v_mfma_f32_32x32x16_bf16 v[48:63], v[10:13], v[164:167], v[48:63]
	ds_read_b64_tr_b16 v[174:175], v242 offset:0x3700
	s_waitcnt lgkmcnt(2)
	v_mfma_f32_32x32x16_bf16 v[32:47], v[6:9], v[168:171], v[32:47]
	v_mfma_f32_32x32x16_bf16 v[16:31], v[2:5], v[168:171], v[16:31]
	s_waitcnt lgkmcnt(0)
	v_mfma_f32_32x32x16_bf16 v[32:47], v[208:211], v[172:175], v[32:47]
	v_mfma_f32_32x32x16_bf16 v[16:31], v[10:13], v[172:175], v[16:31]
	s_branch .LBB0_1242

.LBB0_1317:
	s_and_b64 vcc, exec, s[34:35]
	s_cbranch_vccz .LBB0_1319
	s_cmp_lg_u32 0, -1
	s_cselect_b32 s0, 0, 0
	s_add_i32 s0, s0, 0xc000
	v_add_u32_e32 v0, s0, v232
	ds_read_b64_tr_b16 v[160:161], v0 offset:0x2000
	ds_read_b64_tr_b16 v[162:163], v0 offset:0x2100
	ds_read_b64_tr_b16 v[164:165], v0 offset:0x3000
	ds_read_b64_tr_b16 v[166:167], v0 offset:0x3100
	s_waitcnt lgkmcnt(2)
	v_mfma_f32_32x32x16_bf16 v[128:143], v[6:9], v[160:163], v[128:143]
	ds_read_b64_tr_b16 v[168:169], v0 offset:0x2200
	v_mfma_f32_32x32x16_bf16 v[96:111], v[2:5], v[160:163], v[96:111]
	ds_read_b64_tr_b16 v[170:171], v0 offset:0x2300
	s_waitcnt lgkmcnt(2)
	v_mfma_f32_32x32x16_bf16 v[128:143], v[208:211], v[164:167], v[128:143]
	ds_read_b64_tr_b16 v[172:173], v0 offset:0x3200
	v_mfma_f32_32x32x16_bf16 v[96:111], v[10:13], v[164:167], v[96:111]
	ds_read_b64_tr_b16 v[174:175], v0 offset:0x3300
	s_waitcnt lgkmcnt(2)
	v_mfma_f32_32x32x16_bf16 v[112:127], v[6:9], v[168:171], v[112:127]
	ds_read_b64_tr_b16 v[160:161], v0 offset:0x2400
	v_mfma_f32_32x32x16_bf16 v[80:95], v[2:5], v[168:171], v[80:95]
	ds_read_b64_tr_b16 v[162:163], v0 offset:0x2500
	s_waitcnt lgkmcnt(2)
	v_mfma_f32_32x32x16_bf16 v[112:127], v[208:211], v[172:175], v[112:127]
	ds_read_b64_tr_b16 v[164:165], v0 offset:0x3400
	v_mfma_f32_32x32x16_bf16 v[80:95], v[10:13], v[172:175], v[80:95]
	ds_read_b64_tr_b16 v[166:167], v0 offset:0x3500
	s_waitcnt lgkmcnt(2)
	v_mfma_f32_32x32x16_bf16 v[64:79], v[6:9], v[160:163], v[64:79]
	ds_read_b64_tr_b16 v[168:169], v0 offset:0x2600
	v_mfma_f32_32x32x16_bf16 v[48:63], v[2:5], v[160:163], v[48:63]
	ds_read_b64_tr_b16 v[170:171], v0 offset:0x2700
	s_waitcnt lgkmcnt(2)
	v_mfma_f32_32x32x16_bf16 v[64:79], v[208:211], v[164:167], v[64:79]
	ds_read_b64_tr_b16 v[172:173], v0 offset:0x3600
	v_mfma_f32_32x32x16_bf16 v[48:63], v[10:13], v[164:167], v[48:63]
	ds_read_b64_tr_b16 v[174:175], v0 offset:0x3700
	s_waitcnt lgkmcnt(2)
	v_mfma_f32_32x32x16_bf16 v[32:47], v[6:9], v[168:171], v[32:47]
	v_mfma_f32_32x32x16_bf16 v[16:31], v[2:5], v[168:171], v[16:31]
	s_waitcnt lgkmcnt(0)
	v_mfma_f32_32x32x16_bf16 v[32:47], v[208:211], v[172:175], v[32:47]
	v_mfma_f32_32x32x16_bf16 v[16:31], v[10:13], v[172:175], v[16:31]

.LBB0_1393:
	ds_read_b128 v[144:147], v153
	ds_read_b128 v[156:159], v153 offset:1024
	ds_read_b128 v[160:163], v153 offset:2048
	ds_read_b128 v[164:167], v153 offset:3072
	ds_read_b128 v[168:171], v154
	ds_read_b128 v[172:175], v154 offset:1024
	ds_read_b128 v[176:179], v154 offset:2048
	ds_read_b128 v[180:183], v154 offset:3072
	s_add_u32 s3, s88, 0xfffc0080
	s_addc_u32 s37, s89, -1
	s_cmp_eq_u32 s36, 12
	s_cselect_b32 s91, s0, s37
	s_cselect_b32 s90, s1, s3
	s_cselect_b32 s81, s17, s35
	s_cselect_b32 s80, s27, s33
	s_add_i32 m0, s19, 0xc000
	ds_read_b128 v[184:187], v155
	ds_read_b128 v[188:191], v155 offset:1024
	ds_read_b128 v[192:195], v155 offset:2048
	ds_read_b128 v[196:199], v155 offset:3072
	ds_read_b128 v[200:203], v155 offset:4096
	ds_read_b128 v[204:207], v155 offset:5120
	ds_read_b128 v[208:211], v155 offset:6144
	ds_read_b128 v[212:215], v155 offset:7168
	global_load_lds_dwordx4 v136, s[88:89]
	s_add_i32 m0, s19, 0xe000
	s_nop 0
	global_load_lds_dwordx4 v138, s[88:89]
	s_waitcnt vmcnt(8)
	s_waitcnt lgkmcnt(0)
	s_barrier
	s_setprio 1
	s_waitcnt lgkmcnt(0)
	v_mfma_f32_16x16x32_bf16 v[124:127], v[144:147], v[184:187], v[124:127]
	v_mfma_f32_16x16x32_bf16 v[120:123], v[160:163], v[184:187], v[120:123]
	v_mfma_f32_16x16x32_bf16 v[108:111], v[144:147], v[192:195], v[108:111]
	v_mfma_f32_16x16x32_bf16 v[104:107], v[160:163], v[192:195], v[104:107]
	v_mfma_f32_16x16x32_bf16 v[92:95], v[144:147], v[200:203], v[92:95]
	v_mfma_f32_16x16x32_bf16 v[88:91], v[160:163], v[200:203], v[88:91]
	v_mfma_f32_16x16x32_bf16 v[76:79], v[144:147], v[208:211], v[76:79]
	v_mfma_f32_16x16x32_bf16 v[72:75], v[160:163], v[208:211], v[72:75]
	v_mfma_f32_16x16x32_bf16 v[124:127], v[156:159], v[188:191], v[124:127]
	v_mfma_f32_16x16x32_bf16 v[120:123], v[164:167], v[188:191], v[120:123]
	v_mfma_f32_16x16x32_bf16 v[108:111], v[156:159], v[196:199], v[108:111]
	v_mfma_f32_16x16x32_bf16 v[104:107], v[164:167], v[196:199], v[104:107]
	v_mfma_f32_16x16x32_bf16 v[92:95], v[156:159], v[204:207], v[92:95]
	v_mfma_f32_16x16x32_bf16 v[88:91], v[164:167], v[204:207], v[88:91]
	v_mfma_f32_16x16x32_bf16 v[76:79], v[156:159], v[212:215], v[76:79]
	v_mfma_f32_16x16x32_bf16 v[72:75], v[164:167], v[212:215], v[72:75]
	s_setprio 0
	s_setprio 1
	v_mfma_f32_16x16x32_bf16 v[116:119], v[168:171], v[184:187], v[116:119]
	v_mfma_f32_16x16x32_bf16 v[112:115], v[176:179], v[184:187], v[112:115]
	v_mfma_f32_16x16x32_bf16 v[100:103], v[168:171], v[192:195], v[100:103]
	v_mfma_f32_16x16x32_bf16 v[96:99], v[176:179], v[192:195], v[96:99]
	v_mfma_f32_16x16x32_bf16 v[84:87], v[168:171], v[200:203], v[84:87]
	v_mfma_f32_16x16x32_bf16 v[80:83], v[176:179], v[200:203], v[80:83]
	v_mfma_f32_16x16x32_bf16 v[68:71], v[168:171], v[208:211], v[68:71]
	v_mfma_f32_16x16x32_bf16 v[64:67], v[176:179], v[208:211], v[64:67]
	v_mfma_f32_16x16x32_bf16 v[116:119], v[172:175], v[188:191], v[116:119]
	v_mfma_f32_16x16x32_bf16 v[112:115], v[180:183], v[188:191], v[112:115]
	v_mfma_f32_16x16x32_bf16 v[100:103], v[172:175], v[196:199], v[100:103]
	v_mfma_f32_16x16x32_bf16 v[96:99], v[180:183], v[196:199], v[96:99]
	v_mfma_f32_16x16x32_bf16 v[84:87], v[172:175], v[204:207], v[84:87]
	v_mfma_f32_16x16x32_bf16 v[80:83], v[180:183], v[204:207], v[80:83]
	v_mfma_f32_16x16x32_bf16 v[68:71], v[172:175], v[212:215], v[68:71]
	v_mfma_f32_16x16x32_bf16 v[64:67], v[180:183], v[212:215], v[64:67]
	s_setprio 0
	s_barrier
	s_add_i32 s3, s57, s18
	s_mov_b32 m0, s3
	ds_read_b128 v[184:187], v155 offset:16384
	ds_read_b128 v[188:191], v155 offset:17408
	ds_read_b128 v[192:195], v155 offset:18432
	ds_read_b128 v[196:199], v155 offset:19456
	ds_read_b128 v[200:203], v155 offset:20480
	ds_read_b128 v[204:207], v155 offset:21504
	ds_read_b128 v[208:211], v155 offset:22528
	ds_read_b128 v[212:215], v155 offset:23552
	global_load_lds_dwordx4 v130, s[80:81]
	s_add_i32 m0, s3, 0x2000
	s_add_u32 s42, s80, 0x40000
	s_addc_u32 s43, s81, 0
	s_add_i32 s3, s58, s18
	global_load_lds_dwordx4 v134, s[80:81]
	s_mov_b32 m0, s3
	s_nop 0
	global_load_lds_dwordx4 v130, s[42:43]
	s_add_i32 m0, s3, 0x2000
	s_nop 0
	global_load_lds_dwordx4 v134, s[42:43]
	s_mov_b32 m0, s19
	s_nop 0
	global_load_lds_dwordx4 v128, s[90:91]
	s_mov_b32 m0, s25
	s_nop 0
	global_load_lds_dwordx4 v132, s[90:91]
	s_waitcnt vmcnt(8)
	s_waitcnt lgkmcnt(0)
	s_barrier
	s_setprio 1
	s_waitcnt lgkmcnt(0)
	v_mfma_f32_16x16x32_bf16 v[60:63], v[144:147], v[184:187], v[60:63]
	v_mfma_f32_16x16x32_bf16 v[56:59], v[160:163], v[184:187], v[56:59]
	v_mfma_f32_16x16x32_bf16 v[44:47], v[144:147], v[192:195], v[44:47]
	v_mfma_f32_16x16x32_bf16 v[40:43], v[160:163], v[192:195], v[40:43]
	v_mfma_f32_16x16x32_bf16 v[28:31], v[144:147], v[200:203], v[28:31]
	v_mfma_f32_16x16x32_bf16 v[24:27], v[160:163], v[200:203], v[24:27]
	v_mfma_f32_16x16x32_bf16 v[12:15], v[144:147], v[208:211], v[12:15]
	v_mfma_f32_16x16x32_bf16 v[8:11], v[160:163], v[208:211], v[8:11]
	v_mfma_f32_16x16x32_bf16 v[60:63], v[156:159], v[188:191], v[60:63]
	v_mfma_f32_16x16x32_bf16 v[56:59], v[164:167], v[188:191], v[56:59]
	v_mfma_f32_16x16x32_bf16 v[44:47], v[156:159], v[196:199], v[44:47]
	v_mfma_f32_16x16x32_bf16 v[40:43], v[164:167], v[196:199], v[40:43]
	v_mfma_f32_16x16x32_bf16 v[28:31], v[156:159], v[204:207], v[28:31]
	v_mfma_f32_16x16x32_bf16 v[24:27], v[164:167], v[204:207], v[24:27]
	v_mfma_f32_16x16x32_bf16 v[12:15], v[156:159], v[212:215], v[12:15]
	v_mfma_f32_16x16x32_bf16 v[8:11], v[164:167], v[212:215], v[8:11]
	s_setprio 0
	s_setprio 1
	v_mfma_f32_16x16x32_bf16 v[52:55], v[168:171], v[184:187], v[52:55]
	v_mfma_f32_16x16x32_bf16 v[48:51], v[176:179], v[184:187], v[48:51]
	v_mfma_f32_16x16x32_bf16 v[36:39], v[168:171], v[192:195], v[36:39]
	v_mfma_f32_16x16x32_bf16 v[32:35], v[176:179], v[192:195], v[32:35]
	v_mfma_f32_16x16x32_bf16 v[20:23], v[168:171], v[200:203], v[20:23]
	v_mfma_f32_16x16x32_bf16 v[16:19], v[176:179], v[200:203], v[16:19]
	v_mfma_f32_16x16x32_bf16 v[4:7], v[168:171], v[208:211], v[4:7]
	v_mfma_f32_16x16x32_bf16 v[0:3], v[176:179], v[208:211], v[0:3]
	v_mfma_f32_16x16x32_bf16 v[52:55], v[172:175], v[188:191], v[52:55]
	v_mfma_f32_16x16x32_bf16 v[48:51], v[180:183], v[188:191], v[48:51]
	v_mfma_f32_16x16x32_bf16 v[36:39], v[172:175], v[196:199], v[36:39]
	v_mfma_f32_16x16x32_bf16 v[32:35], v[180:183], v[196:199], v[32:35]
	v_mfma_f32_16x16x32_bf16 v[20:23], v[172:175], v[204:207], v[20:23]
	v_mfma_f32_16x16x32_bf16 v[16:19], v[180:183], v[204:207], v[16:19]
	v_mfma_f32_16x16x32_bf16 v[4:7], v[172:175], v[212:215], v[4:7]
	v_mfma_f32_16x16x32_bf16 v[0:3], v[180:183], v[212:215], v[0:3]
	s_setprio 0
	s_barrier
	s_add_i32 s3, 0, 0x18000
	s_add_i32 s37, 0, 0x1c000
	v_add_u32_e32 v164, s3, v151
	v_add_u32_e32 v180, s37, v151
	ds_read_b128 v[144:147], v164
	ds_read_b128 v[156:159], v164 offset:1024
	ds_read_b128 v[160:163], v164 offset:2048
	ds_read_b128 v[164:167], v164 offset:3072
	ds_read_b128 v[168:171], v180
	ds_read_b128 v[172:175], v180 offset:1024
	ds_read_b128 v[176:179], v180 offset:2048
	ds_read_b128 v[180:183], v180 offset:3072
	s_add_u32 s42, s90, 0x40000
	s_addc_u32 s43, s91, 0
	s_mov_b32 m0, s30
	ds_read_b128 v[184:187], v155 offset:32768
	ds_read_b128 v[188:191], v155 offset:33792
	ds_read_b128 v[192:195], v155 offset:34816
	ds_read_b128 v[196:199], v155 offset:35840
	ds_read_b128 v[200:203], v155 offset:36864
	ds_read_b128 v[204:207], v155 offset:37888
	ds_read_b128 v[208:211], v155 offset:38912
	ds_read_b128 v[212:215], v155 offset:39936
	global_load_lds_dwordx4 v128, s[42:43]
	v_lshl_add_u64 v[222:223], s[42:43], 0, v[132:133]
	s_mov_b32 m0, s31
	s_nop 0
	global_load_lds_dwordx4 v[222:223], off
	s_waitcnt vmcnt(8)
	s_waitcnt lgkmcnt(0)
	s_barrier
	s_setprio 1
	s_waitcnt lgkmcnt(0)
	v_mfma_f32_16x16x32_bf16 v[124:127], v[144:147], v[184:187], v[124:127]
	v_mfma_f32_16x16x32_bf16 v[120:123], v[160:163], v[184:187], v[120:123]
	v_mfma_f32_16x16x32_bf16 v[108:111], v[144:147], v[192:195], v[108:111]
	v_mfma_f32_16x16x32_bf16 v[104:107], v[160:163], v[192:195], v[104:107]
	v_mfma_f32_16x16x32_bf16 v[92:95], v[144:147], v[200:203], v[92:95]
	v_mfma_f32_16x16x32_bf16 v[88:91], v[160:163], v[200:203], v[88:91]
	v_mfma_f32_16x16x32_bf16 v[76:79], v[144:147], v[208:211], v[76:79]
	v_mfma_f32_16x16x32_bf16 v[72:75], v[160:163], v[208:211], v[72:75]
	v_mfma_f32_16x16x32_bf16 v[124:127], v[156:159], v[188:191], v[124:127]
	v_mfma_f32_16x16x32_bf16 v[120:123], v[164:167], v[188:191], v[120:123]
	v_mfma_f32_16x16x32_bf16 v[108:111], v[156:159], v[196:199], v[108:111]
	v_mfma_f32_16x16x32_bf16 v[104:107], v[164:167], v[196:199], v[104:107]
	v_mfma_f32_16x16x32_bf16 v[92:95], v[156:159], v[204:207], v[92:95]
	v_mfma_f32_16x16x32_bf16 v[88:91], v[164:167], v[204:207], v[88:91]
	v_mfma_f32_16x16x32_bf16 v[76:79], v[156:159], v[212:215], v[76:79]
	v_mfma_f32_16x16x32_bf16 v[72:75], v[164:167], v[212:215], v[72:75]
	s_setprio 0
	s_setprio 1
	v_mfma_f32_16x16x32_bf16 v[116:119], v[168:171], v[184:187], v[116:119]
	v_mfma_f32_16x16x32_bf16 v[112:115], v[176:179], v[184:187], v[112:115]
	v_mfma_f32_16x16x32_bf16 v[100:103], v[168:171], v[192:195], v[100:103]
	v_mfma_f32_16x16x32_bf16 v[96:99], v[176:179], v[192:195], v[96:99]
	v_mfma_f32_16x16x32_bf16 v[84:87], v[168:171], v[200:203], v[84:87]
	v_mfma_f32_16x16x32_bf16 v[80:83], v[176:179], v[200:203], v[80:83]
	v_mfma_f32_16x16x32_bf16 v[68:71], v[168:171], v[208:211], v[68:71]
	v_mfma_f32_16x16x32_bf16 v[64:67], v[176:179], v[208:211], v[64:67]
	v_mfma_f32_16x16x32_bf16 v[116:119], v[172:175], v[188:191], v[116:119]
	v_mfma_f32_16x16x32_bf16 v[112:115], v[180:183], v[188:191], v[112:115]
	v_mfma_f32_16x16x32_bf16 v[100:103], v[172:175], v[196:199], v[100:103]
	v_mfma_f32_16x16x32_bf16 v[96:99], v[180:183], v[196:199], v[96:99]
	v_mfma_f32_16x16x32_bf16 v[84:87], v[172:175], v[204:207], v[84:87]
	v_mfma_f32_16x16x32_bf16 v[80:83], v[180:183], v[204:207], v[80:83]
	v_mfma_f32_16x16x32_bf16 v[68:71], v[172:175], v[212:215], v[68:71]
	v_mfma_f32_16x16x32_bf16 v[64:67], v[180:183], v[212:215], v[64:67]
	s_setprio 0
	s_barrier
	s_add_i32 s3, s3, s18
	s_add_u32 s42, s80, 0x80
	s_addc_u32 s43, s81, 0
	s_mov_b32 m0, s3
	ds_read_b128 v[184:187], v155 offset:49152
	ds_read_b128 v[188:191], v155 offset:50176
	ds_read_b128 v[192:195], v155 offset:51200
	ds_read_b128 v[196:199], v155 offset:52224
	ds_read_b128 v[200:203], v155 offset:53248
	ds_read_b128 v[204:207], v155 offset:54272
	ds_read_b128 v[208:211], v155 offset:55296
	ds_read_b128 v[212:215], v155 offset:56320
	global_load_lds_dwordx4 v130, s[42:43]
	s_add_i32 m0, s3, 0x2000
	s_add_i32 s3, s37, s18
	global_load_lds_dwordx4 v134, s[42:43]
	s_add_u32 s42, s42, 0x40000
	s_addc_u32 s43, s43, 0
	s_mov_b32 m0, s3
	s_nop 0
	global_load_lds_dwordx4 v130, s[42:43]
	s_add_i32 m0, s3, 0x2000
	s_nop 0
	global_load_lds_dwordx4 v134, s[42:43]
	s_add_u32 s90, s90, 0x80
	s_addc_u32 s91, s91, 0
	s_mov_b32 m0, s53
	s_nop 0
	global_load_lds_dwordx4 v128, s[90:91]
	s_mov_b32 m0, s56
	s_nop 0
	global_load_lds_dwordx4 v132, s[90:91]
	s_waitcnt vmcnt(8)
	s_waitcnt lgkmcnt(0)
	s_barrier
	s_setprio 1
	s_waitcnt lgkmcnt(0)
	v_mfma_f32_16x16x32_bf16 v[60:63], v[144:147], v[184:187], v[60:63]
	v_mfma_f32_16x16x32_bf16 v[56:59], v[160:163], v[184:187], v[56:59]
	v_mfma_f32_16x16x32_bf16 v[44:47], v[144:147], v[192:195], v[44:47]
	v_mfma_f32_16x16x32_bf16 v[40:43], v[160:163], v[192:195], v[40:43]
	v_mfma_f32_16x16x32_bf16 v[28:31], v[144:147], v[200:203], v[28:31]
	v_mfma_f32_16x16x32_bf16 v[24:27], v[160:163], v[200:203], v[24:27]
	v_mfma_f32_16x16x32_bf16 v[12:15], v[144:147], v[208:211], v[12:15]
	v_mfma_f32_16x16x32_bf16 v[8:11], v[160:163], v[208:211], v[8:11]
	v_mfma_f32_16x16x32_bf16 v[60:63], v[156:159], v[188:191], v[60:63]
	v_mfma_f32_16x16x32_bf16 v[56:59], v[164:167], v[188:191], v[56:59]
	v_mfma_f32_16x16x32_bf16 v[44:47], v[156:159], v[196:199], v[44:47]
	v_mfma_f32_16x16x32_bf16 v[40:43], v[164:167], v[196:199], v[40:43]
	v_mfma_f32_16x16x32_bf16 v[28:31], v[156:159], v[204:207], v[28:31]
	v_mfma_f32_16x16x32_bf16 v[24:27], v[164:167], v[204:207], v[24:27]
	v_mfma_f32_16x16x32_bf16 v[12:15], v[156:159], v[212:215], v[12:15]
	v_mfma_f32_16x16x32_bf16 v[8:11], v[164:167], v[212:215], v[8:11]
	s_setprio 0
	s_setprio 1
	v_mfma_f32_16x16x32_bf16 v[52:55], v[168:171], v[184:187], v[52:55]
	v_mfma_f32_16x16x32_bf16 v[48:51], v[176:179], v[184:187], v[48:51]
	v_mfma_f32_16x16x32_bf16 v[36:39], v[168:171], v[192:195], v[36:39]
	v_mfma_f32_16x16x32_bf16 v[32:35], v[176:179], v[192:195], v[32:35]
	v_mfma_f32_16x16x32_bf16 v[20:23], v[168:171], v[200:203], v[20:23]
	v_mfma_f32_16x16x32_bf16 v[16:19], v[176:179], v[200:203], v[16:19]
	v_mfma_f32_16x16x32_bf16 v[4:7], v[168:171], v[208:211], v[4:7]
	v_mfma_f32_16x16x32_bf16 v[0:3], v[176:179], v[208:211], v[0:3]
	v_mfma_f32_16x16x32_bf16 v[52:55], v[172:175], v[188:191], v[52:55]
	v_mfma_f32_16x16x32_bf16 v[48:51], v[180:183], v[188:191], v[48:51]
	v_mfma_f32_16x16x32_bf16 v[36:39], v[172:175], v[196:199], v[36:39]
	v_mfma_f32_16x16x32_bf16 v[32:35], v[180:183], v[196:199], v[32:35]
	v_mfma_f32_16x16x32_bf16 v[20:23], v[172:175], v[204:207], v[20:23]
	v_mfma_f32_16x16x32_bf16 v[16:19], v[180:183], v[204:207], v[16:19]
	v_mfma_f32_16x16x32_bf16 v[4:7], v[172:175], v[212:215], v[4:7]
	v_mfma_f32_16x16x32_bf16 v[0:3], v[180:183], v[212:215], v[0:3]
	s_setprio 0
	s_barrier
	s_add_i32 s36, s36, 2
	s_add_u32 s88, s88, 0x100
	s_addc_u32 s89, s89, 0
	s_add_u32 s33, s33, 0x100
	s_addc_u32 s35, s35, 0
	s_cmp_gt_u32 s36, 13
	s_cbranch_scc0 .LBB0_1393
	s_and_b64 vcc, exec, s[12:13]
	s_cbranch_vccz .LBB0_1396
	s_barrier

.LBB0_1417:
	ds_read_b128 v[144:147], v157
	ds_read_b128 v[148:151], v157 offset:1024
	ds_read_b128 v[160:163], v157 offset:2048
	ds_read_b128 v[164:167], v157 offset:3072
	ds_read_b128 v[168:171], v158
	ds_read_b128 v[172:175], v158 offset:1024
	ds_read_b128 v[176:179], v158 offset:2048
	ds_read_b128 v[180:183], v158 offset:3072
	s_add_u32 s3, s34, 0xfffe0080
	s_addc_u32 s42, s35, -1
	s_cmp_eq_u32 s37, 4
	s_cselect_b32 s91, s0, s42
	s_cselect_b32 s90, s1, s3
	s_cselect_b32 s81, s24, s36
	s_cselect_b32 s80, s27, s33
	s_add_i32 m0, s19, 0xc000
	ds_read_b128 v[184:187], v159
	ds_read_b128 v[188:191], v159 offset:1024
	ds_read_b128 v[192:195], v159 offset:2048
	ds_read_b128 v[196:199], v159 offset:3072
	ds_read_b128 v[200:203], v159 offset:4096
	ds_read_b128 v[204:207], v159 offset:5120
	ds_read_b128 v[208:211], v159 offset:6144
	ds_read_b128 v[212:215], v159 offset:7168
	global_load_lds_dwordx4 v136, s[34:35]
	s_add_i32 m0, s19, 0xe000
	s_nop 0
	global_load_lds_dwordx4 v138, s[34:35]
	s_waitcnt vmcnt(8)
	s_waitcnt lgkmcnt(0)
	s_barrier
	s_setprio 1
	s_waitcnt lgkmcnt(0)
	v_mfma_f32_16x16x32_bf16 v[124:127], v[144:147], v[184:187], v[124:127]
	v_mfma_f32_16x16x32_bf16 v[120:123], v[160:163], v[184:187], v[120:123]
	v_mfma_f32_16x16x32_bf16 v[108:111], v[144:147], v[192:195], v[108:111]
	v_mfma_f32_16x16x32_bf16 v[104:107], v[160:163], v[192:195], v[104:107]
	v_mfma_f32_16x16x32_bf16 v[92:95], v[144:147], v[200:203], v[92:95]
	v_mfma_f32_16x16x32_bf16 v[88:91], v[160:163], v[200:203], v[88:91]
	v_mfma_f32_16x16x32_bf16 v[76:79], v[144:147], v[208:211], v[76:79]
	v_mfma_f32_16x16x32_bf16 v[72:75], v[160:163], v[208:211], v[72:75]
	v_mfma_f32_16x16x32_bf16 v[124:127], v[148:151], v[188:191], v[124:127]
	v_mfma_f32_16x16x32_bf16 v[120:123], v[164:167], v[188:191], v[120:123]
	v_mfma_f32_16x16x32_bf16 v[108:111], v[148:151], v[196:199], v[108:111]
	v_mfma_f32_16x16x32_bf16 v[104:107], v[164:167], v[196:199], v[104:107]
	v_mfma_f32_16x16x32_bf16 v[92:95], v[148:151], v[204:207], v[92:95]
	v_mfma_f32_16x16x32_bf16 v[88:91], v[164:167], v[204:207], v[88:91]
	v_mfma_f32_16x16x32_bf16 v[76:79], v[148:151], v[212:215], v[76:79]
	v_mfma_f32_16x16x32_bf16 v[72:75], v[164:167], v[212:215], v[72:75]
	s_setprio 0
	s_setprio 1
	v_mfma_f32_16x16x32_bf16 v[116:119], v[168:171], v[184:187], v[116:119]
	v_mfma_f32_16x16x32_bf16 v[112:115], v[176:179], v[184:187], v[112:115]
	v_mfma_f32_16x16x32_bf16 v[100:103], v[168:171], v[192:195], v[100:103]
	v_mfma_f32_16x16x32_bf16 v[96:99], v[176:179], v[192:195], v[96:99]
	v_mfma_f32_16x16x32_bf16 v[84:87], v[168:171], v[200:203], v[84:87]
	v_mfma_f32_16x16x32_bf16 v[80:83], v[176:179], v[200:203], v[80:83]
	v_mfma_f32_16x16x32_bf16 v[68:71], v[168:171], v[208:211], v[68:71]
	v_mfma_f32_16x16x32_bf16 v[64:67], v[176:179], v[208:211], v[64:67]
	v_mfma_f32_16x16x32_bf16 v[116:119], v[172:175], v[188:191], v[116:119]
	v_mfma_f32_16x16x32_bf16 v[112:115], v[180:183], v[188:191], v[112:115]
	v_mfma_f32_16x16x32_bf16 v[100:103], v[172:175], v[196:199], v[100:103]
	v_mfma_f32_16x16x32_bf16 v[96:99], v[180:183], v[196:199], v[96:99]
	v_mfma_f32_16x16x32_bf16 v[84:87], v[172:175], v[204:207], v[84:87]
	v_mfma_f32_16x16x32_bf16 v[80:83], v[180:183], v[204:207], v[80:83]
	v_mfma_f32_16x16x32_bf16 v[68:71], v[172:175], v[212:215], v[68:71]
	v_mfma_f32_16x16x32_bf16 v[64:67], v[180:183], v[212:215], v[64:67]
	s_setprio 0
	s_barrier
	s_add_i32 s3, s78, s18
	s_mov_b32 m0, s3
	ds_read_b128 v[184:187], v159 offset:16384
	ds_read_b128 v[188:191], v159 offset:17408
	ds_read_b128 v[192:195], v159 offset:18432
	ds_read_b128 v[196:199], v159 offset:19456
	ds_read_b128 v[200:203], v159 offset:20480
	ds_read_b128 v[204:207], v159 offset:21504
	ds_read_b128 v[208:211], v159 offset:22528
	ds_read_b128 v[212:215], v159 offset:23552
	global_load_lds_dwordx4 v130, s[80:81]
	s_add_i32 m0, s3, 0x2000
	s_add_u32 s42, s80, 0x20000
	s_addc_u32 s43, s81, 0
	s_add_i32 s3, s79, s18
	global_load_lds_dwordx4 v134, s[80:81]
	s_mov_b32 m0, s3
	s_nop 0
	global_load_lds_dwordx4 v130, s[42:43]
	s_add_i32 m0, s3, 0x2000
	s_nop 0
	global_load_lds_dwordx4 v134, s[42:43]
	s_mov_b32 m0, s19
	s_nop 0
	global_load_lds_dwordx4 v128, s[90:91]
	s_mov_b32 m0, s25
	s_nop 0
	global_load_lds_dwordx4 v132, s[90:91]
	s_waitcnt vmcnt(8)
	s_waitcnt lgkmcnt(0)
	s_barrier
	s_setprio 1
	s_waitcnt lgkmcnt(0)
	v_mfma_f32_16x16x32_bf16 v[60:63], v[144:147], v[184:187], v[60:63]
	v_mfma_f32_16x16x32_bf16 v[56:59], v[160:163], v[184:187], v[56:59]
	v_mfma_f32_16x16x32_bf16 v[44:47], v[144:147], v[192:195], v[44:47]
	v_mfma_f32_16x16x32_bf16 v[40:43], v[160:163], v[192:195], v[40:43]
	v_mfma_f32_16x16x32_bf16 v[28:31], v[144:147], v[200:203], v[28:31]
	v_mfma_f32_16x16x32_bf16 v[24:27], v[160:163], v[200:203], v[24:27]
	v_mfma_f32_16x16x32_bf16 v[12:15], v[144:147], v[208:211], v[12:15]
	v_mfma_f32_16x16x32_bf16 v[8:11], v[160:163], v[208:211], v[8:11]
	v_mfma_f32_16x16x32_bf16 v[60:63], v[148:151], v[188:191], v[60:63]
	v_mfma_f32_16x16x32_bf16 v[56:59], v[164:167], v[188:191], v[56:59]
	v_mfma_f32_16x16x32_bf16 v[44:47], v[148:151], v[196:199], v[44:47]
	v_mfma_f32_16x16x32_bf16 v[40:43], v[164:167], v[196:199], v[40:43]
	v_mfma_f32_16x16x32_bf16 v[28:31], v[148:151], v[204:207], v[28:31]
	v_mfma_f32_16x16x32_bf16 v[24:27], v[164:167], v[204:207], v[24:27]
	v_mfma_f32_16x16x32_bf16 v[12:15], v[148:151], v[212:215], v[12:15]
	v_mfma_f32_16x16x32_bf16 v[8:11], v[164:167], v[212:215], v[8:11]
	s_setprio 0
	s_setprio 1
	v_mfma_f32_16x16x32_bf16 v[52:55], v[168:171], v[184:187], v[52:55]
	v_mfma_f32_16x16x32_bf16 v[48:51], v[176:179], v[184:187], v[48:51]
	v_mfma_f32_16x16x32_bf16 v[36:39], v[168:171], v[192:195], v[36:39]
	v_mfma_f32_16x16x32_bf16 v[32:35], v[176:179], v[192:195], v[32:35]
	v_mfma_f32_16x16x32_bf16 v[20:23], v[168:171], v[200:203], v[20:23]
	v_mfma_f32_16x16x32_bf16 v[16:19], v[176:179], v[200:203], v[16:19]
	v_mfma_f32_16x16x32_bf16 v[4:7], v[168:171], v[208:211], v[4:7]
	v_mfma_f32_16x16x32_bf16 v[0:3], v[176:179], v[208:211], v[0:3]
	v_mfma_f32_16x16x32_bf16 v[52:55], v[172:175], v[188:191], v[52:55]
	v_mfma_f32_16x16x32_bf16 v[48:51], v[180:183], v[188:191], v[48:51]
	v_mfma_f32_16x16x32_bf16 v[36:39], v[172:175], v[196:199], v[36:39]
	v_mfma_f32_16x16x32_bf16 v[32:35], v[180:183], v[196:199], v[32:35]
	v_mfma_f32_16x16x32_bf16 v[20:23], v[172:175], v[204:207], v[20:23]
	v_mfma_f32_16x16x32_bf16 v[16:19], v[180:183], v[204:207], v[16:19]
	v_mfma_f32_16x16x32_bf16 v[4:7], v[172:175], v[212:215], v[4:7]
	v_mfma_f32_16x16x32_bf16 v[0:3], v[180:183], v[212:215], v[0:3]
	s_setprio 0
	s_barrier
	s_add_i32 s3, 0, 0x18000
	s_add_i32 s44, 0, 0x1c000
	v_add_u32_e32 v164, s3, v155
	v_add_u32_e32 v180, s44, v155
	ds_read_b128 v[144:147], v164
	ds_read_b128 v[148:151], v164 offset:1024
	ds_read_b128 v[160:163], v164 offset:2048
	ds_read_b128 v[164:167], v164 offset:3072
	ds_read_b128 v[168:171], v180
	ds_read_b128 v[172:175], v180 offset:1024
	ds_read_b128 v[176:179], v180 offset:2048
	ds_read_b128 v[180:183], v180 offset:3072
	s_add_u32 s42, s90, 0x20000
	s_addc_u32 s43, s91, 0
	s_mov_b32 m0, s30
	ds_read_b128 v[184:187], v159 offset:32768
	ds_read_b128 v[188:191], v159 offset:33792
	ds_read_b128 v[192:195], v159 offset:34816
	ds_read_b128 v[196:199], v159 offset:35840
	ds_read_b128 v[200:203], v159 offset:36864
	ds_read_b128 v[204:207], v159 offset:37888
	ds_read_b128 v[208:211], v159 offset:38912
	ds_read_b128 v[212:215], v159 offset:39936
	global_load_lds_dwordx4 v128, s[42:43]
	v_lshl_add_u64 v[222:223], s[42:43], 0, v[132:133]
	s_mov_b32 m0, s31
	s_nop 0
	global_load_lds_dwordx4 v[222:223], off
	s_waitcnt vmcnt(8)
	s_waitcnt lgkmcnt(0)
	s_barrier
	s_setprio 1
	s_waitcnt lgkmcnt(0)
	v_mfma_f32_16x16x32_bf16 v[124:127], v[144:147], v[184:187], v[124:127]
	v_mfma_f32_16x16x32_bf16 v[120:123], v[160:163], v[184:187], v[120:123]
	v_mfma_f32_16x16x32_bf16 v[108:111], v[144:147], v[192:195], v[108:111]
	v_mfma_f32_16x16x32_bf16 v[104:107], v[160:163], v[192:195], v[104:107]
	v_mfma_f32_16x16x32_bf16 v[92:95], v[144:147], v[200:203], v[92:95]
	v_mfma_f32_16x16x32_bf16 v[88:91], v[160:163], v[200:203], v[88:91]
	v_mfma_f32_16x16x32_bf16 v[76:79], v[144:147], v[208:211], v[76:79]
	v_mfma_f32_16x16x32_bf16 v[72:75], v[160:163], v[208:211], v[72:75]
	v_mfma_f32_16x16x32_bf16 v[124:127], v[148:151], v[188:191], v[124:127]
	v_mfma_f32_16x16x32_bf16 v[120:123], v[164:167], v[188:191], v[120:123]
	v_mfma_f32_16x16x32_bf16 v[108:111], v[148:151], v[196:199], v[108:111]
	v_mfma_f32_16x16x32_bf16 v[104:107], v[164:167], v[196:199], v[104:107]
	v_mfma_f32_16x16x32_bf16 v[92:95], v[148:151], v[204:207], v[92:95]
	v_mfma_f32_16x16x32_bf16 v[88:91], v[164:167], v[204:207], v[88:91]
	v_mfma_f32_16x16x32_bf16 v[76:79], v[148:151], v[212:215], v[76:79]
	v_mfma_f32_16x16x32_bf16 v[72:75], v[164:167], v[212:215], v[72:75]
	s_setprio 0
	s_setprio 1
	v_mfma_f32_16x16x32_bf16 v[116:119], v[168:171], v[184:187], v[116:119]
	v_mfma_f32_16x16x32_bf16 v[112:115], v[176:179], v[184:187], v[112:115]
	v_mfma_f32_16x16x32_bf16 v[100:103], v[168:171], v[192:195], v[100:103]
	v_mfma_f32_16x16x32_bf16 v[96:99], v[176:179], v[192:195], v[96:99]
	v_mfma_f32_16x16x32_bf16 v[84:87], v[168:171], v[200:203], v[84:87]
	v_mfma_f32_16x16x32_bf16 v[80:83], v[176:179], v[200:203], v[80:83]
	v_mfma_f32_16x16x32_bf16 v[68:71], v[168:171], v[208:211], v[68:71]
	v_mfma_f32_16x16x32_bf16 v[64:67], v[176:179], v[208:211], v[64:67]
	v_mfma_f32_16x16x32_bf16 v[116:119], v[172:175], v[188:191], v[116:119]
	v_mfma_f32_16x16x32_bf16 v[112:115], v[180:183], v[188:191], v[112:115]
	v_mfma_f32_16x16x32_bf16 v[100:103], v[172:175], v[196:199], v[100:103]
	v_mfma_f32_16x16x32_bf16 v[96:99], v[180:183], v[196:199], v[96:99]
	v_mfma_f32_16x16x32_bf16 v[84:87], v[172:175], v[204:207], v[84:87]
	v_mfma_f32_16x16x32_bf16 v[80:83], v[180:183], v[204:207], v[80:83]
	v_mfma_f32_16x16x32_bf16 v[68:71], v[172:175], v[212:215], v[68:71]
	v_mfma_f32_16x16x32_bf16 v[64:67], v[180:183], v[212:215], v[64:67]
	s_setprio 0
	s_barrier
	s_add_i32 s3, s3, s18
	s_add_u32 s42, s80, 0x80
	s_addc_u32 s43, s81, 0
	s_mov_b32 m0, s3
	ds_read_b128 v[184:187], v159 offset:49152
	ds_read_b128 v[188:191], v159 offset:50176
	ds_read_b128 v[192:195], v159 offset:51200
	ds_read_b128 v[196:199], v159 offset:52224
	ds_read_b128 v[200:203], v159 offset:53248
	ds_read_b128 v[204:207], v159 offset:54272
	ds_read_b128 v[208:211], v159 offset:55296
	ds_read_b128 v[212:215], v159 offset:56320
	global_load_lds_dwordx4 v130, s[42:43]
	s_add_i32 m0, s3, 0x2000
	s_add_i32 s3, s44, s18
	global_load_lds_dwordx4 v134, s[42:43]
	s_add_u32 s42, s42, 0x20000
	s_addc_u32 s43, s43, 0
	s_mov_b32 m0, s3
	s_nop 0
	global_load_lds_dwordx4 v130, s[42:43]
	s_add_i32 m0, s3, 0x2000
	s_nop 0
	global_load_lds_dwordx4 v134, s[42:43]
	s_add_u32 s90, s90, 0x80
	s_addc_u32 s91, s91, 0
	s_mov_b32 m0, s58
	s_nop 0
	global_load_lds_dwordx4 v128, s[90:91]
	s_mov_b32 m0, s59
	s_nop 0
	global_load_lds_dwordx4 v132, s[90:91]
	s_waitcnt vmcnt(8)
	s_waitcnt lgkmcnt(0)
	s_barrier
	s_setprio 1
	s_waitcnt lgkmcnt(0)
	v_mfma_f32_16x16x32_bf16 v[60:63], v[144:147], v[184:187], v[60:63]
	v_mfma_f32_16x16x32_bf16 v[56:59], v[160:163], v[184:187], v[56:59]
	v_mfma_f32_16x16x32_bf16 v[44:47], v[144:147], v[192:195], v[44:47]
	v_mfma_f32_16x16x32_bf16 v[40:43], v[160:163], v[192:195], v[40:43]
	v_mfma_f32_16x16x32_bf16 v[28:31], v[144:147], v[200:203], v[28:31]
	v_mfma_f32_16x16x32_bf16 v[24:27], v[160:163], v[200:203], v[24:27]
	v_mfma_f32_16x16x32_bf16 v[12:15], v[144:147], v[208:211], v[12:15]
	v_mfma_f32_16x16x32_bf16 v[8:11], v[160:163], v[208:211], v[8:11]
	v_mfma_f32_16x16x32_bf16 v[60:63], v[148:151], v[188:191], v[60:63]
	v_mfma_f32_16x16x32_bf16 v[56:59], v[164:167], v[188:191], v[56:59]
	v_mfma_f32_16x16x32_bf16 v[44:47], v[148:151], v[196:199], v[44:47]
	v_mfma_f32_16x16x32_bf16 v[40:43], v[164:167], v[196:199], v[40:43]
	v_mfma_f32_16x16x32_bf16 v[28:31], v[148:151], v[204:207], v[28:31]
	v_mfma_f32_16x16x32_bf16 v[24:27], v[164:167], v[204:207], v[24:27]
	v_mfma_f32_16x16x32_bf16 v[12:15], v[148:151], v[212:215], v[12:15]
	v_mfma_f32_16x16x32_bf16 v[8:11], v[164:167], v[212:215], v[8:11]
	s_setprio 0
	s_setprio 1
	v_mfma_f32_16x16x32_bf16 v[52:55], v[168:171], v[184:187], v[52:55]
	v_mfma_f32_16x16x32_bf16 v[48:51], v[176:179], v[184:187], v[48:51]
	v_mfma_f32_16x16x32_bf16 v[36:39], v[168:171], v[192:195], v[36:39]
	v_mfma_f32_16x16x32_bf16 v[32:35], v[176:179], v[192:195], v[32:35]
	v_mfma_f32_16x16x32_bf16 v[20:23], v[168:171], v[200:203], v[20:23]
	v_mfma_f32_16x16x32_bf16 v[16:19], v[176:179], v[200:203], v[16:19]
	v_mfma_f32_16x16x32_bf16 v[4:7], v[168:171], v[208:211], v[4:7]
	v_mfma_f32_16x16x32_bf16 v[0:3], v[176:179], v[208:211], v[0:3]
	v_mfma_f32_16x16x32_bf16 v[52:55], v[172:175], v[188:191], v[52:55]
	v_mfma_f32_16x16x32_bf16 v[48:51], v[180:183], v[188:191], v[48:51]
	v_mfma_f32_16x16x32_bf16 v[36:39], v[172:175], v[196:199], v[36:39]
	v_mfma_f32_16x16x32_bf16 v[32:35], v[180:183], v[196:199], v[32:35]
	v_mfma_f32_16x16x32_bf16 v[20:23], v[172:175], v[204:207], v[20:23]
	v_mfma_f32_16x16x32_bf16 v[16:19], v[180:183], v[204:207], v[16:19]
	v_mfma_f32_16x16x32_bf16 v[4:7], v[172:175], v[212:215], v[4:7]
	v_mfma_f32_16x16x32_bf16 v[0:3], v[180:183], v[212:215], v[0:3]
	s_setprio 0
	s_barrier
	s_add_i32 s37, s37, 2
	s_add_u32 s34, s34, 0x100
	s_addc_u32 s35, s35, 0
	s_add_u32 s33, s33, 0x100
	s_addc_u32 s36, s36, 0
	s_cmp_gt_u32 s37, 5
	s_cbranch_scc0 .LBB0_1417
	s_and_b64 vcc, exec, s[14:15]
	s_cbranch_vccz .LBB0_1420
	s_barrier

.LBB0_1493:
	ds_read_b128 v[140:143], v149
	ds_read_b128 v[152:155], v149 offset:1024
	ds_read_b128 v[156:159], v149 offset:2048
	ds_read_b128 v[160:163], v149 offset:3072
	ds_read_b128 v[164:167], v150
	ds_read_b128 v[168:171], v150 offset:1024
	ds_read_b128 v[172:175], v150 offset:2048
	ds_read_b128 v[176:179], v150 offset:3072
	s_add_u32 s3, s86, 0xfff80080
	s_addc_u32 s33, s87, -1
	s_cmp_eq_u32 s27, 28
	s_cselect_b32 s89, s0, s33
	s_cselect_b32 s88, s1, s3
	s_cselect_b32 s81, s15, s24
	s_cselect_b32 s80, s17, s19
	s_add_i32 m0, s30, 0xc000
	ds_read_b128 v[180:183], v151
	ds_read_b128 v[184:187], v151 offset:1024
	ds_read_b128 v[188:191], v151 offset:2048
	ds_read_b128 v[192:195], v151 offset:3072
	ds_read_b128 v[196:199], v151 offset:4096
	ds_read_b128 v[200:203], v151 offset:5120
	ds_read_b128 v[204:207], v151 offset:6144
	ds_read_b128 v[208:211], v151 offset:7168
	global_load_lds_dwordx4 v132, s[86:87]
	s_add_i32 m0, s30, 0xe000
	s_nop 0
	global_load_lds_dwordx4 v134, s[86:87]
	s_waitcnt vmcnt(8)
	s_waitcnt lgkmcnt(0)
	s_barrier
	s_setprio 1
	s_waitcnt lgkmcnt(0)
	v_mfma_f32_16x16x32_bf16 v[124:127], v[140:143], v[180:183], v[124:127]
	v_mfma_f32_16x16x32_bf16 v[120:123], v[156:159], v[180:183], v[120:123]
	v_mfma_f32_16x16x32_bf16 v[108:111], v[140:143], v[188:191], v[108:111]
	v_mfma_f32_16x16x32_bf16 v[104:107], v[156:159], v[188:191], v[104:107]
	v_mfma_f32_16x16x32_bf16 v[92:95], v[140:143], v[196:199], v[92:95]
	v_mfma_f32_16x16x32_bf16 v[88:91], v[156:159], v[196:199], v[88:91]
	v_mfma_f32_16x16x32_bf16 v[76:79], v[140:143], v[204:207], v[76:79]
	v_mfma_f32_16x16x32_bf16 v[72:75], v[156:159], v[204:207], v[72:75]
	v_mfma_f32_16x16x32_bf16 v[124:127], v[152:155], v[184:187], v[124:127]
	v_mfma_f32_16x16x32_bf16 v[120:123], v[160:163], v[184:187], v[120:123]
	v_mfma_f32_16x16x32_bf16 v[108:111], v[152:155], v[192:195], v[108:111]
	v_mfma_f32_16x16x32_bf16 v[104:107], v[160:163], v[192:195], v[104:107]
	v_mfma_f32_16x16x32_bf16 v[92:95], v[152:155], v[200:203], v[92:95]
	v_mfma_f32_16x16x32_bf16 v[88:91], v[160:163], v[200:203], v[88:91]
	v_mfma_f32_16x16x32_bf16 v[76:79], v[152:155], v[208:211], v[76:79]
	v_mfma_f32_16x16x32_bf16 v[72:75], v[160:163], v[208:211], v[72:75]
	s_setprio 0
	s_setprio 1
	v_mfma_f32_16x16x32_bf16 v[116:119], v[164:167], v[180:183], v[116:119]
	v_mfma_f32_16x16x32_bf16 v[112:115], v[172:175], v[180:183], v[112:115]
	v_mfma_f32_16x16x32_bf16 v[100:103], v[164:167], v[188:191], v[100:103]
	v_mfma_f32_16x16x32_bf16 v[96:99], v[172:175], v[188:191], v[96:99]
	v_mfma_f32_16x16x32_bf16 v[84:87], v[164:167], v[196:199], v[84:87]
	v_mfma_f32_16x16x32_bf16 v[80:83], v[172:175], v[196:199], v[80:83]
	v_mfma_f32_16x16x32_bf16 v[68:71], v[164:167], v[204:207], v[68:71]
	v_mfma_f32_16x16x32_bf16 v[64:67], v[172:175], v[204:207], v[64:67]
	v_mfma_f32_16x16x32_bf16 v[116:119], v[168:171], v[184:187], v[116:119]
	v_mfma_f32_16x16x32_bf16 v[112:115], v[176:179], v[184:187], v[112:115]
	v_mfma_f32_16x16x32_bf16 v[100:103], v[168:171], v[192:195], v[100:103]
	v_mfma_f32_16x16x32_bf16 v[96:99], v[176:179], v[192:195], v[96:99]
	v_mfma_f32_16x16x32_bf16 v[84:87], v[168:171], v[200:203], v[84:87]
	v_mfma_f32_16x16x32_bf16 v[80:83], v[176:179], v[200:203], v[80:83]
	v_mfma_f32_16x16x32_bf16 v[68:71], v[168:171], v[208:211], v[68:71]
	v_mfma_f32_16x16x32_bf16 v[64:67], v[176:179], v[208:211], v[64:67]
	s_setprio 0
	s_barrier
	s_add_i32 s3, s59, s25
	s_mov_b32 m0, s3
	ds_read_b128 v[180:183], v151 offset:16384
	ds_read_b128 v[184:187], v151 offset:17408
	ds_read_b128 v[188:191], v151 offset:18432
	ds_read_b128 v[192:195], v151 offset:19456
	ds_read_b128 v[196:199], v151 offset:20480
	ds_read_b128 v[200:203], v151 offset:21504
	ds_read_b128 v[204:207], v151 offset:22528
	ds_read_b128 v[208:211], v151 offset:23552
	global_load_lds_dwordx4 v128, s[80:81]
	s_add_i32 m0, s3, 0x2000
	s_add_u32 s36, s80, 0x80000
	s_addc_u32 s37, s81, 0
	s_add_i32 s3, s68, s25
	global_load_lds_dwordx4 v130, s[80:81]
	s_mov_b32 m0, s3
	s_nop 0
	global_load_lds_dwordx4 v128, s[36:37]
	s_add_i32 m0, s3, 0x2000
	s_nop 0
	global_load_lds_dwordx4 v130, s[36:37]
	s_mov_b32 m0, s30
	s_nop 0
	global_load_lds_dwordx4 v128, s[88:89]
	s_mov_b32 m0, s31
	s_nop 0
	global_load_lds_dwordx4 v130, s[88:89]
	s_waitcnt vmcnt(8)
	s_waitcnt lgkmcnt(0)
	s_barrier
	s_setprio 1
	s_waitcnt lgkmcnt(0)
	v_mfma_f32_16x16x32_bf16 v[60:63], v[140:143], v[180:183], v[60:63]
	v_mfma_f32_16x16x32_bf16 v[56:59], v[156:159], v[180:183], v[56:59]
	v_mfma_f32_16x16x32_bf16 v[44:47], v[140:143], v[188:191], v[44:47]
	v_mfma_f32_16x16x32_bf16 v[40:43], v[156:159], v[188:191], v[40:43]
	v_mfma_f32_16x16x32_bf16 v[28:31], v[140:143], v[196:199], v[28:31]
	v_mfma_f32_16x16x32_bf16 v[24:27], v[156:159], v[196:199], v[24:27]
	v_mfma_f32_16x16x32_bf16 v[12:15], v[140:143], v[204:207], v[12:15]
	v_mfma_f32_16x16x32_bf16 v[8:11], v[156:159], v[204:207], v[8:11]
	v_mfma_f32_16x16x32_bf16 v[60:63], v[152:155], v[184:187], v[60:63]
	v_mfma_f32_16x16x32_bf16 v[56:59], v[160:163], v[184:187], v[56:59]
	v_mfma_f32_16x16x32_bf16 v[44:47], v[152:155], v[192:195], v[44:47]
	v_mfma_f32_16x16x32_bf16 v[40:43], v[160:163], v[192:195], v[40:43]
	v_mfma_f32_16x16x32_bf16 v[28:31], v[152:155], v[200:203], v[28:31]
	v_mfma_f32_16x16x32_bf16 v[24:27], v[160:163], v[200:203], v[24:27]
	v_mfma_f32_16x16x32_bf16 v[12:15], v[152:155], v[208:211], v[12:15]
	v_mfma_f32_16x16x32_bf16 v[8:11], v[160:163], v[208:211], v[8:11]
	s_setprio 0
	s_setprio 1
	v_mfma_f32_16x16x32_bf16 v[52:55], v[164:167], v[180:183], v[52:55]
	v_mfma_f32_16x16x32_bf16 v[48:51], v[172:175], v[180:183], v[48:51]
	v_mfma_f32_16x16x32_bf16 v[36:39], v[164:167], v[188:191], v[36:39]
	v_mfma_f32_16x16x32_bf16 v[32:35], v[172:175], v[188:191], v[32:35]
	v_mfma_f32_16x16x32_bf16 v[20:23], v[164:167], v[196:199], v[20:23]
	v_mfma_f32_16x16x32_bf16 v[16:19], v[172:175], v[196:199], v[16:19]
	v_mfma_f32_16x16x32_bf16 v[4:7], v[164:167], v[204:207], v[4:7]
	v_mfma_f32_16x16x32_bf16 v[0:3], v[172:175], v[204:207], v[0:3]
	v_mfma_f32_16x16x32_bf16 v[52:55], v[168:171], v[184:187], v[52:55]
	v_mfma_f32_16x16x32_bf16 v[48:51], v[176:179], v[184:187], v[48:51]
	v_mfma_f32_16x16x32_bf16 v[36:39], v[168:171], v[192:195], v[36:39]
	v_mfma_f32_16x16x32_bf16 v[32:35], v[176:179], v[192:195], v[32:35]
	v_mfma_f32_16x16x32_bf16 v[20:23], v[168:171], v[200:203], v[20:23]
	v_mfma_f32_16x16x32_bf16 v[16:19], v[176:179], v[200:203], v[16:19]
	v_mfma_f32_16x16x32_bf16 v[4:7], v[168:171], v[208:211], v[4:7]
	v_mfma_f32_16x16x32_bf16 v[0:3], v[176:179], v[208:211], v[0:3]
	s_setprio 0
	s_barrier
	s_add_i32 s3, 0, 0x18000
	s_add_i32 s33, 0, 0x1c000
	v_add_u32_e32 v160, s3, v147
	v_add_u32_e32 v176, s33, v147
	ds_read_b128 v[140:143], v160
	ds_read_b128 v[152:155], v160 offset:1024
	ds_read_b128 v[156:159], v160 offset:2048
	ds_read_b128 v[160:163], v160 offset:3072
	ds_read_b128 v[164:167], v176
	ds_read_b128 v[168:171], v176 offset:1024
	ds_read_b128 v[172:175], v176 offset:2048
	ds_read_b128 v[176:179], v176 offset:3072
	s_add_u32 s36, s88, 0x80000
	s_addc_u32 s37, s89, 0
	s_mov_b32 m0, s52
	ds_read_b128 v[180:183], v151 offset:32768
	ds_read_b128 v[184:187], v151 offset:33792
	ds_read_b128 v[188:191], v151 offset:34816
	ds_read_b128 v[192:195], v151 offset:35840
	ds_read_b128 v[196:199], v151 offset:36864
	ds_read_b128 v[200:203], v151 offset:37888
	ds_read_b128 v[204:207], v151 offset:38912
	ds_read_b128 v[208:211], v151 offset:39936
	global_load_lds_dwordx4 v128, s[36:37]
	v_lshl_add_u64 v[218:219], s[36:37], 0, v[130:131]
	s_mov_b32 m0, s53
	s_nop 0
	global_load_lds_dwordx4 v[218:219], off
	s_waitcnt vmcnt(8)
	s_waitcnt lgkmcnt(0)
	s_barrier
	s_setprio 1
	s_waitcnt lgkmcnt(0)
	v_mfma_f32_16x16x32_bf16 v[124:127], v[140:143], v[180:183], v[124:127]
	v_mfma_f32_16x16x32_bf16 v[120:123], v[156:159], v[180:183], v[120:123]
	v_mfma_f32_16x16x32_bf16 v[108:111], v[140:143], v[188:191], v[108:111]
	v_mfma_f32_16x16x32_bf16 v[104:107], v[156:159], v[188:191], v[104:107]
	v_mfma_f32_16x16x32_bf16 v[92:95], v[140:143], v[196:199], v[92:95]
	v_mfma_f32_16x16x32_bf16 v[88:91], v[156:159], v[196:199], v[88:91]
	v_mfma_f32_16x16x32_bf16 v[76:79], v[140:143], v[204:207], v[76:79]
	v_mfma_f32_16x16x32_bf16 v[72:75], v[156:159], v[204:207], v[72:75]
	v_mfma_f32_16x16x32_bf16 v[124:127], v[152:155], v[184:187], v[124:127]
	v_mfma_f32_16x16x32_bf16 v[120:123], v[160:163], v[184:187], v[120:123]
	v_mfma_f32_16x16x32_bf16 v[108:111], v[152:155], v[192:195], v[108:111]
	v_mfma_f32_16x16x32_bf16 v[104:107], v[160:163], v[192:195], v[104:107]
	v_mfma_f32_16x16x32_bf16 v[92:95], v[152:155], v[200:203], v[92:95]
	v_mfma_f32_16x16x32_bf16 v[88:91], v[160:163], v[200:203], v[88:91]
	v_mfma_f32_16x16x32_bf16 v[76:79], v[152:155], v[208:211], v[76:79]
	v_mfma_f32_16x16x32_bf16 v[72:75], v[160:163], v[208:211], v[72:75]
	s_setprio 0
	s_setprio 1
	v_mfma_f32_16x16x32_bf16 v[116:119], v[164:167], v[180:183], v[116:119]
	v_mfma_f32_16x16x32_bf16 v[112:115], v[172:175], v[180:183], v[112:115]
	v_mfma_f32_16x16x32_bf16 v[100:103], v[164:167], v[188:191], v[100:103]
	v_mfma_f32_16x16x32_bf16 v[96:99], v[172:175], v[188:191], v[96:99]
	v_mfma_f32_16x16x32_bf16 v[84:87], v[164:167], v[196:199], v[84:87]
	v_mfma_f32_16x16x32_bf16 v[80:83], v[172:175], v[196:199], v[80:83]
	v_mfma_f32_16x16x32_bf16 v[68:71], v[164:167], v[204:207], v[68:71]
	v_mfma_f32_16x16x32_bf16 v[64:67], v[172:175], v[204:207], v[64:67]
	v_mfma_f32_16x16x32_bf16 v[116:119], v[168:171], v[184:187], v[116:119]
	v_mfma_f32_16x16x32_bf16 v[112:115], v[176:179], v[184:187], v[112:115]
	v_mfma_f32_16x16x32_bf16 v[100:103], v[168:171], v[192:195], v[100:103]
	v_mfma_f32_16x16x32_bf16 v[96:99], v[176:179], v[192:195], v[96:99]
	v_mfma_f32_16x16x32_bf16 v[84:87], v[168:171], v[200:203], v[84:87]
	v_mfma_f32_16x16x32_bf16 v[80:83], v[176:179], v[200:203], v[80:83]
	v_mfma_f32_16x16x32_bf16 v[68:71], v[168:171], v[208:211], v[68:71]
	v_mfma_f32_16x16x32_bf16 v[64:67], v[176:179], v[208:211], v[64:67]
	s_setprio 0
	s_barrier
	s_add_i32 s3, s3, s25
	s_add_u32 s36, s80, 0x80
	s_addc_u32 s37, s81, 0
	s_mov_b32 m0, s3
	ds_read_b128 v[180:183], v151 offset:49152
	ds_read_b128 v[184:187], v151 offset:50176
	ds_read_b128 v[188:191], v151 offset:51200
	ds_read_b128 v[192:195], v151 offset:52224
	ds_read_b128 v[196:199], v151 offset:53248
	ds_read_b128 v[200:203], v151 offset:54272
	ds_read_b128 v[204:207], v151 offset:55296
	ds_read_b128 v[208:211], v151 offset:56320
	global_load_lds_dwordx4 v128, s[36:37]
	s_add_i32 m0, s3, 0x2000
	s_add_i32 s3, s33, s25
	global_load_lds_dwordx4 v130, s[36:37]
	s_add_u32 s36, s36, 0x80000
	s_addc_u32 s37, s37, 0
	s_mov_b32 m0, s3
	s_nop 0
	global_load_lds_dwordx4 v128, s[36:37]
	s_add_i32 m0, s3, 0x2000
	s_nop 0
	global_load_lds_dwordx4 v130, s[36:37]
	s_add_u32 s88, s88, 0x80
	s_addc_u32 s89, s89, 0
	s_mov_b32 m0, s57
	s_nop 0
	global_load_lds_dwordx4 v128, s[88:89]
	s_mov_b32 m0, s58
	s_nop 0
	global_load_lds_dwordx4 v130, s[88:89]
	s_waitcnt vmcnt(8)
	s_waitcnt lgkmcnt(0)
	s_barrier
	s_setprio 1
	s_waitcnt lgkmcnt(0)
	v_mfma_f32_16x16x32_bf16 v[60:63], v[140:143], v[180:183], v[60:63]
	v_mfma_f32_16x16x32_bf16 v[56:59], v[156:159], v[180:183], v[56:59]
	v_mfma_f32_16x16x32_bf16 v[44:47], v[140:143], v[188:191], v[44:47]
	v_mfma_f32_16x16x32_bf16 v[40:43], v[156:159], v[188:191], v[40:43]
	v_mfma_f32_16x16x32_bf16 v[28:31], v[140:143], v[196:199], v[28:31]
	v_mfma_f32_16x16x32_bf16 v[24:27], v[156:159], v[196:199], v[24:27]
	v_mfma_f32_16x16x32_bf16 v[12:15], v[140:143], v[204:207], v[12:15]
	v_mfma_f32_16x16x32_bf16 v[8:11], v[156:159], v[204:207], v[8:11]
	v_mfma_f32_16x16x32_bf16 v[60:63], v[152:155], v[184:187], v[60:63]
	v_mfma_f32_16x16x32_bf16 v[56:59], v[160:163], v[184:187], v[56:59]
	v_mfma_f32_16x16x32_bf16 v[44:47], v[152:155], v[192:195], v[44:47]
	v_mfma_f32_16x16x32_bf16 v[40:43], v[160:163], v[192:195], v[40:43]
	v_mfma_f32_16x16x32_bf16 v[28:31], v[152:155], v[200:203], v[28:31]
	v_mfma_f32_16x16x32_bf16 v[24:27], v[160:163], v[200:203], v[24:27]
	v_mfma_f32_16x16x32_bf16 v[12:15], v[152:155], v[208:211], v[12:15]
	v_mfma_f32_16x16x32_bf16 v[8:11], v[160:163], v[208:211], v[8:11]
	s_setprio 0
	s_setprio 1
	v_mfma_f32_16x16x32_bf16 v[52:55], v[164:167], v[180:183], v[52:55]
	v_mfma_f32_16x16x32_bf16 v[48:51], v[172:175], v[180:183], v[48:51]
	v_mfma_f32_16x16x32_bf16 v[36:39], v[164:167], v[188:191], v[36:39]
	v_mfma_f32_16x16x32_bf16 v[32:35], v[172:175], v[188:191], v[32:35]
	v_mfma_f32_16x16x32_bf16 v[20:23], v[164:167], v[196:199], v[20:23]
	v_mfma_f32_16x16x32_bf16 v[16:19], v[172:175], v[196:199], v[16:19]
	v_mfma_f32_16x16x32_bf16 v[4:7], v[164:167], v[204:207], v[4:7]
	v_mfma_f32_16x16x32_bf16 v[0:3], v[172:175], v[204:207], v[0:3]
	v_mfma_f32_16x16x32_bf16 v[52:55], v[168:171], v[184:187], v[52:55]
	v_mfma_f32_16x16x32_bf16 v[48:51], v[176:179], v[184:187], v[48:51]
	v_mfma_f32_16x16x32_bf16 v[36:39], v[168:171], v[192:195], v[36:39]
	v_mfma_f32_16x16x32_bf16 v[32:35], v[176:179], v[192:195], v[32:35]
	v_mfma_f32_16x16x32_bf16 v[20:23], v[168:171], v[200:203], v[20:23]
	v_mfma_f32_16x16x32_bf16 v[16:19], v[176:179], v[200:203], v[16:19]
	v_mfma_f32_16x16x32_bf16 v[4:7], v[168:171], v[208:211], v[4:7]
	v_mfma_f32_16x16x32_bf16 v[0:3], v[176:179], v[208:211], v[0:3]
	s_setprio 0
	s_barrier
	s_add_i32 s27, s27, 2
	s_add_u32 s86, s86, 0x100
	s_addc_u32 s87, s87, 0
	s_add_u32 s19, s19, 0x100
	s_addc_u32 s24, s24, 0
	s_cmp_gt_u32 s27, 29
	s_cbranch_scc0 .LBB0_1493
	s_and_b64 vcc, exec, s[12:13]
	s_cbranch_vccz .LBB0_1496
	s_barrier

.LBB0_1624:
	ds_read_b128 v[154:157], v150
	ds_read_b128 v[158:161], v150 offset:1024
	ds_read_b128 v[162:165], v150 offset:2048
	ds_read_b128 v[166:169], v150 offset:3072
	ds_read_b128 v[170:173], v151
	ds_read_b128 v[174:177], v151 offset:1024
	ds_read_b128 v[178:181], v151 offset:2048
	ds_read_b128 v[182:185], v151 offset:3072
	s_add_u32 s3, s88, 0xfff80080
	s_addc_u32 s42, s89, -1
	s_cmp_eq_u32 s37, 28
	s_cselect_b32 s93, s0, s42
	s_cselect_b32 s92, s1, s3
	s_cselect_b32 s91, s27, s36
	s_cselect_b32 s90, s33, s35
	s_add_i32 m0, s9, 0xc000
	ds_read_b128 v[186:189], v152
	ds_read_b128 v[190:193], v152 offset:1024
	ds_read_b128 v[194:197], v152 offset:2048
	ds_read_b128 v[198:201], v152 offset:3072
	ds_read_b128 v[202:205], v152 offset:4096
	ds_read_b128 v[206:209], v152 offset:5120
	ds_read_b128 v[210:213], v152 offset:6144
	ds_read_b128 v[214:217], v152 offset:7168
	global_load_lds_dwordx4 v138, s[88:89]
	s_add_i32 m0, s9, 0xe000
	s_nop 0
	global_load_lds_dwordx4 v140, s[88:89]
	s_waitcnt vmcnt(8)
	s_waitcnt lgkmcnt(0)
	s_barrier
	s_setprio 1
	s_waitcnt lgkmcnt(0)
	v_mfma_f32_16x16x32_bf16 v[124:127], v[154:157], v[186:189], v[124:127]
	v_mfma_f32_16x16x32_bf16 v[120:123], v[162:165], v[186:189], v[120:123]
	v_mfma_f32_16x16x32_bf16 v[108:111], v[154:157], v[194:197], v[108:111]
	v_mfma_f32_16x16x32_bf16 v[104:107], v[162:165], v[194:197], v[104:107]
	v_mfma_f32_16x16x32_bf16 v[92:95], v[154:157], v[202:205], v[92:95]
	v_mfma_f32_16x16x32_bf16 v[88:91], v[162:165], v[202:205], v[88:91]
	v_mfma_f32_16x16x32_bf16 v[76:79], v[154:157], v[210:213], v[76:79]
	v_mfma_f32_16x16x32_bf16 v[72:75], v[162:165], v[210:213], v[72:75]
	v_mfma_f32_16x16x32_bf16 v[124:127], v[158:161], v[190:193], v[124:127]
	v_mfma_f32_16x16x32_bf16 v[120:123], v[166:169], v[190:193], v[120:123]
	v_mfma_f32_16x16x32_bf16 v[108:111], v[158:161], v[198:201], v[108:111]
	v_mfma_f32_16x16x32_bf16 v[104:107], v[166:169], v[198:201], v[104:107]
	v_mfma_f32_16x16x32_bf16 v[92:95], v[158:161], v[206:209], v[92:95]
	v_mfma_f32_16x16x32_bf16 v[88:91], v[166:169], v[206:209], v[88:91]
	v_mfma_f32_16x16x32_bf16 v[76:79], v[158:161], v[214:217], v[76:79]
	v_mfma_f32_16x16x32_bf16 v[72:75], v[166:169], v[214:217], v[72:75]
	s_setprio 0
	s_setprio 1
	v_mfma_f32_16x16x32_bf16 v[116:119], v[170:173], v[186:189], v[116:119]
	v_mfma_f32_16x16x32_bf16 v[112:115], v[178:181], v[186:189], v[112:115]
	v_mfma_f32_16x16x32_bf16 v[100:103], v[170:173], v[194:197], v[100:103]
	v_mfma_f32_16x16x32_bf16 v[96:99], v[178:181], v[194:197], v[96:99]
	v_mfma_f32_16x16x32_bf16 v[84:87], v[170:173], v[202:205], v[84:87]
	v_mfma_f32_16x16x32_bf16 v[80:83], v[178:181], v[202:205], v[80:83]
	v_mfma_f32_16x16x32_bf16 v[68:71], v[170:173], v[210:213], v[68:71]
	v_mfma_f32_16x16x32_bf16 v[64:67], v[178:181], v[210:213], v[64:67]
	v_mfma_f32_16x16x32_bf16 v[116:119], v[174:177], v[190:193], v[116:119]
	v_mfma_f32_16x16x32_bf16 v[112:115], v[182:185], v[190:193], v[112:115]
	v_mfma_f32_16x16x32_bf16 v[100:103], v[174:177], v[198:201], v[100:103]
	v_mfma_f32_16x16x32_bf16 v[96:99], v[182:185], v[198:201], v[96:99]
	v_mfma_f32_16x16x32_bf16 v[84:87], v[174:177], v[206:209], v[84:87]
	v_mfma_f32_16x16x32_bf16 v[80:83], v[182:185], v[206:209], v[80:83]
	v_mfma_f32_16x16x32_bf16 v[68:71], v[174:177], v[214:217], v[68:71]
	v_mfma_f32_16x16x32_bf16 v[64:67], v[182:185], v[214:217], v[64:67]
	s_setprio 0
	s_barrier
	s_add_i32 s3, s48, s8
	s_mov_b32 m0, s3
	ds_read_b128 v[186:189], v152 offset:16384
	ds_read_b128 v[190:193], v152 offset:17408
	ds_read_b128 v[194:197], v152 offset:18432
	ds_read_b128 v[198:201], v152 offset:19456
	ds_read_b128 v[202:205], v152 offset:20480
	ds_read_b128 v[206:209], v152 offset:21504
	ds_read_b128 v[210:213], v152 offset:22528
	ds_read_b128 v[214:217], v152 offset:23552
	global_load_lds_dwordx4 v130, s[90:91]
	s_add_i32 m0, s3, 0x2000
	s_add_u32 s42, s90, 0x80000
	s_addc_u32 s43, s91, 0
	s_add_i32 s3, s49, s8
	global_load_lds_dwordx4 v134, s[90:91]
	s_mov_b32 m0, s3
	s_nop 0
	global_load_lds_dwordx4 v130, s[42:43]
	s_add_i32 m0, s3, 0x2000
	s_nop 0
	global_load_lds_dwordx4 v134, s[42:43]
	s_mov_b32 m0, s9
	s_nop 0
	global_load_lds_dwordx4 v128, s[92:93]
	s_mov_b32 m0, s18
	s_nop 0
	global_load_lds_dwordx4 v132, s[92:93]
	s_waitcnt vmcnt(8)
	s_waitcnt lgkmcnt(0)
	s_barrier
	s_setprio 1
	s_waitcnt lgkmcnt(0)
	v_mfma_f32_16x16x32_bf16 v[60:63], v[154:157], v[186:189], v[60:63]
	v_mfma_f32_16x16x32_bf16 v[56:59], v[162:165], v[186:189], v[56:59]
	v_mfma_f32_16x16x32_bf16 v[44:47], v[154:157], v[194:197], v[44:47]
	v_mfma_f32_16x16x32_bf16 v[40:43], v[162:165], v[194:197], v[40:43]
	v_mfma_f32_16x16x32_bf16 v[28:31], v[154:157], v[202:205], v[28:31]
	v_mfma_f32_16x16x32_bf16 v[24:27], v[162:165], v[202:205], v[24:27]
	v_mfma_f32_16x16x32_bf16 v[12:15], v[154:157], v[210:213], v[12:15]
	v_mfma_f32_16x16x32_bf16 v[8:11], v[162:165], v[210:213], v[8:11]
	v_mfma_f32_16x16x32_bf16 v[60:63], v[158:161], v[190:193], v[60:63]
	v_mfma_f32_16x16x32_bf16 v[56:59], v[166:169], v[190:193], v[56:59]
	v_mfma_f32_16x16x32_bf16 v[44:47], v[158:161], v[198:201], v[44:47]
	v_mfma_f32_16x16x32_bf16 v[40:43], v[166:169], v[198:201], v[40:43]
	v_mfma_f32_16x16x32_bf16 v[28:31], v[158:161], v[206:209], v[28:31]
	v_mfma_f32_16x16x32_bf16 v[24:27], v[166:169], v[206:209], v[24:27]
	v_mfma_f32_16x16x32_bf16 v[12:15], v[158:161], v[214:217], v[12:15]
	v_mfma_f32_16x16x32_bf16 v[8:11], v[166:169], v[214:217], v[8:11]
	s_setprio 0
	s_setprio 1
	v_mfma_f32_16x16x32_bf16 v[52:55], v[170:173], v[186:189], v[52:55]
	v_mfma_f32_16x16x32_bf16 v[48:51], v[178:181], v[186:189], v[48:51]
	v_mfma_f32_16x16x32_bf16 v[36:39], v[170:173], v[194:197], v[36:39]
	v_mfma_f32_16x16x32_bf16 v[32:35], v[178:181], v[194:197], v[32:35]
	v_mfma_f32_16x16x32_bf16 v[20:23], v[170:173], v[202:205], v[20:23]
	v_mfma_f32_16x16x32_bf16 v[16:19], v[178:181], v[202:205], v[16:19]
	v_mfma_f32_16x16x32_bf16 v[4:7], v[170:173], v[210:213], v[4:7]
	v_mfma_f32_16x16x32_bf16 v[0:3], v[178:181], v[210:213], v[0:3]
	v_mfma_f32_16x16x32_bf16 v[52:55], v[174:177], v[190:193], v[52:55]
	v_mfma_f32_16x16x32_bf16 v[48:51], v[182:185], v[190:193], v[48:51]
	v_mfma_f32_16x16x32_bf16 v[36:39], v[174:177], v[198:201], v[36:39]
	v_mfma_f32_16x16x32_bf16 v[32:35], v[182:185], v[198:201], v[32:35]
	v_mfma_f32_16x16x32_bf16 v[20:23], v[174:177], v[206:209], v[20:23]
	v_mfma_f32_16x16x32_bf16 v[16:19], v[182:185], v[206:209], v[16:19]
	v_mfma_f32_16x16x32_bf16 v[4:7], v[174:177], v[214:217], v[4:7]
	v_mfma_f32_16x16x32_bf16 v[0:3], v[182:185], v[214:217], v[0:3]
	s_setprio 0
	s_barrier
	s_add_i32 s3, 0, 0x18000
	v_add_u32_e32 v153, s3, v149
	s_add_i32 s44, 0, 0x1c000
	ds_read_b128 v[154:157], v153
	ds_read_b128 v[158:161], v153 offset:1024
	ds_read_b128 v[162:165], v153 offset:2048
	ds_read_b128 v[166:169], v153 offset:3072
	v_add_u32_e32 v153, s44, v149
	ds_read_b128 v[170:173], v153
	ds_read_b128 v[174:177], v153 offset:1024
	ds_read_b128 v[178:181], v153 offset:2048
	ds_read_b128 v[182:185], v153 offset:3072
	s_add_u32 s42, s92, 0x80000
	s_addc_u32 s43, s93, 0
	s_mov_b32 m0, s19
	ds_read_b128 v[186:189], v152 offset:32768
	ds_read_b128 v[190:193], v152 offset:33792
	ds_read_b128 v[194:197], v152 offset:34816
	ds_read_b128 v[198:201], v152 offset:35840
	ds_read_b128 v[202:205], v152 offset:36864
	ds_read_b128 v[206:209], v152 offset:37888
	ds_read_b128 v[210:213], v152 offset:38912
	ds_read_b128 v[214:217], v152 offset:39936
	global_load_lds_dwordx4 v128, s[42:43]
	v_lshl_add_u64 v[224:225], s[42:43], 0, v[132:133]
	s_mov_b32 m0, s25
	s_nop 0
	global_load_lds_dwordx4 v[224:225], off
	s_waitcnt vmcnt(8)
	s_waitcnt lgkmcnt(0)
	s_barrier
	s_setprio 1
	s_waitcnt lgkmcnt(0)
	v_mfma_f32_16x16x32_bf16 v[124:127], v[154:157], v[186:189], v[124:127]
	v_mfma_f32_16x16x32_bf16 v[120:123], v[162:165], v[186:189], v[120:123]
	v_mfma_f32_16x16x32_bf16 v[108:111], v[154:157], v[194:197], v[108:111]
	v_mfma_f32_16x16x32_bf16 v[104:107], v[162:165], v[194:197], v[104:107]
	v_mfma_f32_16x16x32_bf16 v[92:95], v[154:157], v[202:205], v[92:95]
	v_mfma_f32_16x16x32_bf16 v[88:91], v[162:165], v[202:205], v[88:91]
	v_mfma_f32_16x16x32_bf16 v[76:79], v[154:157], v[210:213], v[76:79]
	v_mfma_f32_16x16x32_bf16 v[72:75], v[162:165], v[210:213], v[72:75]
	v_mfma_f32_16x16x32_bf16 v[124:127], v[158:161], v[190:193], v[124:127]
	v_mfma_f32_16x16x32_bf16 v[120:123], v[166:169], v[190:193], v[120:123]
	v_mfma_f32_16x16x32_bf16 v[108:111], v[158:161], v[198:201], v[108:111]
	v_mfma_f32_16x16x32_bf16 v[104:107], v[166:169], v[198:201], v[104:107]
	v_mfma_f32_16x16x32_bf16 v[92:95], v[158:161], v[206:209], v[92:95]
	v_mfma_f32_16x16x32_bf16 v[88:91], v[166:169], v[206:209], v[88:91]
	v_mfma_f32_16x16x32_bf16 v[76:79], v[158:161], v[214:217], v[76:79]
	v_mfma_f32_16x16x32_bf16 v[72:75], v[166:169], v[214:217], v[72:75]
	s_setprio 0
	s_setprio 1
	v_mfma_f32_16x16x32_bf16 v[116:119], v[170:173], v[186:189], v[116:119]
	v_mfma_f32_16x16x32_bf16 v[112:115], v[178:181], v[186:189], v[112:115]
	v_mfma_f32_16x16x32_bf16 v[100:103], v[170:173], v[194:197], v[100:103]
	v_mfma_f32_16x16x32_bf16 v[96:99], v[178:181], v[194:197], v[96:99]
	v_mfma_f32_16x16x32_bf16 v[84:87], v[170:173], v[202:205], v[84:87]
	v_mfma_f32_16x16x32_bf16 v[80:83], v[178:181], v[202:205], v[80:83]
	v_mfma_f32_16x16x32_bf16 v[68:71], v[170:173], v[210:213], v[68:71]
	v_mfma_f32_16x16x32_bf16 v[64:67], v[178:181], v[210:213], v[64:67]
	v_mfma_f32_16x16x32_bf16 v[116:119], v[174:177], v[190:193], v[116:119]
	v_mfma_f32_16x16x32_bf16 v[112:115], v[182:185], v[190:193], v[112:115]
	v_mfma_f32_16x16x32_bf16 v[100:103], v[174:177], v[198:201], v[100:103]
	v_mfma_f32_16x16x32_bf16 v[96:99], v[182:185], v[198:201], v[96:99]
	v_mfma_f32_16x16x32_bf16 v[84:87], v[174:177], v[206:209], v[84:87]
	v_mfma_f32_16x16x32_bf16 v[80:83], v[182:185], v[206:209], v[80:83]
	v_mfma_f32_16x16x32_bf16 v[68:71], v[174:177], v[214:217], v[68:71]
	v_mfma_f32_16x16x32_bf16 v[64:67], v[182:185], v[214:217], v[64:67]
	s_setprio 0
	s_barrier
	s_add_i32 s3, s3, s8
	s_add_u32 s42, s90, 0x80
	s_addc_u32 s43, s91, 0
	s_mov_b32 m0, s3
	ds_read_b128 v[186:189], v152 offset:49152
	ds_read_b128 v[190:193], v152 offset:50176
	ds_read_b128 v[194:197], v152 offset:51200
	ds_read_b128 v[198:201], v152 offset:52224
	ds_read_b128 v[202:205], v152 offset:53248
	ds_read_b128 v[206:209], v152 offset:54272
	ds_read_b128 v[210:213], v152 offset:55296
	ds_read_b128 v[214:217], v152 offset:56320
	global_load_lds_dwordx4 v130, s[42:43]
	s_add_i32 m0, s3, 0x2000
	s_add_i32 s3, s44, s8
	global_load_lds_dwordx4 v134, s[42:43]
	s_add_u32 s42, s42, 0x80000
	s_addc_u32 s43, s43, 0
	s_mov_b32 m0, s3
	s_nop 0
	global_load_lds_dwordx4 v130, s[42:43]
	s_add_i32 m0, s3, 0x2000
	s_nop 0
	global_load_lds_dwordx4 v134, s[42:43]
	s_add_u32 s92, s92, 0x80
	s_addc_u32 s93, s93, 0
	s_mov_b32 m0, s30
	s_nop 0
	global_load_lds_dwordx4 v128, s[92:93]
	s_mov_b32 m0, s31
	s_nop 0
	global_load_lds_dwordx4 v132, s[92:93]
	s_waitcnt vmcnt(8)
	s_waitcnt lgkmcnt(0)
	s_barrier
	s_setprio 1
	s_waitcnt lgkmcnt(0)
	v_mfma_f32_16x16x32_bf16 v[60:63], v[154:157], v[186:189], v[60:63]
	v_mfma_f32_16x16x32_bf16 v[56:59], v[162:165], v[186:189], v[56:59]
	v_mfma_f32_16x16x32_bf16 v[44:47], v[154:157], v[194:197], v[44:47]
	v_mfma_f32_16x16x32_bf16 v[40:43], v[162:165], v[194:197], v[40:43]
	v_mfma_f32_16x16x32_bf16 v[28:31], v[154:157], v[202:205], v[28:31]
	v_mfma_f32_16x16x32_bf16 v[24:27], v[162:165], v[202:205], v[24:27]
	v_mfma_f32_16x16x32_bf16 v[12:15], v[154:157], v[210:213], v[12:15]
	v_mfma_f32_16x16x32_bf16 v[8:11], v[162:165], v[210:213], v[8:11]
	v_mfma_f32_16x16x32_bf16 v[60:63], v[158:161], v[190:193], v[60:63]
	v_mfma_f32_16x16x32_bf16 v[56:59], v[166:169], v[190:193], v[56:59]
	v_mfma_f32_16x16x32_bf16 v[44:47], v[158:161], v[198:201], v[44:47]
	v_mfma_f32_16x16x32_bf16 v[40:43], v[166:169], v[198:201], v[40:43]
	v_mfma_f32_16x16x32_bf16 v[28:31], v[158:161], v[206:209], v[28:31]
	v_mfma_f32_16x16x32_bf16 v[24:27], v[166:169], v[206:209], v[24:27]
	v_mfma_f32_16x16x32_bf16 v[12:15], v[158:161], v[214:217], v[12:15]
	v_mfma_f32_16x16x32_bf16 v[8:11], v[166:169], v[214:217], v[8:11]
	s_setprio 0
	s_setprio 1
	v_mfma_f32_16x16x32_bf16 v[52:55], v[170:173], v[186:189], v[52:55]
	v_mfma_f32_16x16x32_bf16 v[48:51], v[178:181], v[186:189], v[48:51]
	v_mfma_f32_16x16x32_bf16 v[36:39], v[170:173], v[194:197], v[36:39]
	v_mfma_f32_16x16x32_bf16 v[32:35], v[178:181], v[194:197], v[32:35]
	v_mfma_f32_16x16x32_bf16 v[20:23], v[170:173], v[202:205], v[20:23]
	v_mfma_f32_16x16x32_bf16 v[16:19], v[178:181], v[202:205], v[16:19]
	v_mfma_f32_16x16x32_bf16 v[4:7], v[170:173], v[210:213], v[4:7]
	v_mfma_f32_16x16x32_bf16 v[0:3], v[178:181], v[210:213], v[0:3]
	v_mfma_f32_16x16x32_bf16 v[52:55], v[174:177], v[190:193], v[52:55]
	v_mfma_f32_16x16x32_bf16 v[48:51], v[182:185], v[190:193], v[48:51]
	v_mfma_f32_16x16x32_bf16 v[36:39], v[174:177], v[198:201], v[36:39]
	v_mfma_f32_16x16x32_bf16 v[32:35], v[182:185], v[198:201], v[32:35]
	v_mfma_f32_16x16x32_bf16 v[20:23], v[174:177], v[206:209], v[20:23]
	v_mfma_f32_16x16x32_bf16 v[16:19], v[182:185], v[206:209], v[16:19]
	v_mfma_f32_16x16x32_bf16 v[4:7], v[174:177], v[214:217], v[4:7]
	v_mfma_f32_16x16x32_bf16 v[0:3], v[182:185], v[214:217], v[0:3]
	s_setprio 0
	s_barrier
	s_add_i32 s37, s37, 2
	s_add_u32 s88, s88, 0x100
	s_addc_u32 s89, s89, 0
	s_add_u32 s35, s35, 0x100
	s_addc_u32 s36, s36, 0
	s_cmp_gt_u32 s37, 29
	s_cbranch_scc0 .LBB0_1624
	s_and_b64 vcc, exec, s[16:17]
	s_cbranch_vccz .LBB0_1627
	s_barrier

.LBB0_1700:
	ds_read_b128 v[140:143], v149
	ds_read_b128 v[152:155], v149 offset:1024
	ds_read_b128 v[156:159], v149 offset:2048
	ds_read_b128 v[160:163], v149 offset:3072
	ds_read_b128 v[164:167], v150
	ds_read_b128 v[168:171], v150 offset:1024
	ds_read_b128 v[172:175], v150 offset:2048
	ds_read_b128 v[176:179], v150 offset:3072
	s_add_u32 s3, s86, 0xffe00080
	s_addc_u32 s37, s87, -1
	s_cmpk_eq_i32 s36, 0x7c
	s_cselect_b32 s91, s0, s37
	s_cselect_b32 s90, s1, s3
	s_cselect_b32 s89, s17, s35
	s_cselect_b32 s88, s27, s33
	s_add_i32 m0, s18, 0xc000
	ds_read_b128 v[180:183], v151
	ds_read_b128 v[184:187], v151 offset:1024
	ds_read_b128 v[188:191], v151 offset:2048
	ds_read_b128 v[192:195], v151 offset:3072
	ds_read_b128 v[196:199], v151 offset:4096
	ds_read_b128 v[200:203], v151 offset:5120
	ds_read_b128 v[204:207], v151 offset:6144
	ds_read_b128 v[208:211], v151 offset:7168
	global_load_lds_dwordx4 v132, s[86:87]
	s_add_i32 m0, s18, 0xe000
	s_nop 0
	global_load_lds_dwordx4 v134, s[86:87]
	s_waitcnt vmcnt(8)
	s_waitcnt lgkmcnt(0)
	s_barrier
	s_setprio 1
	s_waitcnt lgkmcnt(0)
	v_mfma_f32_16x16x32_bf16 v[124:127], v[140:143], v[180:183], v[124:127]
	v_mfma_f32_16x16x32_bf16 v[120:123], v[156:159], v[180:183], v[120:123]
	v_mfma_f32_16x16x32_bf16 v[112:115], v[140:143], v[188:191], v[112:115]
	v_mfma_f32_16x16x32_bf16 v[104:107], v[156:159], v[188:191], v[104:107]
	v_mfma_f32_16x16x32_bf16 v[96:99], v[140:143], v[196:199], v[96:99]
	v_mfma_f32_16x16x32_bf16 v[88:91], v[156:159], v[196:199], v[88:91]
	v_mfma_f32_16x16x32_bf16 v[80:83], v[140:143], v[204:207], v[80:83]
	v_mfma_f32_16x16x32_bf16 v[72:75], v[156:159], v[204:207], v[72:75]
	v_mfma_f32_16x16x32_bf16 v[124:127], v[152:155], v[184:187], v[124:127]
	v_mfma_f32_16x16x32_bf16 v[120:123], v[160:163], v[184:187], v[120:123]
	v_mfma_f32_16x16x32_bf16 v[112:115], v[152:155], v[192:195], v[112:115]
	v_mfma_f32_16x16x32_bf16 v[104:107], v[160:163], v[192:195], v[104:107]
	v_mfma_f32_16x16x32_bf16 v[96:99], v[152:155], v[200:203], v[96:99]
	v_mfma_f32_16x16x32_bf16 v[88:91], v[160:163], v[200:203], v[88:91]
	v_mfma_f32_16x16x32_bf16 v[80:83], v[152:155], v[208:211], v[80:83]
	v_mfma_f32_16x16x32_bf16 v[72:75], v[160:163], v[208:211], v[72:75]
	s_setprio 0
	s_setprio 1
	v_mfma_f32_16x16x32_bf16 v[116:119], v[164:167], v[180:183], v[116:119]
	v_mfma_f32_16x16x32_bf16 v[108:111], v[172:175], v[180:183], v[108:111]
	v_mfma_f32_16x16x32_bf16 v[100:103], v[164:167], v[188:191], v[100:103]
	v_mfma_f32_16x16x32_bf16 v[92:95], v[172:175], v[188:191], v[92:95]
	v_mfma_f32_16x16x32_bf16 v[84:87], v[164:167], v[196:199], v[84:87]
	v_mfma_f32_16x16x32_bf16 v[76:79], v[172:175], v[196:199], v[76:79]
	v_mfma_f32_16x16x32_bf16 v[68:71], v[164:167], v[204:207], v[68:71]
	v_mfma_f32_16x16x32_bf16 v[64:67], v[172:175], v[204:207], v[64:67]
	v_mfma_f32_16x16x32_bf16 v[116:119], v[168:171], v[184:187], v[116:119]
	v_mfma_f32_16x16x32_bf16 v[108:111], v[176:179], v[184:187], v[108:111]
	v_mfma_f32_16x16x32_bf16 v[100:103], v[168:171], v[192:195], v[100:103]
	v_mfma_f32_16x16x32_bf16 v[92:95], v[176:179], v[192:195], v[92:95]
	v_mfma_f32_16x16x32_bf16 v[84:87], v[168:171], v[200:203], v[84:87]
	v_mfma_f32_16x16x32_bf16 v[76:79], v[176:179], v[200:203], v[76:79]
	v_mfma_f32_16x16x32_bf16 v[68:71], v[168:171], v[208:211], v[68:71]
	v_mfma_f32_16x16x32_bf16 v[64:67], v[176:179], v[208:211], v[64:67]
	s_setprio 0
	s_barrier
	s_add_i32 s3, s49, s9
	s_mov_b32 m0, s3
	ds_read_b128 v[180:183], v151 offset:16384
	ds_read_b128 v[184:187], v151 offset:17408
	ds_read_b128 v[188:191], v151 offset:18432
	ds_read_b128 v[192:195], v151 offset:19456
	ds_read_b128 v[196:199], v151 offset:20480
	ds_read_b128 v[200:203], v151 offset:21504
	ds_read_b128 v[204:207], v151 offset:22528
	ds_read_b128 v[208:211], v151 offset:23552
	global_load_lds_dwordx4 v128, s[88:89]
	s_add_i32 m0, s3, 0x2000
	s_add_u32 s42, s88, 0x200000
	s_addc_u32 s43, s89, 0
	s_add_i32 s3, s52, s9
	global_load_lds_dwordx4 v130, s[88:89]
	s_mov_b32 m0, s3
	s_nop 0
	global_load_lds_dwordx4 v128, s[42:43]
	s_add_i32 m0, s3, 0x2000
	s_nop 0
	global_load_lds_dwordx4 v130, s[42:43]
	s_mov_b32 m0, s18
	s_nop 0
	global_load_lds_dwordx4 v128, s[90:91]
	s_mov_b32 m0, s19
	s_nop 0
	global_load_lds_dwordx4 v130, s[90:91]
	s_waitcnt vmcnt(8)
	s_waitcnt lgkmcnt(0)
	s_barrier
	s_setprio 1
	s_waitcnt lgkmcnt(0)
	v_mfma_f32_16x16x32_bf16 v[60:63], v[140:143], v[180:183], v[60:63]
	v_mfma_f32_16x16x32_bf16 v[56:59], v[156:159], v[180:183], v[56:59]
	v_mfma_f32_16x16x32_bf16 v[48:51], v[140:143], v[188:191], v[48:51]
	v_mfma_f32_16x16x32_bf16 v[40:43], v[156:159], v[188:191], v[40:43]
	v_mfma_f32_16x16x32_bf16 v[32:35], v[140:143], v[196:199], v[32:35]
	v_mfma_f32_16x16x32_bf16 v[24:27], v[156:159], v[196:199], v[24:27]
	v_mfma_f32_16x16x32_bf16 v[16:19], v[140:143], v[204:207], v[16:19]
	v_mfma_f32_16x16x32_bf16 v[8:11], v[156:159], v[204:207], v[8:11]
	v_mfma_f32_16x16x32_bf16 v[60:63], v[152:155], v[184:187], v[60:63]
	v_mfma_f32_16x16x32_bf16 v[56:59], v[160:163], v[184:187], v[56:59]
	v_mfma_f32_16x16x32_bf16 v[48:51], v[152:155], v[192:195], v[48:51]
	v_mfma_f32_16x16x32_bf16 v[40:43], v[160:163], v[192:195], v[40:43]
	v_mfma_f32_16x16x32_bf16 v[32:35], v[152:155], v[200:203], v[32:35]
	v_mfma_f32_16x16x32_bf16 v[24:27], v[160:163], v[200:203], v[24:27]
	v_mfma_f32_16x16x32_bf16 v[16:19], v[152:155], v[208:211], v[16:19]
	v_mfma_f32_16x16x32_bf16 v[8:11], v[160:163], v[208:211], v[8:11]
	s_setprio 0
	s_setprio 1
	v_mfma_f32_16x16x32_bf16 v[52:55], v[164:167], v[180:183], v[52:55]
	v_mfma_f32_16x16x32_bf16 v[44:47], v[172:175], v[180:183], v[44:47]
	v_mfma_f32_16x16x32_bf16 v[36:39], v[164:167], v[188:191], v[36:39]
	v_mfma_f32_16x16x32_bf16 v[28:31], v[172:175], v[188:191], v[28:31]
	v_mfma_f32_16x16x32_bf16 v[20:23], v[164:167], v[196:199], v[20:23]
	v_mfma_f32_16x16x32_bf16 v[12:15], v[172:175], v[196:199], v[12:15]
	v_mfma_f32_16x16x32_bf16 v[4:7], v[164:167], v[204:207], v[4:7]
	v_mfma_f32_16x16x32_bf16 v[0:3], v[172:175], v[204:207], v[0:3]
	v_mfma_f32_16x16x32_bf16 v[52:55], v[168:171], v[184:187], v[52:55]
	v_mfma_f32_16x16x32_bf16 v[44:47], v[176:179], v[184:187], v[44:47]
	v_mfma_f32_16x16x32_bf16 v[36:39], v[168:171], v[192:195], v[36:39]
	v_mfma_f32_16x16x32_bf16 v[28:31], v[176:179], v[192:195], v[28:31]
	v_mfma_f32_16x16x32_bf16 v[20:23], v[168:171], v[200:203], v[20:23]
	v_mfma_f32_16x16x32_bf16 v[12:15], v[176:179], v[200:203], v[12:15]
	v_mfma_f32_16x16x32_bf16 v[4:7], v[168:171], v[208:211], v[4:7]
	v_mfma_f32_16x16x32_bf16 v[0:3], v[176:179], v[208:211], v[0:3]
	s_setprio 0
	s_barrier
	s_add_i32 s3, 0, 0x18000
	s_add_i32 s37, 0, 0x1c000
	v_add_u32_e32 v160, s3, v147
	v_add_u32_e32 v176, s37, v147
	ds_read_b128 v[140:143], v160
	ds_read_b128 v[152:155], v160 offset:1024
	ds_read_b128 v[156:159], v160 offset:2048
	ds_read_b128 v[160:163], v160 offset:3072
	ds_read_b128 v[164:167], v176
	ds_read_b128 v[168:171], v176 offset:1024
	ds_read_b128 v[172:175], v176 offset:2048
	ds_read_b128 v[176:179], v176 offset:3072
	s_add_u32 s42, s90, 0x200000
	s_addc_u32 s43, s91, 0
	s_mov_b32 m0, s25
	ds_read_b128 v[180:183], v151 offset:32768
	ds_read_b128 v[184:187], v151 offset:33792
	ds_read_b128 v[188:191], v151 offset:34816
	ds_read_b128 v[192:195], v151 offset:35840
	ds_read_b128 v[196:199], v151 offset:36864
	ds_read_b128 v[200:203], v151 offset:37888
	ds_read_b128 v[204:207], v151 offset:38912
	ds_read_b128 v[208:211], v151 offset:39936
	global_load_lds_dwordx4 v128, s[42:43]
	v_lshl_add_u64 v[218:219], s[42:43], 0, v[130:131]
	s_mov_b32 m0, s30
	s_nop 0
	global_load_lds_dwordx4 v[218:219], off
	s_waitcnt vmcnt(8)
	s_waitcnt lgkmcnt(0)
	s_barrier
	s_setprio 1
	s_waitcnt lgkmcnt(0)
	v_mfma_f32_16x16x32_bf16 v[124:127], v[140:143], v[180:183], v[124:127]
	v_mfma_f32_16x16x32_bf16 v[120:123], v[156:159], v[180:183], v[120:123]
	v_mfma_f32_16x16x32_bf16 v[112:115], v[140:143], v[188:191], v[112:115]
	v_mfma_f32_16x16x32_bf16 v[104:107], v[156:159], v[188:191], v[104:107]
	v_mfma_f32_16x16x32_bf16 v[96:99], v[140:143], v[196:199], v[96:99]
	v_mfma_f32_16x16x32_bf16 v[88:91], v[156:159], v[196:199], v[88:91]
	v_mfma_f32_16x16x32_bf16 v[80:83], v[140:143], v[204:207], v[80:83]
	v_mfma_f32_16x16x32_bf16 v[72:75], v[156:159], v[204:207], v[72:75]
	v_mfma_f32_16x16x32_bf16 v[124:127], v[152:155], v[184:187], v[124:127]
	v_mfma_f32_16x16x32_bf16 v[120:123], v[160:163], v[184:187], v[120:123]
	v_mfma_f32_16x16x32_bf16 v[112:115], v[152:155], v[192:195], v[112:115]
	v_mfma_f32_16x16x32_bf16 v[104:107], v[160:163], v[192:195], v[104:107]
	v_mfma_f32_16x16x32_bf16 v[96:99], v[152:155], v[200:203], v[96:99]
	v_mfma_f32_16x16x32_bf16 v[88:91], v[160:163], v[200:203], v[88:91]
	v_mfma_f32_16x16x32_bf16 v[80:83], v[152:155], v[208:211], v[80:83]
	v_mfma_f32_16x16x32_bf16 v[72:75], v[160:163], v[208:211], v[72:75]
	s_setprio 0
	s_setprio 1
	v_mfma_f32_16x16x32_bf16 v[116:119], v[164:167], v[180:183], v[116:119]
	v_mfma_f32_16x16x32_bf16 v[108:111], v[172:175], v[180:183], v[108:111]
	v_mfma_f32_16x16x32_bf16 v[100:103], v[164:167], v[188:191], v[100:103]
	v_mfma_f32_16x16x32_bf16 v[92:95], v[172:175], v[188:191], v[92:95]
	v_mfma_f32_16x16x32_bf16 v[84:87], v[164:167], v[196:199], v[84:87]
	v_mfma_f32_16x16x32_bf16 v[76:79], v[172:175], v[196:199], v[76:79]
	v_mfma_f32_16x16x32_bf16 v[68:71], v[164:167], v[204:207], v[68:71]
	v_mfma_f32_16x16x32_bf16 v[64:67], v[172:175], v[204:207], v[64:67]
	v_mfma_f32_16x16x32_bf16 v[116:119], v[168:171], v[184:187], v[116:119]
	v_mfma_f32_16x16x32_bf16 v[108:111], v[176:179], v[184:187], v[108:111]
	v_mfma_f32_16x16x32_bf16 v[100:103], v[168:171], v[192:195], v[100:103]
	v_mfma_f32_16x16x32_bf16 v[92:95], v[176:179], v[192:195], v[92:95]
	v_mfma_f32_16x16x32_bf16 v[84:87], v[168:171], v[200:203], v[84:87]
	v_mfma_f32_16x16x32_bf16 v[76:79], v[176:179], v[200:203], v[76:79]
	v_mfma_f32_16x16x32_bf16 v[68:71], v[168:171], v[208:211], v[68:71]
	v_mfma_f32_16x16x32_bf16 v[64:67], v[176:179], v[208:211], v[64:67]
	s_setprio 0
	s_barrier
	s_add_i32 s3, s3, s9
	s_add_u32 s42, s88, 0x80
	s_addc_u32 s43, s89, 0
	s_mov_b32 m0, s3
	ds_read_b128 v[180:183], v151 offset:49152
	ds_read_b128 v[184:187], v151 offset:50176
	ds_read_b128 v[188:191], v151 offset:51200
	ds_read_b128 v[192:195], v151 offset:52224
	ds_read_b128 v[196:199], v151 offset:53248
	ds_read_b128 v[200:203], v151 offset:54272
	ds_read_b128 v[204:207], v151 offset:55296
	ds_read_b128 v[208:211], v151 offset:56320
	global_load_lds_dwordx4 v128, s[42:43]
	s_add_i32 m0, s3, 0x2000
	s_add_i32 s3, s37, s9
	global_load_lds_dwordx4 v130, s[42:43]
	s_add_u32 s42, s42, 0x200000
	s_addc_u32 s43, s43, 0
	s_mov_b32 m0, s3
	s_nop 0
	global_load_lds_dwordx4 v128, s[42:43]
	s_add_i32 m0, s3, 0x2000
	s_nop 0
	global_load_lds_dwordx4 v130, s[42:43]
	s_add_u32 s90, s90, 0x80
	s_addc_u32 s91, s91, 0
	s_mov_b32 m0, s8
	s_nop 0
	global_load_lds_dwordx4 v128, s[90:91]
	s_mov_b32 m0, s48
	s_nop 0
	global_load_lds_dwordx4 v130, s[90:91]
	s_waitcnt vmcnt(8)
	s_waitcnt lgkmcnt(0)
	s_barrier
	s_setprio 1
	s_waitcnt lgkmcnt(0)
	v_mfma_f32_16x16x32_bf16 v[60:63], v[140:143], v[180:183], v[60:63]
	v_mfma_f32_16x16x32_bf16 v[56:59], v[156:159], v[180:183], v[56:59]
	v_mfma_f32_16x16x32_bf16 v[48:51], v[140:143], v[188:191], v[48:51]
	v_mfma_f32_16x16x32_bf16 v[40:43], v[156:159], v[188:191], v[40:43]
	v_mfma_f32_16x16x32_bf16 v[32:35], v[140:143], v[196:199], v[32:35]
	v_mfma_f32_16x16x32_bf16 v[24:27], v[156:159], v[196:199], v[24:27]
	v_mfma_f32_16x16x32_bf16 v[16:19], v[140:143], v[204:207], v[16:19]
	v_mfma_f32_16x16x32_bf16 v[8:11], v[156:159], v[204:207], v[8:11]
	v_mfma_f32_16x16x32_bf16 v[60:63], v[152:155], v[184:187], v[60:63]
	v_mfma_f32_16x16x32_bf16 v[56:59], v[160:163], v[184:187], v[56:59]
	v_mfma_f32_16x16x32_bf16 v[48:51], v[152:155], v[192:195], v[48:51]
	v_mfma_f32_16x16x32_bf16 v[40:43], v[160:163], v[192:195], v[40:43]
	v_mfma_f32_16x16x32_bf16 v[32:35], v[152:155], v[200:203], v[32:35]
	v_mfma_f32_16x16x32_bf16 v[24:27], v[160:163], v[200:203], v[24:27]
	v_mfma_f32_16x16x32_bf16 v[16:19], v[152:155], v[208:211], v[16:19]
	v_mfma_f32_16x16x32_bf16 v[8:11], v[160:163], v[208:211], v[8:11]
	s_setprio 0
	s_setprio 1
	v_mfma_f32_16x16x32_bf16 v[52:55], v[164:167], v[180:183], v[52:55]
	v_mfma_f32_16x16x32_bf16 v[44:47], v[172:175], v[180:183], v[44:47]
	v_mfma_f32_16x16x32_bf16 v[36:39], v[164:167], v[188:191], v[36:39]
	v_mfma_f32_16x16x32_bf16 v[28:31], v[172:175], v[188:191], v[28:31]
	v_mfma_f32_16x16x32_bf16 v[20:23], v[164:167], v[196:199], v[20:23]
	v_mfma_f32_16x16x32_bf16 v[12:15], v[172:175], v[196:199], v[12:15]
	v_mfma_f32_16x16x32_bf16 v[4:7], v[164:167], v[204:207], v[4:7]
	v_mfma_f32_16x16x32_bf16 v[0:3], v[172:175], v[204:207], v[0:3]
	v_mfma_f32_16x16x32_bf16 v[52:55], v[168:171], v[184:187], v[52:55]
	v_mfma_f32_16x16x32_bf16 v[44:47], v[176:179], v[184:187], v[44:47]
	v_mfma_f32_16x16x32_bf16 v[36:39], v[168:171], v[192:195], v[36:39]
	v_mfma_f32_16x16x32_bf16 v[28:31], v[176:179], v[192:195], v[28:31]
	v_mfma_f32_16x16x32_bf16 v[20:23], v[168:171], v[200:203], v[20:23]
	v_mfma_f32_16x16x32_bf16 v[12:15], v[176:179], v[200:203], v[12:15]
	v_mfma_f32_16x16x32_bf16 v[4:7], v[168:171], v[208:211], v[4:7]
	v_mfma_f32_16x16x32_bf16 v[0:3], v[176:179], v[208:211], v[0:3]
	s_setprio 0
	s_barrier
	s_add_i32 s36, s36, 2
	s_add_u32 s86, s86, 0x100
	s_addc_u32 s87, s87, 0
	s_add_u32 s33, s33, 0x100
	s_addc_u32 s35, s35, 0
	s_cmpk_gt_u32 s36, 0x7d
	s_cbranch_scc0 .LBB0_1700
	s_and_b64 vcc, exec, s[14:15]
	s_cbranch_vccz .LBB0_1703
	s_barrier

.LBB0_1773:
	ds_read_b128 v[128:131], v173
	ds_read_b128 v[132:135], v173 offset:1024
	ds_read_b128 v[158:161], v173 offset:2048
	ds_read_b128 v[178:181], v173 offset:3072
	ds_read_b128 v[182:185], v174
	ds_read_b128 v[186:189], v174 offset:1024
	ds_read_b128 v[190:193], v174 offset:2048
	ds_read_b128 v[194:197], v174 offset:3072
	s_add_u32 s3, s34, 0xfff80080
	s_addc_u32 s19, s35, -1
	s_cmp_eq_u32 s18, 28
	s_cselect_b32 vcc_hi, s0, s19
	s_cselect_b32 vcc_lo, s1, s3
	s_cselect_b32 s97, s8, s17
	s_cselect_b32 s96, s9, s15
	s_add_i32 m0, s48, 0xc000
	ds_read_b128 v[198:201], v175
	ds_read_b128 v[202:205], v175 offset:1024
	ds_read_b128 v[206:209], v175 offset:2048
	ds_read_b128 v[210:213], v175 offset:3072
	ds_read_b128 v[214:217], v175 offset:4096
	ds_read_b128 v[218:221], v175 offset:5120
	ds_read_b128 v[222:225], v175 offset:6144
	ds_read_b128 v[230:233], v175 offset:7168
	global_load_lds_dwordx4 v148, s[34:35]
	s_add_i32 m0, s48, 0xe000
	s_nop 0
	global_load_lds_dwordx4 v150, s[34:35]
	s_waitcnt vmcnt(8)
	s_waitcnt lgkmcnt(0)
	s_barrier
	s_setprio 1
	s_waitcnt lgkmcnt(0)
	v_mfma_f32_16x16x32_bf16 v[124:127], v[128:131], v[198:201], v[124:127]
	v_mfma_f32_16x16x32_bf16 v[120:123], v[158:161], v[198:201], v[120:123]
	v_mfma_f32_16x16x32_bf16 v[108:111], v[128:131], v[206:209], v[108:111]
	v_mfma_f32_16x16x32_bf16 v[104:107], v[158:161], v[206:209], v[104:107]
	v_mfma_f32_16x16x32_bf16 v[92:95], v[128:131], v[214:217], v[92:95]
	v_mfma_f32_16x16x32_bf16 v[88:91], v[158:161], v[214:217], v[88:91]
	v_mfma_f32_16x16x32_bf16 v[76:79], v[128:131], v[222:225], v[76:79]
	v_mfma_f32_16x16x32_bf16 v[72:75], v[158:161], v[222:225], v[72:75]
	v_mfma_f32_16x16x32_bf16 v[124:127], v[132:135], v[202:205], v[124:127]
	v_mfma_f32_16x16x32_bf16 v[120:123], v[178:181], v[202:205], v[120:123]
	v_mfma_f32_16x16x32_bf16 v[108:111], v[132:135], v[210:213], v[108:111]
	v_mfma_f32_16x16x32_bf16 v[104:107], v[178:181], v[210:213], v[104:107]
	v_mfma_f32_16x16x32_bf16 v[92:95], v[132:135], v[218:221], v[92:95]
	v_mfma_f32_16x16x32_bf16 v[88:91], v[178:181], v[218:221], v[88:91]
	v_mfma_f32_16x16x32_bf16 v[76:79], v[132:135], v[230:233], v[76:79]
	v_mfma_f32_16x16x32_bf16 v[72:75], v[178:181], v[230:233], v[72:75]
	s_setprio 0
	s_setprio 1
	v_mfma_f32_16x16x32_bf16 v[116:119], v[182:185], v[198:201], v[116:119]
	v_mfma_f32_16x16x32_bf16 v[112:115], v[190:193], v[198:201], v[112:115]
	v_mfma_f32_16x16x32_bf16 v[100:103], v[182:185], v[206:209], v[100:103]
	v_mfma_f32_16x16x32_bf16 v[96:99], v[190:193], v[206:209], v[96:99]
	v_mfma_f32_16x16x32_bf16 v[84:87], v[182:185], v[214:217], v[84:87]
	v_mfma_f32_16x16x32_bf16 v[80:83], v[190:193], v[214:217], v[80:83]
	v_mfma_f32_16x16x32_bf16 v[68:71], v[182:185], v[222:225], v[68:71]
	v_mfma_f32_16x16x32_bf16 v[64:67], v[190:193], v[222:225], v[64:67]
	v_mfma_f32_16x16x32_bf16 v[116:119], v[186:189], v[202:205], v[116:119]
	v_mfma_f32_16x16x32_bf16 v[112:115], v[194:197], v[202:205], v[112:115]
	v_mfma_f32_16x16x32_bf16 v[100:103], v[186:189], v[210:213], v[100:103]
	v_mfma_f32_16x16x32_bf16 v[96:99], v[194:197], v[210:213], v[96:99]
	v_mfma_f32_16x16x32_bf16 v[84:87], v[186:189], v[218:221], v[84:87]
	v_mfma_f32_16x16x32_bf16 v[80:83], v[194:197], v[218:221], v[80:83]
	v_mfma_f32_16x16x32_bf16 v[68:71], v[186:189], v[230:233], v[68:71]
	v_mfma_f32_16x16x32_bf16 v[64:67], v[194:197], v[230:233], v[64:67]
	s_setprio 0
	s_barrier
	s_add_i32 s3, s76, s25
	s_mov_b32 m0, s3
	ds_read_b128 v[198:201], v175 offset:16384
	ds_read_b128 v[202:205], v175 offset:17408
	ds_read_b128 v[206:209], v175 offset:18432
	ds_read_b128 v[210:213], v175 offset:19456
	ds_read_b128 v[214:217], v175 offset:20480
	ds_read_b128 v[218:221], v175 offset:21504
	ds_read_b128 v[222:225], v175 offset:22528
	ds_read_b128 v[230:233], v175 offset:23552
	global_load_lds_dwordx4 v138, s[96:97]
	s_add_i32 m0, s3, 0x2000
	s_add_u32 s36, s96, 0x80000
	s_addc_u32 s37, s97, 0
	s_add_i32 s3, s77, s25
	global_load_lds_dwordx4 v142, s[96:97]
	s_mov_b32 m0, s3
	s_nop 0
	global_load_lds_dwordx4 v138, s[36:37]
	s_add_i32 m0, s3, 0x2000
	s_nop 0
	global_load_lds_dwordx4 v142, s[36:37]
	s_mov_b32 m0, s48
	s_nop 0
	global_load_lds_dwordx4 v136, vcc
	s_mov_b32 m0, s49
	s_nop 0
	global_load_lds_dwordx4 v140, vcc
	s_waitcnt vmcnt(8)
	s_waitcnt lgkmcnt(0)
	s_barrier
	s_setprio 1
	s_waitcnt lgkmcnt(0)
	v_mfma_f32_16x16x32_bf16 v[60:63], v[128:131], v[198:201], v[60:63]
	v_mfma_f32_16x16x32_bf16 v[56:59], v[158:161], v[198:201], v[56:59]
	v_mfma_f32_16x16x32_bf16 v[44:47], v[128:131], v[206:209], v[44:47]
	v_mfma_f32_16x16x32_bf16 v[40:43], v[158:161], v[206:209], v[40:43]
	v_mfma_f32_16x16x32_bf16 v[28:31], v[128:131], v[214:217], v[28:31]
	v_mfma_f32_16x16x32_bf16 v[24:27], v[158:161], v[214:217], v[24:27]
	v_mfma_f32_16x16x32_bf16 v[12:15], v[128:131], v[222:225], v[12:15]
	v_mfma_f32_16x16x32_bf16 v[8:11], v[158:161], v[222:225], v[8:11]
	v_mfma_f32_16x16x32_bf16 v[60:63], v[132:135], v[202:205], v[60:63]
	v_mfma_f32_16x16x32_bf16 v[56:59], v[178:181], v[202:205], v[56:59]
	v_mfma_f32_16x16x32_bf16 v[44:47], v[132:135], v[210:213], v[44:47]
	v_mfma_f32_16x16x32_bf16 v[40:43], v[178:181], v[210:213], v[40:43]
	v_mfma_f32_16x16x32_bf16 v[28:31], v[132:135], v[218:221], v[28:31]
	v_mfma_f32_16x16x32_bf16 v[24:27], v[178:181], v[218:221], v[24:27]
	v_mfma_f32_16x16x32_bf16 v[12:15], v[132:135], v[230:233], v[12:15]
	v_mfma_f32_16x16x32_bf16 v[8:11], v[178:181], v[230:233], v[8:11]
	s_setprio 0
	s_setprio 1
	v_mfma_f32_16x16x32_bf16 v[52:55], v[182:185], v[198:201], v[52:55]
	v_mfma_f32_16x16x32_bf16 v[48:51], v[190:193], v[198:201], v[48:51]
	v_mfma_f32_16x16x32_bf16 v[36:39], v[182:185], v[206:209], v[36:39]
	v_mfma_f32_16x16x32_bf16 v[32:35], v[190:193], v[206:209], v[32:35]
	v_mfma_f32_16x16x32_bf16 v[20:23], v[182:185], v[214:217], v[20:23]
	v_mfma_f32_16x16x32_bf16 v[16:19], v[190:193], v[214:217], v[16:19]
	v_mfma_f32_16x16x32_bf16 v[4:7], v[182:185], v[222:225], v[4:7]
	v_mfma_f32_16x16x32_bf16 v[0:3], v[190:193], v[222:225], v[0:3]
	v_mfma_f32_16x16x32_bf16 v[52:55], v[186:189], v[202:205], v[52:55]
	v_mfma_f32_16x16x32_bf16 v[48:51], v[194:197], v[202:205], v[48:51]
	v_mfma_f32_16x16x32_bf16 v[36:39], v[186:189], v[210:213], v[36:39]
	v_mfma_f32_16x16x32_bf16 v[32:35], v[194:197], v[210:213], v[32:35]
	v_mfma_f32_16x16x32_bf16 v[20:23], v[186:189], v[218:221], v[20:23]
	v_mfma_f32_16x16x32_bf16 v[16:19], v[194:197], v[218:221], v[16:19]
	v_mfma_f32_16x16x32_bf16 v[4:7], v[186:189], v[230:233], v[4:7]
	v_mfma_f32_16x16x32_bf16 v[0:3], v[194:197], v[230:233], v[0:3]
	s_setprio 0
	s_barrier
	s_add_i32 s3, 0, 0x18000
	v_add_u32_e32 v144, s3, v165
	s_add_i32 s19, 0, 0x1c000
	ds_read_b128 v[128:131], v144
	ds_read_b128 v[132:135], v144 offset:1024
	ds_read_b128 v[158:161], v144 offset:2048
	ds_read_b128 v[178:181], v144 offset:3072
	v_add_u32_e32 v144, s19, v165
	ds_read_b128 v[182:185], v144
	ds_read_b128 v[186:189], v144 offset:1024
	ds_read_b128 v[190:193], v144 offset:2048
	ds_read_b128 v[194:197], v144 offset:3072
	s_add_u32 s36, vcc_lo, 0x80000
	s_addc_u32 s37, vcc_hi, 0
	s_mov_b32 m0, s52
	ds_read_b128 v[198:201], v175 offset:32768
	ds_read_b128 v[202:205], v175 offset:33792
	ds_read_b128 v[206:209], v175 offset:34816
	ds_read_b128 v[210:213], v175 offset:35840
	ds_read_b128 v[214:217], v175 offset:36864
	ds_read_b128 v[218:221], v175 offset:37888
	ds_read_b128 v[222:225], v175 offset:38912
	ds_read_b128 v[230:233], v175 offset:39936
	global_load_lds_dwordx4 v136, s[36:37]
	s_mov_b32 m0, s53
	s_nop 0
	global_load_lds_dwordx4 v140, s[36:37]
	s_waitcnt vmcnt(8)
	s_waitcnt lgkmcnt(0)
	s_barrier
	s_setprio 1
	s_waitcnt lgkmcnt(0)
	v_mfma_f32_16x16x32_bf16 v[124:127], v[128:131], v[198:201], v[124:127]
	v_mfma_f32_16x16x32_bf16 v[120:123], v[158:161], v[198:201], v[120:123]
	v_mfma_f32_16x16x32_bf16 v[108:111], v[128:131], v[206:209], v[108:111]
	v_mfma_f32_16x16x32_bf16 v[104:107], v[158:161], v[206:209], v[104:107]
	v_mfma_f32_16x16x32_bf16 v[92:95], v[128:131], v[214:217], v[92:95]
	v_mfma_f32_16x16x32_bf16 v[88:91], v[158:161], v[214:217], v[88:91]
	v_mfma_f32_16x16x32_bf16 v[76:79], v[128:131], v[222:225], v[76:79]
	v_mfma_f32_16x16x32_bf16 v[72:75], v[158:161], v[222:225], v[72:75]
	v_mfma_f32_16x16x32_bf16 v[124:127], v[132:135], v[202:205], v[124:127]
	v_mfma_f32_16x16x32_bf16 v[120:123], v[178:181], v[202:205], v[120:123]
	v_mfma_f32_16x16x32_bf16 v[108:111], v[132:135], v[210:213], v[108:111]
	v_mfma_f32_16x16x32_bf16 v[104:107], v[178:181], v[210:213], v[104:107]
	v_mfma_f32_16x16x32_bf16 v[92:95], v[132:135], v[218:221], v[92:95]
	v_mfma_f32_16x16x32_bf16 v[88:91], v[178:181], v[218:221], v[88:91]
	v_mfma_f32_16x16x32_bf16 v[76:79], v[132:135], v[230:233], v[76:79]
	v_mfma_f32_16x16x32_bf16 v[72:75], v[178:181], v[230:233], v[72:75]
	s_setprio 0
	s_setprio 1
	v_mfma_f32_16x16x32_bf16 v[116:119], v[182:185], v[198:201], v[116:119]
	v_mfma_f32_16x16x32_bf16 v[112:115], v[190:193], v[198:201], v[112:115]
	v_mfma_f32_16x16x32_bf16 v[100:103], v[182:185], v[206:209], v[100:103]
	v_mfma_f32_16x16x32_bf16 v[96:99], v[190:193], v[206:209], v[96:99]
	v_mfma_f32_16x16x32_bf16 v[84:87], v[182:185], v[214:217], v[84:87]
	v_mfma_f32_16x16x32_bf16 v[80:83], v[190:193], v[214:217], v[80:83]
	v_mfma_f32_16x16x32_bf16 v[68:71], v[182:185], v[222:225], v[68:71]
	v_mfma_f32_16x16x32_bf16 v[64:67], v[190:193], v[222:225], v[64:67]
	v_mfma_f32_16x16x32_bf16 v[116:119], v[186:189], v[202:205], v[116:119]
	v_mfma_f32_16x16x32_bf16 v[112:115], v[194:197], v[202:205], v[112:115]
	v_mfma_f32_16x16x32_bf16 v[100:103], v[186:189], v[210:213], v[100:103]
	v_mfma_f32_16x16x32_bf16 v[96:99], v[194:197], v[210:213], v[96:99]
	v_mfma_f32_16x16x32_bf16 v[84:87], v[186:189], v[218:221], v[84:87]
	v_mfma_f32_16x16x32_bf16 v[80:83], v[194:197], v[218:221], v[80:83]
	v_mfma_f32_16x16x32_bf16 v[68:71], v[186:189], v[230:233], v[68:71]
	v_mfma_f32_16x16x32_bf16 v[64:67], v[194:197], v[230:233], v[64:67]
	s_setprio 0
	s_barrier
	s_add_i32 s3, s3, s25
	s_add_u32 s36, s96, 0x80
	s_addc_u32 s37, s97, 0
	s_mov_b32 m0, s3
	ds_read_b128 v[198:201], v175 offset:49152
	ds_read_b128 v[202:205], v175 offset:50176
	ds_read_b128 v[206:209], v175 offset:51200
	ds_read_b128 v[210:213], v175 offset:52224
	ds_read_b128 v[214:217], v175 offset:53248
	ds_read_b128 v[218:221], v175 offset:54272
	ds_read_b128 v[222:225], v175 offset:55296
	ds_read_b128 v[230:233], v175 offset:56320
	global_load_lds_dwordx4 v138, s[36:37]
	s_add_i32 m0, s3, 0x2000
	s_add_i32 s3, s19, s25
	global_load_lds_dwordx4 v142, s[36:37]
	s_add_u32 s36, s36, 0x80000
	s_addc_u32 s37, s37, 0
	s_mov_b32 m0, s3
	s_nop 0
	global_load_lds_dwordx4 v138, s[36:37]
	s_add_i32 m0, s3, 0x2000
	s_nop 0
	global_load_lds_dwordx4 v142, s[36:37]
	s_add_u32 vcc_lo, vcc_lo, 0x80
	s_addc_u32 vcc_hi, vcc_hi, 0
	s_mov_b32 m0, s56
	s_nop 0
	global_load_lds_dwordx4 v136, vcc
	s_mov_b32 m0, s57
	s_nop 0
	global_load_lds_dwordx4 v140, vcc
	s_waitcnt vmcnt(8)
	s_waitcnt lgkmcnt(0)
	s_barrier
	s_setprio 1
	s_waitcnt lgkmcnt(0)
	v_mfma_f32_16x16x32_bf16 v[60:63], v[128:131], v[198:201], v[60:63]
	v_mfma_f32_16x16x32_bf16 v[56:59], v[158:161], v[198:201], v[56:59]
	v_mfma_f32_16x16x32_bf16 v[44:47], v[128:131], v[206:209], v[44:47]
	v_mfma_f32_16x16x32_bf16 v[40:43], v[158:161], v[206:209], v[40:43]
	v_mfma_f32_16x16x32_bf16 v[28:31], v[128:131], v[214:217], v[28:31]
	v_mfma_f32_16x16x32_bf16 v[24:27], v[158:161], v[214:217], v[24:27]
	v_mfma_f32_16x16x32_bf16 v[12:15], v[128:131], v[222:225], v[12:15]
	v_mfma_f32_16x16x32_bf16 v[8:11], v[158:161], v[222:225], v[8:11]
	v_mfma_f32_16x16x32_bf16 v[60:63], v[132:135], v[202:205], v[60:63]
	v_mfma_f32_16x16x32_bf16 v[56:59], v[178:181], v[202:205], v[56:59]
	v_mfma_f32_16x16x32_bf16 v[44:47], v[132:135], v[210:213], v[44:47]
	v_mfma_f32_16x16x32_bf16 v[40:43], v[178:181], v[210:213], v[40:43]
	v_mfma_f32_16x16x32_bf16 v[28:31], v[132:135], v[218:221], v[28:31]
	v_mfma_f32_16x16x32_bf16 v[24:27], v[178:181], v[218:221], v[24:27]
	v_mfma_f32_16x16x32_bf16 v[12:15], v[132:135], v[230:233], v[12:15]
	v_mfma_f32_16x16x32_bf16 v[8:11], v[178:181], v[230:233], v[8:11]
	s_setprio 0
	s_setprio 1
	v_mfma_f32_16x16x32_bf16 v[52:55], v[182:185], v[198:201], v[52:55]
	v_mfma_f32_16x16x32_bf16 v[48:51], v[190:193], v[198:201], v[48:51]
	v_mfma_f32_16x16x32_bf16 v[36:39], v[182:185], v[206:209], v[36:39]
	v_mfma_f32_16x16x32_bf16 v[32:35], v[190:193], v[206:209], v[32:35]
	v_mfma_f32_16x16x32_bf16 v[20:23], v[182:185], v[214:217], v[20:23]
	v_mfma_f32_16x16x32_bf16 v[16:19], v[190:193], v[214:217], v[16:19]
	v_mfma_f32_16x16x32_bf16 v[4:7], v[182:185], v[222:225], v[4:7]
	v_mfma_f32_16x16x32_bf16 v[0:3], v[190:193], v[222:225], v[0:3]
	v_mfma_f32_16x16x32_bf16 v[52:55], v[186:189], v[202:205], v[52:55]
	v_mfma_f32_16x16x32_bf16 v[48:51], v[194:197], v[202:205], v[48:51]
	v_mfma_f32_16x16x32_bf16 v[36:39], v[186:189], v[210:213], v[36:39]
	v_mfma_f32_16x16x32_bf16 v[32:35], v[194:197], v[210:213], v[32:35]
	v_mfma_f32_16x16x32_bf16 v[20:23], v[186:189], v[218:221], v[20:23]
	v_mfma_f32_16x16x32_bf16 v[16:19], v[194:197], v[218:221], v[16:19]
	v_mfma_f32_16x16x32_bf16 v[4:7], v[186:189], v[230:233], v[4:7]
	v_mfma_f32_16x16x32_bf16 v[0:3], v[194:197], v[230:233], v[0:3]
	s_setprio 0
	s_barrier
	s_add_i32 s18, s18, 2
	s_add_u32 s34, s34, 0x100
	s_addc_u32 s35, s35, 0
	s_add_u32 s15, s15, 0x100
	s_addc_u32 s17, s17, 0
	s_cmp_gt_u32 s18, 29
	s_cbranch_scc0 .LBB0_1773
	s_and_b64 vcc, exec, s[84:85]
	s_cbranch_vccz .LBB0_1776
	s_barrier

.LBB0_2103:
	s_cmp_eq_u32 s58, 0
	s_cselect_b64 s[0:1], -1, 0
	s_or_b64 s[0:1], s[60:61], s[0:1]
	s_and_b64 vcc, exec, s[0:1]
	s_cbranch_vccnz .Lfz1_c2
	s_add_i32 s0, s68, 0xc000
	s_and_b32 s0, s0, 0xc000
	v_add_u32_e32 v0, s0, v234
	ds_read_b64_tr_b16 v[160:161], v0 offset:0x2000
	ds_read_b64_tr_b16 v[162:163], v0 offset:0x2100
	ds_read_b64_tr_b16 v[164:165], v0 offset:0x3000
	ds_read_b64_tr_b16 v[166:167], v0 offset:0x3100
	s_waitcnt lgkmcnt(2)
	v_mfma_f32_32x32x16_bf16 v[128:143], v[6:9], v[160:163], v[128:143]
	ds_read_b64_tr_b16 v[168:169], v0 offset:0x2200
	v_mfma_f32_32x32x16_bf16 v[96:111], v[2:5], v[160:163], v[96:111]
	ds_read_b64_tr_b16 v[170:171], v0 offset:0x2300
	s_waitcnt lgkmcnt(2)
	v_mfma_f32_32x32x16_bf16 v[128:143], v[208:211], v[164:167], v[128:143]
	ds_read_b64_tr_b16 v[172:173], v0 offset:0x3200
	v_mfma_f32_32x32x16_bf16 v[96:111], v[10:13], v[164:167], v[96:111]
	ds_read_b64_tr_b16 v[174:175], v0 offset:0x3300
	s_waitcnt lgkmcnt(2)
	v_mfma_f32_32x32x16_bf16 v[112:127], v[6:9], v[168:171], v[112:127]
	ds_read_b64_tr_b16 v[160:161], v0 offset:0x2400
	v_mfma_f32_32x32x16_bf16 v[80:95], v[2:5], v[168:171], v[80:95]
	ds_read_b64_tr_b16 v[162:163], v0 offset:0x2500
	s_waitcnt lgkmcnt(2)
	v_mfma_f32_32x32x16_bf16 v[112:127], v[208:211], v[172:175], v[112:127]
	ds_read_b64_tr_b16 v[164:165], v0 offset:0x3400
	v_mfma_f32_32x32x16_bf16 v[80:95], v[10:13], v[172:175], v[80:95]
	ds_read_b64_tr_b16 v[166:167], v0 offset:0x3500
	s_waitcnt lgkmcnt(2)
	v_mfma_f32_32x32x16_bf16 v[64:79], v[6:9], v[160:163], v[64:79]
	ds_read_b64_tr_b16 v[168:169], v0 offset:0x2600
	v_mfma_f32_32x32x16_bf16 v[32:47], v[2:5], v[160:163], v[32:47]
	ds_read_b64_tr_b16 v[170:171], v0 offset:0x2700
	s_waitcnt lgkmcnt(2)
	v_mfma_f32_32x32x16_bf16 v[64:79], v[208:211], v[164:167], v[64:79]
	ds_read_b64_tr_b16 v[172:173], v0 offset:0x3600
	v_mfma_f32_32x32x16_bf16 v[32:47], v[10:13], v[164:167], v[32:47]
	ds_read_b64_tr_b16 v[174:175], v0 offset:0x3700
	s_waitcnt lgkmcnt(2)
	v_mfma_f32_32x32x16_bf16 v[48:63], v[6:9], v[168:171], v[48:63]
	v_mfma_f32_32x32x16_bf16 v[16:31], v[2:5], v[168:171], v[16:31]
	s_waitcnt lgkmcnt(0)
	v_mfma_f32_32x32x16_bf16 v[48:63], v[208:211], v[172:175], v[48:63]
	v_mfma_f32_32x32x16_bf16 v[16:31], v[10:13], v[172:175], v[16:31]
.Lfz1_c2:
	s_and_b32 s27, s68, 0xc000
	v_add_u32_e32 v241, s27, v233
	ds_read_b128 v[144:147], v241 offset:0
	v_xor_b32_e32 v240, 32, v241
	ds_read_b128 v[148:151], v240 offset:0
	v_xor_b32_e32 v239, 64, v241
	ds_read_b128 v[152:155], v239 offset:0
	v_xor_b32_e32 v0, 0x60, v241
	ds_read_b128 v[156:159], v0 offset:0
	s_waitcnt lgkmcnt(0)
	v_mfma_f32_32x32x16_bf16 v[212:227], v[144:147], v[176:179], 0
	v_mfma_f32_32x32x16_bf16 v[212:227], v[148:151], v[180:183], v[212:227]
	v_mfma_f32_32x32x16_bf16 v[212:227], v[152:155], v[184:187], v[212:227]
	v_mfma_f32_32x32x16_bf16 v[212:227], v[156:159], v[188:191], v[212:227]
	ds_read_b128 v[144:147], v241 offset:0x80
	ds_read_b128 v[148:151], v240 offset:0x80
	ds_read_b128 v[152:155], v239 offset:0x80
	ds_read_b128 v[156:159], v0 offset:0x80
	v_cmp_eq_f32_e32 vcc, 0, v238
	v_cmp_eq_f32_e64 s[6:7], 0, v237
	s_and_b64 s[0:1], vcc, s[6:7]
	s_cmp_eq_u64 s[0:1], exec
	s_waitcnt lgkmcnt(0)
	v_mfma_f32_32x32x16_bf16 v[160:175], v[144:147], v[192:195], 0
	v_mfma_f32_32x32x16_bf16 v[160:175], v[148:151], v[196:199], v[160:175]
	v_mfma_f32_32x32x16_bf16 v[160:175], v[152:155], v[200:203], v[160:175]
	v_mfma_f32_32x32x16_bf16 v[160:175], v[156:159], v[204:207], v[160:175]
	s_cbranch_scc0 .LBB0_2105
	v_exp_f32_e32 v144, v212
	v_exp_f32_e32 v145, v213
	v_exp_f32_e32 v146, v214
	v_exp_f32_e32 v147, v215
	v_exp_f32_e32 v148, v216
	v_exp_f32_e32 v149, v217
	v_exp_f32_e32 v150, v218
	v_exp_f32_e32 v151, v219
	v_exp_f32_e32 v152, v220
	v_exp_f32_e32 v153, v221
	v_exp_f32_e32 v154, v222
	v_exp_f32_e32 v155, v223
	v_exp_f32_e32 v156, v224
	v_exp_f32_e32 v157, v225
	v_exp_f32_e32 v158, v226
	v_exp_f32_e32 v159, v227
	v_add_f32_e32 v252, v144, v145
	v_add_f32_e32 v253, v146, v147
	v_add_f32_e32 v254, v148, v149
	v_add_f32_e32 v255, v150, v151
	v_add_f32_e32 v252, v252, v152
	v_add_f32_e32 v253, v253, v153
	v_add_f32_e32 v254, v254, v154
	v_add_f32_e32 v255, v255, v155
	v_add_f32_e32 v252, v252, v156
	v_add_f32_e32 v253, v253, v157
	v_add_f32_e32 v254, v254, v158
	v_add_f32_e32 v255, v255, v159
	v_cvt_pk_bf16_f32 v216, v144, v145
	v_cvt_pk_bf16_f32 v217, v146, v147
	v_add_f32_e32 v252, v252, v253
	v_add_f32_e32 v254, v254, v255
	v_cvt_pk_bf16_f32 v218, v148, v149
	v_cvt_pk_bf16_f32 v219, v150, v151
	v_cvt_pk_bf16_f32 v224, v152, v153
	v_add_f32_e32 v252, v252, v254
	v_cvt_pk_bf16_f32 v225, v154, v155
	v_cvt_pk_bf16_f32 v226, v156, v157
	v_cvt_pk_bf16_f32 v227, v158, v159
	v_add_u32_e32 v253, 0xde801b54, v252
	v_cmp_gt_u32_e32 vcc, 0x3bff7543, v253
	s_cmp_lg_u64 vcc, exec
	s_cbranch_scc1 .LBB0_2140
	v_add_f32_e32 v15, v15, v252
	v_exp_f32_e32 v144, v160
	v_exp_f32_e32 v145, v161
	v_exp_f32_e32 v146, v162
	v_exp_f32_e32 v147, v163
	v_exp_f32_e32 v148, v164
	v_exp_f32_e32 v149, v165
	v_exp_f32_e32 v150, v166
	v_exp_f32_e32 v151, v167
	v_exp_f32_e32 v152, v168
	v_exp_f32_e32 v153, v169
	v_exp_f32_e32 v154, v170
	v_exp_f32_e32 v155, v171
	v_exp_f32_e32 v156, v172
	v_exp_f32_e32 v157, v173
	v_exp_f32_e32 v158, v174
	v_exp_f32_e32 v159, v175
	v_add_f32_e32 v252, v144, v145
	v_add_f32_e32 v253, v146, v147
	v_add_f32_e32 v254, v148, v149
	v_add_f32_e32 v255, v150, v151
	v_add_f32_e32 v252, v252, v152
	v_add_f32_e32 v253, v253, v153
	v_add_f32_e32 v254, v254, v154
	v_add_f32_e32 v255, v255, v155
	v_add_f32_e32 v252, v252, v156
	v_add_f32_e32 v253, v253, v157
	v_add_f32_e32 v254, v254, v158
	v_add_f32_e32 v255, v255, v159
	v_cvt_pk_bf16_f32 v212, v144, v145
	v_cvt_pk_bf16_f32 v213, v146, v147
	v_add_f32_e32 v252, v252, v253
	v_add_f32_e32 v254, v254, v255
	v_cvt_pk_bf16_f32 v214, v148, v149
	v_cvt_pk_bf16_f32 v215, v150, v151
	v_cvt_pk_bf16_f32 v220, v152, v153
	v_add_f32_e32 v252, v252, v254
	v_cvt_pk_bf16_f32 v221, v154, v155
	v_cvt_pk_bf16_f32 v222, v156, v157
	v_cvt_pk_bf16_f32 v223, v158, v159
	v_add_u32_e32 v253, 0xde801b54, v252
	v_cmp_gt_u32_e32 vcc, 0x3bff7543, v253
	s_cmp_lg_u64 vcc, exec
	s_cbranch_scc1 .Lfzsb1_c2
	v_add_f32_e32 v14, v14, v252
	s_branch .LBB0_2121

.LBB0_2121:
	v_add_u32_e32 v242, s27, v234
	ds_read_b64_tr_b16 v[160:161], v242 offset:0x0
	ds_read_b64_tr_b16 v[162:163], v242 offset:0x100
	ds_read_b64_tr_b16 v[164:165], v242 offset:0x1000
	ds_read_b64_tr_b16 v[166:167], v242 offset:0x1100
	s_waitcnt lgkmcnt(2)
	v_mfma_f32_32x32x16_bf16 v[128:143], v[216:219], v[160:163], v[128:143]
	ds_read_b64_tr_b16 v[168:169], v242 offset:0x200
	v_mfma_f32_32x32x16_bf16 v[96:111], v[212:215], v[160:163], v[96:111]
	ds_read_b64_tr_b16 v[170:171], v242 offset:0x300
	s_waitcnt lgkmcnt(2)
	v_mfma_f32_32x32x16_bf16 v[128:143], v[224:227], v[164:167], v[128:143]
	ds_read_b64_tr_b16 v[172:173], v242 offset:0x1200
	v_mfma_f32_32x32x16_bf16 v[96:111], v[220:223], v[164:167], v[96:111]
	ds_read_b64_tr_b16 v[174:175], v242 offset:0x1300
	s_waitcnt lgkmcnt(2)
	v_mfma_f32_32x32x16_bf16 v[112:127], v[216:219], v[168:171], v[112:127]
	ds_read_b64_tr_b16 v[160:161], v242 offset:0x400
	v_mfma_f32_32x32x16_bf16 v[80:95], v[212:215], v[168:171], v[80:95]
	ds_read_b64_tr_b16 v[162:163], v242 offset:0x500
	s_waitcnt lgkmcnt(2)
	v_mfma_f32_32x32x16_bf16 v[112:127], v[224:227], v[172:175], v[112:127]
	ds_read_b64_tr_b16 v[164:165], v242 offset:0x1400
	v_mfma_f32_32x32x16_bf16 v[80:95], v[220:223], v[172:175], v[80:95]
	ds_read_b64_tr_b16 v[166:167], v242 offset:0x1500
	ds_read_b128 v[144:147], v241 offset:0x2000
	ds_read_b128 v[148:151], v240 offset:0x2000
	ds_read_b128 v[156:159], v239 offset:0x2000
	ds_read_b128 v[244:247], v0 offset:0x2000
	s_waitcnt lgkmcnt(6)
	v_mfma_f32_32x32x16_bf16 v[64:79], v[216:219], v[160:163], v[64:79]
	ds_read_b64_tr_b16 v[168:169], v242 offset:0x600
	v_mfma_f32_32x32x16_bf16 v[32:47], v[212:215], v[160:163], v[32:47]
	ds_read_b64_tr_b16 v[170:171], v242 offset:0x700
	s_waitcnt lgkmcnt(6)
	v_mfma_f32_32x32x16_bf16 v[64:79], v[224:227], v[164:167], v[64:79]
	ds_read_b64_tr_b16 v[172:173], v242 offset:0x1600
	v_mfma_f32_32x32x16_bf16 v[32:47], v[220:223], v[164:167], v[32:47]
	ds_read_b64_tr_b16 v[174:175], v242 offset:0x1700
	s_waitcnt lgkmcnt(2)
	v_mfma_f32_32x32x16_bf16 v[48:63], v[216:219], v[168:171], v[48:63]
	v_mfma_f32_32x32x16_bf16 v[16:31], v[212:215], v[168:171], v[16:31]
	s_waitcnt lgkmcnt(0)
	v_mfma_f32_32x32x16_bf16 v[48:63], v[224:227], v[172:175], v[48:63]
	v_mfma_f32_32x32x16_bf16 v[16:31], v[220:223], v[172:175], v[16:31]
	s_waitcnt lgkmcnt(0)
	v_mfma_f32_32x32x16_bf16 v[212:227], v[144:147], v[176:179], 0
	v_mfma_f32_32x32x16_bf16 v[212:227], v[148:151], v[180:183], v[212:227]
	v_mfma_f32_32x32x16_bf16 v[212:227], v[156:159], v[184:187], v[212:227]
	v_mfma_f32_32x32x16_bf16 v[212:227], v[244:247], v[188:191], v[212:227]
	ds_read_b128 v[144:147], v241 offset:0x2080
	ds_read_b128 v[148:151], v240 offset:0x2080
	ds_read_b128 v[152:155], v239 offset:0x2080
	ds_read_b128 v[156:159], v0 offset:0x2080
	v_cmp_eq_f32_e32 vcc, 0, v238
	v_cmp_eq_f32_e64 s[6:7], 0, v237
	s_and_b64 s[0:1], vcc, s[6:7]
	s_cmp_eq_u64 s[0:1], exec
	s_waitcnt lgkmcnt(0)
	v_mfma_f32_32x32x16_bf16 v[160:175], v[144:147], v[192:195], 0
	v_mfma_f32_32x32x16_bf16 v[160:175], v[148:151], v[196:199], v[160:175]
	v_mfma_f32_32x32x16_bf16 v[160:175], v[152:155], v[200:203], v[160:175]
	v_mfma_f32_32x32x16_bf16 v[160:175], v[156:159], v[204:207], v[160:175]
	s_cbranch_scc0 .Lfz2o_c2
	v_exp_f32_e32 v144, v212
	v_exp_f32_e32 v145, v213
	v_exp_f32_e32 v146, v214
	v_exp_f32_e32 v147, v215
	v_exp_f32_e32 v148, v216
	v_exp_f32_e32 v149, v217
	v_exp_f32_e32 v150, v218
	v_exp_f32_e32 v151, v219
	v_exp_f32_e32 v152, v220
	v_exp_f32_e32 v153, v221
	v_exp_f32_e32 v154, v222
	v_exp_f32_e32 v155, v223
	v_exp_f32_e32 v156, v224
	v_exp_f32_e32 v157, v225
	v_exp_f32_e32 v158, v226
	v_exp_f32_e32 v159, v227
	v_add_f32_e32 v252, v144, v145
	v_add_f32_e32 v253, v146, v147
	v_add_f32_e32 v254, v148, v149
	v_add_f32_e32 v255, v150, v151
	v_add_f32_e32 v252, v252, v152
	v_add_f32_e32 v253, v253, v153
	v_add_f32_e32 v254, v254, v154
	v_add_f32_e32 v255, v255, v155
	v_add_f32_e32 v252, v252, v156
	v_add_f32_e32 v253, v253, v157
	v_add_f32_e32 v254, v254, v158
	v_add_f32_e32 v255, v255, v159
	v_cvt_pk_bf16_f32 v6, v144, v145
	v_cvt_pk_bf16_f32 v7, v146, v147
	v_add_f32_e32 v252, v252, v253
	v_add_f32_e32 v254, v254, v255
	v_cvt_pk_bf16_f32 v8, v148, v149
	v_cvt_pk_bf16_f32 v9, v150, v151
	v_cvt_pk_bf16_f32 v208, v152, v153
	v_add_f32_e32 v252, v252, v254
	v_cvt_pk_bf16_f32 v209, v154, v155
	v_cvt_pk_bf16_f32 v210, v156, v157
	v_cvt_pk_bf16_f32 v211, v158, v159
	v_add_u32_e32 v253, 0xde801b54, v252
	v_cmp_gt_u32_e32 vcc, 0x3bff7543, v253
	s_cmp_lg_u64 vcc, exec
	s_cbranch_scc1 .LBB0_2152
	v_add_f32_e32 v15, v15, v252
	v_exp_f32_e32 v144, v160
	v_exp_f32_e32 v145, v161
	v_exp_f32_e32 v146, v162
	v_exp_f32_e32 v147, v163
	v_exp_f32_e32 v148, v164
	v_exp_f32_e32 v149, v165
	v_exp_f32_e32 v150, v166
	v_exp_f32_e32 v151, v167
	v_exp_f32_e32 v152, v168
	v_exp_f32_e32 v153, v169
	v_exp_f32_e32 v154, v170
	v_exp_f32_e32 v155, v171
	v_exp_f32_e32 v156, v172
	v_exp_f32_e32 v157, v173
	v_exp_f32_e32 v158, v174
	v_exp_f32_e32 v159, v175
	v_add_f32_e32 v252, v144, v145
	v_add_f32_e32 v253, v146, v147
	v_add_f32_e32 v254, v148, v149
	v_add_f32_e32 v255, v150, v151
	v_add_f32_e32 v252, v252, v152
	v_add_f32_e32 v253, v253, v153
	v_add_f32_e32 v254, v254, v154
	v_add_f32_e32 v255, v255, v155
	v_add_f32_e32 v252, v252, v156
	v_add_f32_e32 v253, v253, v157
	v_add_f32_e32 v254, v254, v158
	v_add_f32_e32 v255, v255, v159
	v_cvt_pk_bf16_f32 v2, v144, v145
	v_cvt_pk_bf16_f32 v3, v146, v147
	v_add_f32_e32 v252, v252, v253
	v_add_f32_e32 v254, v254, v255
	v_cvt_pk_bf16_f32 v4, v148, v149
	v_cvt_pk_bf16_f32 v5, v150, v151
	v_cvt_pk_bf16_f32 v10, v152, v153
	v_add_f32_e32 v252, v252, v254
	v_cvt_pk_bf16_f32 v11, v154, v155
	v_cvt_pk_bf16_f32 v12, v156, v157
	v_cvt_pk_bf16_f32 v13, v158, v159
	v_add_u32_e32 v253, 0xde801b54, v252
	v_cmp_gt_u32_e32 vcc, 0x3bff7543, v253
	s_cmp_lg_u64 vcc, exec
	s_cbranch_scc1 .Lfzsb2_c2
	v_add_f32_e32 v14, v14, v252
	s_branch .LBB0_2137

.LBB0_2137:
	s_andn2_b64 vcc, exec, s[52:53]
	s_cbranch_vccnz .LBB0_2096
	ds_read_b64_tr_b16 v[160:161], v242 offset:0x2000
	ds_read_b64_tr_b16 v[162:163], v242 offset:0x2100
	ds_read_b64_tr_b16 v[164:165], v242 offset:0x3000
	ds_read_b64_tr_b16 v[166:167], v242 offset:0x3100
	s_waitcnt lgkmcnt(2)
	v_mfma_f32_32x32x16_bf16 v[128:143], v[6:9], v[160:163], v[128:143]
	ds_read_b64_tr_b16 v[168:169], v242 offset:0x2200
	v_mfma_f32_32x32x16_bf16 v[96:111], v[2:5], v[160:163], v[96:111]
	ds_read_b64_tr_b16 v[170:171], v242 offset:0x2300
	s_waitcnt lgkmcnt(2)
	v_mfma_f32_32x32x16_bf16 v[128:143], v[208:211], v[164:167], v[128:143]
	ds_read_b64_tr_b16 v[172:173], v242 offset:0x3200
	v_mfma_f32_32x32x16_bf16 v[96:111], v[10:13], v[164:167], v[96:111]
	ds_read_b64_tr_b16 v[174:175], v242 offset:0x3300
	s_waitcnt lgkmcnt(2)
	v_mfma_f32_32x32x16_bf16 v[112:127], v[6:9], v[168:171], v[112:127]
	ds_read_b64_tr_b16 v[160:161], v242 offset:0x2400
	v_mfma_f32_32x32x16_bf16 v[80:95], v[2:5], v[168:171], v[80:95]
	ds_read_b64_tr_b16 v[162:163], v242 offset:0x2500
	s_waitcnt lgkmcnt(2)
	v_mfma_f32_32x32x16_bf16 v[112:127], v[208:211], v[172:175], v[112:127]
	ds_read_b64_tr_b16 v[164:165], v242 offset:0x3400
	v_mfma_f32_32x32x16_bf16 v[80:95], v[10:13], v[172:175], v[80:95]
	ds_read_b64_tr_b16 v[166:167], v242 offset:0x3500
	s_waitcnt lgkmcnt(2)
	v_mfma_f32_32x32x16_bf16 v[64:79], v[6:9], v[160:163], v[64:79]
	ds_read_b64_tr_b16 v[168:169], v242 offset:0x2600
	v_mfma_f32_32x32x16_bf16 v[32:47], v[2:5], v[160:163], v[32:47]
	ds_read_b64_tr_b16 v[170:171], v242 offset:0x2700
	s_waitcnt lgkmcnt(2)
	v_mfma_f32_32x32x16_bf16 v[64:79], v[208:211], v[164:167], v[64:79]
	ds_read_b64_tr_b16 v[172:173], v242 offset:0x3600
	v_mfma_f32_32x32x16_bf16 v[32:47], v[10:13], v[164:167], v[32:47]
	ds_read_b64_tr_b16 v[174:175], v242 offset:0x3700
	s_waitcnt lgkmcnt(2)
	v_mfma_f32_32x32x16_bf16 v[48:63], v[6:9], v[168:171], v[48:63]
	v_mfma_f32_32x32x16_bf16 v[16:31], v[2:5], v[168:171], v[16:31]
	s_waitcnt lgkmcnt(0)
	v_mfma_f32_32x32x16_bf16 v[48:63], v[208:211], v[172:175], v[48:63]
	v_mfma_f32_32x32x16_bf16 v[16:31], v[10:13], v[172:175], v[16:31]
	s_branch .LBB0_2096

.LBB0_2171:
	s_and_b64 vcc, exec, s[42:43]
	s_cbranch_vccz .LBB0_2173
	s_cmp_lg_u32 0, -1
	s_cselect_b32 s0, 0, 0
	s_add_i32 s0, s0, 0xc000
	v_add_u32_e32 v0, s0, v232
	ds_read_b64_tr_b16 v[160:161], v0 offset:0x2000
	ds_read_b64_tr_b16 v[162:163], v0 offset:0x2100
	ds_read_b64_tr_b16 v[164:165], v0 offset:0x3000
	ds_read_b64_tr_b16 v[166:167], v0 offset:0x3100
	s_waitcnt lgkmcnt(2)
	v_mfma_f32_32x32x16_bf16 v[128:143], v[6:9], v[160:163], v[128:143]
	ds_read_b64_tr_b16 v[168:169], v0 offset:0x2200
	v_mfma_f32_32x32x16_bf16 v[96:111], v[2:5], v[160:163], v[96:111]
	ds_read_b64_tr_b16 v[170:171], v0 offset:0x2300
	s_waitcnt lgkmcnt(2)
	v_mfma_f32_32x32x16_bf16 v[128:143], v[208:211], v[164:167], v[128:143]
	ds_read_b64_tr_b16 v[172:173], v0 offset:0x3200
	v_mfma_f32_32x32x16_bf16 v[96:111], v[10:13], v[164:167], v[96:111]
	ds_read_b64_tr_b16 v[174:175], v0 offset:0x3300
	s_waitcnt lgkmcnt(2)
	v_mfma_f32_32x32x16_bf16 v[112:127], v[6:9], v[168:171], v[112:127]
	ds_read_b64_tr_b16 v[160:161], v0 offset:0x2400
	v_mfma_f32_32x32x16_bf16 v[80:95], v[2:5], v[168:171], v[80:95]
	ds_read_b64_tr_b16 v[162:163], v0 offset:0x2500
	s_waitcnt lgkmcnt(2)
	v_mfma_f32_32x32x16_bf16 v[112:127], v[208:211], v[172:175], v[112:127]
	ds_read_b64_tr_b16 v[164:165], v0 offset:0x3400
	v_mfma_f32_32x32x16_bf16 v[80:95], v[10:13], v[172:175], v[80:95]
	ds_read_b64_tr_b16 v[166:167], v0 offset:0x3500
	s_waitcnt lgkmcnt(2)
	v_mfma_f32_32x32x16_bf16 v[64:79], v[6:9], v[160:163], v[64:79]
	ds_read_b64_tr_b16 v[168:169], v0 offset:0x2600
	v_mfma_f32_32x32x16_bf16 v[32:47], v[2:5], v[160:163], v[32:47]
	ds_read_b64_tr_b16 v[170:171], v0 offset:0x2700
	s_waitcnt lgkmcnt(2)
	v_mfma_f32_32x32x16_bf16 v[64:79], v[208:211], v[164:167], v[64:79]
	ds_read_b64_tr_b16 v[172:173], v0 offset:0x3600
	v_mfma_f32_32x32x16_bf16 v[32:47], v[10:13], v[164:167], v[32:47]
	ds_read_b64_tr_b16 v[174:175], v0 offset:0x3700
	s_waitcnt lgkmcnt(2)
	v_mfma_f32_32x32x16_bf16 v[48:63], v[6:9], v[168:171], v[48:63]
	v_mfma_f32_32x32x16_bf16 v[16:31], v[2:5], v[168:171], v[16:31]
	s_waitcnt lgkmcnt(0)
	v_mfma_f32_32x32x16_bf16 v[48:63], v[208:211], v[172:175], v[48:63]
	v_mfma_f32_32x32x16_bf16 v[16:31], v[10:13], v[172:175], v[16:31]

.LBB0_2248:
	ds_read_b128 v[144:147], v153
	ds_read_b128 v[156:159], v153 offset:1024
	ds_read_b128 v[160:163], v153 offset:2048
	ds_read_b128 v[164:167], v153 offset:3072
	ds_read_b128 v[168:171], v154
	ds_read_b128 v[172:175], v154 offset:1024
	ds_read_b128 v[176:179], v154 offset:2048
	ds_read_b128 v[180:183], v154 offset:3072
	s_add_u32 s3, s52, 0xfffc0080
	s_addc_u32 s45, s53, -1
	s_cmp_eq_u32 s44, 12
	s_cselect_b32 s59, s0, s45
	s_cselect_b32 s58, s1, s3
	s_cselect_b32 s57, s17, s35
	s_cselect_b32 s56, s27, s33
	s_add_i32 m0, s9, 0xc000
	ds_read_b128 v[184:187], v155
	ds_read_b128 v[188:191], v155 offset:1024
	ds_read_b128 v[192:195], v155 offset:2048
	ds_read_b128 v[196:199], v155 offset:3072
	ds_read_b128 v[200:203], v155 offset:4096
	ds_read_b128 v[204:207], v155 offset:5120
	ds_read_b128 v[208:211], v155 offset:6144
	ds_read_b128 v[212:215], v155 offset:7168
	global_load_lds_dwordx4 v136, s[52:53]
	s_add_i32 m0, s9, 0xe000
	s_nop 0
	global_load_lds_dwordx4 v138, s[52:53]
	s_waitcnt vmcnt(8)
	s_waitcnt lgkmcnt(0)
	s_barrier
	s_setprio 1
	s_waitcnt lgkmcnt(0)
	v_mfma_f32_16x16x32_bf16 v[124:127], v[144:147], v[184:187], v[124:127]
	v_mfma_f32_16x16x32_bf16 v[120:123], v[160:163], v[184:187], v[120:123]
	v_mfma_f32_16x16x32_bf16 v[108:111], v[144:147], v[192:195], v[108:111]
	v_mfma_f32_16x16x32_bf16 v[104:107], v[160:163], v[192:195], v[104:107]
	v_mfma_f32_16x16x32_bf16 v[92:95], v[144:147], v[200:203], v[92:95]
	v_mfma_f32_16x16x32_bf16 v[88:91], v[160:163], v[200:203], v[88:91]
	v_mfma_f32_16x16x32_bf16 v[76:79], v[144:147], v[208:211], v[76:79]
	v_mfma_f32_16x16x32_bf16 v[72:75], v[160:163], v[208:211], v[72:75]
	v_mfma_f32_16x16x32_bf16 v[124:127], v[156:159], v[188:191], v[124:127]
	v_mfma_f32_16x16x32_bf16 v[120:123], v[164:167], v[188:191], v[120:123]
	v_mfma_f32_16x16x32_bf16 v[108:111], v[156:159], v[196:199], v[108:111]
	v_mfma_f32_16x16x32_bf16 v[104:107], v[164:167], v[196:199], v[104:107]
	v_mfma_f32_16x16x32_bf16 v[92:95], v[156:159], v[204:207], v[92:95]
	v_mfma_f32_16x16x32_bf16 v[88:91], v[164:167], v[204:207], v[88:91]
	v_mfma_f32_16x16x32_bf16 v[76:79], v[156:159], v[212:215], v[76:79]
	v_mfma_f32_16x16x32_bf16 v[72:75], v[164:167], v[212:215], v[72:75]
	s_setprio 0
	s_setprio 1
	v_mfma_f32_16x16x32_bf16 v[116:119], v[168:171], v[184:187], v[116:119]
	v_mfma_f32_16x16x32_bf16 v[112:115], v[176:179], v[184:187], v[112:115]
	v_mfma_f32_16x16x32_bf16 v[100:103], v[168:171], v[192:195], v[100:103]
	v_mfma_f32_16x16x32_bf16 v[96:99], v[176:179], v[192:195], v[96:99]
	v_mfma_f32_16x16x32_bf16 v[84:87], v[168:171], v[200:203], v[84:87]
	v_mfma_f32_16x16x32_bf16 v[80:83], v[176:179], v[200:203], v[80:83]
	v_mfma_f32_16x16x32_bf16 v[68:71], v[168:171], v[208:211], v[68:71]
	v_mfma_f32_16x16x32_bf16 v[64:67], v[176:179], v[208:211], v[64:67]
	v_mfma_f32_16x16x32_bf16 v[116:119], v[172:175], v[188:191], v[116:119]
	v_mfma_f32_16x16x32_bf16 v[112:115], v[180:183], v[188:191], v[112:115]
	v_mfma_f32_16x16x32_bf16 v[100:103], v[172:175], v[196:199], v[100:103]
	v_mfma_f32_16x16x32_bf16 v[96:99], v[180:183], v[196:199], v[96:99]
	v_mfma_f32_16x16x32_bf16 v[84:87], v[172:175], v[204:207], v[84:87]
	v_mfma_f32_16x16x32_bf16 v[80:83], v[180:183], v[204:207], v[80:83]
	v_mfma_f32_16x16x32_bf16 v[68:71], v[172:175], v[212:215], v[68:71]
	v_mfma_f32_16x16x32_bf16 v[64:67], v[180:183], v[212:215], v[64:67]
	s_setprio 0
	s_barrier
	s_add_i32 s3, s62, s8
	s_mov_b32 m0, s3
	ds_read_b128 v[184:187], v155 offset:16384
	ds_read_b128 v[188:191], v155 offset:17408
	ds_read_b128 v[192:195], v155 offset:18432
	ds_read_b128 v[196:199], v155 offset:19456
	ds_read_b128 v[200:203], v155 offset:20480
	ds_read_b128 v[204:207], v155 offset:21504
	ds_read_b128 v[208:211], v155 offset:22528
	ds_read_b128 v[212:215], v155 offset:23552
	global_load_lds_dwordx4 v130, s[56:57]
	s_add_i32 m0, s3, 0x2000
	s_add_u32 s50, s56, 0x40000
	s_addc_u32 s51, s57, 0
	s_add_i32 s3, s63, s8
	global_load_lds_dwordx4 v134, s[56:57]
	s_mov_b32 m0, s3
	s_nop 0
	global_load_lds_dwordx4 v130, s[50:51]
	s_add_i32 m0, s3, 0x2000
	s_nop 0
	global_load_lds_dwordx4 v134, s[50:51]
	s_mov_b32 m0, s9
	s_nop 0
	global_load_lds_dwordx4 v128, s[58:59]
	s_mov_b32 m0, s18
	s_nop 0
	global_load_lds_dwordx4 v132, s[58:59]
	s_waitcnt vmcnt(8)
	s_waitcnt lgkmcnt(0)
	s_barrier
	s_setprio 1
	s_waitcnt lgkmcnt(0)
	v_mfma_f32_16x16x32_bf16 v[60:63], v[144:147], v[184:187], v[60:63]
	v_mfma_f32_16x16x32_bf16 v[56:59], v[160:163], v[184:187], v[56:59]
	v_mfma_f32_16x16x32_bf16 v[44:47], v[144:147], v[192:195], v[44:47]
	v_mfma_f32_16x16x32_bf16 v[40:43], v[160:163], v[192:195], v[40:43]
	v_mfma_f32_16x16x32_bf16 v[28:31], v[144:147], v[200:203], v[28:31]
	v_mfma_f32_16x16x32_bf16 v[24:27], v[160:163], v[200:203], v[24:27]
	v_mfma_f32_16x16x32_bf16 v[12:15], v[144:147], v[208:211], v[12:15]
	v_mfma_f32_16x16x32_bf16 v[8:11], v[160:163], v[208:211], v[8:11]
	v_mfma_f32_16x16x32_bf16 v[60:63], v[156:159], v[188:191], v[60:63]
	v_mfma_f32_16x16x32_bf16 v[56:59], v[164:167], v[188:191], v[56:59]
	v_mfma_f32_16x16x32_bf16 v[44:47], v[156:159], v[196:199], v[44:47]
	v_mfma_f32_16x16x32_bf16 v[40:43], v[164:167], v[196:199], v[40:43]
	v_mfma_f32_16x16x32_bf16 v[28:31], v[156:159], v[204:207], v[28:31]
	v_mfma_f32_16x16x32_bf16 v[24:27], v[164:167], v[204:207], v[24:27]
	v_mfma_f32_16x16x32_bf16 v[12:15], v[156:159], v[212:215], v[12:15]
	v_mfma_f32_16x16x32_bf16 v[8:11], v[164:167], v[212:215], v[8:11]
	s_setprio 0
	s_setprio 1
	v_mfma_f32_16x16x32_bf16 v[52:55], v[168:171], v[184:187], v[52:55]
	v_mfma_f32_16x16x32_bf16 v[48:51], v[176:179], v[184:187], v[48:51]
	v_mfma_f32_16x16x32_bf16 v[36:39], v[168:171], v[192:195], v[36:39]
	v_mfma_f32_16x16x32_bf16 v[32:35], v[176:179], v[192:195], v[32:35]
	v_mfma_f32_16x16x32_bf16 v[20:23], v[168:171], v[200:203], v[20:23]
	v_mfma_f32_16x16x32_bf16 v[16:19], v[176:179], v[200:203], v[16:19]
	v_mfma_f32_16x16x32_bf16 v[4:7], v[168:171], v[208:211], v[4:7]
	v_mfma_f32_16x16x32_bf16 v[0:3], v[176:179], v[208:211], v[0:3]
	v_mfma_f32_16x16x32_bf16 v[52:55], v[172:175], v[188:191], v[52:55]
	v_mfma_f32_16x16x32_bf16 v[48:51], v[180:183], v[188:191], v[48:51]
	v_mfma_f32_16x16x32_bf16 v[36:39], v[172:175], v[196:199], v[36:39]
	v_mfma_f32_16x16x32_bf16 v[32:35], v[180:183], v[196:199], v[32:35]
	v_mfma_f32_16x16x32_bf16 v[20:23], v[172:175], v[204:207], v[20:23]
	v_mfma_f32_16x16x32_bf16 v[16:19], v[180:183], v[204:207], v[16:19]
	v_mfma_f32_16x16x32_bf16 v[4:7], v[172:175], v[212:215], v[4:7]
	v_mfma_f32_16x16x32_bf16 v[0:3], v[180:183], v[212:215], v[0:3]
	s_setprio 0
	s_barrier
	s_add_i32 s3, 0, 0x18000
	s_add_i32 s45, 0, 0x1c000
	v_add_u32_e32 v164, s3, v151
	v_add_u32_e32 v180, s45, v151
	ds_read_b128 v[144:147], v164
	ds_read_b128 v[156:159], v164 offset:1024
	ds_read_b128 v[160:163], v164 offset:2048
	ds_read_b128 v[164:167], v164 offset:3072
	ds_read_b128 v[168:171], v180
	ds_read_b128 v[172:175], v180 offset:1024
	ds_read_b128 v[176:179], v180 offset:2048
	ds_read_b128 v[180:183], v180 offset:3072
	s_add_u32 s50, s58, 0x40000
	s_addc_u32 s51, s59, 0
	s_mov_b32 m0, s19
	ds_read_b128 v[184:187], v155 offset:32768
	ds_read_b128 v[188:191], v155 offset:33792
	ds_read_b128 v[192:195], v155 offset:34816
	ds_read_b128 v[196:199], v155 offset:35840
	ds_read_b128 v[200:203], v155 offset:36864
	ds_read_b128 v[204:207], v155 offset:37888
	ds_read_b128 v[208:211], v155 offset:38912
	ds_read_b128 v[212:215], v155 offset:39936
	global_load_lds_dwordx4 v128, s[50:51]
	s_mov_b32 m0, s25
	s_nop 0
	global_load_lds_dwordx4 v132, s[50:51]
	s_waitcnt vmcnt(8)
	s_waitcnt lgkmcnt(0)
	s_barrier
	s_setprio 1
	s_waitcnt lgkmcnt(0)
	v_mfma_f32_16x16x32_bf16 v[124:127], v[144:147], v[184:187], v[124:127]
	v_mfma_f32_16x16x32_bf16 v[120:123], v[160:163], v[184:187], v[120:123]
	v_mfma_f32_16x16x32_bf16 v[108:111], v[144:147], v[192:195], v[108:111]
	v_mfma_f32_16x16x32_bf16 v[104:107], v[160:163], v[192:195], v[104:107]
	v_mfma_f32_16x16x32_bf16 v[92:95], v[144:147], v[200:203], v[92:95]
	v_mfma_f32_16x16x32_bf16 v[88:91], v[160:163], v[200:203], v[88:91]
	v_mfma_f32_16x16x32_bf16 v[76:79], v[144:147], v[208:211], v[76:79]
	v_mfma_f32_16x16x32_bf16 v[72:75], v[160:163], v[208:211], v[72:75]
	v_mfma_f32_16x16x32_bf16 v[124:127], v[156:159], v[188:191], v[124:127]
	v_mfma_f32_16x16x32_bf16 v[120:123], v[164:167], v[188:191], v[120:123]
	v_mfma_f32_16x16x32_bf16 v[108:111], v[156:159], v[196:199], v[108:111]
	v_mfma_f32_16x16x32_bf16 v[104:107], v[164:167], v[196:199], v[104:107]
	v_mfma_f32_16x16x32_bf16 v[92:95], v[156:159], v[204:207], v[92:95]
	v_mfma_f32_16x16x32_bf16 v[88:91], v[164:167], v[204:207], v[88:91]
	v_mfma_f32_16x16x32_bf16 v[76:79], v[156:159], v[212:215], v[76:79]
	v_mfma_f32_16x16x32_bf16 v[72:75], v[164:167], v[212:215], v[72:75]
	s_setprio 0
	s_setprio 1
	v_mfma_f32_16x16x32_bf16 v[116:119], v[168:171], v[184:187], v[116:119]
	v_mfma_f32_16x16x32_bf16 v[112:115], v[176:179], v[184:187], v[112:115]
	v_mfma_f32_16x16x32_bf16 v[100:103], v[168:171], v[192:195], v[100:103]
	v_mfma_f32_16x16x32_bf16 v[96:99], v[176:179], v[192:195], v[96:99]
	v_mfma_f32_16x16x32_bf16 v[84:87], v[168:171], v[200:203], v[84:87]
	v_mfma_f32_16x16x32_bf16 v[80:83], v[176:179], v[200:203], v[80:83]
	v_mfma_f32_16x16x32_bf16 v[68:71], v[168:171], v[208:211], v[68:71]
	v_mfma_f32_16x16x32_bf16 v[64:67], v[176:179], v[208:211], v[64:67]
	v_mfma_f32_16x16x32_bf16 v[116:119], v[172:175], v[188:191], v[116:119]
	v_mfma_f32_16x16x32_bf16 v[112:115], v[180:183], v[188:191], v[112:115]
	v_mfma_f32_16x16x32_bf16 v[100:103], v[172:175], v[196:199], v[100:103]
	v_mfma_f32_16x16x32_bf16 v[96:99], v[180:183], v[196:199], v[96:99]
	v_mfma_f32_16x16x32_bf16 v[84:87], v[172:175], v[204:207], v[84:87]
	v_mfma_f32_16x16x32_bf16 v[80:83], v[180:183], v[204:207], v[80:83]
	v_mfma_f32_16x16x32_bf16 v[68:71], v[172:175], v[212:215], v[68:71]
	v_mfma_f32_16x16x32_bf16 v[64:67], v[180:183], v[212:215], v[64:67]
	s_setprio 0
	s_barrier
	s_add_i32 s3, s3, s8
	s_add_u32 s50, s56, 0x80
	s_addc_u32 s51, s57, 0
	s_mov_b32 m0, s3
	ds_read_b128 v[184:187], v155 offset:49152
	ds_read_b128 v[188:191], v155 offset:50176
	ds_read_b128 v[192:195], v155 offset:51200
	ds_read_b128 v[196:199], v155 offset:52224
	ds_read_b128 v[200:203], v155 offset:53248
	ds_read_b128 v[204:207], v155 offset:54272
	ds_read_b128 v[208:211], v155 offset:55296
	ds_read_b128 v[212:215], v155 offset:56320
	global_load_lds_dwordx4 v130, s[50:51]
	s_add_i32 m0, s3, 0x2000
	s_add_i32 s3, s45, s8
	global_load_lds_dwordx4 v134, s[50:51]
	s_add_u32 s50, s50, 0x40000
	s_addc_u32 s51, s51, 0
	s_mov_b32 m0, s3
	s_nop 0
	global_load_lds_dwordx4 v130, s[50:51]
	s_add_i32 m0, s3, 0x2000
	s_nop 0
	global_load_lds_dwordx4 v134, s[50:51]
	s_add_u32 s58, s58, 0x80
	s_addc_u32 s59, s59, 0
	s_mov_b32 m0, s60
	s_nop 0
	global_load_lds_dwordx4 v128, s[58:59]
	s_mov_b32 m0, s61
	s_nop 0
	global_load_lds_dwordx4 v132, s[58:59]
	s_waitcnt vmcnt(8)
	s_waitcnt lgkmcnt(0)
	s_barrier
	s_setprio 1
	s_waitcnt lgkmcnt(0)
	v_mfma_f32_16x16x32_bf16 v[60:63], v[144:147], v[184:187], v[60:63]
	v_mfma_f32_16x16x32_bf16 v[56:59], v[160:163], v[184:187], v[56:59]
	v_mfma_f32_16x16x32_bf16 v[44:47], v[144:147], v[192:195], v[44:47]
	v_mfma_f32_16x16x32_bf16 v[40:43], v[160:163], v[192:195], v[40:43]
	v_mfma_f32_16x16x32_bf16 v[28:31], v[144:147], v[200:203], v[28:31]
	v_mfma_f32_16x16x32_bf16 v[24:27], v[160:163], v[200:203], v[24:27]
	v_mfma_f32_16x16x32_bf16 v[12:15], v[144:147], v[208:211], v[12:15]
	v_mfma_f32_16x16x32_bf16 v[8:11], v[160:163], v[208:211], v[8:11]
	v_mfma_f32_16x16x32_bf16 v[60:63], v[156:159], v[188:191], v[60:63]
	v_mfma_f32_16x16x32_bf16 v[56:59], v[164:167], v[188:191], v[56:59]
	v_mfma_f32_16x16x32_bf16 v[44:47], v[156:159], v[196:199], v[44:47]
	v_mfma_f32_16x16x32_bf16 v[40:43], v[164:167], v[196:199], v[40:43]
	v_mfma_f32_16x16x32_bf16 v[28:31], v[156:159], v[204:207], v[28:31]
	v_mfma_f32_16x16x32_bf16 v[24:27], v[164:167], v[204:207], v[24:27]
	v_mfma_f32_16x16x32_bf16 v[12:15], v[156:159], v[212:215], v[12:15]
	v_mfma_f32_16x16x32_bf16 v[8:11], v[164:167], v[212:215], v[8:11]
	s_setprio 0
	s_setprio 1
	v_mfma_f32_16x16x32_bf16 v[52:55], v[168:171], v[184:187], v[52:55]
	v_mfma_f32_16x16x32_bf16 v[48:51], v[176:179], v[184:187], v[48:51]
	v_mfma_f32_16x16x32_bf16 v[36:39], v[168:171], v[192:195], v[36:39]
	v_mfma_f32_16x16x32_bf16 v[32:35], v[176:179], v[192:195], v[32:35]
	v_mfma_f32_16x16x32_bf16 v[20:23], v[168:171], v[200:203], v[20:23]
	v_mfma_f32_16x16x32_bf16 v[16:19], v[176:179], v[200:203], v[16:19]
	v_mfma_f32_16x16x32_bf16 v[4:7], v[168:171], v[208:211], v[4:7]
	v_mfma_f32_16x16x32_bf16 v[0:3], v[176:179], v[208:211], v[0:3]
	v_mfma_f32_16x16x32_bf16 v[52:55], v[172:175], v[188:191], v[52:55]
	v_mfma_f32_16x16x32_bf16 v[48:51], v[180:183], v[188:191], v[48:51]
	v_mfma_f32_16x16x32_bf16 v[36:39], v[172:175], v[196:199], v[36:39]
	v_mfma_f32_16x16x32_bf16 v[32:35], v[180:183], v[196:199], v[32:35]
	v_mfma_f32_16x16x32_bf16 v[20:23], v[172:175], v[204:207], v[20:23]
	v_mfma_f32_16x16x32_bf16 v[16:19], v[180:183], v[204:207], v[16:19]
	v_mfma_f32_16x16x32_bf16 v[4:7], v[172:175], v[212:215], v[4:7]
	v_mfma_f32_16x16x32_bf16 v[0:3], v[180:183], v[212:215], v[0:3]
	s_setprio 0
	s_barrier
	s_add_i32 s44, s44, 2
	s_add_u32 s52, s52, 0x100
	s_addc_u32 s53, s53, 0
	s_add_u32 s33, s33, 0x100
	s_addc_u32 s35, s35, 0
	s_cmp_gt_u32 s44, 13
	s_cbranch_scc0 .LBB0_2248
	s_and_b64 vcc, exec, s[12:13]
	s_cbranch_vccz .LBB0_2251
	s_barrier

.LBB0_2272:
	ds_read_b128 v[144:147], v155
	ds_read_b128 v[148:151], v155 offset:1024
	ds_read_b128 v[158:161], v155 offset:2048
	ds_read_b128 v[162:165], v155 offset:3072
	ds_read_b128 v[166:169], v156
	ds_read_b128 v[170:173], v156 offset:1024
	ds_read_b128 v[174:177], v156 offset:2048
	ds_read_b128 v[178:181], v156 offset:3072
	s_add_u32 s3, s52, 0xfffe0080
	s_addc_u32 s51, s53, -1
	s_cmp_eq_u32 s50, 4
	s_cselect_b32 s59, s0, s51
	s_cselect_b32 s58, s1, s3
	s_cselect_b32 s57, s17, s45
	s_cselect_b32 s56, s35, s44
	s_add_i32 m0, s9, 0xc000
	ds_read_b128 v[182:185], v157
	ds_read_b128 v[186:189], v157 offset:1024
	ds_read_b128 v[190:193], v157 offset:2048
	ds_read_b128 v[194:197], v157 offset:3072
	ds_read_b128 v[198:201], v157 offset:4096
	ds_read_b128 v[202:205], v157 offset:5120
	ds_read_b128 v[206:209], v157 offset:6144
	ds_read_b128 v[210:213], v157 offset:7168
	global_load_lds_dwordx4 v136, s[52:53]
	s_add_i32 m0, s9, 0xe000
	s_nop 0
	global_load_lds_dwordx4 v138, s[52:53]
	s_waitcnt vmcnt(8)
	s_waitcnt lgkmcnt(0)
	s_barrier
	s_setprio 1
	s_waitcnt lgkmcnt(0)
	v_mfma_f32_16x16x32_bf16 v[124:127], v[144:147], v[182:185], v[124:127]
	v_mfma_f32_16x16x32_bf16 v[120:123], v[158:161], v[182:185], v[120:123]
	v_mfma_f32_16x16x32_bf16 v[108:111], v[144:147], v[190:193], v[108:111]
	v_mfma_f32_16x16x32_bf16 v[104:107], v[158:161], v[190:193], v[104:107]
	v_mfma_f32_16x16x32_bf16 v[92:95], v[144:147], v[198:201], v[92:95]
	v_mfma_f32_16x16x32_bf16 v[88:91], v[158:161], v[198:201], v[88:91]
	v_mfma_f32_16x16x32_bf16 v[76:79], v[144:147], v[206:209], v[76:79]
	v_mfma_f32_16x16x32_bf16 v[72:75], v[158:161], v[206:209], v[72:75]
	v_mfma_f32_16x16x32_bf16 v[124:127], v[148:151], v[186:189], v[124:127]
	v_mfma_f32_16x16x32_bf16 v[120:123], v[162:165], v[186:189], v[120:123]
	v_mfma_f32_16x16x32_bf16 v[108:111], v[148:151], v[194:197], v[108:111]
	v_mfma_f32_16x16x32_bf16 v[104:107], v[162:165], v[194:197], v[104:107]
	v_mfma_f32_16x16x32_bf16 v[92:95], v[148:151], v[202:205], v[92:95]
	v_mfma_f32_16x16x32_bf16 v[88:91], v[162:165], v[202:205], v[88:91]
	v_mfma_f32_16x16x32_bf16 v[76:79], v[148:151], v[210:213], v[76:79]
	v_mfma_f32_16x16x32_bf16 v[72:75], v[162:165], v[210:213], v[72:75]
	s_setprio 0
	s_setprio 1
	v_mfma_f32_16x16x32_bf16 v[116:119], v[166:169], v[182:185], v[116:119]
	v_mfma_f32_16x16x32_bf16 v[112:115], v[174:177], v[182:185], v[112:115]
	v_mfma_f32_16x16x32_bf16 v[100:103], v[166:169], v[190:193], v[100:103]
	v_mfma_f32_16x16x32_bf16 v[96:99], v[174:177], v[190:193], v[96:99]
	v_mfma_f32_16x16x32_bf16 v[84:87], v[166:169], v[198:201], v[84:87]
	v_mfma_f32_16x16x32_bf16 v[80:83], v[174:177], v[198:201], v[80:83]
	v_mfma_f32_16x16x32_bf16 v[68:71], v[166:169], v[206:209], v[68:71]
	v_mfma_f32_16x16x32_bf16 v[64:67], v[174:177], v[206:209], v[64:67]
	v_mfma_f32_16x16x32_bf16 v[116:119], v[170:173], v[186:189], v[116:119]
	v_mfma_f32_16x16x32_bf16 v[112:115], v[178:181], v[186:189], v[112:115]
	v_mfma_f32_16x16x32_bf16 v[100:103], v[170:173], v[194:197], v[100:103]
	v_mfma_f32_16x16x32_bf16 v[96:99], v[178:181], v[194:197], v[96:99]
	v_mfma_f32_16x16x32_bf16 v[84:87], v[170:173], v[202:205], v[84:87]
	v_mfma_f32_16x16x32_bf16 v[80:83], v[178:181], v[202:205], v[80:83]
	v_mfma_f32_16x16x32_bf16 v[68:71], v[170:173], v[210:213], v[68:71]
	v_mfma_f32_16x16x32_bf16 v[64:67], v[178:181], v[210:213], v[64:67]
	s_setprio 0
	s_barrier
	s_add_i32 s3, s61, s8
	s_mov_b32 m0, s3
	ds_read_b128 v[182:185], v157 offset:16384
	ds_read_b128 v[186:189], v157 offset:17408
	ds_read_b128 v[190:193], v157 offset:18432
	ds_read_b128 v[194:197], v157 offset:19456
	ds_read_b128 v[198:201], v157 offset:20480
	ds_read_b128 v[202:205], v157 offset:21504
	ds_read_b128 v[206:209], v157 offset:22528
	ds_read_b128 v[210:213], v157 offset:23552
	global_load_lds_dwordx4 v130, s[56:57]
	s_add_i32 m0, s3, 0x2000
	s_add_u32 s64, s56, 0x20000
	s_addc_u32 s65, s57, 0
	s_add_i32 s3, s62, s8
	global_load_lds_dwordx4 v134, s[56:57]
	s_mov_b32 m0, s3
	s_nop 0
	global_load_lds_dwordx4 v130, s[64:65]
	s_add_i32 m0, s3, 0x2000
	s_nop 0
	global_load_lds_dwordx4 v134, s[64:65]
	s_mov_b32 m0, s9
	s_nop 0
	global_load_lds_dwordx4 v128, s[58:59]
	s_mov_b32 m0, s18
	s_nop 0
	global_load_lds_dwordx4 v132, s[58:59]
	s_waitcnt vmcnt(8)
	s_waitcnt lgkmcnt(0)
	s_barrier
	s_setprio 1
	s_waitcnt lgkmcnt(0)
	v_mfma_f32_16x16x32_bf16 v[60:63], v[144:147], v[182:185], v[60:63]
	v_mfma_f32_16x16x32_bf16 v[56:59], v[158:161], v[182:185], v[56:59]
	v_mfma_f32_16x16x32_bf16 v[44:47], v[144:147], v[190:193], v[44:47]
	v_mfma_f32_16x16x32_bf16 v[40:43], v[158:161], v[190:193], v[40:43]
	v_mfma_f32_16x16x32_bf16 v[28:31], v[144:147], v[198:201], v[28:31]
	v_mfma_f32_16x16x32_bf16 v[24:27], v[158:161], v[198:201], v[24:27]
	v_mfma_f32_16x16x32_bf16 v[12:15], v[144:147], v[206:209], v[12:15]
	v_mfma_f32_16x16x32_bf16 v[8:11], v[158:161], v[206:209], v[8:11]
	v_mfma_f32_16x16x32_bf16 v[60:63], v[148:151], v[186:189], v[60:63]
	v_mfma_f32_16x16x32_bf16 v[56:59], v[162:165], v[186:189], v[56:59]
	v_mfma_f32_16x16x32_bf16 v[44:47], v[148:151], v[194:197], v[44:47]
	v_mfma_f32_16x16x32_bf16 v[40:43], v[162:165], v[194:197], v[40:43]
	v_mfma_f32_16x16x32_bf16 v[28:31], v[148:151], v[202:205], v[28:31]
	v_mfma_f32_16x16x32_bf16 v[24:27], v[162:165], v[202:205], v[24:27]
	v_mfma_f32_16x16x32_bf16 v[12:15], v[148:151], v[210:213], v[12:15]
	v_mfma_f32_16x16x32_bf16 v[8:11], v[162:165], v[210:213], v[8:11]
	s_setprio 0
	s_setprio 1
	v_mfma_f32_16x16x32_bf16 v[52:55], v[166:169], v[182:185], v[52:55]
	v_mfma_f32_16x16x32_bf16 v[48:51], v[174:177], v[182:185], v[48:51]
	v_mfma_f32_16x16x32_bf16 v[36:39], v[166:169], v[190:193], v[36:39]
	v_mfma_f32_16x16x32_bf16 v[32:35], v[174:177], v[190:193], v[32:35]
	v_mfma_f32_16x16x32_bf16 v[20:23], v[166:169], v[198:201], v[20:23]
	v_mfma_f32_16x16x32_bf16 v[16:19], v[174:177], v[198:201], v[16:19]
	v_mfma_f32_16x16x32_bf16 v[4:7], v[166:169], v[206:209], v[4:7]
	v_mfma_f32_16x16x32_bf16 v[0:3], v[174:177], v[206:209], v[0:3]
	v_mfma_f32_16x16x32_bf16 v[52:55], v[170:173], v[186:189], v[52:55]
	v_mfma_f32_16x16x32_bf16 v[48:51], v[178:181], v[186:189], v[48:51]
	v_mfma_f32_16x16x32_bf16 v[36:39], v[170:173], v[194:197], v[36:39]
	v_mfma_f32_16x16x32_bf16 v[32:35], v[178:181], v[194:197], v[32:35]
	v_mfma_f32_16x16x32_bf16 v[20:23], v[170:173], v[202:205], v[20:23]
	v_mfma_f32_16x16x32_bf16 v[16:19], v[178:181], v[202:205], v[16:19]
	v_mfma_f32_16x16x32_bf16 v[4:7], v[170:173], v[210:213], v[4:7]
	v_mfma_f32_16x16x32_bf16 v[0:3], v[178:181], v[210:213], v[0:3]
	s_setprio 0
	s_barrier
	s_add_i32 s3, 0, 0x18000
	s_add_i32 s51, 0, 0x1c000
	v_add_u32_e32 v162, s3, v153
	v_add_u32_e32 v178, s51, v153
	ds_read_b128 v[144:147], v162
	ds_read_b128 v[148:151], v162 offset:1024
	ds_read_b128 v[158:161], v162 offset:2048
	ds_read_b128 v[162:165], v162 offset:3072
	ds_read_b128 v[166:169], v178
	ds_read_b128 v[170:173], v178 offset:1024
	ds_read_b128 v[174:177], v178 offset:2048
	ds_read_b128 v[178:181], v178 offset:3072
	s_add_u32 s58, s58, 0x20000
	s_addc_u32 s59, s59, 0
	s_mov_b32 m0, s19
	ds_read_b128 v[182:185], v157 offset:32768
	ds_read_b128 v[186:189], v157 offset:33792
	ds_read_b128 v[190:193], v157 offset:34816
	ds_read_b128 v[194:197], v157 offset:35840
	ds_read_b128 v[198:201], v157 offset:36864
	ds_read_b128 v[202:205], v157 offset:37888
	ds_read_b128 v[206:209], v157 offset:38912
	ds_read_b128 v[210:213], v157 offset:39936
	global_load_lds_dwordx4 v128, s[58:59]
	s_mov_b32 m0, s25
	s_nop 0
	global_load_lds_dwordx4 v132, s[58:59]
	s_waitcnt vmcnt(8)
	s_waitcnt lgkmcnt(0)
	s_barrier
	s_setprio 1
	s_waitcnt lgkmcnt(0)
	v_mfma_f32_16x16x32_bf16 v[124:127], v[144:147], v[182:185], v[124:127]
	v_mfma_f32_16x16x32_bf16 v[120:123], v[158:161], v[182:185], v[120:123]
	v_mfma_f32_16x16x32_bf16 v[108:111], v[144:147], v[190:193], v[108:111]
	v_mfma_f32_16x16x32_bf16 v[104:107], v[158:161], v[190:193], v[104:107]
	v_mfma_f32_16x16x32_bf16 v[92:95], v[144:147], v[198:201], v[92:95]
	v_mfma_f32_16x16x32_bf16 v[88:91], v[158:161], v[198:201], v[88:91]
	v_mfma_f32_16x16x32_bf16 v[76:79], v[144:147], v[206:209], v[76:79]
	v_mfma_f32_16x16x32_bf16 v[72:75], v[158:161], v[206:209], v[72:75]
	v_mfma_f32_16x16x32_bf16 v[124:127], v[148:151], v[186:189], v[124:127]
	v_mfma_f32_16x16x32_bf16 v[120:123], v[162:165], v[186:189], v[120:123]
	v_mfma_f32_16x16x32_bf16 v[108:111], v[148:151], v[194:197], v[108:111]
	v_mfma_f32_16x16x32_bf16 v[104:107], v[162:165], v[194:197], v[104:107]
	v_mfma_f32_16x16x32_bf16 v[92:95], v[148:151], v[202:205], v[92:95]
	v_mfma_f32_16x16x32_bf16 v[88:91], v[162:165], v[202:205], v[88:91]
	v_mfma_f32_16x16x32_bf16 v[76:79], v[148:151], v[210:213], v[76:79]
	v_mfma_f32_16x16x32_bf16 v[72:75], v[162:165], v[210:213], v[72:75]
	s_setprio 0
	s_setprio 1
	v_mfma_f32_16x16x32_bf16 v[116:119], v[166:169], v[182:185], v[116:119]
	v_mfma_f32_16x16x32_bf16 v[112:115], v[174:177], v[182:185], v[112:115]
	v_mfma_f32_16x16x32_bf16 v[100:103], v[166:169], v[190:193], v[100:103]
	v_mfma_f32_16x16x32_bf16 v[96:99], v[174:177], v[190:193], v[96:99]
	v_mfma_f32_16x16x32_bf16 v[84:87], v[166:169], v[198:201], v[84:87]
	v_mfma_f32_16x16x32_bf16 v[80:83], v[174:177], v[198:201], v[80:83]
	v_mfma_f32_16x16x32_bf16 v[68:71], v[166:169], v[206:209], v[68:71]
	v_mfma_f32_16x16x32_bf16 v[64:67], v[174:177], v[206:209], v[64:67]
	v_mfma_f32_16x16x32_bf16 v[116:119], v[170:173], v[186:189], v[116:119]
	v_mfma_f32_16x16x32_bf16 v[112:115], v[178:181], v[186:189], v[112:115]
	v_mfma_f32_16x16x32_bf16 v[100:103], v[170:173], v[194:197], v[100:103]
	v_mfma_f32_16x16x32_bf16 v[96:99], v[178:181], v[194:197], v[96:99]
	v_mfma_f32_16x16x32_bf16 v[84:87], v[170:173], v[202:205], v[84:87]
	v_mfma_f32_16x16x32_bf16 v[80:83], v[178:181], v[202:205], v[80:83]
	v_mfma_f32_16x16x32_bf16 v[68:71], v[170:173], v[210:213], v[68:71]
	v_mfma_f32_16x16x32_bf16 v[64:67], v[178:181], v[210:213], v[64:67]
	s_setprio 0
	s_barrier
	s_add_i32 s3, s3, s8
	s_add_u32 s56, s56, 0x80
	s_addc_u32 s57, s57, 0
	s_mov_b32 m0, s3
	ds_read_b128 v[182:185], v157 offset:49152
	ds_read_b128 v[186:189], v157 offset:50176
	ds_read_b128 v[190:193], v157 offset:51200
	ds_read_b128 v[194:197], v157 offset:52224
	ds_read_b128 v[198:201], v157 offset:53248
	ds_read_b128 v[202:205], v157 offset:54272
	ds_read_b128 v[206:209], v157 offset:55296
	ds_read_b128 v[210:213], v157 offset:56320
	global_load_lds_dwordx4 v130, s[56:57]
	s_add_i32 m0, s3, 0x2000
	s_add_i32 s3, s51, s8
	global_load_lds_dwordx4 v134, s[56:57]
	s_add_u32 s56, s56, 0x20000
	s_addc_u32 s57, s57, 0
	s_mov_b32 m0, s3
	s_nop 0
	global_load_lds_dwordx4 v130, s[56:57]
	s_add_i32 m0, s3, 0x2000
	s_nop 0
	global_load_lds_dwordx4 v134, s[56:57]
	s_add_u32 s58, s58, 0xfffe0080
	s_addc_u32 s59, s59, -1
	s_mov_b32 m0, s49
	s_nop 0
	global_load_lds_dwordx4 v128, s[58:59]
	s_mov_b32 m0, s60
	s_nop 0
	global_load_lds_dwordx4 v132, s[58:59]
	s_waitcnt vmcnt(8)
	s_waitcnt lgkmcnt(0)
	s_barrier
	s_setprio 1
	s_waitcnt lgkmcnt(0)
	v_mfma_f32_16x16x32_bf16 v[60:63], v[144:147], v[182:185], v[60:63]
	v_mfma_f32_16x16x32_bf16 v[56:59], v[158:161], v[182:185], v[56:59]
	v_mfma_f32_16x16x32_bf16 v[44:47], v[144:147], v[190:193], v[44:47]
	v_mfma_f32_16x16x32_bf16 v[40:43], v[158:161], v[190:193], v[40:43]
	v_mfma_f32_16x16x32_bf16 v[28:31], v[144:147], v[198:201], v[28:31]
	v_mfma_f32_16x16x32_bf16 v[24:27], v[158:161], v[198:201], v[24:27]
	v_mfma_f32_16x16x32_bf16 v[12:15], v[144:147], v[206:209], v[12:15]
	v_mfma_f32_16x16x32_bf16 v[8:11], v[158:161], v[206:209], v[8:11]
	v_mfma_f32_16x16x32_bf16 v[60:63], v[148:151], v[186:189], v[60:63]
	v_mfma_f32_16x16x32_bf16 v[56:59], v[162:165], v[186:189], v[56:59]
	v_mfma_f32_16x16x32_bf16 v[44:47], v[148:151], v[194:197], v[44:47]
	v_mfma_f32_16x16x32_bf16 v[40:43], v[162:165], v[194:197], v[40:43]
	v_mfma_f32_16x16x32_bf16 v[28:31], v[148:151], v[202:205], v[28:31]
	v_mfma_f32_16x16x32_bf16 v[24:27], v[162:165], v[202:205], v[24:27]
	v_mfma_f32_16x16x32_bf16 v[12:15], v[148:151], v[210:213], v[12:15]
	v_mfma_f32_16x16x32_bf16 v[8:11], v[162:165], v[210:213], v[8:11]
	s_setprio 0
	s_setprio 1
	v_mfma_f32_16x16x32_bf16 v[52:55], v[166:169], v[182:185], v[52:55]
	v_mfma_f32_16x16x32_bf16 v[48:51], v[174:177], v[182:185], v[48:51]
	v_mfma_f32_16x16x32_bf16 v[36:39], v[166:169], v[190:193], v[36:39]
	v_mfma_f32_16x16x32_bf16 v[32:35], v[174:177], v[190:193], v[32:35]
	v_mfma_f32_16x16x32_bf16 v[20:23], v[166:169], v[198:201], v[20:23]
	v_mfma_f32_16x16x32_bf16 v[16:19], v[174:177], v[198:201], v[16:19]
	v_mfma_f32_16x16x32_bf16 v[4:7], v[166:169], v[206:209], v[4:7]
	v_mfma_f32_16x16x32_bf16 v[0:3], v[174:177], v[206:209], v[0:3]
	v_mfma_f32_16x16x32_bf16 v[52:55], v[170:173], v[186:189], v[52:55]
	v_mfma_f32_16x16x32_bf16 v[48:51], v[178:181], v[186:189], v[48:51]
	v_mfma_f32_16x16x32_bf16 v[36:39], v[170:173], v[194:197], v[36:39]
	v_mfma_f32_16x16x32_bf16 v[32:35], v[178:181], v[194:197], v[32:35]
	v_mfma_f32_16x16x32_bf16 v[20:23], v[170:173], v[202:205], v[20:23]
	v_mfma_f32_16x16x32_bf16 v[16:19], v[178:181], v[202:205], v[16:19]
	v_mfma_f32_16x16x32_bf16 v[4:7], v[170:173], v[210:213], v[4:7]
	v_mfma_f32_16x16x32_bf16 v[0:3], v[178:181], v[210:213], v[0:3]
	s_setprio 0
	s_barrier
	s_add_i32 s50, s50, 2
	s_add_u32 s52, s52, 0x100
	s_addc_u32 s53, s53, 0
	s_add_u32 s44, s44, 0x100
	s_addc_u32 s45, s45, 0
	s_cmp_gt_u32 s50, 5
	s_cbranch_scc0 .LBB0_2272
	s_and_b64 vcc, exec, s[12:13]
	s_cbranch_vccz .LBB0_2275
	s_barrier

.LBB0_2348:
	ds_read_b128 v[140:143], v149
	ds_read_b128 v[152:155], v149 offset:1024
	ds_read_b128 v[156:159], v149 offset:2048
	ds_read_b128 v[160:163], v149 offset:3072
	ds_read_b128 v[164:167], v150
	ds_read_b128 v[168:171], v150 offset:1024
	ds_read_b128 v[172:175], v150 offset:2048
	ds_read_b128 v[176:179], v150 offset:3072
	s_add_u32 s3, s66, 0xfff80080
	s_addc_u32 s59, s67, -1
	s_cmp_eq_u32 s57, 28
	s_cselect_b32 s75, s0, s59
	s_cselect_b32 s74, s1, s3
	s_cselect_b32 s73, s44, s51
	s_cselect_b32 s72, s45, s50
	s_add_i32 m0, s9, 0xc000
	ds_read_b128 v[180:183], v151
	ds_read_b128 v[184:187], v151 offset:1024
	ds_read_b128 v[188:191], v151 offset:2048
	ds_read_b128 v[192:195], v151 offset:3072
	ds_read_b128 v[196:199], v151 offset:4096
	ds_read_b128 v[200:203], v151 offset:5120
	ds_read_b128 v[204:207], v151 offset:6144
	ds_read_b128 v[208:211], v151 offset:7168
	global_load_lds_dwordx4 v132, s[66:67]
	s_add_i32 m0, s9, 0xe000
	s_nop 0
	global_load_lds_dwordx4 v134, s[66:67]
	s_waitcnt vmcnt(8)
	s_waitcnt lgkmcnt(0)
	s_barrier
	s_setprio 1
	s_waitcnt lgkmcnt(0)
	v_mfma_f32_16x16x32_bf16 v[124:127], v[140:143], v[180:183], v[124:127]
	v_mfma_f32_16x16x32_bf16 v[120:123], v[156:159], v[180:183], v[120:123]
	v_mfma_f32_16x16x32_bf16 v[108:111], v[140:143], v[188:191], v[108:111]
	v_mfma_f32_16x16x32_bf16 v[104:107], v[156:159], v[188:191], v[104:107]
	v_mfma_f32_16x16x32_bf16 v[92:95], v[140:143], v[196:199], v[92:95]
	v_mfma_f32_16x16x32_bf16 v[88:91], v[156:159], v[196:199], v[88:91]
	v_mfma_f32_16x16x32_bf16 v[76:79], v[140:143], v[204:207], v[76:79]
	v_mfma_f32_16x16x32_bf16 v[72:75], v[156:159], v[204:207], v[72:75]
	v_mfma_f32_16x16x32_bf16 v[124:127], v[152:155], v[184:187], v[124:127]
	v_mfma_f32_16x16x32_bf16 v[120:123], v[160:163], v[184:187], v[120:123]
	v_mfma_f32_16x16x32_bf16 v[108:111], v[152:155], v[192:195], v[108:111]
	v_mfma_f32_16x16x32_bf16 v[104:107], v[160:163], v[192:195], v[104:107]
	v_mfma_f32_16x16x32_bf16 v[92:95], v[152:155], v[200:203], v[92:95]
	v_mfma_f32_16x16x32_bf16 v[88:91], v[160:163], v[200:203], v[88:91]
	v_mfma_f32_16x16x32_bf16 v[76:79], v[152:155], v[208:211], v[76:79]
	v_mfma_f32_16x16x32_bf16 v[72:75], v[160:163], v[208:211], v[72:75]
	s_setprio 0
	s_setprio 1
	v_mfma_f32_16x16x32_bf16 v[116:119], v[164:167], v[180:183], v[116:119]
	v_mfma_f32_16x16x32_bf16 v[112:115], v[172:175], v[180:183], v[112:115]
	v_mfma_f32_16x16x32_bf16 v[100:103], v[164:167], v[188:191], v[100:103]
	v_mfma_f32_16x16x32_bf16 v[96:99], v[172:175], v[188:191], v[96:99]
	v_mfma_f32_16x16x32_bf16 v[84:87], v[164:167], v[196:199], v[84:87]
	v_mfma_f32_16x16x32_bf16 v[80:83], v[172:175], v[196:199], v[80:83]
	v_mfma_f32_16x16x32_bf16 v[68:71], v[164:167], v[204:207], v[68:71]
	v_mfma_f32_16x16x32_bf16 v[64:67], v[172:175], v[204:207], v[64:67]
	v_mfma_f32_16x16x32_bf16 v[116:119], v[168:171], v[184:187], v[116:119]
	v_mfma_f32_16x16x32_bf16 v[112:115], v[176:179], v[184:187], v[112:115]
	v_mfma_f32_16x16x32_bf16 v[100:103], v[168:171], v[192:195], v[100:103]
	v_mfma_f32_16x16x32_bf16 v[96:99], v[176:179], v[192:195], v[96:99]
	v_mfma_f32_16x16x32_bf16 v[84:87], v[168:171], v[200:203], v[84:87]
	v_mfma_f32_16x16x32_bf16 v[80:83], v[176:179], v[200:203], v[80:83]
	v_mfma_f32_16x16x32_bf16 v[68:71], v[168:171], v[208:211], v[68:71]
	v_mfma_f32_16x16x32_bf16 v[64:67], v[176:179], v[208:211], v[64:67]
	s_setprio 0
	s_barrier
	s_add_i32 s3, s68, s8
	s_mov_b32 m0, s3
	ds_read_b128 v[180:183], v151 offset:16384
	ds_read_b128 v[184:187], v151 offset:17408
	ds_read_b128 v[188:191], v151 offset:18432
	ds_read_b128 v[192:195], v151 offset:19456
	ds_read_b128 v[196:199], v151 offset:20480
	ds_read_b128 v[200:203], v151 offset:21504
	ds_read_b128 v[204:207], v151 offset:22528
	ds_read_b128 v[208:211], v151 offset:23552
	global_load_lds_dwordx4 v128, s[72:73]
	s_add_i32 m0, s3, 0x2000
	s_add_u32 s70, s72, 0x80000
	s_addc_u32 s71, s73, 0
	s_add_i32 s3, s69, s8
	global_load_lds_dwordx4 v130, s[72:73]
	s_mov_b32 m0, s3
	s_nop 0
	global_load_lds_dwordx4 v128, s[70:71]
	s_add_i32 m0, s3, 0x2000
	s_nop 0
	global_load_lds_dwordx4 v130, s[70:71]
	s_mov_b32 m0, s9
	s_nop 0
	global_load_lds_dwordx4 v128, s[74:75]
	s_mov_b32 m0, s18
	s_nop 0
	global_load_lds_dwordx4 v130, s[74:75]
	s_waitcnt vmcnt(8)
	s_waitcnt lgkmcnt(0)
	s_barrier
	s_setprio 1
	s_waitcnt lgkmcnt(0)
	v_mfma_f32_16x16x32_bf16 v[60:63], v[140:143], v[180:183], v[60:63]
	v_mfma_f32_16x16x32_bf16 v[56:59], v[156:159], v[180:183], v[56:59]
	v_mfma_f32_16x16x32_bf16 v[44:47], v[140:143], v[188:191], v[44:47]
	v_mfma_f32_16x16x32_bf16 v[40:43], v[156:159], v[188:191], v[40:43]
	v_mfma_f32_16x16x32_bf16 v[28:31], v[140:143], v[196:199], v[28:31]
	v_mfma_f32_16x16x32_bf16 v[24:27], v[156:159], v[196:199], v[24:27]
	v_mfma_f32_16x16x32_bf16 v[12:15], v[140:143], v[204:207], v[12:15]
	v_mfma_f32_16x16x32_bf16 v[8:11], v[156:159], v[204:207], v[8:11]
	v_mfma_f32_16x16x32_bf16 v[60:63], v[152:155], v[184:187], v[60:63]
	v_mfma_f32_16x16x32_bf16 v[56:59], v[160:163], v[184:187], v[56:59]
	v_mfma_f32_16x16x32_bf16 v[44:47], v[152:155], v[192:195], v[44:47]
	v_mfma_f32_16x16x32_bf16 v[40:43], v[160:163], v[192:195], v[40:43]
	v_mfma_f32_16x16x32_bf16 v[28:31], v[152:155], v[200:203], v[28:31]
	v_mfma_f32_16x16x32_bf16 v[24:27], v[160:163], v[200:203], v[24:27]
	v_mfma_f32_16x16x32_bf16 v[12:15], v[152:155], v[208:211], v[12:15]
	v_mfma_f32_16x16x32_bf16 v[8:11], v[160:163], v[208:211], v[8:11]
	s_setprio 0
	s_setprio 1
	v_mfma_f32_16x16x32_bf16 v[52:55], v[164:167], v[180:183], v[52:55]
	v_mfma_f32_16x16x32_bf16 v[48:51], v[172:175], v[180:183], v[48:51]
	v_mfma_f32_16x16x32_bf16 v[36:39], v[164:167], v[188:191], v[36:39]
	v_mfma_f32_16x16x32_bf16 v[32:35], v[172:175], v[188:191], v[32:35]
	v_mfma_f32_16x16x32_bf16 v[20:23], v[164:167], v[196:199], v[20:23]
	v_mfma_f32_16x16x32_bf16 v[16:19], v[172:175], v[196:199], v[16:19]
	v_mfma_f32_16x16x32_bf16 v[4:7], v[164:167], v[204:207], v[4:7]
	v_mfma_f32_16x16x32_bf16 v[0:3], v[172:175], v[204:207], v[0:3]
	v_mfma_f32_16x16x32_bf16 v[52:55], v[168:171], v[184:187], v[52:55]
	v_mfma_f32_16x16x32_bf16 v[48:51], v[176:179], v[184:187], v[48:51]
	v_mfma_f32_16x16x32_bf16 v[36:39], v[168:171], v[192:195], v[36:39]
	v_mfma_f32_16x16x32_bf16 v[32:35], v[176:179], v[192:195], v[32:35]
	v_mfma_f32_16x16x32_bf16 v[20:23], v[168:171], v[200:203], v[20:23]
	v_mfma_f32_16x16x32_bf16 v[16:19], v[176:179], v[200:203], v[16:19]
	v_mfma_f32_16x16x32_bf16 v[4:7], v[168:171], v[208:211], v[4:7]
	v_mfma_f32_16x16x32_bf16 v[0:3], v[176:179], v[208:211], v[0:3]
	s_setprio 0
	s_barrier
	s_add_i32 s3, 0, 0x18000
	s_add_i32 s59, 0, 0x1c000
	v_add_u32_e32 v160, s3, v147
	v_add_u32_e32 v176, s59, v147
	ds_read_b128 v[140:143], v160
	ds_read_b128 v[152:155], v160 offset:1024
	ds_read_b128 v[156:159], v160 offset:2048
	ds_read_b128 v[160:163], v160 offset:3072
	ds_read_b128 v[164:167], v176
	ds_read_b128 v[168:171], v176 offset:1024
	ds_read_b128 v[172:175], v176 offset:2048
	ds_read_b128 v[176:179], v176 offset:3072
	s_add_u32 s70, s74, 0x80000
	s_addc_u32 s71, s75, 0
	s_mov_b32 m0, s19
	ds_read_b128 v[180:183], v151 offset:32768
	ds_read_b128 v[184:187], v151 offset:33792
	ds_read_b128 v[188:191], v151 offset:34816
	ds_read_b128 v[192:195], v151 offset:35840
	ds_read_b128 v[196:199], v151 offset:36864
	ds_read_b128 v[200:203], v151 offset:37888
	ds_read_b128 v[204:207], v151 offset:38912
	ds_read_b128 v[208:211], v151 offset:39936
	global_load_lds_dwordx4 v128, s[70:71]
	s_mov_b32 m0, s25
	s_nop 0
	global_load_lds_dwordx4 v130, s[70:71]
	s_waitcnt vmcnt(8)
	s_waitcnt lgkmcnt(0)
	s_barrier
	s_setprio 1
	s_waitcnt lgkmcnt(0)
	v_mfma_f32_16x16x32_bf16 v[124:127], v[140:143], v[180:183], v[124:127]
	v_mfma_f32_16x16x32_bf16 v[120:123], v[156:159], v[180:183], v[120:123]
	v_mfma_f32_16x16x32_bf16 v[108:111], v[140:143], v[188:191], v[108:111]
	v_mfma_f32_16x16x32_bf16 v[104:107], v[156:159], v[188:191], v[104:107]
	v_mfma_f32_16x16x32_bf16 v[92:95], v[140:143], v[196:199], v[92:95]
	v_mfma_f32_16x16x32_bf16 v[88:91], v[156:159], v[196:199], v[88:91]
	v_mfma_f32_16x16x32_bf16 v[76:79], v[140:143], v[204:207], v[76:79]
	v_mfma_f32_16x16x32_bf16 v[72:75], v[156:159], v[204:207], v[72:75]
	v_mfma_f32_16x16x32_bf16 v[124:127], v[152:155], v[184:187], v[124:127]
	v_mfma_f32_16x16x32_bf16 v[120:123], v[160:163], v[184:187], v[120:123]
	v_mfma_f32_16x16x32_bf16 v[108:111], v[152:155], v[192:195], v[108:111]
	v_mfma_f32_16x16x32_bf16 v[104:107], v[160:163], v[192:195], v[104:107]
	v_mfma_f32_16x16x32_bf16 v[92:95], v[152:155], v[200:203], v[92:95]
	v_mfma_f32_16x16x32_bf16 v[88:91], v[160:163], v[200:203], v[88:91]
	v_mfma_f32_16x16x32_bf16 v[76:79], v[152:155], v[208:211], v[76:79]
	v_mfma_f32_16x16x32_bf16 v[72:75], v[160:163], v[208:211], v[72:75]
	s_setprio 0
	s_setprio 1
	v_mfma_f32_16x16x32_bf16 v[116:119], v[164:167], v[180:183], v[116:119]
	v_mfma_f32_16x16x32_bf16 v[112:115], v[172:175], v[180:183], v[112:115]
	v_mfma_f32_16x16x32_bf16 v[100:103], v[164:167], v[188:191], v[100:103]
	v_mfma_f32_16x16x32_bf16 v[96:99], v[172:175], v[188:191], v[96:99]
	v_mfma_f32_16x16x32_bf16 v[84:87], v[164:167], v[196:199], v[84:87]
	v_mfma_f32_16x16x32_bf16 v[80:83], v[172:175], v[196:199], v[80:83]
	v_mfma_f32_16x16x32_bf16 v[68:71], v[164:167], v[204:207], v[68:71]
	v_mfma_f32_16x16x32_bf16 v[64:67], v[172:175], v[204:207], v[64:67]
	v_mfma_f32_16x16x32_bf16 v[116:119], v[168:171], v[184:187], v[116:119]
	v_mfma_f32_16x16x32_bf16 v[112:115], v[176:179], v[184:187], v[112:115]
	v_mfma_f32_16x16x32_bf16 v[100:103], v[168:171], v[192:195], v[100:103]
	v_mfma_f32_16x16x32_bf16 v[96:99], v[176:179], v[192:195], v[96:99]
	v_mfma_f32_16x16x32_bf16 v[84:87], v[168:171], v[200:203], v[84:87]
	v_mfma_f32_16x16x32_bf16 v[80:83], v[176:179], v[200:203], v[80:83]
	v_mfma_f32_16x16x32_bf16 v[68:71], v[168:171], v[208:211], v[68:71]
	v_mfma_f32_16x16x32_bf16 v[64:67], v[176:179], v[208:211], v[64:67]
	s_setprio 0
	s_barrier
	s_add_i32 s3, s3, s8
	s_add_u32 s70, s72, 0x80
	s_addc_u32 s71, s73, 0
	s_mov_b32 m0, s3
	ds_read_b128 v[180:183], v151 offset:49152
	ds_read_b128 v[184:187], v151 offset:50176
	ds_read_b128 v[188:191], v151 offset:51200
	ds_read_b128 v[192:195], v151 offset:52224
	ds_read_b128 v[196:199], v151 offset:53248
	ds_read_b128 v[200:203], v151 offset:54272
	ds_read_b128 v[204:207], v151 offset:55296
	ds_read_b128 v[208:211], v151 offset:56320
	global_load_lds_dwordx4 v128, s[70:71]
	s_add_i32 m0, s3, 0x2000
	s_add_i32 s3, s59, s8
	global_load_lds_dwordx4 v130, s[70:71]
	s_add_u32 s70, s70, 0x80000
	s_addc_u32 s71, s71, 0
	s_mov_b32 m0, s3
	s_nop 0
	global_load_lds_dwordx4 v128, s[70:71]
	s_add_i32 m0, s3, 0x2000
	s_nop 0
	global_load_lds_dwordx4 v130, s[70:71]
	s_add_u32 s74, s74, 0x80
	s_addc_u32 s75, s75, 0
	s_mov_b32 m0, s33
	s_nop 0
	global_load_lds_dwordx4 v128, s[74:75]
	s_mov_b32 m0, s65
	s_nop 0
	global_load_lds_dwordx4 v130, s[74:75]
	s_waitcnt vmcnt(8)
	s_waitcnt lgkmcnt(0)
	s_barrier
	s_setprio 1
	s_waitcnt lgkmcnt(0)
	v_mfma_f32_16x16x32_bf16 v[60:63], v[140:143], v[180:183], v[60:63]
	v_mfma_f32_16x16x32_bf16 v[56:59], v[156:159], v[180:183], v[56:59]
	v_mfma_f32_16x16x32_bf16 v[44:47], v[140:143], v[188:191], v[44:47]
	v_mfma_f32_16x16x32_bf16 v[40:43], v[156:159], v[188:191], v[40:43]
	v_mfma_f32_16x16x32_bf16 v[28:31], v[140:143], v[196:199], v[28:31]
	v_mfma_f32_16x16x32_bf16 v[24:27], v[156:159], v[196:199], v[24:27]
	v_mfma_f32_16x16x32_bf16 v[12:15], v[140:143], v[204:207], v[12:15]
	v_mfma_f32_16x16x32_bf16 v[8:11], v[156:159], v[204:207], v[8:11]
	v_mfma_f32_16x16x32_bf16 v[60:63], v[152:155], v[184:187], v[60:63]
	v_mfma_f32_16x16x32_bf16 v[56:59], v[160:163], v[184:187], v[56:59]
	v_mfma_f32_16x16x32_bf16 v[44:47], v[152:155], v[192:195], v[44:47]
	v_mfma_f32_16x16x32_bf16 v[40:43], v[160:163], v[192:195], v[40:43]
	v_mfma_f32_16x16x32_bf16 v[28:31], v[152:155], v[200:203], v[28:31]
	v_mfma_f32_16x16x32_bf16 v[24:27], v[160:163], v[200:203], v[24:27]
	v_mfma_f32_16x16x32_bf16 v[12:15], v[152:155], v[208:211], v[12:15]
	v_mfma_f32_16x16x32_bf16 v[8:11], v[160:163], v[208:211], v[8:11]
	s_setprio 0
	s_setprio 1
	v_mfma_f32_16x16x32_bf16 v[52:55], v[164:167], v[180:183], v[52:55]
	v_mfma_f32_16x16x32_bf16 v[48:51], v[172:175], v[180:183], v[48:51]
	v_mfma_f32_16x16x32_bf16 v[36:39], v[164:167], v[188:191], v[36:39]
	v_mfma_f32_16x16x32_bf16 v[32:35], v[172:175], v[188:191], v[32:35]
	v_mfma_f32_16x16x32_bf16 v[20:23], v[164:167], v[196:199], v[20:23]
	v_mfma_f32_16x16x32_bf16 v[16:19], v[172:175], v[196:199], v[16:19]
	v_mfma_f32_16x16x32_bf16 v[4:7], v[164:167], v[204:207], v[4:7]
	v_mfma_f32_16x16x32_bf16 v[0:3], v[172:175], v[204:207], v[0:3]
	v_mfma_f32_16x16x32_bf16 v[52:55], v[168:171], v[184:187], v[52:55]
	v_mfma_f32_16x16x32_bf16 v[48:51], v[176:179], v[184:187], v[48:51]
	v_mfma_f32_16x16x32_bf16 v[36:39], v[168:171], v[192:195], v[36:39]
	v_mfma_f32_16x16x32_bf16 v[32:35], v[176:179], v[192:195], v[32:35]
	v_mfma_f32_16x16x32_bf16 v[20:23], v[168:171], v[200:203], v[20:23]
	v_mfma_f32_16x16x32_bf16 v[16:19], v[176:179], v[200:203], v[16:19]
	v_mfma_f32_16x16x32_bf16 v[4:7], v[168:171], v[208:211], v[4:7]
	v_mfma_f32_16x16x32_bf16 v[0:3], v[176:179], v[208:211], v[0:3]
	s_setprio 0
	s_barrier
	s_add_i32 s57, s57, 2
	s_add_u32 s66, s66, 0x100
	s_addc_u32 s67, s67, 0
	s_add_u32 s50, s50, 0x100
	s_addc_u32 s51, s51, 0
	s_cmp_gt_u32 s57, 29
	s_cbranch_scc0 .LBB0_2348
	s_and_b64 vcc, exec, s[14:15]
	s_cbranch_vccz .LBB0_2351
	s_barrier

.LBB0_2479:
	ds_read_b128 v[154:157], v150
	ds_read_b128 v[158:161], v150 offset:1024
	ds_read_b128 v[162:165], v150 offset:2048
	ds_read_b128 v[166:169], v150 offset:3072
	ds_read_b128 v[170:173], v151
	ds_read_b128 v[174:177], v151 offset:1024
	ds_read_b128 v[178:181], v151 offset:2048
	ds_read_b128 v[182:185], v151 offset:3072
	s_add_u32 s3, s42, 0xfff80080
	s_addc_u32 s44, s43, -1
	s_cmp_eq_u32 s51, 28
	s_cselect_b32 s49, s0, s44
	s_cselect_b32 s48, s1, s3
	s_cselect_b32 s45, s15, s50
	s_cselect_b32 s44, s17, s41
	s_add_i32 m0, s19, 0xc000
	ds_read_b128 v[186:189], v152
	ds_read_b128 v[190:193], v152 offset:1024
	ds_read_b128 v[194:197], v152 offset:2048
	ds_read_b128 v[198:201], v152 offset:3072
	ds_read_b128 v[202:205], v152 offset:4096
	ds_read_b128 v[206:209], v152 offset:5120
	ds_read_b128 v[210:213], v152 offset:6144
	ds_read_b128 v[214:217], v152 offset:7168
	global_load_lds_dwordx4 v138, s[42:43]
	s_add_i32 m0, s19, 0xe000
	s_nop 0
	global_load_lds_dwordx4 v140, s[42:43]
	s_waitcnt vmcnt(8)
	s_waitcnt lgkmcnt(0)
	s_barrier
	s_setprio 1
	s_waitcnt lgkmcnt(0)
	v_mfma_f32_16x16x32_bf16 v[124:127], v[154:157], v[186:189], v[124:127]
	v_mfma_f32_16x16x32_bf16 v[120:123], v[162:165], v[186:189], v[120:123]
	v_mfma_f32_16x16x32_bf16 v[108:111], v[154:157], v[194:197], v[108:111]
	v_mfma_f32_16x16x32_bf16 v[104:107], v[162:165], v[194:197], v[104:107]
	v_mfma_f32_16x16x32_bf16 v[92:95], v[154:157], v[202:205], v[92:95]
	v_mfma_f32_16x16x32_bf16 v[88:91], v[162:165], v[202:205], v[88:91]
	v_mfma_f32_16x16x32_bf16 v[76:79], v[154:157], v[210:213], v[76:79]
	v_mfma_f32_16x16x32_bf16 v[72:75], v[162:165], v[210:213], v[72:75]
	v_mfma_f32_16x16x32_bf16 v[124:127], v[158:161], v[190:193], v[124:127]
	v_mfma_f32_16x16x32_bf16 v[120:123], v[166:169], v[190:193], v[120:123]
	v_mfma_f32_16x16x32_bf16 v[108:111], v[158:161], v[198:201], v[108:111]
	v_mfma_f32_16x16x32_bf16 v[104:107], v[166:169], v[198:201], v[104:107]
	v_mfma_f32_16x16x32_bf16 v[92:95], v[158:161], v[206:209], v[92:95]
	v_mfma_f32_16x16x32_bf16 v[88:91], v[166:169], v[206:209], v[88:91]
	v_mfma_f32_16x16x32_bf16 v[76:79], v[158:161], v[214:217], v[76:79]
	v_mfma_f32_16x16x32_bf16 v[72:75], v[166:169], v[214:217], v[72:75]
	s_setprio 0
	s_setprio 1
	v_mfma_f32_16x16x32_bf16 v[116:119], v[170:173], v[186:189], v[116:119]
	v_mfma_f32_16x16x32_bf16 v[112:115], v[178:181], v[186:189], v[112:115]
	v_mfma_f32_16x16x32_bf16 v[100:103], v[170:173], v[194:197], v[100:103]
	v_mfma_f32_16x16x32_bf16 v[96:99], v[178:181], v[194:197], v[96:99]
	v_mfma_f32_16x16x32_bf16 v[84:87], v[170:173], v[202:205], v[84:87]
	v_mfma_f32_16x16x32_bf16 v[80:83], v[178:181], v[202:205], v[80:83]
	v_mfma_f32_16x16x32_bf16 v[68:71], v[170:173], v[210:213], v[68:71]
	v_mfma_f32_16x16x32_bf16 v[64:67], v[178:181], v[210:213], v[64:67]
	v_mfma_f32_16x16x32_bf16 v[116:119], v[174:177], v[190:193], v[116:119]
	v_mfma_f32_16x16x32_bf16 v[112:115], v[182:185], v[190:193], v[112:115]
	v_mfma_f32_16x16x32_bf16 v[100:103], v[174:177], v[198:201], v[100:103]
	v_mfma_f32_16x16x32_bf16 v[96:99], v[182:185], v[198:201], v[96:99]
	v_mfma_f32_16x16x32_bf16 v[84:87], v[174:177], v[206:209], v[84:87]
	v_mfma_f32_16x16x32_bf16 v[80:83], v[182:185], v[206:209], v[80:83]
	v_mfma_f32_16x16x32_bf16 v[68:71], v[174:177], v[214:217], v[68:71]
	v_mfma_f32_16x16x32_bf16 v[64:67], v[182:185], v[214:217], v[64:67]
	s_setprio 0
	s_barrier
	s_add_i32 s3, s54, s18
	s_mov_b32 m0, s3
	ds_read_b128 v[186:189], v152 offset:16384
	ds_read_b128 v[190:193], v152 offset:17408
	ds_read_b128 v[194:197], v152 offset:18432
	ds_read_b128 v[198:201], v152 offset:19456
	ds_read_b128 v[202:205], v152 offset:20480
	ds_read_b128 v[206:209], v152 offset:21504
	ds_read_b128 v[210:213], v152 offset:22528
	ds_read_b128 v[214:217], v152 offset:23552
	global_load_lds_dwordx4 v130, s[44:45]
	s_add_i32 m0, s3, 0x2000
	s_add_u32 s58, s44, 0x80000
	s_addc_u32 s59, s45, 0
	s_add_i32 s3, s55, s18
	global_load_lds_dwordx4 v134, s[44:45]
	s_mov_b32 m0, s3
	s_nop 0
	global_load_lds_dwordx4 v130, s[58:59]
	s_add_i32 m0, s3, 0x2000
	s_nop 0
	global_load_lds_dwordx4 v134, s[58:59]
	s_mov_b32 m0, s19
	s_nop 0
	global_load_lds_dwordx4 v128, s[48:49]
	s_mov_b32 m0, s25
	s_nop 0
	global_load_lds_dwordx4 v132, s[48:49]
	s_waitcnt vmcnt(8)
	s_waitcnt lgkmcnt(0)
	s_barrier
	s_setprio 1
	s_waitcnt lgkmcnt(0)
	v_mfma_f32_16x16x32_bf16 v[60:63], v[154:157], v[186:189], v[60:63]
	v_mfma_f32_16x16x32_bf16 v[56:59], v[162:165], v[186:189], v[56:59]
	v_mfma_f32_16x16x32_bf16 v[44:47], v[154:157], v[194:197], v[44:47]
	v_mfma_f32_16x16x32_bf16 v[40:43], v[162:165], v[194:197], v[40:43]
	v_mfma_f32_16x16x32_bf16 v[28:31], v[154:157], v[202:205], v[28:31]
	v_mfma_f32_16x16x32_bf16 v[24:27], v[162:165], v[202:205], v[24:27]
	v_mfma_f32_16x16x32_bf16 v[12:15], v[154:157], v[210:213], v[12:15]
	v_mfma_f32_16x16x32_bf16 v[8:11], v[162:165], v[210:213], v[8:11]
	v_mfma_f32_16x16x32_bf16 v[60:63], v[158:161], v[190:193], v[60:63]
	v_mfma_f32_16x16x32_bf16 v[56:59], v[166:169], v[190:193], v[56:59]
	v_mfma_f32_16x16x32_bf16 v[44:47], v[158:161], v[198:201], v[44:47]
	v_mfma_f32_16x16x32_bf16 v[40:43], v[166:169], v[198:201], v[40:43]
	v_mfma_f32_16x16x32_bf16 v[28:31], v[158:161], v[206:209], v[28:31]
	v_mfma_f32_16x16x32_bf16 v[24:27], v[166:169], v[206:209], v[24:27]
	v_mfma_f32_16x16x32_bf16 v[12:15], v[158:161], v[214:217], v[12:15]
	v_mfma_f32_16x16x32_bf16 v[8:11], v[166:169], v[214:217], v[8:11]
	s_setprio 0
	s_setprio 1
	v_mfma_f32_16x16x32_bf16 v[52:55], v[170:173], v[186:189], v[52:55]
	v_mfma_f32_16x16x32_bf16 v[48:51], v[178:181], v[186:189], v[48:51]
	v_mfma_f32_16x16x32_bf16 v[36:39], v[170:173], v[194:197], v[36:39]
	v_mfma_f32_16x16x32_bf16 v[32:35], v[178:181], v[194:197], v[32:35]
	v_mfma_f32_16x16x32_bf16 v[20:23], v[170:173], v[202:205], v[20:23]
	v_mfma_f32_16x16x32_bf16 v[16:19], v[178:181], v[202:205], v[16:19]
	v_mfma_f32_16x16x32_bf16 v[4:7], v[170:173], v[210:213], v[4:7]
	v_mfma_f32_16x16x32_bf16 v[0:3], v[178:181], v[210:213], v[0:3]
	v_mfma_f32_16x16x32_bf16 v[52:55], v[174:177], v[190:193], v[52:55]
	v_mfma_f32_16x16x32_bf16 v[48:51], v[182:185], v[190:193], v[48:51]
	v_mfma_f32_16x16x32_bf16 v[36:39], v[174:177], v[198:201], v[36:39]
	v_mfma_f32_16x16x32_bf16 v[32:35], v[182:185], v[198:201], v[32:35]
	v_mfma_f32_16x16x32_bf16 v[20:23], v[174:177], v[206:209], v[20:23]
	v_mfma_f32_16x16x32_bf16 v[16:19], v[182:185], v[206:209], v[16:19]
	v_mfma_f32_16x16x32_bf16 v[4:7], v[174:177], v[214:217], v[4:7]
	v_mfma_f32_16x16x32_bf16 v[0:3], v[182:185], v[214:217], v[0:3]
	s_setprio 0
	s_barrier
	s_add_i32 s3, 0, 0x18000
	v_add_u32_e32 v153, s3, v149
	s_add_i32 s57, 0, 0x1c000
	ds_read_b128 v[154:157], v153
	ds_read_b128 v[158:161], v153 offset:1024
	ds_read_b128 v[162:165], v153 offset:2048
	ds_read_b128 v[166:169], v153 offset:3072
	v_add_u32_e32 v153, s57, v149
	ds_read_b128 v[170:173], v153
	ds_read_b128 v[174:177], v153 offset:1024
	ds_read_b128 v[178:181], v153 offset:2048
	ds_read_b128 v[182:185], v153 offset:3072
	s_add_u32 s48, s48, 0x80000
	s_addc_u32 s49, s49, 0
	s_mov_b32 m0, s27
	ds_read_b128 v[186:189], v152 offset:32768
	ds_read_b128 v[190:193], v152 offset:33792
	ds_read_b128 v[194:197], v152 offset:34816
	ds_read_b128 v[198:201], v152 offset:35840
	ds_read_b128 v[202:205], v152 offset:36864
	ds_read_b128 v[206:209], v152 offset:37888
	ds_read_b128 v[210:213], v152 offset:38912
	ds_read_b128 v[214:217], v152 offset:39936
	global_load_lds_dwordx4 v128, s[48:49]
	s_mov_b32 m0, s33
	s_nop 0
	global_load_lds_dwordx4 v132, s[48:49]
	s_waitcnt vmcnt(8)
	s_waitcnt lgkmcnt(0)
	s_barrier
	s_setprio 1
	s_waitcnt lgkmcnt(0)
	v_mfma_f32_16x16x32_bf16 v[124:127], v[154:157], v[186:189], v[124:127]
	v_mfma_f32_16x16x32_bf16 v[120:123], v[162:165], v[186:189], v[120:123]
	v_mfma_f32_16x16x32_bf16 v[108:111], v[154:157], v[194:197], v[108:111]
	v_mfma_f32_16x16x32_bf16 v[104:107], v[162:165], v[194:197], v[104:107]
	v_mfma_f32_16x16x32_bf16 v[92:95], v[154:157], v[202:205], v[92:95]
	v_mfma_f32_16x16x32_bf16 v[88:91], v[162:165], v[202:205], v[88:91]
	v_mfma_f32_16x16x32_bf16 v[76:79], v[154:157], v[210:213], v[76:79]
	v_mfma_f32_16x16x32_bf16 v[72:75], v[162:165], v[210:213], v[72:75]
	v_mfma_f32_16x16x32_bf16 v[124:127], v[158:161], v[190:193], v[124:127]
	v_mfma_f32_16x16x32_bf16 v[120:123], v[166:169], v[190:193], v[120:123]
	v_mfma_f32_16x16x32_bf16 v[108:111], v[158:161], v[198:201], v[108:111]
	v_mfma_f32_16x16x32_bf16 v[104:107], v[166:169], v[198:201], v[104:107]
	v_mfma_f32_16x16x32_bf16 v[92:95], v[158:161], v[206:209], v[92:95]
	v_mfma_f32_16x16x32_bf16 v[88:91], v[166:169], v[206:209], v[88:91]
	v_mfma_f32_16x16x32_bf16 v[76:79], v[158:161], v[214:217], v[76:79]
	v_mfma_f32_16x16x32_bf16 v[72:75], v[166:169], v[214:217], v[72:75]
	s_setprio 0
	s_setprio 1
	v_mfma_f32_16x16x32_bf16 v[116:119], v[170:173], v[186:189], v[116:119]
	v_mfma_f32_16x16x32_bf16 v[112:115], v[178:181], v[186:189], v[112:115]
	v_mfma_f32_16x16x32_bf16 v[100:103], v[170:173], v[194:197], v[100:103]
	v_mfma_f32_16x16x32_bf16 v[96:99], v[178:181], v[194:197], v[96:99]
	v_mfma_f32_16x16x32_bf16 v[84:87], v[170:173], v[202:205], v[84:87]
	v_mfma_f32_16x16x32_bf16 v[80:83], v[178:181], v[202:205], v[80:83]
	v_mfma_f32_16x16x32_bf16 v[68:71], v[170:173], v[210:213], v[68:71]
	v_mfma_f32_16x16x32_bf16 v[64:67], v[178:181], v[210:213], v[64:67]
	v_mfma_f32_16x16x32_bf16 v[116:119], v[174:177], v[190:193], v[116:119]
	v_mfma_f32_16x16x32_bf16 v[112:115], v[182:185], v[190:193], v[112:115]
	v_mfma_f32_16x16x32_bf16 v[100:103], v[174:177], v[198:201], v[100:103]
	v_mfma_f32_16x16x32_bf16 v[96:99], v[182:185], v[198:201], v[96:99]
	v_mfma_f32_16x16x32_bf16 v[84:87], v[174:177], v[206:209], v[84:87]
	v_mfma_f32_16x16x32_bf16 v[80:83], v[182:185], v[206:209], v[80:83]
	v_mfma_f32_16x16x32_bf16 v[68:71], v[174:177], v[214:217], v[68:71]
	v_mfma_f32_16x16x32_bf16 v[64:67], v[182:185], v[214:217], v[64:67]
	s_setprio 0
	s_barrier
	s_add_i32 s3, s3, s18
	s_add_u32 s44, s44, 0x80
	s_addc_u32 s45, s45, 0
	s_mov_b32 m0, s3
	ds_read_b128 v[186:189], v152 offset:49152
	ds_read_b128 v[190:193], v152 offset:50176
	ds_read_b128 v[194:197], v152 offset:51200
	ds_read_b128 v[198:201], v152 offset:52224
	ds_read_b128 v[202:205], v152 offset:53248
	ds_read_b128 v[206:209], v152 offset:54272
	ds_read_b128 v[210:213], v152 offset:55296
	ds_read_b128 v[214:217], v152 offset:56320
	global_load_lds_dwordx4 v130, s[44:45]
	s_add_i32 m0, s3, 0x2000
	s_add_i32 s3, s57, s18
	global_load_lds_dwordx4 v134, s[44:45]
	s_add_u32 s44, s44, 0x80000
	s_addc_u32 s45, s45, 0
	s_mov_b32 m0, s3
	s_nop 0
	global_load_lds_dwordx4 v130, s[44:45]
	s_add_i32 m0, s3, 0x2000
	s_nop 0
	global_load_lds_dwordx4 v134, s[44:45]
	s_add_u32 s48, s48, 0xfff80080
	s_addc_u32 s49, s49, -1
	s_mov_b32 m0, s52
	s_nop 0
	global_load_lds_dwordx4 v128, s[48:49]
	s_mov_b32 m0, s53
	s_nop 0
	global_load_lds_dwordx4 v132, s[48:49]
	s_waitcnt vmcnt(8)
	s_waitcnt lgkmcnt(0)
	s_barrier
	s_setprio 1
	s_waitcnt lgkmcnt(0)
	v_mfma_f32_16x16x32_bf16 v[60:63], v[154:157], v[186:189], v[60:63]
	v_mfma_f32_16x16x32_bf16 v[56:59], v[162:165], v[186:189], v[56:59]
	v_mfma_f32_16x16x32_bf16 v[44:47], v[154:157], v[194:197], v[44:47]
	v_mfma_f32_16x16x32_bf16 v[40:43], v[162:165], v[194:197], v[40:43]
	v_mfma_f32_16x16x32_bf16 v[28:31], v[154:157], v[202:205], v[28:31]
	v_mfma_f32_16x16x32_bf16 v[24:27], v[162:165], v[202:205], v[24:27]
	v_mfma_f32_16x16x32_bf16 v[12:15], v[154:157], v[210:213], v[12:15]
	v_mfma_f32_16x16x32_bf16 v[8:11], v[162:165], v[210:213], v[8:11]
	v_mfma_f32_16x16x32_bf16 v[60:63], v[158:161], v[190:193], v[60:63]
	v_mfma_f32_16x16x32_bf16 v[56:59], v[166:169], v[190:193], v[56:59]
	v_mfma_f32_16x16x32_bf16 v[44:47], v[158:161], v[198:201], v[44:47]
	v_mfma_f32_16x16x32_bf16 v[40:43], v[166:169], v[198:201], v[40:43]
	v_mfma_f32_16x16x32_bf16 v[28:31], v[158:161], v[206:209], v[28:31]
	v_mfma_f32_16x16x32_bf16 v[24:27], v[166:169], v[206:209], v[24:27]
	v_mfma_f32_16x16x32_bf16 v[12:15], v[158:161], v[214:217], v[12:15]
	v_mfma_f32_16x16x32_bf16 v[8:11], v[166:169], v[214:217], v[8:11]
	s_setprio 0
	s_setprio 1
	v_mfma_f32_16x16x32_bf16 v[52:55], v[170:173], v[186:189], v[52:55]
	v_mfma_f32_16x16x32_bf16 v[48:51], v[178:181], v[186:189], v[48:51]
	v_mfma_f32_16x16x32_bf16 v[36:39], v[170:173], v[194:197], v[36:39]
	v_mfma_f32_16x16x32_bf16 v[32:35], v[178:181], v[194:197], v[32:35]
	v_mfma_f32_16x16x32_bf16 v[20:23], v[170:173], v[202:205], v[20:23]
	v_mfma_f32_16x16x32_bf16 v[16:19], v[178:181], v[202:205], v[16:19]
	v_mfma_f32_16x16x32_bf16 v[4:7], v[170:173], v[210:213], v[4:7]
	v_mfma_f32_16x16x32_bf16 v[0:3], v[178:181], v[210:213], v[0:3]
	v_mfma_f32_16x16x32_bf16 v[52:55], v[174:177], v[190:193], v[52:55]
	v_mfma_f32_16x16x32_bf16 v[48:51], v[182:185], v[190:193], v[48:51]
	v_mfma_f32_16x16x32_bf16 v[36:39], v[174:177], v[198:201], v[36:39]
	v_mfma_f32_16x16x32_bf16 v[32:35], v[182:185], v[198:201], v[32:35]
	v_mfma_f32_16x16x32_bf16 v[20:23], v[174:177], v[206:209], v[20:23]
	v_mfma_f32_16x16x32_bf16 v[16:19], v[182:185], v[206:209], v[16:19]
	v_mfma_f32_16x16x32_bf16 v[4:7], v[174:177], v[214:217], v[4:7]
	v_mfma_f32_16x16x32_bf16 v[0:3], v[182:185], v[214:217], v[0:3]
	s_setprio 0
	s_barrier
	s_add_i32 s51, s51, 2
	s_add_u32 s42, s42, 0x100
	s_addc_u32 s43, s43, 0
	s_add_u32 s41, s41, 0x100
	s_addc_u32 s50, s50, 0
	s_cmp_gt_u32 s51, 29
	s_cbranch_scc0 .LBB0_2479
	s_and_b64 vcc, exec, s[12:13]
	s_cbranch_vccz .LBB0_2482
	s_barrier

.LBB0_2555:
	ds_read_b128 v[140:143], v149
	ds_read_b128 v[152:155], v149 offset:1024
	ds_read_b128 v[156:159], v149 offset:2048
	ds_read_b128 v[160:163], v149 offset:3072
	ds_read_b128 v[164:167], v150
	ds_read_b128 v[168:171], v150 offset:1024
	ds_read_b128 v[172:175], v150 offset:2048
	ds_read_b128 v[176:179], v150 offset:3072
	s_add_u32 s3, s48, 0xffe00080
	s_addc_u32 s52, s49, -1
	s_cmpk_eq_i32 s64, 0x7c
	s_cselect_b32 s55, s0, s52
	s_cselect_b32 s54, s1, s3
	s_cselect_b32 s53, s35, s51
	s_cselect_b32 s52, s37, s50
	s_add_i32 m0, s27, 0xc000
	ds_read_b128 v[180:183], v151
	ds_read_b128 v[184:187], v151 offset:1024
	ds_read_b128 v[188:191], v151 offset:2048
	ds_read_b128 v[192:195], v151 offset:3072
	ds_read_b128 v[196:199], v151 offset:4096
	ds_read_b128 v[200:203], v151 offset:5120
	ds_read_b128 v[204:207], v151 offset:6144
	ds_read_b128 v[208:211], v151 offset:7168
	global_load_lds_dwordx4 v132, s[48:49]
	s_add_i32 m0, s27, 0xe000
	s_nop 0
	global_load_lds_dwordx4 v134, s[48:49]
	s_waitcnt vmcnt(8)
	s_waitcnt lgkmcnt(0)
	s_barrier
	s_setprio 1
	s_waitcnt lgkmcnt(0)
	v_mfma_f32_16x16x32_bf16 v[124:127], v[140:143], v[180:183], v[124:127]
	v_mfma_f32_16x16x32_bf16 v[120:123], v[156:159], v[180:183], v[120:123]
	v_mfma_f32_16x16x32_bf16 v[112:115], v[140:143], v[188:191], v[112:115]
	v_mfma_f32_16x16x32_bf16 v[104:107], v[156:159], v[188:191], v[104:107]
	v_mfma_f32_16x16x32_bf16 v[96:99], v[140:143], v[196:199], v[96:99]
	v_mfma_f32_16x16x32_bf16 v[88:91], v[156:159], v[196:199], v[88:91]
	v_mfma_f32_16x16x32_bf16 v[80:83], v[140:143], v[204:207], v[80:83]
	v_mfma_f32_16x16x32_bf16 v[72:75], v[156:159], v[204:207], v[72:75]
	v_mfma_f32_16x16x32_bf16 v[124:127], v[152:155], v[184:187], v[124:127]
	v_mfma_f32_16x16x32_bf16 v[120:123], v[160:163], v[184:187], v[120:123]
	v_mfma_f32_16x16x32_bf16 v[112:115], v[152:155], v[192:195], v[112:115]
	v_mfma_f32_16x16x32_bf16 v[104:107], v[160:163], v[192:195], v[104:107]
	v_mfma_f32_16x16x32_bf16 v[96:99], v[152:155], v[200:203], v[96:99]
	v_mfma_f32_16x16x32_bf16 v[88:91], v[160:163], v[200:203], v[88:91]
	v_mfma_f32_16x16x32_bf16 v[80:83], v[152:155], v[208:211], v[80:83]
	v_mfma_f32_16x16x32_bf16 v[72:75], v[160:163], v[208:211], v[72:75]
	s_setprio 0
	s_setprio 1
	v_mfma_f32_16x16x32_bf16 v[116:119], v[164:167], v[180:183], v[116:119]
	v_mfma_f32_16x16x32_bf16 v[108:111], v[172:175], v[180:183], v[108:111]
	v_mfma_f32_16x16x32_bf16 v[100:103], v[164:167], v[188:191], v[100:103]
	v_mfma_f32_16x16x32_bf16 v[92:95], v[172:175], v[188:191], v[92:95]
	v_mfma_f32_16x16x32_bf16 v[84:87], v[164:167], v[196:199], v[84:87]
	v_mfma_f32_16x16x32_bf16 v[76:79], v[172:175], v[196:199], v[76:79]
	v_mfma_f32_16x16x32_bf16 v[68:71], v[164:167], v[204:207], v[68:71]
	v_mfma_f32_16x16x32_bf16 v[64:67], v[172:175], v[204:207], v[64:67]
	v_mfma_f32_16x16x32_bf16 v[116:119], v[168:171], v[184:187], v[116:119]
	v_mfma_f32_16x16x32_bf16 v[108:111], v[176:179], v[184:187], v[108:111]
	v_mfma_f32_16x16x32_bf16 v[100:103], v[168:171], v[192:195], v[100:103]
	v_mfma_f32_16x16x32_bf16 v[92:95], v[176:179], v[192:195], v[92:95]
	v_mfma_f32_16x16x32_bf16 v[84:87], v[168:171], v[200:203], v[84:87]
	v_mfma_f32_16x16x32_bf16 v[76:79], v[176:179], v[200:203], v[76:79]
	v_mfma_f32_16x16x32_bf16 v[68:71], v[168:171], v[208:211], v[68:71]
	v_mfma_f32_16x16x32_bf16 v[64:67], v[176:179], v[208:211], v[64:67]
	s_setprio 0
	s_barrier
	s_add_i32 s3, s58, s25
	s_mov_b32 m0, s3
	ds_read_b128 v[180:183], v151 offset:16384
	ds_read_b128 v[184:187], v151 offset:17408
	ds_read_b128 v[188:191], v151 offset:18432
	ds_read_b128 v[192:195], v151 offset:19456
	ds_read_b128 v[196:199], v151 offset:20480
	ds_read_b128 v[200:203], v151 offset:21504
	ds_read_b128 v[204:207], v151 offset:22528
	ds_read_b128 v[208:211], v151 offset:23552
	global_load_lds_dwordx4 v128, s[52:53]
	s_add_i32 m0, s3, 0x2000
	s_add_u32 s66, s52, 0x200000
	s_addc_u32 s67, s53, 0
	s_add_i32 s3, s59, s25
	global_load_lds_dwordx4 v130, s[52:53]
	s_mov_b32 m0, s3
	s_nop 0
	global_load_lds_dwordx4 v128, s[66:67]
	s_add_i32 m0, s3, 0x2000
	s_nop 0
	global_load_lds_dwordx4 v130, s[66:67]
	s_mov_b32 m0, s27
	s_nop 0
	global_load_lds_dwordx4 v128, s[54:55]
	s_mov_b32 m0, s30
	s_nop 0
	global_load_lds_dwordx4 v130, s[54:55]
	s_waitcnt vmcnt(8)
	s_waitcnt lgkmcnt(0)
	s_barrier
	s_setprio 1
	s_waitcnt lgkmcnt(0)
	v_mfma_f32_16x16x32_bf16 v[60:63], v[140:143], v[180:183], v[60:63]
	v_mfma_f32_16x16x32_bf16 v[56:59], v[156:159], v[180:183], v[56:59]
	v_mfma_f32_16x16x32_bf16 v[48:51], v[140:143], v[188:191], v[48:51]
	v_mfma_f32_16x16x32_bf16 v[40:43], v[156:159], v[188:191], v[40:43]
	v_mfma_f32_16x16x32_bf16 v[32:35], v[140:143], v[196:199], v[32:35]
	v_mfma_f32_16x16x32_bf16 v[24:27], v[156:159], v[196:199], v[24:27]
	v_mfma_f32_16x16x32_bf16 v[16:19], v[140:143], v[204:207], v[16:19]
	v_mfma_f32_16x16x32_bf16 v[8:11], v[156:159], v[204:207], v[8:11]
	v_mfma_f32_16x16x32_bf16 v[60:63], v[152:155], v[184:187], v[60:63]
	v_mfma_f32_16x16x32_bf16 v[56:59], v[160:163], v[184:187], v[56:59]
	v_mfma_f32_16x16x32_bf16 v[48:51], v[152:155], v[192:195], v[48:51]
	v_mfma_f32_16x16x32_bf16 v[40:43], v[160:163], v[192:195], v[40:43]
	v_mfma_f32_16x16x32_bf16 v[32:35], v[152:155], v[200:203], v[32:35]
	v_mfma_f32_16x16x32_bf16 v[24:27], v[160:163], v[200:203], v[24:27]
	v_mfma_f32_16x16x32_bf16 v[16:19], v[152:155], v[208:211], v[16:19]
	v_mfma_f32_16x16x32_bf16 v[8:11], v[160:163], v[208:211], v[8:11]
	s_setprio 0
	s_setprio 1
	v_mfma_f32_16x16x32_bf16 v[52:55], v[164:167], v[180:183], v[52:55]
	v_mfma_f32_16x16x32_bf16 v[44:47], v[172:175], v[180:183], v[44:47]
	v_mfma_f32_16x16x32_bf16 v[36:39], v[164:167], v[188:191], v[36:39]
	v_mfma_f32_16x16x32_bf16 v[28:31], v[172:175], v[188:191], v[28:31]
	v_mfma_f32_16x16x32_bf16 v[20:23], v[164:167], v[196:199], v[20:23]
	v_mfma_f32_16x16x32_bf16 v[12:15], v[172:175], v[196:199], v[12:15]
	v_mfma_f32_16x16x32_bf16 v[4:7], v[164:167], v[204:207], v[4:7]
	v_mfma_f32_16x16x32_bf16 v[0:3], v[172:175], v[204:207], v[0:3]
	v_mfma_f32_16x16x32_bf16 v[52:55], v[168:171], v[184:187], v[52:55]
	v_mfma_f32_16x16x32_bf16 v[44:47], v[176:179], v[184:187], v[44:47]
	v_mfma_f32_16x16x32_bf16 v[36:39], v[168:171], v[192:195], v[36:39]
	v_mfma_f32_16x16x32_bf16 v[28:31], v[176:179], v[192:195], v[28:31]
	v_mfma_f32_16x16x32_bf16 v[20:23], v[168:171], v[200:203], v[20:23]
	v_mfma_f32_16x16x32_bf16 v[12:15], v[176:179], v[200:203], v[12:15]
	v_mfma_f32_16x16x32_bf16 v[4:7], v[168:171], v[208:211], v[4:7]
	v_mfma_f32_16x16x32_bf16 v[0:3], v[176:179], v[208:211], v[0:3]
	s_setprio 0
	s_barrier
	s_add_i32 s3, 0, 0x18000
	s_add_i32 s65, 0, 0x1c000
	v_add_u32_e32 v160, s3, v147
	v_add_u32_e32 v176, s65, v147
	ds_read_b128 v[140:143], v160
	ds_read_b128 v[152:155], v160 offset:1024
	ds_read_b128 v[156:159], v160 offset:2048
	ds_read_b128 v[160:163], v160 offset:3072
	ds_read_b128 v[164:167], v176
	ds_read_b128 v[168:171], v176 offset:1024
	ds_read_b128 v[172:175], v176 offset:2048
	ds_read_b128 v[176:179], v176 offset:3072
	s_add_u32 s54, s54, 0x200000
	s_addc_u32 s55, s55, 0
	s_mov_b32 m0, s31
	ds_read_b128 v[180:183], v151 offset:32768
	ds_read_b128 v[184:187], v151 offset:33792
	ds_read_b128 v[188:191], v151 offset:34816
	ds_read_b128 v[192:195], v151 offset:35840
	ds_read_b128 v[196:199], v151 offset:36864
	ds_read_b128 v[200:203], v151 offset:37888
	ds_read_b128 v[204:207], v151 offset:38912
	ds_read_b128 v[208:211], v151 offset:39936
	global_load_lds_dwordx4 v128, s[54:55]
	s_mov_b32 m0, s33
	s_nop 0
	global_load_lds_dwordx4 v130, s[54:55]
	s_waitcnt vmcnt(8)
	s_waitcnt lgkmcnt(0)
	s_barrier
	s_setprio 1
	s_waitcnt lgkmcnt(0)
	v_mfma_f32_16x16x32_bf16 v[124:127], v[140:143], v[180:183], v[124:127]
	v_mfma_f32_16x16x32_bf16 v[120:123], v[156:159], v[180:183], v[120:123]
	v_mfma_f32_16x16x32_bf16 v[112:115], v[140:143], v[188:191], v[112:115]
	v_mfma_f32_16x16x32_bf16 v[104:107], v[156:159], v[188:191], v[104:107]
	v_mfma_f32_16x16x32_bf16 v[96:99], v[140:143], v[196:199], v[96:99]
	v_mfma_f32_16x16x32_bf16 v[88:91], v[156:159], v[196:199], v[88:91]
	v_mfma_f32_16x16x32_bf16 v[80:83], v[140:143], v[204:207], v[80:83]
	v_mfma_f32_16x16x32_bf16 v[72:75], v[156:159], v[204:207], v[72:75]
	v_mfma_f32_16x16x32_bf16 v[124:127], v[152:155], v[184:187], v[124:127]
	v_mfma_f32_16x16x32_bf16 v[120:123], v[160:163], v[184:187], v[120:123]
	v_mfma_f32_16x16x32_bf16 v[112:115], v[152:155], v[192:195], v[112:115]
	v_mfma_f32_16x16x32_bf16 v[104:107], v[160:163], v[192:195], v[104:107]
	v_mfma_f32_16x16x32_bf16 v[96:99], v[152:155], v[200:203], v[96:99]
	v_mfma_f32_16x16x32_bf16 v[88:91], v[160:163], v[200:203], v[88:91]
	v_mfma_f32_16x16x32_bf16 v[80:83], v[152:155], v[208:211], v[80:83]
	v_mfma_f32_16x16x32_bf16 v[72:75], v[160:163], v[208:211], v[72:75]
	s_setprio 0
	s_setprio 1
	v_mfma_f32_16x16x32_bf16 v[116:119], v[164:167], v[180:183], v[116:119]
	v_mfma_f32_16x16x32_bf16 v[108:111], v[172:175], v[180:183], v[108:111]
	v_mfma_f32_16x16x32_bf16 v[100:103], v[164:167], v[188:191], v[100:103]
	v_mfma_f32_16x16x32_bf16 v[92:95], v[172:175], v[188:191], v[92:95]
	v_mfma_f32_16x16x32_bf16 v[84:87], v[164:167], v[196:199], v[84:87]
	v_mfma_f32_16x16x32_bf16 v[76:79], v[172:175], v[196:199], v[76:79]
	v_mfma_f32_16x16x32_bf16 v[68:71], v[164:167], v[204:207], v[68:71]
	v_mfma_f32_16x16x32_bf16 v[64:67], v[172:175], v[204:207], v[64:67]
	v_mfma_f32_16x16x32_bf16 v[116:119], v[168:171], v[184:187], v[116:119]
	v_mfma_f32_16x16x32_bf16 v[108:111], v[176:179], v[184:187], v[108:111]
	v_mfma_f32_16x16x32_bf16 v[100:103], v[168:171], v[192:195], v[100:103]
	v_mfma_f32_16x16x32_bf16 v[92:95], v[176:179], v[192:195], v[92:95]
	v_mfma_f32_16x16x32_bf16 v[84:87], v[168:171], v[200:203], v[84:87]
	v_mfma_f32_16x16x32_bf16 v[76:79], v[176:179], v[200:203], v[76:79]
	v_mfma_f32_16x16x32_bf16 v[68:71], v[168:171], v[208:211], v[68:71]
	v_mfma_f32_16x16x32_bf16 v[64:67], v[176:179], v[208:211], v[64:67]
	s_setprio 0
	s_barrier
	s_add_i32 s3, s3, s25
	s_add_u32 s52, s52, 0x80
	s_addc_u32 s53, s53, 0
	s_mov_b32 m0, s3
	ds_read_b128 v[180:183], v151 offset:49152
	ds_read_b128 v[184:187], v151 offset:50176
	ds_read_b128 v[188:191], v151 offset:51200
	ds_read_b128 v[192:195], v151 offset:52224
	ds_read_b128 v[196:199], v151 offset:53248
	ds_read_b128 v[200:203], v151 offset:54272
	ds_read_b128 v[204:207], v151 offset:55296
	ds_read_b128 v[208:211], v151 offset:56320
	global_load_lds_dwordx4 v128, s[52:53]
	s_add_i32 m0, s3, 0x2000
	s_add_i32 s3, s65, s25
	global_load_lds_dwordx4 v130, s[52:53]
	s_add_u32 s52, s52, 0x200000
	s_addc_u32 s53, s53, 0
	s_mov_b32 m0, s3
	s_nop 0
	global_load_lds_dwordx4 v128, s[52:53]
	s_add_i32 m0, s3, 0x2000
	s_nop 0
	global_load_lds_dwordx4 v130, s[52:53]
	s_add_u32 s54, s54, 0xffe00080
	s_addc_u32 s55, s55, -1
	s_mov_b32 m0, s56
	s_nop 0
	global_load_lds_dwordx4 v128, s[54:55]
	s_mov_b32 m0, s57
	s_nop 0
	global_load_lds_dwordx4 v130, s[54:55]
	s_waitcnt vmcnt(8)
	s_waitcnt lgkmcnt(0)
	s_barrier
	s_setprio 1
	s_waitcnt lgkmcnt(0)
	v_mfma_f32_16x16x32_bf16 v[60:63], v[140:143], v[180:183], v[60:63]
	v_mfma_f32_16x16x32_bf16 v[56:59], v[156:159], v[180:183], v[56:59]
	v_mfma_f32_16x16x32_bf16 v[48:51], v[140:143], v[188:191], v[48:51]
	v_mfma_f32_16x16x32_bf16 v[40:43], v[156:159], v[188:191], v[40:43]
	v_mfma_f32_16x16x32_bf16 v[32:35], v[140:143], v[196:199], v[32:35]
	v_mfma_f32_16x16x32_bf16 v[24:27], v[156:159], v[196:199], v[24:27]
	v_mfma_f32_16x16x32_bf16 v[16:19], v[140:143], v[204:207], v[16:19]
	v_mfma_f32_16x16x32_bf16 v[8:11], v[156:159], v[204:207], v[8:11]
	v_mfma_f32_16x16x32_bf16 v[60:63], v[152:155], v[184:187], v[60:63]
	v_mfma_f32_16x16x32_bf16 v[56:59], v[160:163], v[184:187], v[56:59]
	v_mfma_f32_16x16x32_bf16 v[48:51], v[152:155], v[192:195], v[48:51]
	v_mfma_f32_16x16x32_bf16 v[40:43], v[160:163], v[192:195], v[40:43]
	v_mfma_f32_16x16x32_bf16 v[32:35], v[152:155], v[200:203], v[32:35]
	v_mfma_f32_16x16x32_bf16 v[24:27], v[160:163], v[200:203], v[24:27]
	v_mfma_f32_16x16x32_bf16 v[16:19], v[152:155], v[208:211], v[16:19]
	v_mfma_f32_16x16x32_bf16 v[8:11], v[160:163], v[208:211], v[8:11]
	s_setprio 0
	s_setprio 1
	v_mfma_f32_16x16x32_bf16 v[52:55], v[164:167], v[180:183], v[52:55]
	v_mfma_f32_16x16x32_bf16 v[44:47], v[172:175], v[180:183], v[44:47]
	v_mfma_f32_16x16x32_bf16 v[36:39], v[164:167], v[188:191], v[36:39]
	v_mfma_f32_16x16x32_bf16 v[28:31], v[172:175], v[188:191], v[28:31]
	v_mfma_f32_16x16x32_bf16 v[20:23], v[164:167], v[196:199], v[20:23]
	v_mfma_f32_16x16x32_bf16 v[12:15], v[172:175], v[196:199], v[12:15]
	v_mfma_f32_16x16x32_bf16 v[4:7], v[164:167], v[204:207], v[4:7]
	v_mfma_f32_16x16x32_bf16 v[0:3], v[172:175], v[204:207], v[0:3]
	v_mfma_f32_16x16x32_bf16 v[52:55], v[168:171], v[184:187], v[52:55]
	v_mfma_f32_16x16x32_bf16 v[44:47], v[176:179], v[184:187], v[44:47]
	v_mfma_f32_16x16x32_bf16 v[36:39], v[168:171], v[192:195], v[36:39]
	v_mfma_f32_16x16x32_bf16 v[28:31], v[176:179], v[192:195], v[28:31]
	v_mfma_f32_16x16x32_bf16 v[20:23], v[168:171], v[200:203], v[20:23]
	v_mfma_f32_16x16x32_bf16 v[12:15], v[176:179], v[200:203], v[12:15]
	v_mfma_f32_16x16x32_bf16 v[4:7], v[168:171], v[208:211], v[4:7]
	v_mfma_f32_16x16x32_bf16 v[0:3], v[176:179], v[208:211], v[0:3]
	s_setprio 0
	s_barrier
	s_add_i32 s64, s64, 2
	s_add_u32 s48, s48, 0x100
	s_addc_u32 s49, s49, 0
	s_add_u32 s50, s50, 0x100
	s_addc_u32 s51, s51, 0
	s_cmpk_gt_u32 s64, 0x7d
	s_cbranch_scc0 .LBB0_2555
	s_and_b64 vcc, exec, s[10:11]
	s_cbranch_vccz .LBB0_2558
	s_barrier
